# K-loop: remaining LDS-DMA address adds removed (saddr form + instruction offset 128 with M0-128, A pointer copy in s[98:99])
# baseline (speedup 1.0000x reference)
.LBB0_410:
	ds_read_b128 v[154:157], v149
	ds_read_b128 v[158:161], v149 offset:1024
	ds_read_b128 v[162:165], v149 offset:2048
	ds_read_b128 v[166:169], v149 offset:3072
	ds_read_b128 v[170:173], v150
	ds_read_b128 v[174:177], v150 offset:1024
	ds_read_b128 v[178:181], v150 offset:2048
	ds_read_b128 v[182:185], v150 offset:3072
	s_add_u32 s30, s28, 0xfffc0080
	s_addc_u32 s31, s29, -1
	s_cmp_eq_u32 s71, 12
	s_cselect_b32 s35, s21, s31
	s_cselect_b32 s34, s61, s30
	s_cselect_b32 s31, s19, s70
	s_cselect_b32 s30, s62, s63
	s_add_i32 m0, s27, 0xc000
	ds_read_b128 v[186:189], v151
	ds_read_b128 v[190:193], v151 offset:1024
	ds_read_b128 v[196:199], v151 offset:2048
	ds_read_b128 v[200:203], v151 offset:3072
	ds_read_b128 v[204:207], v151 offset:4096
	ds_read_b128 v[208:211], v151 offset:5120
	ds_read_b128 v[212:215], v151 offset:6144
	ds_read_b128 v[216:219], v151 offset:7168
	global_load_lds_dwordx4 v136, s[28:29]
	s_add_i32 m0, s27, 0xe000
	s_nop 0
	global_load_lds_dwordx4 v138, s[28:29]
	s_waitcnt vmcnt(8)
	s_waitcnt lgkmcnt(0)
	s_barrier
	s_setprio 1
	s_waitcnt lgkmcnt(0)
	v_mfma_f32_16x16x32_bf16 v[116:119], v[154:157], v[186:189], v[116:119]
	v_mfma_f32_16x16x32_bf16 v[112:115], v[162:165], v[186:189], v[112:115]
	v_mfma_f32_16x16x32_bf16 v[100:103], v[154:157], v[196:199], v[100:103]
	v_mfma_f32_16x16x32_bf16 v[96:99], v[162:165], v[196:199], v[96:99]
	v_mfma_f32_16x16x32_bf16 v[84:87], v[154:157], v[204:207], v[84:87]
	v_mfma_f32_16x16x32_bf16 v[80:83], v[162:165], v[204:207], v[80:83]
	v_mfma_f32_16x16x32_bf16 v[68:71], v[154:157], v[212:215], v[68:71]
	v_mfma_f32_16x16x32_bf16 v[64:67], v[162:165], v[212:215], v[64:67]
	v_mfma_f32_16x16x32_bf16 v[116:119], v[158:161], v[190:193], v[116:119]
	v_mfma_f32_16x16x32_bf16 v[112:115], v[166:169], v[190:193], v[112:115]
	v_mfma_f32_16x16x32_bf16 v[100:103], v[158:161], v[200:203], v[100:103]
	v_mfma_f32_16x16x32_bf16 v[96:99], v[166:169], v[200:203], v[96:99]
	v_mfma_f32_16x16x32_bf16 v[84:87], v[158:161], v[208:211], v[84:87]
	v_mfma_f32_16x16x32_bf16 v[80:83], v[166:169], v[208:211], v[80:83]
	v_mfma_f32_16x16x32_bf16 v[68:71], v[158:161], v[216:219], v[68:71]
	v_mfma_f32_16x16x32_bf16 v[64:67], v[166:169], v[216:219], v[64:67]
	s_setprio 0
	s_setprio 1
	v_mfma_f32_16x16x32_bf16 v[124:127], v[170:173], v[186:189], v[124:127]
	v_mfma_f32_16x16x32_bf16 v[120:123], v[178:181], v[186:189], v[120:123]
	v_mfma_f32_16x16x32_bf16 v[108:111], v[170:173], v[196:199], v[108:111]
	v_mfma_f32_16x16x32_bf16 v[104:107], v[178:181], v[196:199], v[104:107]
	v_mfma_f32_16x16x32_bf16 v[92:95], v[170:173], v[204:207], v[92:95]
	v_mfma_f32_16x16x32_bf16 v[88:91], v[178:181], v[204:207], v[88:91]
	v_mfma_f32_16x16x32_bf16 v[76:79], v[170:173], v[212:215], v[76:79]
	v_mfma_f32_16x16x32_bf16 v[72:75], v[178:181], v[212:215], v[72:75]
	v_mfma_f32_16x16x32_bf16 v[124:127], v[174:177], v[190:193], v[124:127]
	v_mfma_f32_16x16x32_bf16 v[120:123], v[182:185], v[190:193], v[120:123]
	v_mfma_f32_16x16x32_bf16 v[108:111], v[174:177], v[200:203], v[108:111]
	v_mfma_f32_16x16x32_bf16 v[104:107], v[182:185], v[200:203], v[104:107]
	v_mfma_f32_16x16x32_bf16 v[92:95], v[174:177], v[208:211], v[92:95]
	v_mfma_f32_16x16x32_bf16 v[88:91], v[182:185], v[208:211], v[88:91]
	v_mfma_f32_16x16x32_bf16 v[76:79], v[174:177], v[216:219], v[76:79]
	v_mfma_f32_16x16x32_bf16 v[72:75], v[182:185], v[216:219], v[72:75]
	s_setprio 0
	s_barrier
	s_add_i32 s72, s54, s41
	s_mov_b32 m0, s72
	ds_read_b128 v[186:189], v151 offset:16384
	ds_read_b128 v[190:193], v151 offset:17408
	ds_read_b128 v[196:199], v151 offset:18432
	ds_read_b128 v[200:203], v151 offset:19456
	ds_read_b128 v[204:207], v151 offset:20480
	ds_read_b128 v[208:211], v151 offset:21504
	ds_read_b128 v[212:215], v151 offset:22528
	ds_read_b128 v[216:219], v151 offset:23552
	global_load_lds_dwordx4 v132, s[30:31]
	s_add_i32 m0, s72, 0x2000
	s_add_u32 s72, s30, 0x40000
	s_addc_u32 s73, s31, 0
	s_add_i32 s77, s55, s41
	global_load_lds_dwordx4 v128, s[30:31]
	s_mov_b32 m0, s77
	s_mov_b64 s[98:99], s[34:35]
	global_load_lds_dwordx4 v132, s[72:73]
	s_add_i32 m0, s77, 0x2000
	s_nop 0
	global_load_lds_dwordx4 v128, s[72:73]
	s_waitcnt vmcnt(6)
	s_waitcnt lgkmcnt(0)
	s_barrier
	s_setprio 1
	s_waitcnt lgkmcnt(0)
	v_mfma_f32_16x16x32_bf16 v[52:55], v[154:157], v[186:189], v[52:55]
	v_mfma_f32_16x16x32_bf16 v[48:51], v[162:165], v[186:189], v[48:51]
	v_mfma_f32_16x16x32_bf16 v[36:39], v[154:157], v[196:199], v[36:39]
	v_mfma_f32_16x16x32_bf16 v[32:35], v[162:165], v[196:199], v[32:35]
	v_mfma_f32_16x16x32_bf16 v[20:23], v[154:157], v[204:207], v[20:23]
	v_mfma_f32_16x16x32_bf16 v[16:19], v[162:165], v[204:207], v[16:19]
	v_mfma_f32_16x16x32_bf16 v[4:7], v[154:157], v[212:215], v[4:7]
	v_mfma_f32_16x16x32_bf16 v[0:3], v[162:165], v[212:215], v[0:3]
	v_mfma_f32_16x16x32_bf16 v[52:55], v[158:161], v[190:193], v[52:55]
	v_mfma_f32_16x16x32_bf16 v[48:51], v[166:169], v[190:193], v[48:51]
	v_mfma_f32_16x16x32_bf16 v[36:39], v[158:161], v[200:203], v[36:39]
	v_mfma_f32_16x16x32_bf16 v[32:35], v[166:169], v[200:203], v[32:35]
	v_mfma_f32_16x16x32_bf16 v[20:23], v[158:161], v[208:211], v[20:23]
	v_mfma_f32_16x16x32_bf16 v[16:19], v[166:169], v[208:211], v[16:19]
	v_mfma_f32_16x16x32_bf16 v[4:7], v[158:161], v[216:219], v[4:7]
	v_mfma_f32_16x16x32_bf16 v[0:3], v[166:169], v[216:219], v[0:3]
	s_setprio 0
	s_setprio 1
	v_mfma_f32_16x16x32_bf16 v[60:63], v[170:173], v[186:189], v[60:63]
	v_mfma_f32_16x16x32_bf16 v[56:59], v[178:181], v[186:189], v[56:59]
	v_mfma_f32_16x16x32_bf16 v[44:47], v[170:173], v[196:199], v[44:47]
	v_mfma_f32_16x16x32_bf16 v[40:43], v[178:181], v[196:199], v[40:43]
	v_mfma_f32_16x16x32_bf16 v[28:31], v[170:173], v[204:207], v[28:31]
	v_mfma_f32_16x16x32_bf16 v[24:27], v[178:181], v[204:207], v[24:27]
	v_mfma_f32_16x16x32_bf16 v[12:15], v[170:173], v[212:215], v[12:15]
	v_mfma_f32_16x16x32_bf16 v[8:11], v[178:181], v[212:215], v[8:11]
	v_mfma_f32_16x16x32_bf16 v[60:63], v[174:177], v[190:193], v[60:63]
	v_mfma_f32_16x16x32_bf16 v[56:59], v[182:185], v[190:193], v[56:59]
	v_mfma_f32_16x16x32_bf16 v[44:47], v[174:177], v[200:203], v[44:47]
	v_mfma_f32_16x16x32_bf16 v[40:43], v[182:185], v[200:203], v[40:43]
	v_mfma_f32_16x16x32_bf16 v[28:31], v[174:177], v[208:211], v[28:31]
	v_mfma_f32_16x16x32_bf16 v[24:27], v[182:185], v[208:211], v[24:27]
	v_mfma_f32_16x16x32_bf16 v[12:15], v[174:177], v[216:219], v[12:15]
	v_mfma_f32_16x16x32_bf16 v[8:11], v[182:185], v[216:219], v[8:11]
	s_setprio 0
	s_barrier
	s_add_i32 s72, 0, 0x18000
	v_add_u32_e32 v153, s72, v147
	s_add_i32 s73, 0, 0x1c000
	ds_read_b128 v[154:157], v153
	ds_read_b128 v[158:161], v153 offset:1024
	ds_read_b128 v[162:165], v153 offset:2048
	ds_read_b128 v[166:169], v153 offset:3072
	v_add_u32_e32 v153, s73, v147
	ds_read_b128 v[170:173], v153
	ds_read_b128 v[174:177], v153 offset:1024
	ds_read_b128 v[178:181], v153 offset:2048
	ds_read_b128 v[182:185], v153 offset:3072
	s_add_u32 s34, s34, 0x40000
	s_addc_u32 s35, s35, 0
	ds_read_b128 v[186:189], v151 offset:32768
	ds_read_b128 v[190:193], v151 offset:33792
	ds_read_b128 v[196:199], v151 offset:34816
	ds_read_b128 v[200:203], v151 offset:35840
	ds_read_b128 v[204:207], v151 offset:36864
	ds_read_b128 v[208:211], v151 offset:37888
	ds_read_b128 v[212:215], v151 offset:38912
	ds_read_b128 v[216:219], v151 offset:39936
	s_mov_b32 m0, s27
	s_nop 0
	global_load_lds_dwordx4 v134, s[98:99]
	s_mov_b32 m0, s43
	s_nop 0
	global_load_lds_dwordx4 v130, s[98:99]
	s_mov_b32 m0, s44
	s_nop 0
	global_load_lds_dwordx4 v134, s[34:35]
	s_mov_b32 m0, s45
	s_nop 0
	global_load_lds_dwordx4 v130, s[34:35]
	s_waitcnt vmcnt(8)
	s_waitcnt lgkmcnt(0)
	s_barrier
	s_setprio 1
	s_waitcnt lgkmcnt(0)
	v_mfma_f32_16x16x32_bf16 v[116:119], v[154:157], v[186:189], v[116:119]
	v_mfma_f32_16x16x32_bf16 v[112:115], v[162:165], v[186:189], v[112:115]
	v_mfma_f32_16x16x32_bf16 v[100:103], v[154:157], v[196:199], v[100:103]
	v_mfma_f32_16x16x32_bf16 v[96:99], v[162:165], v[196:199], v[96:99]
	v_mfma_f32_16x16x32_bf16 v[84:87], v[154:157], v[204:207], v[84:87]
	v_mfma_f32_16x16x32_bf16 v[80:83], v[162:165], v[204:207], v[80:83]
	v_mfma_f32_16x16x32_bf16 v[68:71], v[154:157], v[212:215], v[68:71]
	v_mfma_f32_16x16x32_bf16 v[64:67], v[162:165], v[212:215], v[64:67]
	v_mfma_f32_16x16x32_bf16 v[116:119], v[158:161], v[190:193], v[116:119]
	v_mfma_f32_16x16x32_bf16 v[112:115], v[166:169], v[190:193], v[112:115]
	v_mfma_f32_16x16x32_bf16 v[100:103], v[158:161], v[200:203], v[100:103]
	v_mfma_f32_16x16x32_bf16 v[96:99], v[166:169], v[200:203], v[96:99]
	v_mfma_f32_16x16x32_bf16 v[84:87], v[158:161], v[208:211], v[84:87]
	v_mfma_f32_16x16x32_bf16 v[80:83], v[166:169], v[208:211], v[80:83]
	v_mfma_f32_16x16x32_bf16 v[68:71], v[158:161], v[216:219], v[68:71]
	v_mfma_f32_16x16x32_bf16 v[64:67], v[166:169], v[216:219], v[64:67]
	s_setprio 0
	s_setprio 1
	v_mfma_f32_16x16x32_bf16 v[124:127], v[170:173], v[186:189], v[124:127]
	v_mfma_f32_16x16x32_bf16 v[120:123], v[178:181], v[186:189], v[120:123]
	v_mfma_f32_16x16x32_bf16 v[108:111], v[170:173], v[196:199], v[108:111]
	v_mfma_f32_16x16x32_bf16 v[104:107], v[178:181], v[196:199], v[104:107]
	v_mfma_f32_16x16x32_bf16 v[92:95], v[170:173], v[204:207], v[92:95]
	v_mfma_f32_16x16x32_bf16 v[88:91], v[178:181], v[204:207], v[88:91]
	v_mfma_f32_16x16x32_bf16 v[76:79], v[170:173], v[212:215], v[76:79]
	v_mfma_f32_16x16x32_bf16 v[72:75], v[178:181], v[212:215], v[72:75]
	v_mfma_f32_16x16x32_bf16 v[124:127], v[174:177], v[190:193], v[124:127]
	v_mfma_f32_16x16x32_bf16 v[120:123], v[182:185], v[190:193], v[120:123]
	v_mfma_f32_16x16x32_bf16 v[108:111], v[174:177], v[200:203], v[108:111]
	v_mfma_f32_16x16x32_bf16 v[104:107], v[182:185], v[200:203], v[104:107]
	v_mfma_f32_16x16x32_bf16 v[92:95], v[174:177], v[208:211], v[92:95]
	v_mfma_f32_16x16x32_bf16 v[88:91], v[182:185], v[208:211], v[88:91]
	v_mfma_f32_16x16x32_bf16 v[76:79], v[174:177], v[216:219], v[76:79]
	v_mfma_f32_16x16x32_bf16 v[72:75], v[182:185], v[216:219], v[72:75]
	s_setprio 0
	s_barrier
	s_add_i32 s34, s72, s41
	s_add_i32 m0, s34, 0xffffff80
	ds_read_b128 v[186:189], v151 offset:49152
	ds_read_b128 v[190:193], v151 offset:50176
	ds_read_b128 v[196:199], v151 offset:51200
	ds_read_b128 v[200:203], v151 offset:52224
	ds_read_b128 v[204:207], v151 offset:53248
	ds_read_b128 v[208:211], v151 offset:54272
	ds_read_b128 v[212:215], v151 offset:55296
	ds_read_b128 v[216:219], v151 offset:56320
	global_load_lds_dwordx4 v132, s[30:31] offset:128
	s_add_i32 m0, s34, 0x1f80
	s_add_i32 s34, s73, s41
	global_load_lds_dwordx4 v128, s[30:31] offset:128
	s_add_u32 s30, s30, 0x40080
	s_addc_u32 s31, s31, 0
	s_mov_b32 m0, s34
	s_nop 0
	global_load_lds_dwordx4 v132, s[30:31]
	s_add_i32 m0, s34, 0x2000
	s_nop 0
	global_load_lds_dwordx4 v128, s[30:31]
	s_waitcnt vmcnt(6)
	s_waitcnt lgkmcnt(0)
	s_barrier
	s_setprio 1
	s_waitcnt lgkmcnt(0)
	v_mfma_f32_16x16x32_bf16 v[52:55], v[154:157], v[186:189], v[52:55]
	v_mfma_f32_16x16x32_bf16 v[48:51], v[162:165], v[186:189], v[48:51]
	v_mfma_f32_16x16x32_bf16 v[36:39], v[154:157], v[196:199], v[36:39]
	v_mfma_f32_16x16x32_bf16 v[32:35], v[162:165], v[196:199], v[32:35]
	v_mfma_f32_16x16x32_bf16 v[20:23], v[154:157], v[204:207], v[20:23]
	v_mfma_f32_16x16x32_bf16 v[16:19], v[162:165], v[204:207], v[16:19]
	v_mfma_f32_16x16x32_bf16 v[4:7], v[154:157], v[212:215], v[4:7]
	v_mfma_f32_16x16x32_bf16 v[0:3], v[162:165], v[212:215], v[0:3]
	v_mfma_f32_16x16x32_bf16 v[52:55], v[158:161], v[190:193], v[52:55]
	v_mfma_f32_16x16x32_bf16 v[48:51], v[166:169], v[190:193], v[48:51]
	v_mfma_f32_16x16x32_bf16 v[36:39], v[158:161], v[200:203], v[36:39]
	v_mfma_f32_16x16x32_bf16 v[32:35], v[166:169], v[200:203], v[32:35]
	v_mfma_f32_16x16x32_bf16 v[20:23], v[158:161], v[208:211], v[20:23]
	v_mfma_f32_16x16x32_bf16 v[16:19], v[166:169], v[208:211], v[16:19]
	v_mfma_f32_16x16x32_bf16 v[4:7], v[158:161], v[216:219], v[4:7]
	v_mfma_f32_16x16x32_bf16 v[0:3], v[166:169], v[216:219], v[0:3]
	s_setprio 0
	s_setprio 1
	v_mfma_f32_16x16x32_bf16 v[60:63], v[170:173], v[186:189], v[60:63]
	v_mfma_f32_16x16x32_bf16 v[56:59], v[178:181], v[186:189], v[56:59]
	v_mfma_f32_16x16x32_bf16 v[44:47], v[170:173], v[196:199], v[44:47]
	v_mfma_f32_16x16x32_bf16 v[40:43], v[178:181], v[196:199], v[40:43]
	v_mfma_f32_16x16x32_bf16 v[28:31], v[170:173], v[204:207], v[28:31]
	v_mfma_f32_16x16x32_bf16 v[24:27], v[178:181], v[204:207], v[24:27]
	v_mfma_f32_16x16x32_bf16 v[12:15], v[170:173], v[212:215], v[12:15]
	v_mfma_f32_16x16x32_bf16 v[8:11], v[178:181], v[212:215], v[8:11]
	v_mfma_f32_16x16x32_bf16 v[60:63], v[174:177], v[190:193], v[60:63]
	v_mfma_f32_16x16x32_bf16 v[56:59], v[182:185], v[190:193], v[56:59]
	v_mfma_f32_16x16x32_bf16 v[44:47], v[174:177], v[200:203], v[44:47]
	v_mfma_f32_16x16x32_bf16 v[40:43], v[182:185], v[200:203], v[40:43]
	v_mfma_f32_16x16x32_bf16 v[28:31], v[174:177], v[208:211], v[28:31]
	v_mfma_f32_16x16x32_bf16 v[24:27], v[182:185], v[208:211], v[24:27]
	v_mfma_f32_16x16x32_bf16 v[12:15], v[174:177], v[216:219], v[12:15]
	v_mfma_f32_16x16x32_bf16 v[8:11], v[182:185], v[216:219], v[8:11]
	s_setprio 0
	s_barrier
	s_add_i32 m0, s51, 0xffffff80
	s_nop 0
	global_load_lds_dwordx4 v134, s[98:99] offset:128
	s_add_i32 m0, s52, 0xffffff80
	s_nop 0
	global_load_lds_dwordx4 v130, s[98:99] offset:128
	s_add_i32 s71, s71, 2
	s_add_u32 s28, s28, 0x100
	s_addc_u32 s29, s29, 0
	s_add_u32 s63, s63, 0x100
	s_addc_u32 s70, s70, 0
	s_cmp_gt_u32 s71, 13
	s_cbranch_scc0 .LBB0_410
	s_and_b64 vcc, exec, s[16:17]
	s_cbranch_vccz .LBB0_413
	s_barrier

.LBB0_532:
	ds_read_b128 v[146:149], v155
	ds_read_b128 v[160:163], v155 offset:1024
	ds_read_b128 v[164:167], v155 offset:2048
	ds_read_b128 v[168:171], v155 offset:3072
	ds_read_b128 v[172:175], v156
	ds_read_b128 v[176:179], v156 offset:1024
	ds_read_b128 v[180:183], v156 offset:2048
	ds_read_b128 v[184:187], v156 offset:3072
	s_add_u32 s30, s28, 0x100
	s_addc_u32 s31, s29, 0
	s_cmp_eq_u32 s77, 40
	s_cselect_b32 s37, s1, s31
	s_cselect_b32 s36, s0, s30
	s_cselect_b32 s35, s27, s73
	s_cselect_b32 s34, s26, s72
	v_lshl_add_u64 v[150:151], s[28:29], 0, v[138:139]
	s_add_i32 m0, s44, 0xc000
	ds_read_b128 v[188:191], v157
	ds_read_b128 v[196:199], v157 offset:1024
	ds_read_b128 v[200:203], v157 offset:2048
	ds_read_b128 v[204:207], v157 offset:3072
	ds_read_b128 v[208:211], v157 offset:4096
	ds_read_b128 v[212:215], v157 offset:5120
	ds_read_b128 v[216:219], v157 offset:6144
	ds_read_b128 v[220:223], v157 offset:7168
	global_load_lds_dwordx4 v[150:151], off
	v_lshl_add_u64 v[150:151], s[28:29], 0, v[140:141]
	s_add_i32 m0, s44, 0xe000
	s_nop 0
	global_load_lds_dwordx4 v[150:151], off
	s_waitcnt vmcnt(8)
	s_waitcnt lgkmcnt(0)
	s_barrier
	s_setprio 1
	s_waitcnt lgkmcnt(0)
	v_mfma_f32_16x16x32_bf16 v[124:127], v[146:149], v[188:191], v[124:127]
	v_mfma_f32_16x16x32_bf16 v[120:123], v[164:167], v[188:191], v[120:123]
	v_mfma_f32_16x16x32_bf16 v[108:111], v[146:149], v[200:203], v[108:111]
	v_mfma_f32_16x16x32_bf16 v[104:107], v[164:167], v[200:203], v[104:107]
	v_mfma_f32_16x16x32_bf16 v[92:95], v[146:149], v[208:211], v[92:95]
	v_mfma_f32_16x16x32_bf16 v[88:91], v[164:167], v[208:211], v[88:91]
	v_mfma_f32_16x16x32_bf16 v[76:79], v[146:149], v[216:219], v[76:79]
	v_mfma_f32_16x16x32_bf16 v[72:75], v[164:167], v[216:219], v[72:75]
	v_mfma_f32_16x16x32_bf16 v[124:127], v[160:163], v[196:199], v[124:127]
	v_mfma_f32_16x16x32_bf16 v[120:123], v[168:171], v[196:199], v[120:123]
	v_mfma_f32_16x16x32_bf16 v[108:111], v[160:163], v[204:207], v[108:111]
	v_mfma_f32_16x16x32_bf16 v[104:107], v[168:171], v[204:207], v[104:107]
	v_mfma_f32_16x16x32_bf16 v[92:95], v[160:163], v[212:215], v[92:95]
	v_mfma_f32_16x16x32_bf16 v[88:91], v[168:171], v[212:215], v[88:91]
	v_mfma_f32_16x16x32_bf16 v[76:79], v[160:163], v[220:223], v[76:79]
	v_mfma_f32_16x16x32_bf16 v[72:75], v[168:171], v[220:223], v[72:75]
	s_setprio 0
	s_setprio 1
	v_mfma_f32_16x16x32_bf16 v[116:119], v[172:175], v[188:191], v[116:119]
	v_mfma_f32_16x16x32_bf16 v[112:115], v[180:183], v[188:191], v[112:115]
	v_mfma_f32_16x16x32_bf16 v[100:103], v[172:175], v[200:203], v[100:103]
	v_mfma_f32_16x16x32_bf16 v[96:99], v[180:183], v[200:203], v[96:99]
	v_mfma_f32_16x16x32_bf16 v[84:87], v[172:175], v[208:211], v[84:87]
	v_mfma_f32_16x16x32_bf16 v[80:83], v[180:183], v[208:211], v[80:83]
	v_mfma_f32_16x16x32_bf16 v[68:71], v[172:175], v[216:219], v[68:71]
	v_mfma_f32_16x16x32_bf16 v[64:67], v[180:183], v[216:219], v[64:67]
	v_mfma_f32_16x16x32_bf16 v[116:119], v[176:179], v[196:199], v[116:119]
	v_mfma_f32_16x16x32_bf16 v[112:115], v[184:187], v[196:199], v[112:115]
	v_mfma_f32_16x16x32_bf16 v[100:103], v[176:179], v[204:207], v[100:103]
	v_mfma_f32_16x16x32_bf16 v[96:99], v[184:187], v[204:207], v[96:99]
	v_mfma_f32_16x16x32_bf16 v[84:87], v[176:179], v[212:215], v[84:87]
	v_mfma_f32_16x16x32_bf16 v[80:83], v[184:187], v[212:215], v[80:83]
	v_mfma_f32_16x16x32_bf16 v[68:71], v[176:179], v[220:223], v[68:71]
	v_mfma_f32_16x16x32_bf16 v[64:67], v[184:187], v[220:223], v[64:67]
	s_setprio 0
	s_barrier
	s_add_i32 s28, s60, s43
	v_lshl_add_u64 v[150:151], s[34:35], 0, v[132:133]
	s_mov_b32 m0, s28
	ds_read_b128 v[188:191], v157 offset:16384
	ds_read_b128 v[196:199], v157 offset:17408
	ds_read_b128 v[200:203], v157 offset:18432
	ds_read_b128 v[204:207], v157 offset:19456
	ds_read_b128 v[208:211], v157 offset:20480
	ds_read_b128 v[212:215], v157 offset:21504
	ds_read_b128 v[216:219], v157 offset:22528
	ds_read_b128 v[220:223], v157 offset:23552
	global_load_lds_dwordx4 v[150:151], off
	s_add_i32 m0, s28, 0x2000
	s_add_u32 s28, s34, 0xb0000
	v_lshl_add_u64 v[192:193], s[34:35], 0, v[136:137]
	s_addc_u32 s29, s35, 0
	s_add_i32 s78, s61, s43
	global_load_lds_dwordx4 v[192:193], off
	s_mov_b32 m0, s78
	s_mov_b64 s[98:99], s[36:37]
	global_load_lds_dwordx4 v132, s[28:29]
	s_add_i32 m0, s78, 0x2000
	s_nop 0
	global_load_lds_dwordx4 v136, s[28:29]
	s_waitcnt vmcnt(6)
	s_waitcnt lgkmcnt(0)
	s_barrier
	s_setprio 1
	s_waitcnt lgkmcnt(0)
	v_mfma_f32_16x16x32_bf16 v[60:63], v[146:149], v[188:191], v[60:63]
	v_mfma_f32_16x16x32_bf16 v[56:59], v[164:167], v[188:191], v[56:59]
	v_mfma_f32_16x16x32_bf16 v[44:47], v[146:149], v[200:203], v[44:47]
	v_mfma_f32_16x16x32_bf16 v[40:43], v[164:167], v[200:203], v[40:43]
	v_mfma_f32_16x16x32_bf16 v[28:31], v[146:149], v[208:211], v[28:31]
	v_mfma_f32_16x16x32_bf16 v[24:27], v[164:167], v[208:211], v[24:27]
	v_mfma_f32_16x16x32_bf16 v[12:15], v[146:149], v[216:219], v[12:15]
	v_mfma_f32_16x16x32_bf16 v[8:11], v[164:167], v[216:219], v[8:11]
	v_mfma_f32_16x16x32_bf16 v[60:63], v[160:163], v[196:199], v[60:63]
	v_mfma_f32_16x16x32_bf16 v[56:59], v[168:171], v[196:199], v[56:59]
	v_mfma_f32_16x16x32_bf16 v[44:47], v[160:163], v[204:207], v[44:47]
	v_mfma_f32_16x16x32_bf16 v[40:43], v[168:171], v[204:207], v[40:43]
	v_mfma_f32_16x16x32_bf16 v[28:31], v[160:163], v[212:215], v[28:31]
	v_mfma_f32_16x16x32_bf16 v[24:27], v[168:171], v[212:215], v[24:27]
	v_mfma_f32_16x16x32_bf16 v[12:15], v[160:163], v[220:223], v[12:15]
	v_mfma_f32_16x16x32_bf16 v[8:11], v[168:171], v[220:223], v[8:11]
	s_setprio 0
	s_setprio 1
	v_mfma_f32_16x16x32_bf16 v[52:55], v[172:175], v[188:191], v[52:55]
	v_mfma_f32_16x16x32_bf16 v[48:51], v[180:183], v[188:191], v[48:51]
	v_mfma_f32_16x16x32_bf16 v[36:39], v[172:175], v[200:203], v[36:39]
	v_mfma_f32_16x16x32_bf16 v[32:35], v[180:183], v[200:203], v[32:35]
	v_mfma_f32_16x16x32_bf16 v[20:23], v[172:175], v[208:211], v[20:23]
	v_mfma_f32_16x16x32_bf16 v[16:19], v[180:183], v[208:211], v[16:19]
	v_mfma_f32_16x16x32_bf16 v[4:7], v[172:175], v[216:219], v[4:7]
	v_mfma_f32_16x16x32_bf16 v[0:3], v[180:183], v[216:219], v[0:3]
	v_mfma_f32_16x16x32_bf16 v[52:55], v[176:179], v[196:199], v[52:55]
	v_mfma_f32_16x16x32_bf16 v[48:51], v[184:187], v[196:199], v[48:51]
	v_mfma_f32_16x16x32_bf16 v[36:39], v[176:179], v[204:207], v[36:39]
	v_mfma_f32_16x16x32_bf16 v[32:35], v[184:187], v[204:207], v[32:35]
	v_mfma_f32_16x16x32_bf16 v[20:23], v[176:179], v[212:215], v[20:23]
	v_mfma_f32_16x16x32_bf16 v[16:19], v[184:187], v[212:215], v[16:19]
	v_mfma_f32_16x16x32_bf16 v[4:7], v[176:179], v[220:223], v[4:7]
	v_mfma_f32_16x16x32_bf16 v[0:3], v[184:187], v[220:223], v[0:3]
	s_setprio 0
	s_barrier
	s_add_i32 s78, 0, 0x18000
	v_add_u32_e32 v159, s78, v153
	s_add_i32 s79, 0, 0x1c000
	ds_read_b128 v[146:149], v159
	ds_read_b128 v[160:163], v159 offset:1024
	ds_read_b128 v[164:167], v159 offset:2048
	ds_read_b128 v[168:171], v159 offset:3072
	v_add_u32_e32 v159, s79, v153
	ds_read_b128 v[172:175], v159
	ds_read_b128 v[176:179], v159 offset:1024
	ds_read_b128 v[180:183], v159 offset:2048
	ds_read_b128 v[184:187], v159 offset:3072
	s_add_u32 s28, s36, 0xb0000
	s_addc_u32 s29, s37, 0
	ds_read_b128 v[188:191], v157 offset:32768
	ds_read_b128 v[196:199], v157 offset:33792
	ds_read_b128 v[200:203], v157 offset:34816
	ds_read_b128 v[204:207], v157 offset:35840
	ds_read_b128 v[208:211], v157 offset:36864
	ds_read_b128 v[212:215], v157 offset:37888
	ds_read_b128 v[216:219], v157 offset:38912
	ds_read_b128 v[220:223], v157 offset:39936
	s_mov_b32 m0, s44
	s_nop 0
	global_load_lds_dwordx4 v130, s[98:99]
	s_mov_b32 m0, s45
	s_nop 0
	global_load_lds_dwordx4 v134, s[98:99]
	s_mov_b32 m0, s50
	s_nop 0
	global_load_lds_dwordx4 v130, s[28:29]
	s_mov_b32 m0, s51
	s_nop 0
	global_load_lds_dwordx4 v134, s[28:29]
	s_waitcnt vmcnt(8)
	s_waitcnt lgkmcnt(0)
	s_barrier
	s_setprio 1
	s_waitcnt lgkmcnt(0)
	v_mfma_f32_16x16x32_bf16 v[124:127], v[146:149], v[188:191], v[124:127]
	v_mfma_f32_16x16x32_bf16 v[120:123], v[164:167], v[188:191], v[120:123]
	v_mfma_f32_16x16x32_bf16 v[108:111], v[146:149], v[200:203], v[108:111]
	v_mfma_f32_16x16x32_bf16 v[104:107], v[164:167], v[200:203], v[104:107]
	v_mfma_f32_16x16x32_bf16 v[92:95], v[146:149], v[208:211], v[92:95]
	v_mfma_f32_16x16x32_bf16 v[88:91], v[164:167], v[208:211], v[88:91]
	v_mfma_f32_16x16x32_bf16 v[76:79], v[146:149], v[216:219], v[76:79]
	v_mfma_f32_16x16x32_bf16 v[72:75], v[164:167], v[216:219], v[72:75]
	v_mfma_f32_16x16x32_bf16 v[124:127], v[160:163], v[196:199], v[124:127]
	v_mfma_f32_16x16x32_bf16 v[120:123], v[168:171], v[196:199], v[120:123]
	v_mfma_f32_16x16x32_bf16 v[108:111], v[160:163], v[204:207], v[108:111]
	v_mfma_f32_16x16x32_bf16 v[104:107], v[168:171], v[204:207], v[104:107]
	v_mfma_f32_16x16x32_bf16 v[92:95], v[160:163], v[212:215], v[92:95]
	v_mfma_f32_16x16x32_bf16 v[88:91], v[168:171], v[212:215], v[88:91]
	v_mfma_f32_16x16x32_bf16 v[76:79], v[160:163], v[220:223], v[76:79]
	v_mfma_f32_16x16x32_bf16 v[72:75], v[168:171], v[220:223], v[72:75]
	s_setprio 0
	s_setprio 1
	v_mfma_f32_16x16x32_bf16 v[116:119], v[172:175], v[188:191], v[116:119]
	v_mfma_f32_16x16x32_bf16 v[112:115], v[180:183], v[188:191], v[112:115]
	v_mfma_f32_16x16x32_bf16 v[100:103], v[172:175], v[200:203], v[100:103]
	v_mfma_f32_16x16x32_bf16 v[96:99], v[180:183], v[200:203], v[96:99]
	v_mfma_f32_16x16x32_bf16 v[84:87], v[172:175], v[208:211], v[84:87]
	v_mfma_f32_16x16x32_bf16 v[80:83], v[180:183], v[208:211], v[80:83]
	v_mfma_f32_16x16x32_bf16 v[68:71], v[172:175], v[216:219], v[68:71]
	v_mfma_f32_16x16x32_bf16 v[64:67], v[180:183], v[216:219], v[64:67]
	v_mfma_f32_16x16x32_bf16 v[116:119], v[176:179], v[196:199], v[116:119]
	v_mfma_f32_16x16x32_bf16 v[112:115], v[184:187], v[196:199], v[112:115]
	v_mfma_f32_16x16x32_bf16 v[100:103], v[176:179], v[204:207], v[100:103]
	v_mfma_f32_16x16x32_bf16 v[96:99], v[184:187], v[204:207], v[96:99]
	v_mfma_f32_16x16x32_bf16 v[84:87], v[176:179], v[212:215], v[84:87]
	v_mfma_f32_16x16x32_bf16 v[80:83], v[184:187], v[212:215], v[80:83]
	v_mfma_f32_16x16x32_bf16 v[68:71], v[176:179], v[220:223], v[68:71]
	v_mfma_f32_16x16x32_bf16 v[64:67], v[184:187], v[220:223], v[64:67]
	s_setprio 0
	s_barrier
	s_add_i32 s28, s78, s43
	v_lshl_add_u64 v[150:151], v[150:151], 0, s[22:23]
	s_mov_b32 m0, s28
	ds_read_b128 v[188:191], v157 offset:49152
	ds_read_b128 v[196:199], v157 offset:50176
	ds_read_b128 v[200:203], v157 offset:51200
	ds_read_b128 v[204:207], v157 offset:52224
	ds_read_b128 v[208:211], v157 offset:53248
	ds_read_b128 v[212:215], v157 offset:54272
	ds_read_b128 v[216:219], v157 offset:55296
	ds_read_b128 v[220:223], v157 offset:56320
	global_load_lds_dwordx4 v[150:151], off
	s_add_i32 m0, s28, 0x2000
	s_add_u32 s28, s34, 0xb0080
	v_lshl_add_u64 v[150:151], v[192:193], 0, s[22:23]
	s_addc_u32 s29, s35, 0
	s_add_i32 s34, s79, s43
	global_load_lds_dwordx4 v[150:151], off
	s_mov_b32 m0, s34
	s_nop 0
	global_load_lds_dwordx4 v132, s[28:29]
	s_add_i32 m0, s34, 0x2000
	s_nop 0
	global_load_lds_dwordx4 v136, s[28:29]
	s_waitcnt vmcnt(6)
	s_waitcnt lgkmcnt(0)
	s_barrier
	s_setprio 1
	s_waitcnt lgkmcnt(0)
	v_mfma_f32_16x16x32_bf16 v[60:63], v[146:149], v[188:191], v[60:63]
	v_mfma_f32_16x16x32_bf16 v[56:59], v[164:167], v[188:191], v[56:59]
	v_mfma_f32_16x16x32_bf16 v[44:47], v[146:149], v[200:203], v[44:47]
	v_mfma_f32_16x16x32_bf16 v[40:43], v[164:167], v[200:203], v[40:43]
	v_mfma_f32_16x16x32_bf16 v[28:31], v[146:149], v[208:211], v[28:31]
	v_mfma_f32_16x16x32_bf16 v[24:27], v[164:167], v[208:211], v[24:27]
	v_mfma_f32_16x16x32_bf16 v[12:15], v[146:149], v[216:219], v[12:15]
	v_mfma_f32_16x16x32_bf16 v[8:11], v[164:167], v[216:219], v[8:11]
	v_mfma_f32_16x16x32_bf16 v[60:63], v[160:163], v[196:199], v[60:63]
	v_mfma_f32_16x16x32_bf16 v[56:59], v[168:171], v[196:199], v[56:59]
	v_mfma_f32_16x16x32_bf16 v[44:47], v[160:163], v[204:207], v[44:47]
	v_mfma_f32_16x16x32_bf16 v[40:43], v[168:171], v[204:207], v[40:43]
	v_mfma_f32_16x16x32_bf16 v[28:31], v[160:163], v[212:215], v[28:31]
	v_mfma_f32_16x16x32_bf16 v[24:27], v[168:171], v[212:215], v[24:27]
	v_mfma_f32_16x16x32_bf16 v[12:15], v[160:163], v[220:223], v[12:15]
	v_mfma_f32_16x16x32_bf16 v[8:11], v[168:171], v[220:223], v[8:11]
	s_setprio 0
	s_setprio 1
	v_mfma_f32_16x16x32_bf16 v[52:55], v[172:175], v[188:191], v[52:55]
	v_mfma_f32_16x16x32_bf16 v[48:51], v[180:183], v[188:191], v[48:51]
	v_mfma_f32_16x16x32_bf16 v[36:39], v[172:175], v[200:203], v[36:39]
	v_mfma_f32_16x16x32_bf16 v[32:35], v[180:183], v[200:203], v[32:35]
	v_mfma_f32_16x16x32_bf16 v[20:23], v[172:175], v[208:211], v[20:23]
	v_mfma_f32_16x16x32_bf16 v[16:19], v[180:183], v[208:211], v[16:19]
	v_mfma_f32_16x16x32_bf16 v[4:7], v[172:175], v[216:219], v[4:7]
	v_mfma_f32_16x16x32_bf16 v[0:3], v[180:183], v[216:219], v[0:3]
	v_mfma_f32_16x16x32_bf16 v[52:55], v[176:179], v[196:199], v[52:55]
	v_mfma_f32_16x16x32_bf16 v[48:51], v[184:187], v[196:199], v[48:51]
	v_mfma_f32_16x16x32_bf16 v[36:39], v[176:179], v[204:207], v[36:39]
	v_mfma_f32_16x16x32_bf16 v[32:35], v[184:187], v[204:207], v[32:35]
	v_mfma_f32_16x16x32_bf16 v[20:23], v[176:179], v[212:215], v[20:23]
	v_mfma_f32_16x16x32_bf16 v[16:19], v[184:187], v[212:215], v[16:19]
	v_mfma_f32_16x16x32_bf16 v[4:7], v[176:179], v[220:223], v[4:7]
	v_mfma_f32_16x16x32_bf16 v[0:3], v[184:187], v[220:223], v[0:3]
	s_setprio 0
	s_barrier
	s_add_i32 m0, s55, 0xffffff80
	s_nop 0
	global_load_lds_dwordx4 v130, s[98:99] offset:128
	s_add_i32 m0, s58, 0xffffff80
	s_nop 0
	global_load_lds_dwordx4 v134, s[98:99] offset:128
	s_add_i32 s77, s77, 2
	s_add_u32 s72, s72, 0x100
	s_addc_u32 s73, s73, 0
	s_cmp_gt_u32 s77, 41
	s_mov_b64 s[28:29], s[30:31]
	s_cbranch_scc0 .LBB0_532
	s_and_b64 vcc, exec, s[24:25]
	s_cbranch_vccz .LBB0_535
	s_barrier

.LBB0_626:
	ds_read_b128 v[152:155], v157
	ds_read_b128 v[162:165], v157 offset:1024
	ds_read_b128 v[166:169], v157 offset:2048
	ds_read_b128 v[170:173], v157 offset:3072
	ds_read_b128 v[174:177], v158
	ds_read_b128 v[178:181], v158 offset:1024
	ds_read_b128 v[182:185], v158 offset:2048
	ds_read_b128 v[186:189], v158 offset:3072
	s_add_u32 s40, s38, 0xfffc0080
	s_addc_u32 s41, s39, -1
	s_cmp_eq_u32 s86, 12
	s_cselect_b32 s43, s1, s41
	s_cselect_b32 s42, s11, s40
	s_cselect_b32 s41, s12, s85
	s_cselect_b32 s40, s29, s31
	s_add_i32 m0, s58, 0xc000
	ds_read_b128 v[190:193], v159
	ds_read_b128 v[196:199], v159 offset:1024
	ds_read_b128 v[200:203], v159 offset:2048
	ds_read_b128 v[204:207], v159 offset:3072
	ds_read_b128 v[208:211], v159 offset:4096
	ds_read_b128 v[212:215], v159 offset:5120
	ds_read_b128 v[216:219], v159 offset:6144
	ds_read_b128 v[220:223], v159 offset:7168
	global_load_lds_dwordx4 v144, s[38:39]
	s_add_i32 m0, s58, 0xe000
	s_nop 0
	global_load_lds_dwordx4 v146, s[38:39]
	s_waitcnt vmcnt(8)
	s_waitcnt lgkmcnt(0)
	s_barrier
	s_setprio 1
	s_waitcnt lgkmcnt(0)
	v_mfma_f32_16x16x32_bf16 v[124:127], v[152:155], v[190:193], v[124:127]
	v_mfma_f32_16x16x32_bf16 v[120:123], v[166:169], v[190:193], v[120:123]
	v_mfma_f32_16x16x32_bf16 v[108:111], v[152:155], v[200:203], v[108:111]
	v_mfma_f32_16x16x32_bf16 v[104:107], v[166:169], v[200:203], v[104:107]
	v_mfma_f32_16x16x32_bf16 v[92:95], v[152:155], v[208:211], v[92:95]
	v_mfma_f32_16x16x32_bf16 v[88:91], v[166:169], v[208:211], v[88:91]
	v_mfma_f32_16x16x32_bf16 v[76:79], v[152:155], v[216:219], v[76:79]
	v_mfma_f32_16x16x32_bf16 v[72:75], v[166:169], v[216:219], v[72:75]
	v_mfma_f32_16x16x32_bf16 v[124:127], v[162:165], v[196:199], v[124:127]
	v_mfma_f32_16x16x32_bf16 v[120:123], v[170:173], v[196:199], v[120:123]
	v_mfma_f32_16x16x32_bf16 v[108:111], v[162:165], v[204:207], v[108:111]
	v_mfma_f32_16x16x32_bf16 v[104:107], v[170:173], v[204:207], v[104:107]
	v_mfma_f32_16x16x32_bf16 v[92:95], v[162:165], v[212:215], v[92:95]
	v_mfma_f32_16x16x32_bf16 v[88:91], v[170:173], v[212:215], v[88:91]
	v_mfma_f32_16x16x32_bf16 v[76:79], v[162:165], v[220:223], v[76:79]
	v_mfma_f32_16x16x32_bf16 v[72:75], v[170:173], v[220:223], v[72:75]
	s_setprio 0
	s_setprio 1
	v_mfma_f32_16x16x32_bf16 v[116:119], v[174:177], v[190:193], v[116:119]
	v_mfma_f32_16x16x32_bf16 v[112:115], v[182:185], v[190:193], v[112:115]
	v_mfma_f32_16x16x32_bf16 v[100:103], v[174:177], v[200:203], v[100:103]
	v_mfma_f32_16x16x32_bf16 v[96:99], v[182:185], v[200:203], v[96:99]
	v_mfma_f32_16x16x32_bf16 v[84:87], v[174:177], v[208:211], v[84:87]
	v_mfma_f32_16x16x32_bf16 v[80:83], v[182:185], v[208:211], v[80:83]
	v_mfma_f32_16x16x32_bf16 v[68:71], v[174:177], v[216:219], v[68:71]
	v_mfma_f32_16x16x32_bf16 v[64:67], v[182:185], v[216:219], v[64:67]
	v_mfma_f32_16x16x32_bf16 v[116:119], v[178:181], v[196:199], v[116:119]
	v_mfma_f32_16x16x32_bf16 v[112:115], v[186:189], v[196:199], v[112:115]
	v_mfma_f32_16x16x32_bf16 v[100:103], v[178:181], v[204:207], v[100:103]
	v_mfma_f32_16x16x32_bf16 v[96:99], v[186:189], v[204:207], v[96:99]
	v_mfma_f32_16x16x32_bf16 v[84:87], v[178:181], v[212:215], v[84:87]
	v_mfma_f32_16x16x32_bf16 v[80:83], v[186:189], v[212:215], v[80:83]
	v_mfma_f32_16x16x32_bf16 v[68:71], v[178:181], v[220:223], v[68:71]
	v_mfma_f32_16x16x32_bf16 v[64:67], v[186:189], v[220:223], v[64:67]
	s_setprio 0
	s_barrier
	s_add_i32 s87, s73, s55
	s_mov_b32 m0, s87
	ds_read_b128 v[190:193], v159 offset:16384
	ds_read_b128 v[196:199], v159 offset:17408
	ds_read_b128 v[200:203], v159 offset:18432
	ds_read_b128 v[204:207], v159 offset:19456
	ds_read_b128 v[208:211], v159 offset:20480
	ds_read_b128 v[212:215], v159 offset:21504
	ds_read_b128 v[216:219], v159 offset:22528
	ds_read_b128 v[220:223], v159 offset:23552
	global_load_lds_dwordx4 v130, s[40:41]
	s_add_i32 m0, s87, 0x2000
	s_add_u32 s88, s40, 0x40000
	s_addc_u32 s89, s41, 0
	s_add_i32 s87, s77, s55
	global_load_lds_dwordx4 v134, s[40:41]
	s_mov_b32 m0, s87
	s_mov_b64 s[98:99], s[42:43]
	global_load_lds_dwordx4 v130, s[88:89]
	s_add_i32 m0, s87, 0x2000
	s_nop 0
	global_load_lds_dwordx4 v134, s[88:89]
	s_waitcnt vmcnt(6)
	s_waitcnt lgkmcnt(0)
	s_barrier
	s_setprio 1
	s_waitcnt lgkmcnt(0)
	v_mfma_f32_16x16x32_bf16 v[60:63], v[152:155], v[190:193], v[60:63]
	v_mfma_f32_16x16x32_bf16 v[56:59], v[166:169], v[190:193], v[56:59]
	v_mfma_f32_16x16x32_bf16 v[44:47], v[152:155], v[200:203], v[44:47]
	v_mfma_f32_16x16x32_bf16 v[40:43], v[166:169], v[200:203], v[40:43]
	v_mfma_f32_16x16x32_bf16 v[28:31], v[152:155], v[208:211], v[28:31]
	v_mfma_f32_16x16x32_bf16 v[24:27], v[166:169], v[208:211], v[24:27]
	v_mfma_f32_16x16x32_bf16 v[12:15], v[152:155], v[216:219], v[12:15]
	v_mfma_f32_16x16x32_bf16 v[8:11], v[166:169], v[216:219], v[8:11]
	v_mfma_f32_16x16x32_bf16 v[60:63], v[162:165], v[196:199], v[60:63]
	v_mfma_f32_16x16x32_bf16 v[56:59], v[170:173], v[196:199], v[56:59]
	v_mfma_f32_16x16x32_bf16 v[44:47], v[162:165], v[204:207], v[44:47]
	v_mfma_f32_16x16x32_bf16 v[40:43], v[170:173], v[204:207], v[40:43]
	v_mfma_f32_16x16x32_bf16 v[28:31], v[162:165], v[212:215], v[28:31]
	v_mfma_f32_16x16x32_bf16 v[24:27], v[170:173], v[212:215], v[24:27]
	v_mfma_f32_16x16x32_bf16 v[12:15], v[162:165], v[220:223], v[12:15]
	v_mfma_f32_16x16x32_bf16 v[8:11], v[170:173], v[220:223], v[8:11]
	s_setprio 0
	s_setprio 1
	v_mfma_f32_16x16x32_bf16 v[52:55], v[174:177], v[190:193], v[52:55]
	v_mfma_f32_16x16x32_bf16 v[48:51], v[182:185], v[190:193], v[48:51]
	v_mfma_f32_16x16x32_bf16 v[36:39], v[174:177], v[200:203], v[36:39]
	v_mfma_f32_16x16x32_bf16 v[32:35], v[182:185], v[200:203], v[32:35]
	v_mfma_f32_16x16x32_bf16 v[20:23], v[174:177], v[208:211], v[20:23]
	v_mfma_f32_16x16x32_bf16 v[16:19], v[182:185], v[208:211], v[16:19]
	v_mfma_f32_16x16x32_bf16 v[4:7], v[174:177], v[216:219], v[4:7]
	v_mfma_f32_16x16x32_bf16 v[0:3], v[182:185], v[216:219], v[0:3]
	v_mfma_f32_16x16x32_bf16 v[52:55], v[178:181], v[196:199], v[52:55]
	v_mfma_f32_16x16x32_bf16 v[48:51], v[186:189], v[196:199], v[48:51]
	v_mfma_f32_16x16x32_bf16 v[36:39], v[178:181], v[204:207], v[36:39]
	v_mfma_f32_16x16x32_bf16 v[32:35], v[186:189], v[204:207], v[32:35]
	v_mfma_f32_16x16x32_bf16 v[20:23], v[178:181], v[212:215], v[20:23]
	v_mfma_f32_16x16x32_bf16 v[16:19], v[186:189], v[212:215], v[16:19]
	v_mfma_f32_16x16x32_bf16 v[4:7], v[178:181], v[220:223], v[4:7]
	v_mfma_f32_16x16x32_bf16 v[0:3], v[186:189], v[220:223], v[0:3]
	s_setprio 0
	s_barrier
	s_add_i32 s87, 0, 0x18000
	v_add_u32_e32 v136, s87, v141
	s_add_i32 s88, 0, 0x1c000
	ds_read_b128 v[152:155], v136
	ds_read_b128 v[162:165], v136 offset:1024
	ds_read_b128 v[166:169], v136 offset:2048
	ds_read_b128 v[170:173], v136 offset:3072
	v_add_u32_e32 v136, s88, v141
	ds_read_b128 v[174:177], v136
	ds_read_b128 v[178:181], v136 offset:1024
	ds_read_b128 v[182:185], v136 offset:2048
	ds_read_b128 v[186:189], v136 offset:3072
	s_add_u32 s42, s42, 0x40000
	s_addc_u32 s43, s43, 0
	ds_read_b128 v[190:193], v159 offset:32768
	ds_read_b128 v[196:199], v159 offset:33792
	ds_read_b128 v[200:203], v159 offset:34816
	ds_read_b128 v[204:207], v159 offset:35840
	ds_read_b128 v[208:211], v159 offset:36864
	ds_read_b128 v[212:215], v159 offset:37888
	ds_read_b128 v[216:219], v159 offset:38912
	ds_read_b128 v[220:223], v159 offset:39936
	s_mov_b32 m0, s58
	s_nop 0
	global_load_lds_dwordx4 v128, s[98:99]
	s_mov_b32 m0, s59
	s_nop 0
	global_load_lds_dwordx4 v132, s[98:99]
	s_mov_b32 m0, s60
	s_nop 0
	global_load_lds_dwordx4 v128, s[42:43]
	s_mov_b32 m0, s61
	s_nop 0
	global_load_lds_dwordx4 v132, s[42:43]
	s_waitcnt vmcnt(8)
	s_waitcnt lgkmcnt(0)
	s_barrier
	s_setprio 1
	s_waitcnt lgkmcnt(0)
	v_mfma_f32_16x16x32_bf16 v[124:127], v[152:155], v[190:193], v[124:127]
	v_mfma_f32_16x16x32_bf16 v[120:123], v[166:169], v[190:193], v[120:123]
	v_mfma_f32_16x16x32_bf16 v[108:111], v[152:155], v[200:203], v[108:111]
	v_mfma_f32_16x16x32_bf16 v[104:107], v[166:169], v[200:203], v[104:107]
	v_mfma_f32_16x16x32_bf16 v[92:95], v[152:155], v[208:211], v[92:95]
	v_mfma_f32_16x16x32_bf16 v[88:91], v[166:169], v[208:211], v[88:91]
	v_mfma_f32_16x16x32_bf16 v[76:79], v[152:155], v[216:219], v[76:79]
	v_mfma_f32_16x16x32_bf16 v[72:75], v[166:169], v[216:219], v[72:75]
	v_mfma_f32_16x16x32_bf16 v[124:127], v[162:165], v[196:199], v[124:127]
	v_mfma_f32_16x16x32_bf16 v[120:123], v[170:173], v[196:199], v[120:123]
	v_mfma_f32_16x16x32_bf16 v[108:111], v[162:165], v[204:207], v[108:111]
	v_mfma_f32_16x16x32_bf16 v[104:107], v[170:173], v[204:207], v[104:107]
	v_mfma_f32_16x16x32_bf16 v[92:95], v[162:165], v[212:215], v[92:95]
	v_mfma_f32_16x16x32_bf16 v[88:91], v[170:173], v[212:215], v[88:91]
	v_mfma_f32_16x16x32_bf16 v[76:79], v[162:165], v[220:223], v[76:79]
	v_mfma_f32_16x16x32_bf16 v[72:75], v[170:173], v[220:223], v[72:75]
	s_setprio 0
	s_setprio 1
	v_mfma_f32_16x16x32_bf16 v[116:119], v[174:177], v[190:193], v[116:119]
	v_mfma_f32_16x16x32_bf16 v[112:115], v[182:185], v[190:193], v[112:115]
	v_mfma_f32_16x16x32_bf16 v[100:103], v[174:177], v[200:203], v[100:103]
	v_mfma_f32_16x16x32_bf16 v[96:99], v[182:185], v[200:203], v[96:99]
	v_mfma_f32_16x16x32_bf16 v[84:87], v[174:177], v[208:211], v[84:87]
	v_mfma_f32_16x16x32_bf16 v[80:83], v[182:185], v[208:211], v[80:83]
	v_mfma_f32_16x16x32_bf16 v[68:71], v[174:177], v[216:219], v[68:71]
	v_mfma_f32_16x16x32_bf16 v[64:67], v[182:185], v[216:219], v[64:67]
	v_mfma_f32_16x16x32_bf16 v[116:119], v[178:181], v[196:199], v[116:119]
	v_mfma_f32_16x16x32_bf16 v[112:115], v[186:189], v[196:199], v[112:115]
	v_mfma_f32_16x16x32_bf16 v[100:103], v[178:181], v[204:207], v[100:103]
	v_mfma_f32_16x16x32_bf16 v[96:99], v[186:189], v[204:207], v[96:99]
	v_mfma_f32_16x16x32_bf16 v[84:87], v[178:181], v[212:215], v[84:87]
	v_mfma_f32_16x16x32_bf16 v[80:83], v[186:189], v[212:215], v[80:83]
	v_mfma_f32_16x16x32_bf16 v[68:71], v[178:181], v[220:223], v[68:71]
	v_mfma_f32_16x16x32_bf16 v[64:67], v[186:189], v[220:223], v[64:67]
	s_setprio 0
	s_barrier
	s_add_i32 s42, s87, s55
	s_add_i32 m0, s42, 0xffffff80
	ds_read_b128 v[190:193], v159 offset:49152
	ds_read_b128 v[196:199], v159 offset:50176
	ds_read_b128 v[200:203], v159 offset:51200
	ds_read_b128 v[204:207], v159 offset:52224
	ds_read_b128 v[208:211], v159 offset:53248
	ds_read_b128 v[212:215], v159 offset:54272
	ds_read_b128 v[216:219], v159 offset:55296
	ds_read_b128 v[220:223], v159 offset:56320
	global_load_lds_dwordx4 v130, s[40:41] offset:128
	s_add_i32 m0, s42, 0x1f80
	s_add_i32 s42, s88, s55
	global_load_lds_dwordx4 v134, s[40:41] offset:128
	s_add_u32 s40, s40, 0x40080
	s_addc_u32 s41, s41, 0
	s_mov_b32 m0, s42
	s_nop 0
	global_load_lds_dwordx4 v130, s[40:41]
	s_add_i32 m0, s42, 0x2000
	s_nop 0
	global_load_lds_dwordx4 v134, s[40:41]
	s_waitcnt vmcnt(6)
	s_waitcnt lgkmcnt(0)
	s_barrier
	s_setprio 1
	s_waitcnt lgkmcnt(0)
	v_mfma_f32_16x16x32_bf16 v[60:63], v[152:155], v[190:193], v[60:63]
	v_mfma_f32_16x16x32_bf16 v[56:59], v[166:169], v[190:193], v[56:59]
	v_mfma_f32_16x16x32_bf16 v[44:47], v[152:155], v[200:203], v[44:47]
	v_mfma_f32_16x16x32_bf16 v[40:43], v[166:169], v[200:203], v[40:43]
	v_mfma_f32_16x16x32_bf16 v[28:31], v[152:155], v[208:211], v[28:31]
	v_mfma_f32_16x16x32_bf16 v[24:27], v[166:169], v[208:211], v[24:27]
	v_mfma_f32_16x16x32_bf16 v[12:15], v[152:155], v[216:219], v[12:15]
	v_mfma_f32_16x16x32_bf16 v[8:11], v[166:169], v[216:219], v[8:11]
	v_mfma_f32_16x16x32_bf16 v[60:63], v[162:165], v[196:199], v[60:63]
	v_mfma_f32_16x16x32_bf16 v[56:59], v[170:173], v[196:199], v[56:59]
	v_mfma_f32_16x16x32_bf16 v[44:47], v[162:165], v[204:207], v[44:47]
	v_mfma_f32_16x16x32_bf16 v[40:43], v[170:173], v[204:207], v[40:43]
	v_mfma_f32_16x16x32_bf16 v[28:31], v[162:165], v[212:215], v[28:31]
	v_mfma_f32_16x16x32_bf16 v[24:27], v[170:173], v[212:215], v[24:27]
	v_mfma_f32_16x16x32_bf16 v[12:15], v[162:165], v[220:223], v[12:15]
	v_mfma_f32_16x16x32_bf16 v[8:11], v[170:173], v[220:223], v[8:11]
	s_setprio 0
	s_setprio 1
	v_mfma_f32_16x16x32_bf16 v[52:55], v[174:177], v[190:193], v[52:55]
	v_mfma_f32_16x16x32_bf16 v[48:51], v[182:185], v[190:193], v[48:51]
	v_mfma_f32_16x16x32_bf16 v[36:39], v[174:177], v[200:203], v[36:39]
	v_mfma_f32_16x16x32_bf16 v[32:35], v[182:185], v[200:203], v[32:35]
	v_mfma_f32_16x16x32_bf16 v[20:23], v[174:177], v[208:211], v[20:23]
	v_mfma_f32_16x16x32_bf16 v[16:19], v[182:185], v[208:211], v[16:19]
	v_mfma_f32_16x16x32_bf16 v[4:7], v[174:177], v[216:219], v[4:7]
	v_mfma_f32_16x16x32_bf16 v[0:3], v[182:185], v[216:219], v[0:3]
	v_mfma_f32_16x16x32_bf16 v[52:55], v[178:181], v[196:199], v[52:55]
	v_mfma_f32_16x16x32_bf16 v[48:51], v[186:189], v[196:199], v[48:51]
	v_mfma_f32_16x16x32_bf16 v[36:39], v[178:181], v[204:207], v[36:39]
	v_mfma_f32_16x16x32_bf16 v[32:35], v[186:189], v[204:207], v[32:35]
	v_mfma_f32_16x16x32_bf16 v[20:23], v[178:181], v[212:215], v[20:23]
	v_mfma_f32_16x16x32_bf16 v[16:19], v[186:189], v[212:215], v[16:19]
	v_mfma_f32_16x16x32_bf16 v[4:7], v[178:181], v[220:223], v[4:7]
	v_mfma_f32_16x16x32_bf16 v[0:3], v[186:189], v[220:223], v[0:3]
	s_setprio 0
	s_barrier
	s_add_i32 m0, s70, 0xffffff80
	s_nop 0
	global_load_lds_dwordx4 v128, s[98:99] offset:128
	s_add_i32 m0, s71, 0xffffff80
	s_nop 0
	global_load_lds_dwordx4 v132, s[98:99] offset:128
	s_add_i32 s86, s86, 2
	s_add_u32 s38, s38, 0x100
	s_addc_u32 s39, s39, 0
	s_add_u32 s31, s31, 0x100
	s_addc_u32 s85, s85, 0
	s_cmp_gt_u32 s86, 13
	s_cbranch_scc0 .LBB0_626
	s_and_b64 vcc, exec, s[26:27]
	s_cbranch_vccz .LBB0_629
	s_barrier

.LBB0_760:
	ds_read_b128 v[148:151], v144
	ds_read_b128 v[152:155], v144 offset:1024
	ds_read_b128 v[156:159], v144 offset:2048
	ds_read_b128 v[160:163], v144 offset:3072
	ds_read_b128 v[164:167], v145
	ds_read_b128 v[168:171], v145 offset:1024
	ds_read_b128 v[172:175], v145 offset:2048
	ds_read_b128 v[176:179], v145 offset:3072
	s_add_u32 s36, s34, 0x100
	s_addc_u32 s37, s35, 0
	s_cmp_eq_u32 s83, 4
	s_cselect_b32 s41, s29, s37
	s_cselect_b32 s40, s28, s36
	s_cselect_b32 s39, s31, s25
	s_cselect_b32 s38, s30, s13
	v_lshl_add_u64 v[192:193], s[34:35], 0, v[138:139]
	s_add_i32 m0, s58, 0xc000
	ds_read_b128 v[180:183], v146
	ds_read_b128 v[184:187], v146 offset:1024
	ds_read_b128 v[188:191], v146 offset:2048
	ds_read_b128 v[196:199], v146 offset:3072
	ds_read_b128 v[200:203], v146 offset:4096
	ds_read_b128 v[204:207], v146 offset:5120
	ds_read_b128 v[208:211], v146 offset:6144
	ds_read_b128 v[212:215], v146 offset:7168
	global_load_lds_dwordx4 v[192:193], off
	v_lshl_add_u64 v[192:193], s[34:35], 0, v[140:141]
	s_add_i32 m0, s58, 0xe000
	s_nop 0
	global_load_lds_dwordx4 v[192:193], off
	s_waitcnt vmcnt(8)
	s_waitcnt lgkmcnt(0)
	s_barrier
	s_setprio 1
	s_waitcnt lgkmcnt(0)
	v_mfma_f32_16x16x32_bf16 v[124:127], v[148:151], v[180:183], v[124:127]
	v_mfma_f32_16x16x32_bf16 v[120:123], v[156:159], v[180:183], v[120:123]
	v_mfma_f32_16x16x32_bf16 v[116:119], v[148:151], v[188:191], v[116:119]
	v_mfma_f32_16x16x32_bf16 v[112:115], v[156:159], v[188:191], v[112:115]
	v_mfma_f32_16x16x32_bf16 v[104:107], v[148:151], v[200:203], v[104:107]
	v_mfma_f32_16x16x32_bf16 v[96:99], v[156:159], v[200:203], v[96:99]
	v_mfma_f32_16x16x32_bf16 v[88:91], v[148:151], v[208:211], v[88:91]
	v_mfma_f32_16x16x32_bf16 v[80:83], v[156:159], v[208:211], v[80:83]
	v_mfma_f32_16x16x32_bf16 v[124:127], v[152:155], v[184:187], v[124:127]
	v_mfma_f32_16x16x32_bf16 v[120:123], v[160:163], v[184:187], v[120:123]
	v_mfma_f32_16x16x32_bf16 v[116:119], v[152:155], v[196:199], v[116:119]
	v_mfma_f32_16x16x32_bf16 v[112:115], v[160:163], v[196:199], v[112:115]
	v_mfma_f32_16x16x32_bf16 v[104:107], v[152:155], v[204:207], v[104:107]
	v_mfma_f32_16x16x32_bf16 v[96:99], v[160:163], v[204:207], v[96:99]
	v_mfma_f32_16x16x32_bf16 v[88:91], v[152:155], v[212:215], v[88:91]
	v_mfma_f32_16x16x32_bf16 v[80:83], v[160:163], v[212:215], v[80:83]
	s_setprio 0
	s_setprio 1
	v_mfma_f32_16x16x32_bf16 v[108:111], v[164:167], v[180:183], v[108:111]
	v_mfma_f32_16x16x32_bf16 v[100:103], v[172:175], v[180:183], v[100:103]
	v_mfma_f32_16x16x32_bf16 v[92:95], v[164:167], v[188:191], v[92:95]
	v_mfma_f32_16x16x32_bf16 v[84:87], v[172:175], v[188:191], v[84:87]
	v_mfma_f32_16x16x32_bf16 v[76:79], v[164:167], v[200:203], v[76:79]
	v_mfma_f32_16x16x32_bf16 v[72:75], v[172:175], v[200:203], v[72:75]
	v_mfma_f32_16x16x32_bf16 v[68:71], v[164:167], v[208:211], v[68:71]
	v_mfma_f32_16x16x32_bf16 v[64:67], v[172:175], v[208:211], v[64:67]
	v_mfma_f32_16x16x32_bf16 v[108:111], v[168:171], v[184:187], v[108:111]
	v_mfma_f32_16x16x32_bf16 v[100:103], v[176:179], v[184:187], v[100:103]
	v_mfma_f32_16x16x32_bf16 v[92:95], v[168:171], v[196:199], v[92:95]
	v_mfma_f32_16x16x32_bf16 v[84:87], v[176:179], v[196:199], v[84:87]
	v_mfma_f32_16x16x32_bf16 v[76:79], v[168:171], v[204:207], v[76:79]
	v_mfma_f32_16x16x32_bf16 v[72:75], v[176:179], v[204:207], v[72:75]
	v_mfma_f32_16x16x32_bf16 v[68:71], v[168:171], v[212:215], v[68:71]
	v_mfma_f32_16x16x32_bf16 v[64:67], v[176:179], v[212:215], v[64:67]
	s_setprio 0
	s_barrier
	s_add_i32 s34, s77, s51
	v_lshl_add_u64 v[192:193], s[38:39], 0, v[132:133]
	s_mov_b32 m0, s34
	ds_read_b128 v[180:183], v146 offset:16384
	ds_read_b128 v[184:187], v146 offset:17408
	ds_read_b128 v[188:191], v146 offset:18432
	ds_read_b128 v[196:199], v146 offset:19456
	ds_read_b128 v[200:203], v146 offset:20480
	ds_read_b128 v[204:207], v146 offset:21504
	ds_read_b128 v[208:211], v146 offset:22528
	ds_read_b128 v[212:215], v146 offset:23552
	global_load_lds_dwordx4 v[192:193], off
	s_add_i32 m0, s34, 0x2000
	s_add_u32 s34, s38, 0x20000
	v_lshl_add_u64 v[216:217], s[38:39], 0, v[128:129]
	s_addc_u32 s35, s39, 0
	s_add_i32 s84, s78, s51
	global_load_lds_dwordx4 v[216:217], off
	s_mov_b32 m0, s84
	s_mov_b64 s[98:99], s[40:41]
	global_load_lds_dwordx4 v132, s[34:35]
	s_add_i32 m0, s84, 0x2000
	s_nop 0
	global_load_lds_dwordx4 v128, s[34:35]
	s_waitcnt vmcnt(6)
	s_waitcnt lgkmcnt(0)
	s_barrier
	s_setprio 1
	s_waitcnt lgkmcnt(0)
	v_mfma_f32_16x16x32_bf16 v[60:63], v[148:151], v[180:183], v[60:63]
	v_mfma_f32_16x16x32_bf16 v[56:59], v[156:159], v[180:183], v[56:59]
	v_mfma_f32_16x16x32_bf16 v[52:55], v[148:151], v[188:191], v[52:55]
	v_mfma_f32_16x16x32_bf16 v[48:51], v[156:159], v[188:191], v[48:51]
	v_mfma_f32_16x16x32_bf16 v[40:43], v[148:151], v[200:203], v[40:43]
	v_mfma_f32_16x16x32_bf16 v[32:35], v[156:159], v[200:203], v[32:35]
	v_mfma_f32_16x16x32_bf16 v[24:27], v[148:151], v[208:211], v[24:27]
	v_mfma_f32_16x16x32_bf16 v[16:19], v[156:159], v[208:211], v[16:19]
	v_mfma_f32_16x16x32_bf16 v[60:63], v[152:155], v[184:187], v[60:63]
	v_mfma_f32_16x16x32_bf16 v[56:59], v[160:163], v[184:187], v[56:59]
	v_mfma_f32_16x16x32_bf16 v[52:55], v[152:155], v[196:199], v[52:55]
	v_mfma_f32_16x16x32_bf16 v[48:51], v[160:163], v[196:199], v[48:51]
	v_mfma_f32_16x16x32_bf16 v[40:43], v[152:155], v[204:207], v[40:43]
	v_mfma_f32_16x16x32_bf16 v[32:35], v[160:163], v[204:207], v[32:35]
	v_mfma_f32_16x16x32_bf16 v[24:27], v[152:155], v[212:215], v[24:27]
	v_mfma_f32_16x16x32_bf16 v[16:19], v[160:163], v[212:215], v[16:19]
	s_setprio 0
	s_setprio 1
	v_mfma_f32_16x16x32_bf16 v[44:47], v[164:167], v[180:183], v[44:47]
	v_mfma_f32_16x16x32_bf16 v[36:39], v[172:175], v[180:183], v[36:39]
	v_mfma_f32_16x16x32_bf16 v[28:31], v[164:167], v[188:191], v[28:31]
	v_mfma_f32_16x16x32_bf16 v[20:23], v[172:175], v[188:191], v[20:23]
	v_mfma_f32_16x16x32_bf16 v[12:15], v[164:167], v[200:203], v[12:15]
	v_mfma_f32_16x16x32_bf16 v[8:11], v[172:175], v[200:203], v[8:11]
	v_mfma_f32_16x16x32_bf16 v[4:7], v[164:167], v[208:211], v[4:7]
	v_mfma_f32_16x16x32_bf16 v[0:3], v[172:175], v[208:211], v[0:3]
	v_mfma_f32_16x16x32_bf16 v[44:47], v[168:171], v[184:187], v[44:47]
	v_mfma_f32_16x16x32_bf16 v[36:39], v[176:179], v[184:187], v[36:39]
	v_mfma_f32_16x16x32_bf16 v[28:31], v[168:171], v[196:199], v[28:31]
	v_mfma_f32_16x16x32_bf16 v[20:23], v[176:179], v[196:199], v[20:23]
	v_mfma_f32_16x16x32_bf16 v[12:15], v[168:171], v[204:207], v[12:15]
	v_mfma_f32_16x16x32_bf16 v[8:11], v[176:179], v[204:207], v[8:11]
	v_mfma_f32_16x16x32_bf16 v[4:7], v[168:171], v[212:215], v[4:7]
	v_mfma_f32_16x16x32_bf16 v[0:3], v[176:179], v[212:215], v[0:3]
	s_setprio 0
	s_barrier
	s_add_i32 s84, 0, 0x18000
	v_add_u32_e32 v147, s84, v143
	s_add_i32 s85, 0, 0x1c000
	ds_read_b128 v[148:151], v147
	ds_read_b128 v[152:155], v147 offset:1024
	ds_read_b128 v[156:159], v147 offset:2048
	ds_read_b128 v[160:163], v147 offset:3072
	v_add_u32_e32 v147, s85, v143
	ds_read_b128 v[164:167], v147
	ds_read_b128 v[168:171], v147 offset:1024
	ds_read_b128 v[172:175], v147 offset:2048
	ds_read_b128 v[176:179], v147 offset:3072
	s_add_u32 s34, s40, 0x30000
	s_addc_u32 s35, s41, 0
	ds_read_b128 v[180:183], v146 offset:32768
	ds_read_b128 v[184:187], v146 offset:33792
	ds_read_b128 v[188:191], v146 offset:34816
	ds_read_b128 v[196:199], v146 offset:35840
	ds_read_b128 v[200:203], v146 offset:36864
	ds_read_b128 v[204:207], v146 offset:37888
	ds_read_b128 v[208:211], v146 offset:38912
	ds_read_b128 v[212:215], v146 offset:39936
	s_mov_b32 m0, s58
	s_nop 0
	global_load_lds_dwordx4 v134, s[98:99]
	s_mov_b32 m0, s59
	s_nop 0
	global_load_lds_dwordx4 v130, s[98:99]
	s_mov_b32 m0, s60
	s_nop 0
	global_load_lds_dwordx4 v134, s[34:35]
	s_mov_b32 m0, s61
	s_nop 0
	global_load_lds_dwordx4 v130, s[34:35]
	s_waitcnt vmcnt(8)
	s_waitcnt lgkmcnt(0)
	s_barrier
	s_setprio 1
	s_waitcnt lgkmcnt(0)
	v_mfma_f32_16x16x32_bf16 v[124:127], v[148:151], v[180:183], v[124:127]
	v_mfma_f32_16x16x32_bf16 v[120:123], v[156:159], v[180:183], v[120:123]
	v_mfma_f32_16x16x32_bf16 v[116:119], v[148:151], v[188:191], v[116:119]
	v_mfma_f32_16x16x32_bf16 v[112:115], v[156:159], v[188:191], v[112:115]
	v_mfma_f32_16x16x32_bf16 v[104:107], v[148:151], v[200:203], v[104:107]
	v_mfma_f32_16x16x32_bf16 v[96:99], v[156:159], v[200:203], v[96:99]
	v_mfma_f32_16x16x32_bf16 v[88:91], v[148:151], v[208:211], v[88:91]
	v_mfma_f32_16x16x32_bf16 v[80:83], v[156:159], v[208:211], v[80:83]
	v_mfma_f32_16x16x32_bf16 v[124:127], v[152:155], v[184:187], v[124:127]
	v_mfma_f32_16x16x32_bf16 v[120:123], v[160:163], v[184:187], v[120:123]
	v_mfma_f32_16x16x32_bf16 v[116:119], v[152:155], v[196:199], v[116:119]
	v_mfma_f32_16x16x32_bf16 v[112:115], v[160:163], v[196:199], v[112:115]
	v_mfma_f32_16x16x32_bf16 v[104:107], v[152:155], v[204:207], v[104:107]
	v_mfma_f32_16x16x32_bf16 v[96:99], v[160:163], v[204:207], v[96:99]
	v_mfma_f32_16x16x32_bf16 v[88:91], v[152:155], v[212:215], v[88:91]
	v_mfma_f32_16x16x32_bf16 v[80:83], v[160:163], v[212:215], v[80:83]
	s_setprio 0
	s_setprio 1
	v_mfma_f32_16x16x32_bf16 v[108:111], v[164:167], v[180:183], v[108:111]
	v_mfma_f32_16x16x32_bf16 v[100:103], v[172:175], v[180:183], v[100:103]
	v_mfma_f32_16x16x32_bf16 v[92:95], v[164:167], v[188:191], v[92:95]
	v_mfma_f32_16x16x32_bf16 v[84:87], v[172:175], v[188:191], v[84:87]
	v_mfma_f32_16x16x32_bf16 v[76:79], v[164:167], v[200:203], v[76:79]
	v_mfma_f32_16x16x32_bf16 v[72:75], v[172:175], v[200:203], v[72:75]
	v_mfma_f32_16x16x32_bf16 v[68:71], v[164:167], v[208:211], v[68:71]
	v_mfma_f32_16x16x32_bf16 v[64:67], v[172:175], v[208:211], v[64:67]
	v_mfma_f32_16x16x32_bf16 v[108:111], v[168:171], v[184:187], v[108:111]
	v_mfma_f32_16x16x32_bf16 v[100:103], v[176:179], v[184:187], v[100:103]
	v_mfma_f32_16x16x32_bf16 v[92:95], v[168:171], v[196:199], v[92:95]
	v_mfma_f32_16x16x32_bf16 v[84:87], v[176:179], v[196:199], v[84:87]
	v_mfma_f32_16x16x32_bf16 v[76:79], v[168:171], v[204:207], v[76:79]
	v_mfma_f32_16x16x32_bf16 v[72:75], v[176:179], v[204:207], v[72:75]
	v_mfma_f32_16x16x32_bf16 v[68:71], v[168:171], v[212:215], v[68:71]
	v_mfma_f32_16x16x32_bf16 v[64:67], v[176:179], v[212:215], v[64:67]
	s_setprio 0
	s_barrier
	s_add_i32 s34, s84, s51
	v_lshl_add_u64 v[192:193], v[192:193], 0, s[10:11]
	s_mov_b32 m0, s34
	ds_read_b128 v[180:183], v146 offset:49152
	ds_read_b128 v[184:187], v146 offset:50176
	ds_read_b128 v[188:191], v146 offset:51200
	ds_read_b128 v[196:199], v146 offset:52224
	ds_read_b128 v[200:203], v146 offset:53248
	ds_read_b128 v[204:207], v146 offset:54272
	ds_read_b128 v[208:211], v146 offset:55296
	ds_read_b128 v[212:215], v146 offset:56320
	global_load_lds_dwordx4 v[192:193], off
	s_add_i32 m0, s34, 0x2000
	s_add_u32 s34, s38, 0x20080
	v_lshl_add_u64 v[192:193], v[216:217], 0, s[10:11]
	s_addc_u32 s35, s39, 0
	s_add_i32 s38, s85, s51
	global_load_lds_dwordx4 v[192:193], off
	s_mov_b32 m0, s38
	s_nop 0
	global_load_lds_dwordx4 v132, s[34:35]
	s_add_i32 m0, s38, 0x2000
	s_nop 0
	global_load_lds_dwordx4 v128, s[34:35]
	s_waitcnt vmcnt(6)
	s_waitcnt lgkmcnt(0)
	s_barrier
	s_setprio 1
	s_waitcnt lgkmcnt(0)
	v_mfma_f32_16x16x32_bf16 v[60:63], v[148:151], v[180:183], v[60:63]
	v_mfma_f32_16x16x32_bf16 v[56:59], v[156:159], v[180:183], v[56:59]
	v_mfma_f32_16x16x32_bf16 v[52:55], v[148:151], v[188:191], v[52:55]
	v_mfma_f32_16x16x32_bf16 v[48:51], v[156:159], v[188:191], v[48:51]
	v_mfma_f32_16x16x32_bf16 v[40:43], v[148:151], v[200:203], v[40:43]
	v_mfma_f32_16x16x32_bf16 v[32:35], v[156:159], v[200:203], v[32:35]
	v_mfma_f32_16x16x32_bf16 v[24:27], v[148:151], v[208:211], v[24:27]
	v_mfma_f32_16x16x32_bf16 v[16:19], v[156:159], v[208:211], v[16:19]
	v_mfma_f32_16x16x32_bf16 v[60:63], v[152:155], v[184:187], v[60:63]
	v_mfma_f32_16x16x32_bf16 v[56:59], v[160:163], v[184:187], v[56:59]
	v_mfma_f32_16x16x32_bf16 v[52:55], v[152:155], v[196:199], v[52:55]
	v_mfma_f32_16x16x32_bf16 v[48:51], v[160:163], v[196:199], v[48:51]
	v_mfma_f32_16x16x32_bf16 v[40:43], v[152:155], v[204:207], v[40:43]
	v_mfma_f32_16x16x32_bf16 v[32:35], v[160:163], v[204:207], v[32:35]
	v_mfma_f32_16x16x32_bf16 v[24:27], v[152:155], v[212:215], v[24:27]
	v_mfma_f32_16x16x32_bf16 v[16:19], v[160:163], v[212:215], v[16:19]
	s_setprio 0
	s_setprio 1
	v_mfma_f32_16x16x32_bf16 v[44:47], v[164:167], v[180:183], v[44:47]
	v_mfma_f32_16x16x32_bf16 v[36:39], v[172:175], v[180:183], v[36:39]
	v_mfma_f32_16x16x32_bf16 v[28:31], v[164:167], v[188:191], v[28:31]
	v_mfma_f32_16x16x32_bf16 v[20:23], v[172:175], v[188:191], v[20:23]
	v_mfma_f32_16x16x32_bf16 v[12:15], v[164:167], v[200:203], v[12:15]
	v_mfma_f32_16x16x32_bf16 v[8:11], v[172:175], v[200:203], v[8:11]
	v_mfma_f32_16x16x32_bf16 v[4:7], v[164:167], v[208:211], v[4:7]
	v_mfma_f32_16x16x32_bf16 v[0:3], v[172:175], v[208:211], v[0:3]
	v_mfma_f32_16x16x32_bf16 v[44:47], v[168:171], v[184:187], v[44:47]
	v_mfma_f32_16x16x32_bf16 v[36:39], v[176:179], v[184:187], v[36:39]
	v_mfma_f32_16x16x32_bf16 v[28:31], v[168:171], v[196:199], v[28:31]
	v_mfma_f32_16x16x32_bf16 v[20:23], v[176:179], v[196:199], v[20:23]
	v_mfma_f32_16x16x32_bf16 v[12:15], v[168:171], v[204:207], v[12:15]
	v_mfma_f32_16x16x32_bf16 v[8:11], v[176:179], v[204:207], v[8:11]
	v_mfma_f32_16x16x32_bf16 v[4:7], v[168:171], v[212:215], v[4:7]
	v_mfma_f32_16x16x32_bf16 v[0:3], v[176:179], v[212:215], v[0:3]
	s_setprio 0
	s_barrier
	s_add_i32 m0, s71, 0xffffff80
	s_nop 0
	global_load_lds_dwordx4 v134, s[98:99] offset:128
	s_add_i32 m0, s72, 0xffffff80
	s_nop 0
	global_load_lds_dwordx4 v130, s[98:99] offset:128
	s_add_i32 s83, s83, 2
	s_add_u32 s13, s13, 0x100
	s_addc_u32 s25, s25, 0
	s_cmp_gt_u32 s83, 5
	s_mov_b64 s[34:35], s[36:37]
	s_cbranch_scc0 .LBB0_760
	s_and_b64 vcc, exec, s[16:17]
	s_cbranch_vccz .LBB0_763
	s_barrier

.LBB0_786:
	ds_read_b128 v[144:147], v153
	ds_read_b128 v[158:161], v153 offset:1024
	ds_read_b128 v[162:165], v153 offset:2048
	ds_read_b128 v[166:169], v153 offset:3072
	ds_read_b128 v[170:173], v154
	ds_read_b128 v[174:177], v154 offset:1024
	ds_read_b128 v[178:181], v154 offset:2048
	ds_read_b128 v[182:185], v154 offset:3072
	s_add_u32 s34, s30, 0xfffc0080
	s_addc_u32 s35, s31, -1
	s_cmp_eq_u32 s82, 12
	s_cselect_b32 s37, s25, s35
	s_cselect_b32 s36, s78, s34
	s_cselect_b32 s35, s23, s81
	s_cselect_b32 s34, s79, s80
	s_add_i32 m0, s50, 0xc000
	ds_read_b128 v[186:189], v155
	ds_read_b128 v[190:193], v155 offset:1024
	ds_read_b128 v[196:199], v155 offset:2048
	ds_read_b128 v[200:203], v155 offset:3072
	ds_read_b128 v[204:207], v155 offset:4096
	ds_read_b128 v[208:211], v155 offset:5120
	ds_read_b128 v[212:215], v155 offset:6144
	ds_read_b128 v[216:219], v155 offset:7168
	global_load_lds_dwordx4 v136, s[30:31]
	s_add_i32 m0, s50, 0xe000
	s_nop 0
	global_load_lds_dwordx4 v138, s[30:31]
	s_waitcnt vmcnt(8)
	s_waitcnt lgkmcnt(0)
	s_barrier
	s_setprio 1
	s_waitcnt lgkmcnt(0)
	v_mfma_f32_16x16x32_bf16 v[124:127], v[144:147], v[186:189], v[124:127]
	v_mfma_f32_16x16x32_bf16 v[120:123], v[162:165], v[186:189], v[120:123]
	v_mfma_f32_16x16x32_bf16 v[108:111], v[144:147], v[196:199], v[108:111]
	v_mfma_f32_16x16x32_bf16 v[104:107], v[162:165], v[196:199], v[104:107]
	v_mfma_f32_16x16x32_bf16 v[92:95], v[144:147], v[204:207], v[92:95]
	v_mfma_f32_16x16x32_bf16 v[88:91], v[162:165], v[204:207], v[88:91]
	v_mfma_f32_16x16x32_bf16 v[76:79], v[144:147], v[212:215], v[76:79]
	v_mfma_f32_16x16x32_bf16 v[72:75], v[162:165], v[212:215], v[72:75]
	v_mfma_f32_16x16x32_bf16 v[124:127], v[158:161], v[190:193], v[124:127]
	v_mfma_f32_16x16x32_bf16 v[120:123], v[166:169], v[190:193], v[120:123]
	v_mfma_f32_16x16x32_bf16 v[108:111], v[158:161], v[200:203], v[108:111]
	v_mfma_f32_16x16x32_bf16 v[104:107], v[166:169], v[200:203], v[104:107]
	v_mfma_f32_16x16x32_bf16 v[92:95], v[158:161], v[208:211], v[92:95]
	v_mfma_f32_16x16x32_bf16 v[88:91], v[166:169], v[208:211], v[88:91]
	v_mfma_f32_16x16x32_bf16 v[76:79], v[158:161], v[216:219], v[76:79]
	v_mfma_f32_16x16x32_bf16 v[72:75], v[166:169], v[216:219], v[72:75]
	s_setprio 0
	s_setprio 1
	v_mfma_f32_16x16x32_bf16 v[116:119], v[170:173], v[186:189], v[116:119]
	v_mfma_f32_16x16x32_bf16 v[112:115], v[178:181], v[186:189], v[112:115]
	v_mfma_f32_16x16x32_bf16 v[100:103], v[170:173], v[196:199], v[100:103]
	v_mfma_f32_16x16x32_bf16 v[96:99], v[178:181], v[196:199], v[96:99]
	v_mfma_f32_16x16x32_bf16 v[84:87], v[170:173], v[204:207], v[84:87]
	v_mfma_f32_16x16x32_bf16 v[80:83], v[178:181], v[204:207], v[80:83]
	v_mfma_f32_16x16x32_bf16 v[68:71], v[170:173], v[212:215], v[68:71]
	v_mfma_f32_16x16x32_bf16 v[64:67], v[178:181], v[212:215], v[64:67]
	v_mfma_f32_16x16x32_bf16 v[116:119], v[174:177], v[190:193], v[116:119]
	v_mfma_f32_16x16x32_bf16 v[112:115], v[182:185], v[190:193], v[112:115]
	v_mfma_f32_16x16x32_bf16 v[100:103], v[174:177], v[200:203], v[100:103]
	v_mfma_f32_16x16x32_bf16 v[96:99], v[182:185], v[200:203], v[96:99]
	v_mfma_f32_16x16x32_bf16 v[84:87], v[174:177], v[208:211], v[84:87]
	v_mfma_f32_16x16x32_bf16 v[80:83], v[182:185], v[208:211], v[80:83]
	v_mfma_f32_16x16x32_bf16 v[68:71], v[174:177], v[216:219], v[68:71]
	v_mfma_f32_16x16x32_bf16 v[64:67], v[182:185], v[216:219], v[64:67]
	s_setprio 0
	s_barrier
	s_add_i32 s83, s70, s45
	s_mov_b32 m0, s83
	ds_read_b128 v[186:189], v155 offset:16384
	ds_read_b128 v[190:193], v155 offset:17408
	ds_read_b128 v[196:199], v155 offset:18432
	ds_read_b128 v[200:203], v155 offset:19456
	ds_read_b128 v[204:207], v155 offset:20480
	ds_read_b128 v[208:211], v155 offset:21504
	ds_read_b128 v[212:215], v155 offset:22528
	ds_read_b128 v[216:219], v155 offset:23552
	global_load_lds_dwordx4 v130, s[34:35]
	s_add_i32 m0, s83, 0x2000
	s_add_u32 s84, s34, 0x40000
	s_addc_u32 s85, s35, 0
	s_add_i32 s83, s71, s45
	global_load_lds_dwordx4 v134, s[34:35]
	s_mov_b32 m0, s83
	s_mov_b64 s[98:99], s[36:37]
	global_load_lds_dwordx4 v130, s[84:85]
	s_add_i32 m0, s83, 0x2000
	s_nop 0
	global_load_lds_dwordx4 v134, s[84:85]
	s_waitcnt vmcnt(6)
	s_waitcnt lgkmcnt(0)
	s_barrier
	s_setprio 1
	s_waitcnt lgkmcnt(0)
	v_mfma_f32_16x16x32_bf16 v[60:63], v[144:147], v[186:189], v[60:63]
	v_mfma_f32_16x16x32_bf16 v[56:59], v[162:165], v[186:189], v[56:59]
	v_mfma_f32_16x16x32_bf16 v[44:47], v[144:147], v[196:199], v[44:47]
	v_mfma_f32_16x16x32_bf16 v[40:43], v[162:165], v[196:199], v[40:43]
	v_mfma_f32_16x16x32_bf16 v[28:31], v[144:147], v[204:207], v[28:31]
	v_mfma_f32_16x16x32_bf16 v[24:27], v[162:165], v[204:207], v[24:27]
	v_mfma_f32_16x16x32_bf16 v[12:15], v[144:147], v[212:215], v[12:15]
	v_mfma_f32_16x16x32_bf16 v[8:11], v[162:165], v[212:215], v[8:11]
	v_mfma_f32_16x16x32_bf16 v[60:63], v[158:161], v[190:193], v[60:63]
	v_mfma_f32_16x16x32_bf16 v[56:59], v[166:169], v[190:193], v[56:59]
	v_mfma_f32_16x16x32_bf16 v[44:47], v[158:161], v[200:203], v[44:47]
	v_mfma_f32_16x16x32_bf16 v[40:43], v[166:169], v[200:203], v[40:43]
	v_mfma_f32_16x16x32_bf16 v[28:31], v[158:161], v[208:211], v[28:31]
	v_mfma_f32_16x16x32_bf16 v[24:27], v[166:169], v[208:211], v[24:27]
	v_mfma_f32_16x16x32_bf16 v[12:15], v[158:161], v[216:219], v[12:15]
	v_mfma_f32_16x16x32_bf16 v[8:11], v[166:169], v[216:219], v[8:11]
	s_setprio 0
	s_setprio 1
	v_mfma_f32_16x16x32_bf16 v[52:55], v[170:173], v[186:189], v[52:55]
	v_mfma_f32_16x16x32_bf16 v[48:51], v[178:181], v[186:189], v[48:51]
	v_mfma_f32_16x16x32_bf16 v[36:39], v[170:173], v[196:199], v[36:39]
	v_mfma_f32_16x16x32_bf16 v[32:35], v[178:181], v[196:199], v[32:35]
	v_mfma_f32_16x16x32_bf16 v[20:23], v[170:173], v[204:207], v[20:23]
	v_mfma_f32_16x16x32_bf16 v[16:19], v[178:181], v[204:207], v[16:19]
	v_mfma_f32_16x16x32_bf16 v[4:7], v[170:173], v[212:215], v[4:7]
	v_mfma_f32_16x16x32_bf16 v[0:3], v[178:181], v[212:215], v[0:3]
	v_mfma_f32_16x16x32_bf16 v[52:55], v[174:177], v[190:193], v[52:55]
	v_mfma_f32_16x16x32_bf16 v[48:51], v[182:185], v[190:193], v[48:51]
	v_mfma_f32_16x16x32_bf16 v[36:39], v[174:177], v[200:203], v[36:39]
	v_mfma_f32_16x16x32_bf16 v[32:35], v[182:185], v[200:203], v[32:35]
	v_mfma_f32_16x16x32_bf16 v[20:23], v[174:177], v[208:211], v[20:23]
	v_mfma_f32_16x16x32_bf16 v[16:19], v[182:185], v[208:211], v[16:19]
	v_mfma_f32_16x16x32_bf16 v[4:7], v[174:177], v[216:219], v[4:7]
	v_mfma_f32_16x16x32_bf16 v[0:3], v[182:185], v[216:219], v[0:3]
	s_setprio 0
	s_barrier
	s_add_i32 s83, 0, 0x18000
	v_add_u32_e32 v157, s83, v151
	s_add_i32 s84, 0, 0x1c000
	ds_read_b128 v[144:147], v157
	ds_read_b128 v[158:161], v157 offset:1024
	ds_read_b128 v[162:165], v157 offset:2048
	ds_read_b128 v[166:169], v157 offset:3072
	v_add_u32_e32 v157, s84, v151
	ds_read_b128 v[170:173], v157
	ds_read_b128 v[174:177], v157 offset:1024
	ds_read_b128 v[178:181], v157 offset:2048
	ds_read_b128 v[182:185], v157 offset:3072
	s_add_u32 s36, s36, 0x40000
	s_addc_u32 s37, s37, 0
	ds_read_b128 v[186:189], v155 offset:32768
	ds_read_b128 v[190:193], v155 offset:33792
	ds_read_b128 v[196:199], v155 offset:34816
	ds_read_b128 v[200:203], v155 offset:35840
	ds_read_b128 v[204:207], v155 offset:36864
	ds_read_b128 v[208:211], v155 offset:37888
	ds_read_b128 v[212:215], v155 offset:38912
	ds_read_b128 v[216:219], v155 offset:39936
	s_mov_b32 m0, s50
	s_nop 0
	global_load_lds_dwordx4 v128, s[98:99]
	s_mov_b32 m0, s51
	s_nop 0
	global_load_lds_dwordx4 v132, s[98:99]
	s_mov_b32 m0, s58
	s_nop 0
	global_load_lds_dwordx4 v128, s[36:37]
	s_mov_b32 m0, s59
	s_nop 0
	global_load_lds_dwordx4 v132, s[36:37]
	s_waitcnt vmcnt(8)
	s_waitcnt lgkmcnt(0)
	s_barrier
	s_setprio 1
	s_waitcnt lgkmcnt(0)
	v_mfma_f32_16x16x32_bf16 v[124:127], v[144:147], v[186:189], v[124:127]
	v_mfma_f32_16x16x32_bf16 v[120:123], v[162:165], v[186:189], v[120:123]
	v_mfma_f32_16x16x32_bf16 v[108:111], v[144:147], v[196:199], v[108:111]
	v_mfma_f32_16x16x32_bf16 v[104:107], v[162:165], v[196:199], v[104:107]
	v_mfma_f32_16x16x32_bf16 v[92:95], v[144:147], v[204:207], v[92:95]
	v_mfma_f32_16x16x32_bf16 v[88:91], v[162:165], v[204:207], v[88:91]
	v_mfma_f32_16x16x32_bf16 v[76:79], v[144:147], v[212:215], v[76:79]
	v_mfma_f32_16x16x32_bf16 v[72:75], v[162:165], v[212:215], v[72:75]
	v_mfma_f32_16x16x32_bf16 v[124:127], v[158:161], v[190:193], v[124:127]
	v_mfma_f32_16x16x32_bf16 v[120:123], v[166:169], v[190:193], v[120:123]
	v_mfma_f32_16x16x32_bf16 v[108:111], v[158:161], v[200:203], v[108:111]
	v_mfma_f32_16x16x32_bf16 v[104:107], v[166:169], v[200:203], v[104:107]
	v_mfma_f32_16x16x32_bf16 v[92:95], v[158:161], v[208:211], v[92:95]
	v_mfma_f32_16x16x32_bf16 v[88:91], v[166:169], v[208:211], v[88:91]
	v_mfma_f32_16x16x32_bf16 v[76:79], v[158:161], v[216:219], v[76:79]
	v_mfma_f32_16x16x32_bf16 v[72:75], v[166:169], v[216:219], v[72:75]
	s_setprio 0
	s_setprio 1
	v_mfma_f32_16x16x32_bf16 v[116:119], v[170:173], v[186:189], v[116:119]
	v_mfma_f32_16x16x32_bf16 v[112:115], v[178:181], v[186:189], v[112:115]
	v_mfma_f32_16x16x32_bf16 v[100:103], v[170:173], v[196:199], v[100:103]
	v_mfma_f32_16x16x32_bf16 v[96:99], v[178:181], v[196:199], v[96:99]
	v_mfma_f32_16x16x32_bf16 v[84:87], v[170:173], v[204:207], v[84:87]
	v_mfma_f32_16x16x32_bf16 v[80:83], v[178:181], v[204:207], v[80:83]
	v_mfma_f32_16x16x32_bf16 v[68:71], v[170:173], v[212:215], v[68:71]
	v_mfma_f32_16x16x32_bf16 v[64:67], v[178:181], v[212:215], v[64:67]
	v_mfma_f32_16x16x32_bf16 v[116:119], v[174:177], v[190:193], v[116:119]
	v_mfma_f32_16x16x32_bf16 v[112:115], v[182:185], v[190:193], v[112:115]
	v_mfma_f32_16x16x32_bf16 v[100:103], v[174:177], v[200:203], v[100:103]
	v_mfma_f32_16x16x32_bf16 v[96:99], v[182:185], v[200:203], v[96:99]
	v_mfma_f32_16x16x32_bf16 v[84:87], v[174:177], v[208:211], v[84:87]
	v_mfma_f32_16x16x32_bf16 v[80:83], v[182:185], v[208:211], v[80:83]
	v_mfma_f32_16x16x32_bf16 v[68:71], v[174:177], v[216:219], v[68:71]
	v_mfma_f32_16x16x32_bf16 v[64:67], v[182:185], v[216:219], v[64:67]
	s_setprio 0
	s_barrier
	s_add_i32 s36, s83, s45
	s_add_i32 m0, s36, 0xffffff80
	ds_read_b128 v[186:189], v155 offset:49152
	ds_read_b128 v[190:193], v155 offset:50176
	ds_read_b128 v[196:199], v155 offset:51200
	ds_read_b128 v[200:203], v155 offset:52224
	ds_read_b128 v[204:207], v155 offset:53248
	ds_read_b128 v[208:211], v155 offset:54272
	ds_read_b128 v[212:215], v155 offset:55296
	ds_read_b128 v[216:219], v155 offset:56320
	global_load_lds_dwordx4 v130, s[34:35] offset:128
	s_add_i32 m0, s36, 0x1f80
	s_add_i32 s36, s84, s45
	global_load_lds_dwordx4 v134, s[34:35] offset:128
	s_add_u32 s34, s34, 0x40080
	s_addc_u32 s35, s35, 0
	s_mov_b32 m0, s36
	s_nop 0
	global_load_lds_dwordx4 v130, s[34:35]
	s_add_i32 m0, s36, 0x2000
	s_nop 0
	global_load_lds_dwordx4 v134, s[34:35]
	s_waitcnt vmcnt(6)
	s_waitcnt lgkmcnt(0)
	s_barrier
	s_setprio 1
	s_waitcnt lgkmcnt(0)
	v_mfma_f32_16x16x32_bf16 v[60:63], v[144:147], v[186:189], v[60:63]
	v_mfma_f32_16x16x32_bf16 v[56:59], v[162:165], v[186:189], v[56:59]
	v_mfma_f32_16x16x32_bf16 v[44:47], v[144:147], v[196:199], v[44:47]
	v_mfma_f32_16x16x32_bf16 v[40:43], v[162:165], v[196:199], v[40:43]
	v_mfma_f32_16x16x32_bf16 v[28:31], v[144:147], v[204:207], v[28:31]
	v_mfma_f32_16x16x32_bf16 v[24:27], v[162:165], v[204:207], v[24:27]
	v_mfma_f32_16x16x32_bf16 v[12:15], v[144:147], v[212:215], v[12:15]
	v_mfma_f32_16x16x32_bf16 v[8:11], v[162:165], v[212:215], v[8:11]
	v_mfma_f32_16x16x32_bf16 v[60:63], v[158:161], v[190:193], v[60:63]
	v_mfma_f32_16x16x32_bf16 v[56:59], v[166:169], v[190:193], v[56:59]
	v_mfma_f32_16x16x32_bf16 v[44:47], v[158:161], v[200:203], v[44:47]
	v_mfma_f32_16x16x32_bf16 v[40:43], v[166:169], v[200:203], v[40:43]
	v_mfma_f32_16x16x32_bf16 v[28:31], v[158:161], v[208:211], v[28:31]
	v_mfma_f32_16x16x32_bf16 v[24:27], v[166:169], v[208:211], v[24:27]
	v_mfma_f32_16x16x32_bf16 v[12:15], v[158:161], v[216:219], v[12:15]
	v_mfma_f32_16x16x32_bf16 v[8:11], v[166:169], v[216:219], v[8:11]
	s_setprio 0
	s_setprio 1
	v_mfma_f32_16x16x32_bf16 v[52:55], v[170:173], v[186:189], v[52:55]
	v_mfma_f32_16x16x32_bf16 v[48:51], v[178:181], v[186:189], v[48:51]
	v_mfma_f32_16x16x32_bf16 v[36:39], v[170:173], v[196:199], v[36:39]
	v_mfma_f32_16x16x32_bf16 v[32:35], v[178:181], v[196:199], v[32:35]
	v_mfma_f32_16x16x32_bf16 v[20:23], v[170:173], v[204:207], v[20:23]
	v_mfma_f32_16x16x32_bf16 v[16:19], v[178:181], v[204:207], v[16:19]
	v_mfma_f32_16x16x32_bf16 v[4:7], v[170:173], v[212:215], v[4:7]
	v_mfma_f32_16x16x32_bf16 v[0:3], v[178:181], v[212:215], v[0:3]
	v_mfma_f32_16x16x32_bf16 v[52:55], v[174:177], v[190:193], v[52:55]
	v_mfma_f32_16x16x32_bf16 v[48:51], v[182:185], v[190:193], v[48:51]
	v_mfma_f32_16x16x32_bf16 v[36:39], v[174:177], v[200:203], v[36:39]
	v_mfma_f32_16x16x32_bf16 v[32:35], v[182:185], v[200:203], v[32:35]
	v_mfma_f32_16x16x32_bf16 v[20:23], v[174:177], v[208:211], v[20:23]
	v_mfma_f32_16x16x32_bf16 v[16:19], v[182:185], v[208:211], v[16:19]
	v_mfma_f32_16x16x32_bf16 v[4:7], v[174:177], v[216:219], v[4:7]
	v_mfma_f32_16x16x32_bf16 v[0:3], v[182:185], v[216:219], v[0:3]
	s_setprio 0
	s_barrier
	s_add_i32 m0, s61, 0xffffff80
	s_nop 0
	global_load_lds_dwordx4 v128, s[98:99] offset:128
	s_add_i32 m0, s62, 0xffffff80
	s_nop 0
	global_load_lds_dwordx4 v132, s[98:99] offset:128
	s_add_i32 s82, s82, 2
	s_add_u32 s30, s30, 0x100
	s_addc_u32 s31, s31, 0
	s_add_u32 s80, s80, 0x100
	s_addc_u32 s81, s81, 0
	s_cmp_gt_u32 s82, 13
	s_cbranch_scc0 .LBB0_786
	s_and_b64 vcc, exec, s[20:21]
	s_cbranch_vccz .LBB0_789
	s_barrier

.LBB0_923:
	ds_read_b128 v[152:155], v148
	ds_read_b128 v[156:159], v148 offset:1024
	ds_read_b128 v[160:163], v148 offset:2048
	ds_read_b128 v[164:167], v148 offset:3072
	ds_read_b128 v[168:171], v149
	ds_read_b128 v[172:175], v149 offset:1024
	ds_read_b128 v[176:179], v149 offset:2048
	ds_read_b128 v[180:183], v149 offset:3072
	s_add_u32 s26, s24, 0x100
	s_addc_u32 s27, s25, 0
	s_cmp_eq_u32 s79, 8
	s_cselect_b32 s31, s21, s27
	s_cselect_b32 s30, s20, s26
	s_cselect_b32 s29, s23, s78
	s_cselect_b32 s28, s22, s73
	s_mov_b32 m0, s60
	v_lshl_add_u64 v[192:193], s[24:25], 0, v[138:139]
	ds_read_b128 v[184:187], v150
	ds_read_b128 v[188:191], v150 offset:1024
	ds_read_b128 v[196:199], v150 offset:2048
	ds_read_b128 v[200:203], v150 offset:3072
	ds_read_b128 v[204:207], v150 offset:4096
	ds_read_b128 v[208:211], v150 offset:5120
	ds_read_b128 v[212:215], v150 offset:6144
	ds_read_b128 v[216:219], v150 offset:7168
	global_load_lds_dwordx4 v[192:193], off
	v_lshl_add_u64 v[192:193], s[24:25], 0, v[140:141]
	s_add_i32 m0, s40, 0xe000
	s_nop 0
	global_load_lds_dwordx4 v[192:193], off
	s_waitcnt vmcnt(8)
	s_waitcnt lgkmcnt(0)
	s_barrier
	s_setprio 1
	s_waitcnt lgkmcnt(0)
	v_mfma_f32_16x16x32_bf16 v[124:127], v[152:155], v[184:187], v[124:127]
	v_mfma_f32_16x16x32_bf16 v[120:123], v[160:163], v[184:187], v[120:123]
	v_mfma_f32_16x16x32_bf16 v[108:111], v[152:155], v[196:199], v[108:111]
	v_mfma_f32_16x16x32_bf16 v[104:107], v[160:163], v[196:199], v[104:107]
	v_mfma_f32_16x16x32_bf16 v[92:95], v[152:155], v[204:207], v[92:95]
	v_mfma_f32_16x16x32_bf16 v[88:91], v[160:163], v[204:207], v[88:91]
	v_mfma_f32_16x16x32_bf16 v[76:79], v[152:155], v[212:215], v[76:79]
	v_mfma_f32_16x16x32_bf16 v[72:75], v[160:163], v[212:215], v[72:75]
	v_mfma_f32_16x16x32_bf16 v[124:127], v[156:159], v[188:191], v[124:127]
	v_mfma_f32_16x16x32_bf16 v[120:123], v[164:167], v[188:191], v[120:123]
	v_mfma_f32_16x16x32_bf16 v[108:111], v[156:159], v[200:203], v[108:111]
	v_mfma_f32_16x16x32_bf16 v[104:107], v[164:167], v[200:203], v[104:107]
	v_mfma_f32_16x16x32_bf16 v[92:95], v[156:159], v[208:211], v[92:95]
	v_mfma_f32_16x16x32_bf16 v[88:91], v[164:167], v[208:211], v[88:91]
	v_mfma_f32_16x16x32_bf16 v[76:79], v[156:159], v[216:219], v[76:79]
	v_mfma_f32_16x16x32_bf16 v[72:75], v[164:167], v[216:219], v[72:75]
	s_setprio 0
	s_setprio 1
	v_mfma_f32_16x16x32_bf16 v[116:119], v[168:171], v[184:187], v[116:119]
	v_mfma_f32_16x16x32_bf16 v[112:115], v[176:179], v[184:187], v[112:115]
	v_mfma_f32_16x16x32_bf16 v[100:103], v[168:171], v[196:199], v[100:103]
	v_mfma_f32_16x16x32_bf16 v[96:99], v[176:179], v[196:199], v[96:99]
	v_mfma_f32_16x16x32_bf16 v[84:87], v[168:171], v[204:207], v[84:87]
	v_mfma_f32_16x16x32_bf16 v[80:83], v[176:179], v[204:207], v[80:83]
	v_mfma_f32_16x16x32_bf16 v[68:71], v[168:171], v[212:215], v[68:71]
	v_mfma_f32_16x16x32_bf16 v[64:67], v[176:179], v[212:215], v[64:67]
	v_mfma_f32_16x16x32_bf16 v[116:119], v[172:175], v[188:191], v[116:119]
	v_mfma_f32_16x16x32_bf16 v[112:115], v[180:183], v[188:191], v[112:115]
	v_mfma_f32_16x16x32_bf16 v[100:103], v[172:175], v[200:203], v[100:103]
	v_mfma_f32_16x16x32_bf16 v[96:99], v[180:183], v[200:203], v[96:99]
	v_mfma_f32_16x16x32_bf16 v[84:87], v[172:175], v[208:211], v[84:87]
	v_mfma_f32_16x16x32_bf16 v[80:83], v[180:183], v[208:211], v[80:83]
	v_mfma_f32_16x16x32_bf16 v[68:71], v[172:175], v[216:219], v[68:71]
	v_mfma_f32_16x16x32_bf16 v[64:67], v[180:183], v[216:219], v[64:67]
	s_setprio 0
	s_barrier
	s_add_i32 s24, s58, s39
	v_lshl_add_u64 v[192:193], s[28:29], 0, v[132:133]
	s_mov_b32 m0, s24
	ds_read_b128 v[184:187], v150 offset:16384
	ds_read_b128 v[188:191], v150 offset:17408
	ds_read_b128 v[196:199], v150 offset:18432
	ds_read_b128 v[200:203], v150 offset:19456
	ds_read_b128 v[204:207], v150 offset:20480
	ds_read_b128 v[208:211], v150 offset:21504
	ds_read_b128 v[212:215], v150 offset:22528
	ds_read_b128 v[216:219], v150 offset:23552
	global_load_lds_dwordx4 v[192:193], off
	s_add_i32 m0, s24, 0x2000
	s_add_u32 s24, s28, 0x30000
	v_lshl_add_u64 v[220:221], s[28:29], 0, v[128:129]
	s_addc_u32 s25, s29, 0
	s_add_i32 s80, s59, s39
	global_load_lds_dwordx4 v[220:221], off
	s_mov_b32 m0, s80
	s_mov_b64 s[98:99], s[30:31]
	global_load_lds_dwordx4 v132, s[24:25]
	s_add_i32 m0, s80, 0x2000
	s_nop 0
	global_load_lds_dwordx4 v128, s[24:25]
	s_waitcnt vmcnt(6)
	s_waitcnt lgkmcnt(0)
	s_barrier
	s_setprio 1
	s_waitcnt lgkmcnt(0)
	v_mfma_f32_16x16x32_bf16 v[60:63], v[152:155], v[184:187], v[60:63]
	v_mfma_f32_16x16x32_bf16 v[56:59], v[160:163], v[184:187], v[56:59]
	v_mfma_f32_16x16x32_bf16 v[44:47], v[152:155], v[196:199], v[44:47]
	v_mfma_f32_16x16x32_bf16 v[40:43], v[160:163], v[196:199], v[40:43]
	v_mfma_f32_16x16x32_bf16 v[28:31], v[152:155], v[204:207], v[28:31]
	v_mfma_f32_16x16x32_bf16 v[24:27], v[160:163], v[204:207], v[24:27]
	v_mfma_f32_16x16x32_bf16 v[12:15], v[152:155], v[212:215], v[12:15]
	v_mfma_f32_16x16x32_bf16 v[8:11], v[160:163], v[212:215], v[8:11]
	v_mfma_f32_16x16x32_bf16 v[60:63], v[156:159], v[188:191], v[60:63]
	v_mfma_f32_16x16x32_bf16 v[56:59], v[164:167], v[188:191], v[56:59]
	v_mfma_f32_16x16x32_bf16 v[44:47], v[156:159], v[200:203], v[44:47]
	v_mfma_f32_16x16x32_bf16 v[40:43], v[164:167], v[200:203], v[40:43]
	v_mfma_f32_16x16x32_bf16 v[28:31], v[156:159], v[208:211], v[28:31]
	v_mfma_f32_16x16x32_bf16 v[24:27], v[164:167], v[208:211], v[24:27]
	v_mfma_f32_16x16x32_bf16 v[12:15], v[156:159], v[216:219], v[12:15]
	v_mfma_f32_16x16x32_bf16 v[8:11], v[164:167], v[216:219], v[8:11]
	s_setprio 0
	s_setprio 1
	v_mfma_f32_16x16x32_bf16 v[52:55], v[168:171], v[184:187], v[52:55]
	v_mfma_f32_16x16x32_bf16 v[48:51], v[176:179], v[184:187], v[48:51]
	v_mfma_f32_16x16x32_bf16 v[36:39], v[168:171], v[196:199], v[36:39]
	v_mfma_f32_16x16x32_bf16 v[32:35], v[176:179], v[196:199], v[32:35]
	v_mfma_f32_16x16x32_bf16 v[20:23], v[168:171], v[204:207], v[20:23]
	v_mfma_f32_16x16x32_bf16 v[16:19], v[176:179], v[204:207], v[16:19]
	v_mfma_f32_16x16x32_bf16 v[4:7], v[168:171], v[212:215], v[4:7]
	v_mfma_f32_16x16x32_bf16 v[0:3], v[176:179], v[212:215], v[0:3]
	v_mfma_f32_16x16x32_bf16 v[52:55], v[172:175], v[188:191], v[52:55]
	v_mfma_f32_16x16x32_bf16 v[48:51], v[180:183], v[188:191], v[48:51]
	v_mfma_f32_16x16x32_bf16 v[36:39], v[172:175], v[200:203], v[36:39]
	v_mfma_f32_16x16x32_bf16 v[32:35], v[180:183], v[200:203], v[32:35]
	v_mfma_f32_16x16x32_bf16 v[20:23], v[172:175], v[208:211], v[20:23]
	v_mfma_f32_16x16x32_bf16 v[16:19], v[180:183], v[208:211], v[16:19]
	v_mfma_f32_16x16x32_bf16 v[4:7], v[172:175], v[216:219], v[4:7]
	v_mfma_f32_16x16x32_bf16 v[0:3], v[180:183], v[216:219], v[0:3]
	s_setprio 0
	s_barrier
	s_add_i32 s80, 0, 0x18000
	v_add_u32_e32 v151, s80, v142
	s_add_i32 s81, 0, 0x1c000
	ds_read_b128 v[152:155], v151
	ds_read_b128 v[156:159], v151 offset:1024
	ds_read_b128 v[160:163], v151 offset:2048
	ds_read_b128 v[164:167], v151 offset:3072
	v_add_u32_e32 v151, s81, v142
	ds_read_b128 v[168:171], v151
	ds_read_b128 v[172:175], v151 offset:1024
	ds_read_b128 v[176:179], v151 offset:2048
	ds_read_b128 v[180:183], v151 offset:3072
	s_add_u32 s24, s30, 0x30000
	s_addc_u32 s25, s31, 0
	ds_read_b128 v[184:187], v150 offset:32768
	ds_read_b128 v[188:191], v150 offset:33792
	ds_read_b128 v[196:199], v150 offset:34816
	ds_read_b128 v[200:203], v150 offset:35840
	ds_read_b128 v[204:207], v150 offset:36864
	ds_read_b128 v[208:211], v150 offset:37888
	ds_read_b128 v[212:215], v150 offset:38912
	ds_read_b128 v[216:219], v150 offset:39936
	s_mov_b32 m0, s40
	s_nop 0
	global_load_lds_dwordx4 v134, s[98:99]
	s_mov_b32 m0, s41
	s_nop 0
	global_load_lds_dwordx4 v130, s[98:99]
	s_mov_b32 m0, s42
	s_nop 0
	global_load_lds_dwordx4 v134, s[24:25]
	s_mov_b32 m0, s43
	s_nop 0
	global_load_lds_dwordx4 v130, s[24:25]
	s_waitcnt vmcnt(8)
	s_waitcnt lgkmcnt(0)
	s_barrier
	s_setprio 1
	s_waitcnt lgkmcnt(0)
	v_mfma_f32_16x16x32_bf16 v[124:127], v[152:155], v[184:187], v[124:127]
	v_mfma_f32_16x16x32_bf16 v[120:123], v[160:163], v[184:187], v[120:123]
	v_mfma_f32_16x16x32_bf16 v[108:111], v[152:155], v[196:199], v[108:111]
	v_mfma_f32_16x16x32_bf16 v[104:107], v[160:163], v[196:199], v[104:107]
	v_mfma_f32_16x16x32_bf16 v[92:95], v[152:155], v[204:207], v[92:95]
	v_mfma_f32_16x16x32_bf16 v[88:91], v[160:163], v[204:207], v[88:91]
	v_mfma_f32_16x16x32_bf16 v[76:79], v[152:155], v[212:215], v[76:79]
	v_mfma_f32_16x16x32_bf16 v[72:75], v[160:163], v[212:215], v[72:75]
	v_mfma_f32_16x16x32_bf16 v[124:127], v[156:159], v[188:191], v[124:127]
	v_mfma_f32_16x16x32_bf16 v[120:123], v[164:167], v[188:191], v[120:123]
	v_mfma_f32_16x16x32_bf16 v[108:111], v[156:159], v[200:203], v[108:111]
	v_mfma_f32_16x16x32_bf16 v[104:107], v[164:167], v[200:203], v[104:107]
	v_mfma_f32_16x16x32_bf16 v[92:95], v[156:159], v[208:211], v[92:95]
	v_mfma_f32_16x16x32_bf16 v[88:91], v[164:167], v[208:211], v[88:91]
	v_mfma_f32_16x16x32_bf16 v[76:79], v[156:159], v[216:219], v[76:79]
	v_mfma_f32_16x16x32_bf16 v[72:75], v[164:167], v[216:219], v[72:75]
	s_setprio 0
	s_setprio 1
	v_mfma_f32_16x16x32_bf16 v[116:119], v[168:171], v[184:187], v[116:119]
	v_mfma_f32_16x16x32_bf16 v[112:115], v[176:179], v[184:187], v[112:115]
	v_mfma_f32_16x16x32_bf16 v[100:103], v[168:171], v[196:199], v[100:103]
	v_mfma_f32_16x16x32_bf16 v[96:99], v[176:179], v[196:199], v[96:99]
	v_mfma_f32_16x16x32_bf16 v[84:87], v[168:171], v[204:207], v[84:87]
	v_mfma_f32_16x16x32_bf16 v[80:83], v[176:179], v[204:207], v[80:83]
	v_mfma_f32_16x16x32_bf16 v[68:71], v[168:171], v[212:215], v[68:71]
	v_mfma_f32_16x16x32_bf16 v[64:67], v[176:179], v[212:215], v[64:67]
	v_mfma_f32_16x16x32_bf16 v[116:119], v[172:175], v[188:191], v[116:119]
	v_mfma_f32_16x16x32_bf16 v[112:115], v[180:183], v[188:191], v[112:115]
	v_mfma_f32_16x16x32_bf16 v[100:103], v[172:175], v[200:203], v[100:103]
	v_mfma_f32_16x16x32_bf16 v[96:99], v[180:183], v[200:203], v[96:99]
	v_mfma_f32_16x16x32_bf16 v[84:87], v[172:175], v[208:211], v[84:87]
	v_mfma_f32_16x16x32_bf16 v[80:83], v[180:183], v[208:211], v[80:83]
	v_mfma_f32_16x16x32_bf16 v[68:71], v[172:175], v[216:219], v[68:71]
	v_mfma_f32_16x16x32_bf16 v[64:67], v[180:183], v[216:219], v[64:67]
	s_setprio 0
	s_barrier
	s_add_i32 s24, s80, s39
	v_lshl_add_u64 v[192:193], v[192:193], 0, s[16:17]
	s_mov_b32 m0, s24
	ds_read_b128 v[184:187], v150 offset:49152
	ds_read_b128 v[188:191], v150 offset:50176
	ds_read_b128 v[196:199], v150 offset:51200
	ds_read_b128 v[200:203], v150 offset:52224
	ds_read_b128 v[204:207], v150 offset:53248
	ds_read_b128 v[208:211], v150 offset:54272
	ds_read_b128 v[212:215], v150 offset:55296
	ds_read_b128 v[216:219], v150 offset:56320
	global_load_lds_dwordx4 v[192:193], off
	s_add_i32 m0, s24, 0x2000
	s_add_u32 s24, s28, 0x30080
	v_lshl_add_u64 v[192:193], v[220:221], 0, s[16:17]
	s_addc_u32 s25, s29, 0
	s_add_i32 s28, s81, s39
	global_load_lds_dwordx4 v[192:193], off
	s_mov_b32 m0, s28
	s_nop 0
	global_load_lds_dwordx4 v132, s[24:25]
	s_add_i32 m0, s28, 0x2000
	s_nop 0
	global_load_lds_dwordx4 v128, s[24:25]
	s_waitcnt vmcnt(6)
	s_waitcnt lgkmcnt(0)
	s_barrier
	s_setprio 1
	s_waitcnt lgkmcnt(0)
	v_mfma_f32_16x16x32_bf16 v[60:63], v[152:155], v[184:187], v[60:63]
	v_mfma_f32_16x16x32_bf16 v[56:59], v[160:163], v[184:187], v[56:59]
	v_mfma_f32_16x16x32_bf16 v[44:47], v[152:155], v[196:199], v[44:47]
	v_mfma_f32_16x16x32_bf16 v[40:43], v[160:163], v[196:199], v[40:43]
	v_mfma_f32_16x16x32_bf16 v[28:31], v[152:155], v[204:207], v[28:31]
	v_mfma_f32_16x16x32_bf16 v[24:27], v[160:163], v[204:207], v[24:27]
	v_mfma_f32_16x16x32_bf16 v[12:15], v[152:155], v[212:215], v[12:15]
	v_mfma_f32_16x16x32_bf16 v[8:11], v[160:163], v[212:215], v[8:11]
	v_mfma_f32_16x16x32_bf16 v[60:63], v[156:159], v[188:191], v[60:63]
	v_mfma_f32_16x16x32_bf16 v[56:59], v[164:167], v[188:191], v[56:59]
	v_mfma_f32_16x16x32_bf16 v[44:47], v[156:159], v[200:203], v[44:47]
	v_mfma_f32_16x16x32_bf16 v[40:43], v[164:167], v[200:203], v[40:43]
	v_mfma_f32_16x16x32_bf16 v[28:31], v[156:159], v[208:211], v[28:31]
	v_mfma_f32_16x16x32_bf16 v[24:27], v[164:167], v[208:211], v[24:27]
	v_mfma_f32_16x16x32_bf16 v[12:15], v[156:159], v[216:219], v[12:15]
	v_mfma_f32_16x16x32_bf16 v[8:11], v[164:167], v[216:219], v[8:11]
	s_setprio 0
	s_setprio 1
	v_mfma_f32_16x16x32_bf16 v[52:55], v[168:171], v[184:187], v[52:55]
	v_mfma_f32_16x16x32_bf16 v[48:51], v[176:179], v[184:187], v[48:51]
	v_mfma_f32_16x16x32_bf16 v[36:39], v[168:171], v[196:199], v[36:39]
	v_mfma_f32_16x16x32_bf16 v[32:35], v[176:179], v[196:199], v[32:35]
	v_mfma_f32_16x16x32_bf16 v[20:23], v[168:171], v[204:207], v[20:23]
	v_mfma_f32_16x16x32_bf16 v[16:19], v[176:179], v[204:207], v[16:19]
	v_mfma_f32_16x16x32_bf16 v[4:7], v[168:171], v[212:215], v[4:7]
	v_mfma_f32_16x16x32_bf16 v[0:3], v[176:179], v[212:215], v[0:3]
	v_mfma_f32_16x16x32_bf16 v[52:55], v[172:175], v[188:191], v[52:55]
	v_mfma_f32_16x16x32_bf16 v[48:51], v[180:183], v[188:191], v[48:51]
	v_mfma_f32_16x16x32_bf16 v[36:39], v[172:175], v[200:203], v[36:39]
	v_mfma_f32_16x16x32_bf16 v[32:35], v[180:183], v[200:203], v[32:35]
	v_mfma_f32_16x16x32_bf16 v[20:23], v[172:175], v[208:211], v[20:23]
	v_mfma_f32_16x16x32_bf16 v[16:19], v[180:183], v[208:211], v[16:19]
	v_mfma_f32_16x16x32_bf16 v[4:7], v[172:175], v[216:219], v[4:7]
	v_mfma_f32_16x16x32_bf16 v[0:3], v[180:183], v[216:219], v[0:3]
	s_setprio 0
	s_barrier
	s_add_i32 m0, s45, 0xffffff80
	s_nop 0
	global_load_lds_dwordx4 v134, s[98:99] offset:128
	s_add_i32 m0, s50, 0xffffff80
	s_nop 0
	global_load_lds_dwordx4 v130, s[98:99] offset:128
	s_add_i32 s79, s79, 2
	s_add_u32 s73, s73, 0x100
	s_addc_u32 s78, s78, 0
	s_cmp_gt_u32 s79, 9
	s_mov_b64 s[24:25], s[26:27]
	s_cbranch_scc0 .LBB0_923
	s_and_b64 vcc, exec, s[18:19]
	s_cbranch_vccz .LBB0_926
	s_barrier

.LBB0_947:
	ds_read_b128 v[144:147], v153
	ds_read_b128 v[158:161], v153 offset:1024
	ds_read_b128 v[162:165], v153 offset:2048
	ds_read_b128 v[166:169], v153 offset:3072
	ds_read_b128 v[170:173], v154
	ds_read_b128 v[174:177], v154 offset:1024
	ds_read_b128 v[178:181], v154 offset:2048
	ds_read_b128 v[182:185], v154 offset:3072
	s_add_u32 s36, s34, 0xfffc0080
	s_addc_u32 s37, s35, -1
	s_cmp_eq_u32 s85, 12
	s_cselect_b32 s39, s27, s37
	s_cselect_b32 s38, s81, s36
	s_cselect_b32 s37, s25, s84
	s_cselect_b32 s36, s82, s83
	s_add_i32 m0, s59, 0xc000
	ds_read_b128 v[186:189], v155
	ds_read_b128 v[190:193], v155 offset:1024
	ds_read_b128 v[196:199], v155 offset:2048
	ds_read_b128 v[200:203], v155 offset:3072
	ds_read_b128 v[204:207], v155 offset:4096
	ds_read_b128 v[208:211], v155 offset:5120
	ds_read_b128 v[212:215], v155 offset:6144
	ds_read_b128 v[216:219], v155 offset:7168
	global_load_lds_dwordx4 v136, s[34:35]
	s_add_i32 m0, s59, 0xe000
	s_nop 0
	global_load_lds_dwordx4 v138, s[34:35]
	s_waitcnt vmcnt(8)
	s_waitcnt lgkmcnt(0)
	s_barrier
	s_setprio 1
	s_waitcnt lgkmcnt(0)
	v_mfma_f32_16x16x32_bf16 v[124:127], v[144:147], v[186:189], v[124:127]
	v_mfma_f32_16x16x32_bf16 v[120:123], v[162:165], v[186:189], v[120:123]
	v_mfma_f32_16x16x32_bf16 v[108:111], v[144:147], v[196:199], v[108:111]
	v_mfma_f32_16x16x32_bf16 v[104:107], v[162:165], v[196:199], v[104:107]
	v_mfma_f32_16x16x32_bf16 v[92:95], v[144:147], v[204:207], v[92:95]
	v_mfma_f32_16x16x32_bf16 v[88:91], v[162:165], v[204:207], v[88:91]
	v_mfma_f32_16x16x32_bf16 v[76:79], v[144:147], v[212:215], v[76:79]
	v_mfma_f32_16x16x32_bf16 v[72:75], v[162:165], v[212:215], v[72:75]
	v_mfma_f32_16x16x32_bf16 v[124:127], v[158:161], v[190:193], v[124:127]
	v_mfma_f32_16x16x32_bf16 v[120:123], v[166:169], v[190:193], v[120:123]
	v_mfma_f32_16x16x32_bf16 v[108:111], v[158:161], v[200:203], v[108:111]
	v_mfma_f32_16x16x32_bf16 v[104:107], v[166:169], v[200:203], v[104:107]
	v_mfma_f32_16x16x32_bf16 v[92:95], v[158:161], v[208:211], v[92:95]
	v_mfma_f32_16x16x32_bf16 v[88:91], v[166:169], v[208:211], v[88:91]
	v_mfma_f32_16x16x32_bf16 v[76:79], v[158:161], v[216:219], v[76:79]
	v_mfma_f32_16x16x32_bf16 v[72:75], v[166:169], v[216:219], v[72:75]
	s_setprio 0
	s_setprio 1
	v_mfma_f32_16x16x32_bf16 v[116:119], v[170:173], v[186:189], v[116:119]
	v_mfma_f32_16x16x32_bf16 v[112:115], v[178:181], v[186:189], v[112:115]
	v_mfma_f32_16x16x32_bf16 v[100:103], v[170:173], v[196:199], v[100:103]
	v_mfma_f32_16x16x32_bf16 v[96:99], v[178:181], v[196:199], v[96:99]
	v_mfma_f32_16x16x32_bf16 v[84:87], v[170:173], v[204:207], v[84:87]
	v_mfma_f32_16x16x32_bf16 v[80:83], v[178:181], v[204:207], v[80:83]
	v_mfma_f32_16x16x32_bf16 v[68:71], v[170:173], v[212:215], v[68:71]
	v_mfma_f32_16x16x32_bf16 v[64:67], v[178:181], v[212:215], v[64:67]
	v_mfma_f32_16x16x32_bf16 v[116:119], v[174:177], v[190:193], v[116:119]
	v_mfma_f32_16x16x32_bf16 v[112:115], v[182:185], v[190:193], v[112:115]
	v_mfma_f32_16x16x32_bf16 v[100:103], v[174:177], v[200:203], v[100:103]
	v_mfma_f32_16x16x32_bf16 v[96:99], v[182:185], v[200:203], v[96:99]
	v_mfma_f32_16x16x32_bf16 v[84:87], v[174:177], v[208:211], v[84:87]
	v_mfma_f32_16x16x32_bf16 v[80:83], v[182:185], v[208:211], v[80:83]
	v_mfma_f32_16x16x32_bf16 v[68:71], v[174:177], v[216:219], v[68:71]
	v_mfma_f32_16x16x32_bf16 v[64:67], v[182:185], v[216:219], v[64:67]
	s_setprio 0
	s_barrier
	s_add_i32 s86, s73, s58
	s_mov_b32 m0, s86
	ds_read_b128 v[186:189], v155 offset:16384
	ds_read_b128 v[190:193], v155 offset:17408
	ds_read_b128 v[196:199], v155 offset:18432
	ds_read_b128 v[200:203], v155 offset:19456
	ds_read_b128 v[204:207], v155 offset:20480
	ds_read_b128 v[208:211], v155 offset:21504
	ds_read_b128 v[212:215], v155 offset:22528
	ds_read_b128 v[216:219], v155 offset:23552
	global_load_lds_dwordx4 v130, s[36:37]
	s_add_i32 m0, s86, 0x2000
	s_add_u32 s86, s36, 0x40000
	s_addc_u32 s87, s37, 0
	s_add_i32 s88, s78, s58
	global_load_lds_dwordx4 v134, s[36:37]
	s_mov_b32 m0, s88
	s_mov_b64 s[98:99], s[38:39]
	global_load_lds_dwordx4 v130, s[86:87]
	s_add_i32 m0, s88, 0x2000
	s_nop 0
	global_load_lds_dwordx4 v134, s[86:87]
	s_waitcnt vmcnt(6)
	s_waitcnt lgkmcnt(0)
	s_barrier
	s_setprio 1
	s_waitcnt lgkmcnt(0)
	v_mfma_f32_16x16x32_bf16 v[60:63], v[144:147], v[186:189], v[60:63]
	v_mfma_f32_16x16x32_bf16 v[56:59], v[162:165], v[186:189], v[56:59]
	v_mfma_f32_16x16x32_bf16 v[44:47], v[144:147], v[196:199], v[44:47]
	v_mfma_f32_16x16x32_bf16 v[40:43], v[162:165], v[196:199], v[40:43]
	v_mfma_f32_16x16x32_bf16 v[28:31], v[144:147], v[204:207], v[28:31]
	v_mfma_f32_16x16x32_bf16 v[24:27], v[162:165], v[204:207], v[24:27]
	v_mfma_f32_16x16x32_bf16 v[12:15], v[144:147], v[212:215], v[12:15]
	v_mfma_f32_16x16x32_bf16 v[8:11], v[162:165], v[212:215], v[8:11]
	v_mfma_f32_16x16x32_bf16 v[60:63], v[158:161], v[190:193], v[60:63]
	v_mfma_f32_16x16x32_bf16 v[56:59], v[166:169], v[190:193], v[56:59]
	v_mfma_f32_16x16x32_bf16 v[44:47], v[158:161], v[200:203], v[44:47]
	v_mfma_f32_16x16x32_bf16 v[40:43], v[166:169], v[200:203], v[40:43]
	v_mfma_f32_16x16x32_bf16 v[28:31], v[158:161], v[208:211], v[28:31]
	v_mfma_f32_16x16x32_bf16 v[24:27], v[166:169], v[208:211], v[24:27]
	v_mfma_f32_16x16x32_bf16 v[12:15], v[158:161], v[216:219], v[12:15]
	v_mfma_f32_16x16x32_bf16 v[8:11], v[166:169], v[216:219], v[8:11]
	s_setprio 0
	s_setprio 1
	v_mfma_f32_16x16x32_bf16 v[52:55], v[170:173], v[186:189], v[52:55]
	v_mfma_f32_16x16x32_bf16 v[48:51], v[178:181], v[186:189], v[48:51]
	v_mfma_f32_16x16x32_bf16 v[36:39], v[170:173], v[196:199], v[36:39]
	v_mfma_f32_16x16x32_bf16 v[32:35], v[178:181], v[196:199], v[32:35]
	v_mfma_f32_16x16x32_bf16 v[20:23], v[170:173], v[204:207], v[20:23]
	v_mfma_f32_16x16x32_bf16 v[16:19], v[178:181], v[204:207], v[16:19]
	v_mfma_f32_16x16x32_bf16 v[4:7], v[170:173], v[212:215], v[4:7]
	v_mfma_f32_16x16x32_bf16 v[0:3], v[178:181], v[212:215], v[0:3]
	v_mfma_f32_16x16x32_bf16 v[52:55], v[174:177], v[190:193], v[52:55]
	v_mfma_f32_16x16x32_bf16 v[48:51], v[182:185], v[190:193], v[48:51]
	v_mfma_f32_16x16x32_bf16 v[36:39], v[174:177], v[200:203], v[36:39]
	v_mfma_f32_16x16x32_bf16 v[32:35], v[182:185], v[200:203], v[32:35]
	v_mfma_f32_16x16x32_bf16 v[20:23], v[174:177], v[208:211], v[20:23]
	v_mfma_f32_16x16x32_bf16 v[16:19], v[182:185], v[208:211], v[16:19]
	v_mfma_f32_16x16x32_bf16 v[4:7], v[174:177], v[216:219], v[4:7]
	v_mfma_f32_16x16x32_bf16 v[0:3], v[182:185], v[216:219], v[0:3]
	s_setprio 0
	s_barrier
	s_add_i32 s86, 0, 0x18000
	v_add_u32_e32 v157, s86, v151
	s_add_i32 s87, 0, 0x1c000
	ds_read_b128 v[144:147], v157
	ds_read_b128 v[158:161], v157 offset:1024
	ds_read_b128 v[162:165], v157 offset:2048
	ds_read_b128 v[166:169], v157 offset:3072
	v_add_u32_e32 v157, s87, v151
	ds_read_b128 v[170:173], v157
	ds_read_b128 v[174:177], v157 offset:1024
	ds_read_b128 v[178:181], v157 offset:2048
	ds_read_b128 v[182:185], v157 offset:3072
	s_add_u32 s38, s38, 0x40000
	s_addc_u32 s39, s39, 0
	ds_read_b128 v[186:189], v155 offset:32768
	ds_read_b128 v[190:193], v155 offset:33792
	ds_read_b128 v[196:199], v155 offset:34816
	ds_read_b128 v[200:203], v155 offset:35840
	ds_read_b128 v[204:207], v155 offset:36864
	ds_read_b128 v[208:211], v155 offset:37888
	ds_read_b128 v[212:215], v155 offset:38912
	ds_read_b128 v[216:219], v155 offset:39936
	s_mov_b32 m0, s59
	s_nop 0
	global_load_lds_dwordx4 v128, s[98:99]
	s_mov_b32 m0, s60
	s_nop 0
	global_load_lds_dwordx4 v132, s[98:99]
	s_mov_b32 m0, s61
	s_nop 0
	global_load_lds_dwordx4 v128, s[38:39]
	s_mov_b32 m0, s62
	s_nop 0
	global_load_lds_dwordx4 v132, s[38:39]
	s_waitcnt vmcnt(8)
	s_waitcnt lgkmcnt(0)
	s_barrier
	s_setprio 1
	s_waitcnt lgkmcnt(0)
	v_mfma_f32_16x16x32_bf16 v[124:127], v[144:147], v[186:189], v[124:127]
	v_mfma_f32_16x16x32_bf16 v[120:123], v[162:165], v[186:189], v[120:123]
	v_mfma_f32_16x16x32_bf16 v[108:111], v[144:147], v[196:199], v[108:111]
	v_mfma_f32_16x16x32_bf16 v[104:107], v[162:165], v[196:199], v[104:107]
	v_mfma_f32_16x16x32_bf16 v[92:95], v[144:147], v[204:207], v[92:95]
	v_mfma_f32_16x16x32_bf16 v[88:91], v[162:165], v[204:207], v[88:91]
	v_mfma_f32_16x16x32_bf16 v[76:79], v[144:147], v[212:215], v[76:79]
	v_mfma_f32_16x16x32_bf16 v[72:75], v[162:165], v[212:215], v[72:75]
	v_mfma_f32_16x16x32_bf16 v[124:127], v[158:161], v[190:193], v[124:127]
	v_mfma_f32_16x16x32_bf16 v[120:123], v[166:169], v[190:193], v[120:123]
	v_mfma_f32_16x16x32_bf16 v[108:111], v[158:161], v[200:203], v[108:111]
	v_mfma_f32_16x16x32_bf16 v[104:107], v[166:169], v[200:203], v[104:107]
	v_mfma_f32_16x16x32_bf16 v[92:95], v[158:161], v[208:211], v[92:95]
	v_mfma_f32_16x16x32_bf16 v[88:91], v[166:169], v[208:211], v[88:91]
	v_mfma_f32_16x16x32_bf16 v[76:79], v[158:161], v[216:219], v[76:79]
	v_mfma_f32_16x16x32_bf16 v[72:75], v[166:169], v[216:219], v[72:75]
	s_setprio 0
	s_setprio 1
	v_mfma_f32_16x16x32_bf16 v[116:119], v[170:173], v[186:189], v[116:119]
	v_mfma_f32_16x16x32_bf16 v[112:115], v[178:181], v[186:189], v[112:115]
	v_mfma_f32_16x16x32_bf16 v[100:103], v[170:173], v[196:199], v[100:103]
	v_mfma_f32_16x16x32_bf16 v[96:99], v[178:181], v[196:199], v[96:99]
	v_mfma_f32_16x16x32_bf16 v[84:87], v[170:173], v[204:207], v[84:87]
	v_mfma_f32_16x16x32_bf16 v[80:83], v[178:181], v[204:207], v[80:83]
	v_mfma_f32_16x16x32_bf16 v[68:71], v[170:173], v[212:215], v[68:71]
	v_mfma_f32_16x16x32_bf16 v[64:67], v[178:181], v[212:215], v[64:67]
	v_mfma_f32_16x16x32_bf16 v[116:119], v[174:177], v[190:193], v[116:119]
	v_mfma_f32_16x16x32_bf16 v[112:115], v[182:185], v[190:193], v[112:115]
	v_mfma_f32_16x16x32_bf16 v[100:103], v[174:177], v[200:203], v[100:103]
	v_mfma_f32_16x16x32_bf16 v[96:99], v[182:185], v[200:203], v[96:99]
	v_mfma_f32_16x16x32_bf16 v[84:87], v[174:177], v[208:211], v[84:87]
	v_mfma_f32_16x16x32_bf16 v[80:83], v[182:185], v[208:211], v[80:83]
	v_mfma_f32_16x16x32_bf16 v[68:71], v[174:177], v[216:219], v[68:71]
	v_mfma_f32_16x16x32_bf16 v[64:67], v[182:185], v[216:219], v[64:67]
	s_setprio 0
	s_barrier
	s_add_i32 s38, s86, s58
	s_add_i32 m0, s38, 0xffffff80
	ds_read_b128 v[186:189], v155 offset:49152
	ds_read_b128 v[190:193], v155 offset:50176
	ds_read_b128 v[196:199], v155 offset:51200
	ds_read_b128 v[200:203], v155 offset:52224
	ds_read_b128 v[204:207], v155 offset:53248
	ds_read_b128 v[208:211], v155 offset:54272
	ds_read_b128 v[212:215], v155 offset:55296
	ds_read_b128 v[216:219], v155 offset:56320
	global_load_lds_dwordx4 v130, s[36:37] offset:128
	s_add_i32 m0, s38, 0x1f80
	s_add_i32 s38, s87, s58
	global_load_lds_dwordx4 v134, s[36:37] offset:128
	s_add_u32 s36, s36, 0x40080
	s_addc_u32 s37, s37, 0
	s_mov_b32 m0, s38
	s_nop 0
	global_load_lds_dwordx4 v130, s[36:37]
	s_add_i32 m0, s38, 0x2000
	s_nop 0
	global_load_lds_dwordx4 v134, s[36:37]
	s_waitcnt vmcnt(6)
	s_waitcnt lgkmcnt(0)
	s_barrier
	s_setprio 1
	s_waitcnt lgkmcnt(0)
	v_mfma_f32_16x16x32_bf16 v[60:63], v[144:147], v[186:189], v[60:63]
	v_mfma_f32_16x16x32_bf16 v[56:59], v[162:165], v[186:189], v[56:59]
	v_mfma_f32_16x16x32_bf16 v[44:47], v[144:147], v[196:199], v[44:47]
	v_mfma_f32_16x16x32_bf16 v[40:43], v[162:165], v[196:199], v[40:43]
	v_mfma_f32_16x16x32_bf16 v[28:31], v[144:147], v[204:207], v[28:31]
	v_mfma_f32_16x16x32_bf16 v[24:27], v[162:165], v[204:207], v[24:27]
	v_mfma_f32_16x16x32_bf16 v[12:15], v[144:147], v[212:215], v[12:15]
	v_mfma_f32_16x16x32_bf16 v[8:11], v[162:165], v[212:215], v[8:11]
	v_mfma_f32_16x16x32_bf16 v[60:63], v[158:161], v[190:193], v[60:63]
	v_mfma_f32_16x16x32_bf16 v[56:59], v[166:169], v[190:193], v[56:59]
	v_mfma_f32_16x16x32_bf16 v[44:47], v[158:161], v[200:203], v[44:47]
	v_mfma_f32_16x16x32_bf16 v[40:43], v[166:169], v[200:203], v[40:43]
	v_mfma_f32_16x16x32_bf16 v[28:31], v[158:161], v[208:211], v[28:31]
	v_mfma_f32_16x16x32_bf16 v[24:27], v[166:169], v[208:211], v[24:27]
	v_mfma_f32_16x16x32_bf16 v[12:15], v[158:161], v[216:219], v[12:15]
	v_mfma_f32_16x16x32_bf16 v[8:11], v[166:169], v[216:219], v[8:11]
	s_setprio 0
	s_setprio 1
	v_mfma_f32_16x16x32_bf16 v[52:55], v[170:173], v[186:189], v[52:55]
	v_mfma_f32_16x16x32_bf16 v[48:51], v[178:181], v[186:189], v[48:51]
	v_mfma_f32_16x16x32_bf16 v[36:39], v[170:173], v[196:199], v[36:39]
	v_mfma_f32_16x16x32_bf16 v[32:35], v[178:181], v[196:199], v[32:35]
	v_mfma_f32_16x16x32_bf16 v[20:23], v[170:173], v[204:207], v[20:23]
	v_mfma_f32_16x16x32_bf16 v[16:19], v[178:181], v[204:207], v[16:19]
	v_mfma_f32_16x16x32_bf16 v[4:7], v[170:173], v[212:215], v[4:7]
	v_mfma_f32_16x16x32_bf16 v[0:3], v[178:181], v[212:215], v[0:3]
	v_mfma_f32_16x16x32_bf16 v[52:55], v[174:177], v[190:193], v[52:55]
	v_mfma_f32_16x16x32_bf16 v[48:51], v[182:185], v[190:193], v[48:51]
	v_mfma_f32_16x16x32_bf16 v[36:39], v[174:177], v[200:203], v[36:39]
	v_mfma_f32_16x16x32_bf16 v[32:35], v[182:185], v[200:203], v[32:35]
	v_mfma_f32_16x16x32_bf16 v[20:23], v[174:177], v[208:211], v[20:23]
	v_mfma_f32_16x16x32_bf16 v[16:19], v[182:185], v[208:211], v[16:19]
	v_mfma_f32_16x16x32_bf16 v[4:7], v[174:177], v[216:219], v[4:7]
	v_mfma_f32_16x16x32_bf16 v[0:3], v[182:185], v[216:219], v[0:3]
	s_setprio 0
	s_barrier
	s_add_i32 m0, s70, 0xffffff80
	s_nop 0
	global_load_lds_dwordx4 v128, s[98:99] offset:128
	s_add_i32 m0, s71, 0xffffff80
	s_nop 0
	global_load_lds_dwordx4 v132, s[98:99] offset:128
	s_add_i32 s85, s85, 2
	s_add_u32 s34, s34, 0x100
	s_addc_u32 s35, s35, 0
	s_add_u32 s83, s83, 0x100
	s_addc_u32 s84, s84, 0
	s_cmp_gt_u32 s85, 13
	s_cbranch_scc0 .LBB0_947
	s_and_b64 vcc, exec, s[22:23]
	s_cbranch_vccz .LBB0_950
	s_barrier

.LBB0_1023:
	ds_read_b128 v[144:147], v153
	ds_read_b128 v[156:159], v153 offset:1024
	ds_read_b128 v[160:163], v153 offset:2048
	ds_read_b128 v[164:167], v153 offset:3072
	ds_read_b128 v[168:171], v154
	ds_read_b128 v[172:175], v154 offset:1024
	ds_read_b128 v[176:179], v154 offset:2048
	ds_read_b128 v[180:183], v154 offset:3072
	s_add_u32 s44, s42, 0xfffe0080
	s_addc_u32 s45, s43, -1
	s_cmp_eq_u32 s87, 4
	s_cselect_b32 s59, s35, s45
	s_cselect_b32 s58, s83, s44
	s_cselect_b32 s45, s31, s86
	s_cselect_b32 s44, s84, s85
	s_add_i32 m0, s41, 0xc000
	ds_read_b128 v[184:187], v155
	ds_read_b128 v[188:191], v155 offset:1024
	ds_read_b128 v[196:199], v155 offset:2048
	ds_read_b128 v[200:203], v155 offset:3072
	ds_read_b128 v[204:207], v155 offset:4096
	ds_read_b128 v[208:211], v155 offset:5120
	ds_read_b128 v[212:215], v155 offset:6144
	ds_read_b128 v[216:219], v155 offset:7168
	global_load_lds_dwordx4 v136, s[42:43]
	s_add_i32 m0, s41, 0xe000
	s_nop 0
	global_load_lds_dwordx4 v138, s[42:43]
	s_waitcnt vmcnt(8)
	s_waitcnt lgkmcnt(0)
	s_barrier
	s_setprio 1
	s_waitcnt lgkmcnt(0)
	v_mfma_f32_16x16x32_bf16 v[124:127], v[144:147], v[184:187], v[124:127]
	v_mfma_f32_16x16x32_bf16 v[120:123], v[160:163], v[184:187], v[120:123]
	v_mfma_f32_16x16x32_bf16 v[108:111], v[144:147], v[196:199], v[108:111]
	v_mfma_f32_16x16x32_bf16 v[104:107], v[160:163], v[196:199], v[104:107]
	v_mfma_f32_16x16x32_bf16 v[92:95], v[144:147], v[204:207], v[92:95]
	v_mfma_f32_16x16x32_bf16 v[88:91], v[160:163], v[204:207], v[88:91]
	v_mfma_f32_16x16x32_bf16 v[76:79], v[144:147], v[212:215], v[76:79]
	v_mfma_f32_16x16x32_bf16 v[72:75], v[160:163], v[212:215], v[72:75]
	v_mfma_f32_16x16x32_bf16 v[124:127], v[156:159], v[188:191], v[124:127]
	v_mfma_f32_16x16x32_bf16 v[120:123], v[164:167], v[188:191], v[120:123]
	v_mfma_f32_16x16x32_bf16 v[108:111], v[156:159], v[200:203], v[108:111]
	v_mfma_f32_16x16x32_bf16 v[104:107], v[164:167], v[200:203], v[104:107]
	v_mfma_f32_16x16x32_bf16 v[92:95], v[156:159], v[208:211], v[92:95]
	v_mfma_f32_16x16x32_bf16 v[88:91], v[164:167], v[208:211], v[88:91]
	v_mfma_f32_16x16x32_bf16 v[76:79], v[156:159], v[216:219], v[76:79]
	v_mfma_f32_16x16x32_bf16 v[72:75], v[164:167], v[216:219], v[72:75]
	s_setprio 0
	s_setprio 1
	v_mfma_f32_16x16x32_bf16 v[116:119], v[168:171], v[184:187], v[116:119]
	v_mfma_f32_16x16x32_bf16 v[112:115], v[176:179], v[184:187], v[112:115]
	v_mfma_f32_16x16x32_bf16 v[100:103], v[168:171], v[196:199], v[100:103]
	v_mfma_f32_16x16x32_bf16 v[96:99], v[176:179], v[196:199], v[96:99]
	v_mfma_f32_16x16x32_bf16 v[84:87], v[168:171], v[204:207], v[84:87]
	v_mfma_f32_16x16x32_bf16 v[80:83], v[176:179], v[204:207], v[80:83]
	v_mfma_f32_16x16x32_bf16 v[68:71], v[168:171], v[212:215], v[68:71]
	v_mfma_f32_16x16x32_bf16 v[64:67], v[176:179], v[212:215], v[64:67]
	v_mfma_f32_16x16x32_bf16 v[116:119], v[172:175], v[188:191], v[116:119]
	v_mfma_f32_16x16x32_bf16 v[112:115], v[180:183], v[188:191], v[112:115]
	v_mfma_f32_16x16x32_bf16 v[100:103], v[172:175], v[200:203], v[100:103]
	v_mfma_f32_16x16x32_bf16 v[96:99], v[180:183], v[200:203], v[96:99]
	v_mfma_f32_16x16x32_bf16 v[84:87], v[172:175], v[208:211], v[84:87]
	v_mfma_f32_16x16x32_bf16 v[80:83], v[180:183], v[208:211], v[80:83]
	v_mfma_f32_16x16x32_bf16 v[68:71], v[172:175], v[216:219], v[68:71]
	v_mfma_f32_16x16x32_bf16 v[64:67], v[180:183], v[216:219], v[64:67]
	s_setprio 0
	s_barrier
	s_add_i32 s88, s80, s62
	s_mov_b32 m0, s88
	ds_read_b128 v[184:187], v155 offset:16384
	ds_read_b128 v[188:191], v155 offset:17408
	ds_read_b128 v[196:199], v155 offset:18432
	ds_read_b128 v[200:203], v155 offset:19456
	ds_read_b128 v[204:207], v155 offset:20480
	ds_read_b128 v[208:211], v155 offset:21504
	ds_read_b128 v[212:215], v155 offset:22528
	ds_read_b128 v[216:219], v155 offset:23552
	global_load_lds_dwordx4 v130, s[44:45]
	s_add_i32 m0, s88, 0x2000
	s_add_u32 s88, s44, 0x20000
	s_addc_u32 s89, s45, 0
	s_add_i32 s90, s81, s62
	global_load_lds_dwordx4 v134, s[44:45]
	s_mov_b32 m0, s90
	s_mov_b64 s[98:99], s[58:59]
	global_load_lds_dwordx4 v130, s[88:89]
	s_add_i32 m0, s90, 0x2000
	s_nop 0
	global_load_lds_dwordx4 v134, s[88:89]
	s_waitcnt vmcnt(6)
	s_waitcnt lgkmcnt(0)
	s_barrier
	s_setprio 1
	s_waitcnt lgkmcnt(0)
	v_mfma_f32_16x16x32_bf16 v[60:63], v[144:147], v[184:187], v[60:63]
	v_mfma_f32_16x16x32_bf16 v[56:59], v[160:163], v[184:187], v[56:59]
	v_mfma_f32_16x16x32_bf16 v[44:47], v[144:147], v[196:199], v[44:47]
	v_mfma_f32_16x16x32_bf16 v[40:43], v[160:163], v[196:199], v[40:43]
	v_mfma_f32_16x16x32_bf16 v[28:31], v[144:147], v[204:207], v[28:31]
	v_mfma_f32_16x16x32_bf16 v[24:27], v[160:163], v[204:207], v[24:27]
	v_mfma_f32_16x16x32_bf16 v[12:15], v[144:147], v[212:215], v[12:15]
	v_mfma_f32_16x16x32_bf16 v[8:11], v[160:163], v[212:215], v[8:11]
	v_mfma_f32_16x16x32_bf16 v[60:63], v[156:159], v[188:191], v[60:63]
	v_mfma_f32_16x16x32_bf16 v[56:59], v[164:167], v[188:191], v[56:59]
	v_mfma_f32_16x16x32_bf16 v[44:47], v[156:159], v[200:203], v[44:47]
	v_mfma_f32_16x16x32_bf16 v[40:43], v[164:167], v[200:203], v[40:43]
	v_mfma_f32_16x16x32_bf16 v[28:31], v[156:159], v[208:211], v[28:31]
	v_mfma_f32_16x16x32_bf16 v[24:27], v[164:167], v[208:211], v[24:27]
	v_mfma_f32_16x16x32_bf16 v[12:15], v[156:159], v[216:219], v[12:15]
	v_mfma_f32_16x16x32_bf16 v[8:11], v[164:167], v[216:219], v[8:11]
	s_setprio 0
	s_setprio 1
	v_mfma_f32_16x16x32_bf16 v[52:55], v[168:171], v[184:187], v[52:55]
	v_mfma_f32_16x16x32_bf16 v[48:51], v[176:179], v[184:187], v[48:51]
	v_mfma_f32_16x16x32_bf16 v[36:39], v[168:171], v[196:199], v[36:39]
	v_mfma_f32_16x16x32_bf16 v[32:35], v[176:179], v[196:199], v[32:35]
	v_mfma_f32_16x16x32_bf16 v[20:23], v[168:171], v[204:207], v[20:23]
	v_mfma_f32_16x16x32_bf16 v[16:19], v[176:179], v[204:207], v[16:19]
	v_mfma_f32_16x16x32_bf16 v[4:7], v[168:171], v[212:215], v[4:7]
	v_mfma_f32_16x16x32_bf16 v[0:3], v[176:179], v[212:215], v[0:3]
	v_mfma_f32_16x16x32_bf16 v[52:55], v[172:175], v[188:191], v[52:55]
	v_mfma_f32_16x16x32_bf16 v[48:51], v[180:183], v[188:191], v[48:51]
	v_mfma_f32_16x16x32_bf16 v[36:39], v[172:175], v[200:203], v[36:39]
	v_mfma_f32_16x16x32_bf16 v[32:35], v[180:183], v[200:203], v[32:35]
	v_mfma_f32_16x16x32_bf16 v[20:23], v[172:175], v[208:211], v[20:23]
	v_mfma_f32_16x16x32_bf16 v[16:19], v[180:183], v[208:211], v[16:19]
	v_mfma_f32_16x16x32_bf16 v[4:7], v[172:175], v[216:219], v[4:7]
	v_mfma_f32_16x16x32_bf16 v[0:3], v[180:183], v[216:219], v[0:3]
	s_setprio 0
	s_barrier
	s_add_i32 s88, 0, 0x18000
	s_add_i32 s89, 0, 0x1c000
	v_add_u32_e32 v164, s88, v151
	v_add_u32_e32 v180, s89, v151
	ds_read_b128 v[144:147], v164
	ds_read_b128 v[156:159], v164 offset:1024
	ds_read_b128 v[160:163], v164 offset:2048
	ds_read_b128 v[164:167], v164 offset:3072
	ds_read_b128 v[168:171], v180
	ds_read_b128 v[172:175], v180 offset:1024
	ds_read_b128 v[176:179], v180 offset:2048
	ds_read_b128 v[180:183], v180 offset:3072
	s_add_u32 s58, s58, 0x20000
	s_addc_u32 s59, s59, 0
	ds_read_b128 v[184:187], v155 offset:32768
	ds_read_b128 v[188:191], v155 offset:33792
	ds_read_b128 v[196:199], v155 offset:34816
	ds_read_b128 v[200:203], v155 offset:35840
	ds_read_b128 v[204:207], v155 offset:36864
	ds_read_b128 v[208:211], v155 offset:37888
	ds_read_b128 v[212:215], v155 offset:38912
	ds_read_b128 v[216:219], v155 offset:39936
	s_mov_b32 m0, s41
	s_nop 0
	global_load_lds_dwordx4 v128, s[98:99]
	s_mov_b32 m0, s63
	s_nop 0
	global_load_lds_dwordx4 v132, s[98:99]
	s_mov_b32 m0, s70
	s_nop 0
	global_load_lds_dwordx4 v128, s[58:59]
	s_mov_b32 m0, s71
	s_nop 0
	global_load_lds_dwordx4 v132, s[58:59]
	s_waitcnt vmcnt(8)
	s_waitcnt lgkmcnt(0)
	s_barrier
	s_setprio 1
	s_waitcnt lgkmcnt(0)
	v_mfma_f32_16x16x32_bf16 v[124:127], v[144:147], v[184:187], v[124:127]
	v_mfma_f32_16x16x32_bf16 v[120:123], v[160:163], v[184:187], v[120:123]
	v_mfma_f32_16x16x32_bf16 v[108:111], v[144:147], v[196:199], v[108:111]
	v_mfma_f32_16x16x32_bf16 v[104:107], v[160:163], v[196:199], v[104:107]
	v_mfma_f32_16x16x32_bf16 v[92:95], v[144:147], v[204:207], v[92:95]
	v_mfma_f32_16x16x32_bf16 v[88:91], v[160:163], v[204:207], v[88:91]
	v_mfma_f32_16x16x32_bf16 v[76:79], v[144:147], v[212:215], v[76:79]
	v_mfma_f32_16x16x32_bf16 v[72:75], v[160:163], v[212:215], v[72:75]
	v_mfma_f32_16x16x32_bf16 v[124:127], v[156:159], v[188:191], v[124:127]
	v_mfma_f32_16x16x32_bf16 v[120:123], v[164:167], v[188:191], v[120:123]
	v_mfma_f32_16x16x32_bf16 v[108:111], v[156:159], v[200:203], v[108:111]
	v_mfma_f32_16x16x32_bf16 v[104:107], v[164:167], v[200:203], v[104:107]
	v_mfma_f32_16x16x32_bf16 v[92:95], v[156:159], v[208:211], v[92:95]
	v_mfma_f32_16x16x32_bf16 v[88:91], v[164:167], v[208:211], v[88:91]
	v_mfma_f32_16x16x32_bf16 v[76:79], v[156:159], v[216:219], v[76:79]
	v_mfma_f32_16x16x32_bf16 v[72:75], v[164:167], v[216:219], v[72:75]
	s_setprio 0
	s_setprio 1
	v_mfma_f32_16x16x32_bf16 v[116:119], v[168:171], v[184:187], v[116:119]
	v_mfma_f32_16x16x32_bf16 v[112:115], v[176:179], v[184:187], v[112:115]
	v_mfma_f32_16x16x32_bf16 v[100:103], v[168:171], v[196:199], v[100:103]
	v_mfma_f32_16x16x32_bf16 v[96:99], v[176:179], v[196:199], v[96:99]
	v_mfma_f32_16x16x32_bf16 v[84:87], v[168:171], v[204:207], v[84:87]
	v_mfma_f32_16x16x32_bf16 v[80:83], v[176:179], v[204:207], v[80:83]
	v_mfma_f32_16x16x32_bf16 v[68:71], v[168:171], v[212:215], v[68:71]
	v_mfma_f32_16x16x32_bf16 v[64:67], v[176:179], v[212:215], v[64:67]
	v_mfma_f32_16x16x32_bf16 v[116:119], v[172:175], v[188:191], v[116:119]
	v_mfma_f32_16x16x32_bf16 v[112:115], v[180:183], v[188:191], v[112:115]
	v_mfma_f32_16x16x32_bf16 v[100:103], v[172:175], v[200:203], v[100:103]
	v_mfma_f32_16x16x32_bf16 v[96:99], v[180:183], v[200:203], v[96:99]
	v_mfma_f32_16x16x32_bf16 v[84:87], v[172:175], v[208:211], v[84:87]
	v_mfma_f32_16x16x32_bf16 v[80:83], v[180:183], v[208:211], v[80:83]
	v_mfma_f32_16x16x32_bf16 v[68:71], v[172:175], v[216:219], v[68:71]
	v_mfma_f32_16x16x32_bf16 v[64:67], v[180:183], v[216:219], v[64:67]
	s_setprio 0
	s_barrier
	s_add_i32 s58, s88, s62
	s_add_i32 m0, s58, 0xffffff80
	ds_read_b128 v[184:187], v155 offset:49152
	ds_read_b128 v[188:191], v155 offset:50176
	ds_read_b128 v[196:199], v155 offset:51200
	ds_read_b128 v[200:203], v155 offset:52224
	ds_read_b128 v[204:207], v155 offset:53248
	ds_read_b128 v[208:211], v155 offset:54272
	ds_read_b128 v[212:215], v155 offset:55296
	ds_read_b128 v[216:219], v155 offset:56320
	global_load_lds_dwordx4 v130, s[44:45] offset:128
	s_add_i32 m0, s58, 0x1f80
	s_add_i32 s58, s89, s62
	global_load_lds_dwordx4 v134, s[44:45] offset:128
	s_add_u32 s44, s44, 0x20080
	s_addc_u32 s45, s45, 0
	s_mov_b32 m0, s58
	s_nop 0
	global_load_lds_dwordx4 v130, s[44:45]
	s_add_i32 m0, s58, 0x2000
	s_nop 0
	global_load_lds_dwordx4 v134, s[44:45]
	s_waitcnt vmcnt(6)
	s_waitcnt lgkmcnt(0)
	s_barrier
	s_setprio 1
	s_waitcnt lgkmcnt(0)
	v_mfma_f32_16x16x32_bf16 v[60:63], v[144:147], v[184:187], v[60:63]
	v_mfma_f32_16x16x32_bf16 v[56:59], v[160:163], v[184:187], v[56:59]
	v_mfma_f32_16x16x32_bf16 v[44:47], v[144:147], v[196:199], v[44:47]
	v_mfma_f32_16x16x32_bf16 v[40:43], v[160:163], v[196:199], v[40:43]
	v_mfma_f32_16x16x32_bf16 v[28:31], v[144:147], v[204:207], v[28:31]
	v_mfma_f32_16x16x32_bf16 v[24:27], v[160:163], v[204:207], v[24:27]
	v_mfma_f32_16x16x32_bf16 v[12:15], v[144:147], v[212:215], v[12:15]
	v_mfma_f32_16x16x32_bf16 v[8:11], v[160:163], v[212:215], v[8:11]
	v_mfma_f32_16x16x32_bf16 v[60:63], v[156:159], v[188:191], v[60:63]
	v_mfma_f32_16x16x32_bf16 v[56:59], v[164:167], v[188:191], v[56:59]
	v_mfma_f32_16x16x32_bf16 v[44:47], v[156:159], v[200:203], v[44:47]
	v_mfma_f32_16x16x32_bf16 v[40:43], v[164:167], v[200:203], v[40:43]
	v_mfma_f32_16x16x32_bf16 v[28:31], v[156:159], v[208:211], v[28:31]
	v_mfma_f32_16x16x32_bf16 v[24:27], v[164:167], v[208:211], v[24:27]
	v_mfma_f32_16x16x32_bf16 v[12:15], v[156:159], v[216:219], v[12:15]
	v_mfma_f32_16x16x32_bf16 v[8:11], v[164:167], v[216:219], v[8:11]
	s_setprio 0
	s_setprio 1
	v_mfma_f32_16x16x32_bf16 v[52:55], v[168:171], v[184:187], v[52:55]
	v_mfma_f32_16x16x32_bf16 v[48:51], v[176:179], v[184:187], v[48:51]
	v_mfma_f32_16x16x32_bf16 v[36:39], v[168:171], v[196:199], v[36:39]
	v_mfma_f32_16x16x32_bf16 v[32:35], v[176:179], v[196:199], v[32:35]
	v_mfma_f32_16x16x32_bf16 v[20:23], v[168:171], v[204:207], v[20:23]
	v_mfma_f32_16x16x32_bf16 v[16:19], v[176:179], v[204:207], v[16:19]
	v_mfma_f32_16x16x32_bf16 v[4:7], v[168:171], v[212:215], v[4:7]
	v_mfma_f32_16x16x32_bf16 v[0:3], v[176:179], v[212:215], v[0:3]
	v_mfma_f32_16x16x32_bf16 v[52:55], v[172:175], v[188:191], v[52:55]
	v_mfma_f32_16x16x32_bf16 v[48:51], v[180:183], v[188:191], v[48:51]
	v_mfma_f32_16x16x32_bf16 v[36:39], v[172:175], v[200:203], v[36:39]
	v_mfma_f32_16x16x32_bf16 v[32:35], v[180:183], v[200:203], v[32:35]
	v_mfma_f32_16x16x32_bf16 v[20:23], v[172:175], v[208:211], v[20:23]
	v_mfma_f32_16x16x32_bf16 v[16:19], v[180:183], v[208:211], v[16:19]
	v_mfma_f32_16x16x32_bf16 v[4:7], v[172:175], v[216:219], v[4:7]
	v_mfma_f32_16x16x32_bf16 v[0:3], v[180:183], v[216:219], v[0:3]
	s_setprio 0
	s_barrier
	s_add_i32 m0, s73, 0xffffff80
	s_nop 0
	global_load_lds_dwordx4 v128, s[98:99] offset:128
	s_add_i32 m0, s78, 0xffffff80
	s_nop 0
	global_load_lds_dwordx4 v132, s[98:99] offset:128
	s_add_i32 s87, s87, 2
	s_add_u32 s42, s42, 0x100
	s_addc_u32 s43, s43, 0
	s_add_u32 s85, s85, 0x100
	s_addc_u32 s86, s86, 0
	s_cmp_gt_u32 s87, 5
	s_cbranch_scc0 .LBB0_1023
	s_and_b64 vcc, exec, s[22:23]
	s_cbranch_vccz .LBB0_1026
	s_barrier

.LBB0_1421:
	ds_read_b128 v[146:149], v155
	ds_read_b128 v[160:163], v155 offset:1024
	ds_read_b128 v[164:167], v155 offset:2048
	ds_read_b128 v[168:171], v155 offset:3072
	ds_read_b128 v[172:175], v156
	ds_read_b128 v[176:179], v156 offset:1024
	ds_read_b128 v[180:183], v156 offset:2048
	ds_read_b128 v[184:187], v156 offset:3072
	s_add_u32 s40, s0, 0xfffc0080
	s_addc_u32 s41, s1, -1
	s_cmp_eq_u32 s83, 12
	s_cselect_b32 s43, s25, s41
	s_cselect_b32 s42, s27, s40
	s_cselect_b32 s41, s31, s82
	s_cselect_b32 s40, s30, s29
	s_add_i32 m0, s39, 0xc000
	ds_read_b128 v[188:191], v157
	ds_read_b128 v[196:199], v157 offset:1024
	ds_read_b128 v[200:203], v157 offset:2048
	ds_read_b128 v[204:207], v157 offset:3072
	ds_read_b128 v[208:211], v157 offset:4096
	ds_read_b128 v[212:215], v157 offset:5120
	ds_read_b128 v[216:219], v157 offset:6144
	ds_read_b128 v[220:223], v157 offset:7168
	global_load_lds_dwordx4 v138, s[0:1]
	s_add_i32 m0, s39, 0xe000
	s_nop 0
	global_load_lds_dwordx4 v140, s[0:1]
	s_waitcnt vmcnt(8)
	s_waitcnt lgkmcnt(0)
	s_barrier
	s_setprio 1
	s_waitcnt lgkmcnt(0)
	v_mfma_f32_16x16x32_bf16 v[124:127], v[146:149], v[188:191], v[124:127]
	v_mfma_f32_16x16x32_bf16 v[120:123], v[164:167], v[188:191], v[120:123]
	v_mfma_f32_16x16x32_bf16 v[108:111], v[146:149], v[200:203], v[108:111]
	v_mfma_f32_16x16x32_bf16 v[104:107], v[164:167], v[200:203], v[104:107]
	v_mfma_f32_16x16x32_bf16 v[92:95], v[146:149], v[208:211], v[92:95]
	v_mfma_f32_16x16x32_bf16 v[88:91], v[164:167], v[208:211], v[88:91]
	v_mfma_f32_16x16x32_bf16 v[76:79], v[146:149], v[216:219], v[76:79]
	v_mfma_f32_16x16x32_bf16 v[72:75], v[164:167], v[216:219], v[72:75]
	v_mfma_f32_16x16x32_bf16 v[124:127], v[160:163], v[196:199], v[124:127]
	v_mfma_f32_16x16x32_bf16 v[120:123], v[168:171], v[196:199], v[120:123]
	v_mfma_f32_16x16x32_bf16 v[108:111], v[160:163], v[204:207], v[108:111]
	v_mfma_f32_16x16x32_bf16 v[104:107], v[168:171], v[204:207], v[104:107]
	v_mfma_f32_16x16x32_bf16 v[92:95], v[160:163], v[212:215], v[92:95]
	v_mfma_f32_16x16x32_bf16 v[88:91], v[168:171], v[212:215], v[88:91]
	v_mfma_f32_16x16x32_bf16 v[76:79], v[160:163], v[220:223], v[76:79]
	v_mfma_f32_16x16x32_bf16 v[72:75], v[168:171], v[220:223], v[72:75]
	s_setprio 0
	s_setprio 1
	v_mfma_f32_16x16x32_bf16 v[116:119], v[172:175], v[188:191], v[116:119]
	v_mfma_f32_16x16x32_bf16 v[112:115], v[180:183], v[188:191], v[112:115]
	v_mfma_f32_16x16x32_bf16 v[100:103], v[172:175], v[200:203], v[100:103]
	v_mfma_f32_16x16x32_bf16 v[96:99], v[180:183], v[200:203], v[96:99]
	v_mfma_f32_16x16x32_bf16 v[84:87], v[172:175], v[208:211], v[84:87]
	v_mfma_f32_16x16x32_bf16 v[80:83], v[180:183], v[208:211], v[80:83]
	v_mfma_f32_16x16x32_bf16 v[68:71], v[172:175], v[216:219], v[68:71]
	v_mfma_f32_16x16x32_bf16 v[64:67], v[180:183], v[216:219], v[64:67]
	v_mfma_f32_16x16x32_bf16 v[116:119], v[176:179], v[196:199], v[116:119]
	v_mfma_f32_16x16x32_bf16 v[112:115], v[184:187], v[196:199], v[112:115]
	v_mfma_f32_16x16x32_bf16 v[100:103], v[176:179], v[204:207], v[100:103]
	v_mfma_f32_16x16x32_bf16 v[96:99], v[184:187], v[204:207], v[96:99]
	v_mfma_f32_16x16x32_bf16 v[84:87], v[176:179], v[212:215], v[84:87]
	v_mfma_f32_16x16x32_bf16 v[80:83], v[184:187], v[212:215], v[80:83]
	v_mfma_f32_16x16x32_bf16 v[68:71], v[176:179], v[220:223], v[68:71]
	v_mfma_f32_16x16x32_bf16 v[64:67], v[184:187], v[220:223], v[64:67]
	s_setprio 0
	s_barrier
	s_add_i32 s84, s78, s60
	s_mov_b32 m0, s84
	ds_read_b128 v[188:191], v157 offset:16384
	ds_read_b128 v[196:199], v157 offset:17408
	ds_read_b128 v[200:203], v157 offset:18432
	ds_read_b128 v[204:207], v157 offset:19456
	ds_read_b128 v[208:211], v157 offset:20480
	ds_read_b128 v[212:215], v157 offset:21504
	ds_read_b128 v[216:219], v157 offset:22528
	ds_read_b128 v[220:223], v157 offset:23552
	global_load_lds_dwordx4 v132, s[40:41]
	s_add_i32 m0, s84, 0x2000
	s_add_u32 s84, s40, 0x40000
	s_addc_u32 s85, s41, 0
	s_add_i32 s86, s79, s60
	global_load_lds_dwordx4 v136, s[40:41]
	s_mov_b32 m0, s86
	s_mov_b64 s[98:99], s[42:43]
	global_load_lds_dwordx4 v132, s[84:85]
	s_add_i32 m0, s86, 0x2000
	s_nop 0
	global_load_lds_dwordx4 v136, s[84:85]
	s_waitcnt vmcnt(6)
	s_waitcnt lgkmcnt(0)
	s_barrier
	s_setprio 1
	s_waitcnt lgkmcnt(0)
	v_mfma_f32_16x16x32_bf16 v[60:63], v[146:149], v[188:191], v[60:63]
	v_mfma_f32_16x16x32_bf16 v[56:59], v[164:167], v[188:191], v[56:59]
	v_mfma_f32_16x16x32_bf16 v[44:47], v[146:149], v[200:203], v[44:47]
	v_mfma_f32_16x16x32_bf16 v[40:43], v[164:167], v[200:203], v[40:43]
	v_mfma_f32_16x16x32_bf16 v[28:31], v[146:149], v[208:211], v[28:31]
	v_mfma_f32_16x16x32_bf16 v[24:27], v[164:167], v[208:211], v[24:27]
	v_mfma_f32_16x16x32_bf16 v[12:15], v[146:149], v[216:219], v[12:15]
	v_mfma_f32_16x16x32_bf16 v[8:11], v[164:167], v[216:219], v[8:11]
	v_mfma_f32_16x16x32_bf16 v[60:63], v[160:163], v[196:199], v[60:63]
	v_mfma_f32_16x16x32_bf16 v[56:59], v[168:171], v[196:199], v[56:59]
	v_mfma_f32_16x16x32_bf16 v[44:47], v[160:163], v[204:207], v[44:47]
	v_mfma_f32_16x16x32_bf16 v[40:43], v[168:171], v[204:207], v[40:43]
	v_mfma_f32_16x16x32_bf16 v[28:31], v[160:163], v[212:215], v[28:31]
	v_mfma_f32_16x16x32_bf16 v[24:27], v[168:171], v[212:215], v[24:27]
	v_mfma_f32_16x16x32_bf16 v[12:15], v[160:163], v[220:223], v[12:15]
	v_mfma_f32_16x16x32_bf16 v[8:11], v[168:171], v[220:223], v[8:11]
	s_setprio 0
	s_setprio 1
	v_mfma_f32_16x16x32_bf16 v[52:55], v[172:175], v[188:191], v[52:55]
	v_mfma_f32_16x16x32_bf16 v[48:51], v[180:183], v[188:191], v[48:51]
	v_mfma_f32_16x16x32_bf16 v[36:39], v[172:175], v[200:203], v[36:39]
	v_mfma_f32_16x16x32_bf16 v[32:35], v[180:183], v[200:203], v[32:35]
	v_mfma_f32_16x16x32_bf16 v[20:23], v[172:175], v[208:211], v[20:23]
	v_mfma_f32_16x16x32_bf16 v[16:19], v[180:183], v[208:211], v[16:19]
	v_mfma_f32_16x16x32_bf16 v[4:7], v[172:175], v[216:219], v[4:7]
	v_mfma_f32_16x16x32_bf16 v[0:3], v[180:183], v[216:219], v[0:3]
	v_mfma_f32_16x16x32_bf16 v[52:55], v[176:179], v[196:199], v[52:55]
	v_mfma_f32_16x16x32_bf16 v[48:51], v[184:187], v[196:199], v[48:51]
	v_mfma_f32_16x16x32_bf16 v[36:39], v[176:179], v[204:207], v[36:39]
	v_mfma_f32_16x16x32_bf16 v[32:35], v[184:187], v[204:207], v[32:35]
	v_mfma_f32_16x16x32_bf16 v[20:23], v[176:179], v[212:215], v[20:23]
	v_mfma_f32_16x16x32_bf16 v[16:19], v[184:187], v[212:215], v[16:19]
	v_mfma_f32_16x16x32_bf16 v[4:7], v[176:179], v[220:223], v[4:7]
	v_mfma_f32_16x16x32_bf16 v[0:3], v[184:187], v[220:223], v[0:3]
	s_setprio 0
	s_barrier
	s_add_i32 s84, 0, 0x18000
	v_add_u32_e32 v159, s84, v153
	s_add_i32 s85, 0, 0x1c000
	ds_read_b128 v[146:149], v159
	ds_read_b128 v[160:163], v159 offset:1024
	ds_read_b128 v[164:167], v159 offset:2048
	ds_read_b128 v[168:171], v159 offset:3072
	v_add_u32_e32 v159, s85, v153
	ds_read_b128 v[172:175], v159
	ds_read_b128 v[176:179], v159 offset:1024
	ds_read_b128 v[180:183], v159 offset:2048
	ds_read_b128 v[184:187], v159 offset:3072
	s_add_u32 s42, s42, 0x40000
	s_addc_u32 s43, s43, 0
	ds_read_b128 v[188:191], v157 offset:32768
	ds_read_b128 v[196:199], v157 offset:33792
	ds_read_b128 v[200:203], v157 offset:34816
	ds_read_b128 v[204:207], v157 offset:35840
	ds_read_b128 v[208:211], v157 offset:36864
	ds_read_b128 v[212:215], v157 offset:37888
	ds_read_b128 v[216:219], v157 offset:38912
	ds_read_b128 v[220:223], v157 offset:39936
	s_mov_b32 m0, s39
	s_nop 0
	global_load_lds_dwordx4 v130, s[98:99]
	s_mov_b32 m0, s61
	s_nop 0
	global_load_lds_dwordx4 v134, s[98:99]
	s_mov_b32 m0, s62
	s_nop 0
	global_load_lds_dwordx4 v130, s[42:43]
	s_mov_b32 m0, s63
	s_nop 0
	global_load_lds_dwordx4 v134, s[42:43]
	s_waitcnt vmcnt(8)
	s_waitcnt lgkmcnt(0)
	s_barrier
	s_setprio 1
	s_waitcnt lgkmcnt(0)
	v_mfma_f32_16x16x32_bf16 v[124:127], v[146:149], v[188:191], v[124:127]
	v_mfma_f32_16x16x32_bf16 v[120:123], v[164:167], v[188:191], v[120:123]
	v_mfma_f32_16x16x32_bf16 v[108:111], v[146:149], v[200:203], v[108:111]
	v_mfma_f32_16x16x32_bf16 v[104:107], v[164:167], v[200:203], v[104:107]
	v_mfma_f32_16x16x32_bf16 v[92:95], v[146:149], v[208:211], v[92:95]
	v_mfma_f32_16x16x32_bf16 v[88:91], v[164:167], v[208:211], v[88:91]
	v_mfma_f32_16x16x32_bf16 v[76:79], v[146:149], v[216:219], v[76:79]
	v_mfma_f32_16x16x32_bf16 v[72:75], v[164:167], v[216:219], v[72:75]
	v_mfma_f32_16x16x32_bf16 v[124:127], v[160:163], v[196:199], v[124:127]
	v_mfma_f32_16x16x32_bf16 v[120:123], v[168:171], v[196:199], v[120:123]
	v_mfma_f32_16x16x32_bf16 v[108:111], v[160:163], v[204:207], v[108:111]
	v_mfma_f32_16x16x32_bf16 v[104:107], v[168:171], v[204:207], v[104:107]
	v_mfma_f32_16x16x32_bf16 v[92:95], v[160:163], v[212:215], v[92:95]
	v_mfma_f32_16x16x32_bf16 v[88:91], v[168:171], v[212:215], v[88:91]
	v_mfma_f32_16x16x32_bf16 v[76:79], v[160:163], v[220:223], v[76:79]
	v_mfma_f32_16x16x32_bf16 v[72:75], v[168:171], v[220:223], v[72:75]
	s_setprio 0
	s_setprio 1
	v_mfma_f32_16x16x32_bf16 v[116:119], v[172:175], v[188:191], v[116:119]
	v_mfma_f32_16x16x32_bf16 v[112:115], v[180:183], v[188:191], v[112:115]
	v_mfma_f32_16x16x32_bf16 v[100:103], v[172:175], v[200:203], v[100:103]
	v_mfma_f32_16x16x32_bf16 v[96:99], v[180:183], v[200:203], v[96:99]
	v_mfma_f32_16x16x32_bf16 v[84:87], v[172:175], v[208:211], v[84:87]
	v_mfma_f32_16x16x32_bf16 v[80:83], v[180:183], v[208:211], v[80:83]
	v_mfma_f32_16x16x32_bf16 v[68:71], v[172:175], v[216:219], v[68:71]
	v_mfma_f32_16x16x32_bf16 v[64:67], v[180:183], v[216:219], v[64:67]
	v_mfma_f32_16x16x32_bf16 v[116:119], v[176:179], v[196:199], v[116:119]
	v_mfma_f32_16x16x32_bf16 v[112:115], v[184:187], v[196:199], v[112:115]
	v_mfma_f32_16x16x32_bf16 v[100:103], v[176:179], v[204:207], v[100:103]
	v_mfma_f32_16x16x32_bf16 v[96:99], v[184:187], v[204:207], v[96:99]
	v_mfma_f32_16x16x32_bf16 v[84:87], v[176:179], v[212:215], v[84:87]
	v_mfma_f32_16x16x32_bf16 v[80:83], v[184:187], v[212:215], v[80:83]
	v_mfma_f32_16x16x32_bf16 v[68:71], v[176:179], v[220:223], v[68:71]
	v_mfma_f32_16x16x32_bf16 v[64:67], v[184:187], v[220:223], v[64:67]
	s_setprio 0
	s_barrier
	s_add_i32 s42, s84, s60
	s_add_i32 m0, s42, 0xffffff80
	ds_read_b128 v[188:191], v157 offset:49152
	ds_read_b128 v[196:199], v157 offset:50176
	ds_read_b128 v[200:203], v157 offset:51200
	ds_read_b128 v[204:207], v157 offset:52224
	ds_read_b128 v[208:211], v157 offset:53248
	ds_read_b128 v[212:215], v157 offset:54272
	ds_read_b128 v[216:219], v157 offset:55296
	ds_read_b128 v[220:223], v157 offset:56320
	global_load_lds_dwordx4 v132, s[40:41] offset:128
	s_add_i32 m0, s42, 0x1f80
	s_add_i32 s42, s85, s60
	global_load_lds_dwordx4 v136, s[40:41] offset:128
	s_add_u32 s40, s40, 0x40080
	s_addc_u32 s41, s41, 0
	s_mov_b32 m0, s42
	s_nop 0
	global_load_lds_dwordx4 v132, s[40:41]
	s_add_i32 m0, s42, 0x2000
	s_nop 0
	global_load_lds_dwordx4 v136, s[40:41]
	s_waitcnt vmcnt(6)
	s_waitcnt lgkmcnt(0)
	s_barrier
	s_setprio 1
	s_waitcnt lgkmcnt(0)
	v_mfma_f32_16x16x32_bf16 v[60:63], v[146:149], v[188:191], v[60:63]
	v_mfma_f32_16x16x32_bf16 v[56:59], v[164:167], v[188:191], v[56:59]
	v_mfma_f32_16x16x32_bf16 v[44:47], v[146:149], v[200:203], v[44:47]
	v_mfma_f32_16x16x32_bf16 v[40:43], v[164:167], v[200:203], v[40:43]
	v_mfma_f32_16x16x32_bf16 v[28:31], v[146:149], v[208:211], v[28:31]
	v_mfma_f32_16x16x32_bf16 v[24:27], v[164:167], v[208:211], v[24:27]
	v_mfma_f32_16x16x32_bf16 v[12:15], v[146:149], v[216:219], v[12:15]
	v_mfma_f32_16x16x32_bf16 v[8:11], v[164:167], v[216:219], v[8:11]
	v_mfma_f32_16x16x32_bf16 v[60:63], v[160:163], v[196:199], v[60:63]
	v_mfma_f32_16x16x32_bf16 v[56:59], v[168:171], v[196:199], v[56:59]
	v_mfma_f32_16x16x32_bf16 v[44:47], v[160:163], v[204:207], v[44:47]
	v_mfma_f32_16x16x32_bf16 v[40:43], v[168:171], v[204:207], v[40:43]
	v_mfma_f32_16x16x32_bf16 v[28:31], v[160:163], v[212:215], v[28:31]
	v_mfma_f32_16x16x32_bf16 v[24:27], v[168:171], v[212:215], v[24:27]
	v_mfma_f32_16x16x32_bf16 v[12:15], v[160:163], v[220:223], v[12:15]
	v_mfma_f32_16x16x32_bf16 v[8:11], v[168:171], v[220:223], v[8:11]
	s_setprio 0
	s_setprio 1
	v_mfma_f32_16x16x32_bf16 v[52:55], v[172:175], v[188:191], v[52:55]
	v_mfma_f32_16x16x32_bf16 v[48:51], v[180:183], v[188:191], v[48:51]
	v_mfma_f32_16x16x32_bf16 v[36:39], v[172:175], v[200:203], v[36:39]
	v_mfma_f32_16x16x32_bf16 v[32:35], v[180:183], v[200:203], v[32:35]
	v_mfma_f32_16x16x32_bf16 v[20:23], v[172:175], v[208:211], v[20:23]
	v_mfma_f32_16x16x32_bf16 v[16:19], v[180:183], v[208:211], v[16:19]
	v_mfma_f32_16x16x32_bf16 v[4:7], v[172:175], v[216:219], v[4:7]
	v_mfma_f32_16x16x32_bf16 v[0:3], v[180:183], v[216:219], v[0:3]
	v_mfma_f32_16x16x32_bf16 v[52:55], v[176:179], v[196:199], v[52:55]
	v_mfma_f32_16x16x32_bf16 v[48:51], v[184:187], v[196:199], v[48:51]
	v_mfma_f32_16x16x32_bf16 v[36:39], v[176:179], v[204:207], v[36:39]
	v_mfma_f32_16x16x32_bf16 v[32:35], v[184:187], v[204:207], v[32:35]
	v_mfma_f32_16x16x32_bf16 v[20:23], v[176:179], v[212:215], v[20:23]
	v_mfma_f32_16x16x32_bf16 v[16:19], v[184:187], v[212:215], v[16:19]
	v_mfma_f32_16x16x32_bf16 v[4:7], v[176:179], v[220:223], v[4:7]
	v_mfma_f32_16x16x32_bf16 v[0:3], v[184:187], v[220:223], v[0:3]
	s_setprio 0
	s_barrier
	s_add_i32 m0, s70, 0xffffff80
	s_nop 0
	global_load_lds_dwordx4 v130, s[98:99] offset:128
	s_add_i32 m0, s71, 0xffffff80
	s_nop 0
	global_load_lds_dwordx4 v134, s[98:99] offset:128
	s_add_i32 s83, s83, 2
	s_add_u32 s0, s0, 0x100
	s_addc_u32 s1, s1, 0
	s_add_u32 s29, s29, 0x100
	s_addc_u32 s82, s82, 0
	s_cmp_gt_u32 s83, 13
	s_cbranch_scc0 .LBB0_1421
	s_and_b64 vcc, exec, s[22:23]
	s_cbranch_vccz .LBB0_1424
	s_barrier

.LBB0_1451:
	ds_read_b128 v[144:147], v159
	ds_read_b128 v[148:151], v159 offset:1024
	ds_read_b128 v[152:155], v159 offset:2048
	ds_read_b128 v[162:165], v159 offset:3072
	ds_read_b128 v[166:169], v160
	ds_read_b128 v[170:173], v160 offset:1024
	ds_read_b128 v[174:177], v160 offset:2048
	ds_read_b128 v[178:181], v160 offset:3072
	s_add_u32 s41, s58, 0xfffe0080
	s_addc_u32 s43, s59, -1
	s_cmp_eq_u32 s39, 4
	s_cselect_b32 s71, s1, s43
	s_cselect_b32 s70, s0, s41
	s_cselect_b32 s63, s45, s17
	s_cselect_b32 s62, s44, s15
	s_add_i32 m0, s83, 0xc000
	ds_read_b128 v[182:185], v161
	ds_read_b128 v[186:189], v161 offset:1024
	ds_read_b128 v[190:193], v161 offset:2048
	ds_read_b128 v[196:199], v161 offset:3072
	ds_read_b128 v[200:203], v161 offset:4096
	ds_read_b128 v[204:207], v161 offset:5120
	ds_read_b128 v[208:211], v161 offset:6144
	ds_read_b128 v[212:215], v161 offset:7168
	global_load_lds_dwordx4 v136, s[58:59]
	s_add_i32 m0, s83, 0xe000
	s_nop 0
	global_load_lds_dwordx4 v138, s[58:59]
	s_waitcnt vmcnt(8)
	s_waitcnt lgkmcnt(0)
	s_barrier
	s_setprio 1
	s_waitcnt lgkmcnt(0)
	v_mfma_f32_16x16x32_bf16 v[124:127], v[144:147], v[182:185], v[124:127]
	v_mfma_f32_16x16x32_bf16 v[120:123], v[152:155], v[182:185], v[120:123]
	v_mfma_f32_16x16x32_bf16 v[108:111], v[144:147], v[190:193], v[108:111]
	v_mfma_f32_16x16x32_bf16 v[104:107], v[152:155], v[190:193], v[104:107]
	v_mfma_f32_16x16x32_bf16 v[92:95], v[144:147], v[200:203], v[92:95]
	v_mfma_f32_16x16x32_bf16 v[88:91], v[152:155], v[200:203], v[88:91]
	v_mfma_f32_16x16x32_bf16 v[76:79], v[144:147], v[208:211], v[76:79]
	v_mfma_f32_16x16x32_bf16 v[72:75], v[152:155], v[208:211], v[72:75]
	v_mfma_f32_16x16x32_bf16 v[124:127], v[148:151], v[186:189], v[124:127]
	v_mfma_f32_16x16x32_bf16 v[120:123], v[162:165], v[186:189], v[120:123]
	v_mfma_f32_16x16x32_bf16 v[108:111], v[148:151], v[196:199], v[108:111]
	v_mfma_f32_16x16x32_bf16 v[104:107], v[162:165], v[196:199], v[104:107]
	v_mfma_f32_16x16x32_bf16 v[92:95], v[148:151], v[204:207], v[92:95]
	v_mfma_f32_16x16x32_bf16 v[88:91], v[162:165], v[204:207], v[88:91]
	v_mfma_f32_16x16x32_bf16 v[76:79], v[148:151], v[212:215], v[76:79]
	v_mfma_f32_16x16x32_bf16 v[72:75], v[162:165], v[212:215], v[72:75]
	s_setprio 0
	s_setprio 1
	v_mfma_f32_16x16x32_bf16 v[116:119], v[166:169], v[182:185], v[116:119]
	v_mfma_f32_16x16x32_bf16 v[112:115], v[174:177], v[182:185], v[112:115]
	v_mfma_f32_16x16x32_bf16 v[100:103], v[166:169], v[190:193], v[100:103]
	v_mfma_f32_16x16x32_bf16 v[96:99], v[174:177], v[190:193], v[96:99]
	v_mfma_f32_16x16x32_bf16 v[84:87], v[166:169], v[200:203], v[84:87]
	v_mfma_f32_16x16x32_bf16 v[80:83], v[174:177], v[200:203], v[80:83]
	v_mfma_f32_16x16x32_bf16 v[68:71], v[166:169], v[208:211], v[68:71]
	v_mfma_f32_16x16x32_bf16 v[64:67], v[174:177], v[208:211], v[64:67]
	v_mfma_f32_16x16x32_bf16 v[116:119], v[170:173], v[186:189], v[116:119]
	v_mfma_f32_16x16x32_bf16 v[112:115], v[178:181], v[186:189], v[112:115]
	v_mfma_f32_16x16x32_bf16 v[100:103], v[170:173], v[196:199], v[100:103]
	v_mfma_f32_16x16x32_bf16 v[96:99], v[178:181], v[196:199], v[96:99]
	v_mfma_f32_16x16x32_bf16 v[84:87], v[170:173], v[204:207], v[84:87]
	v_mfma_f32_16x16x32_bf16 v[80:83], v[178:181], v[204:207], v[80:83]
	v_mfma_f32_16x16x32_bf16 v[68:71], v[170:173], v[212:215], v[68:71]
	v_mfma_f32_16x16x32_bf16 v[64:67], v[178:181], v[212:215], v[64:67]
	s_setprio 0
	s_barrier
	s_add_i32 s41, s90, s80
	s_mov_b32 m0, s41
	ds_read_b128 v[182:185], v161 offset:16384
	ds_read_b128 v[186:189], v161 offset:17408
	ds_read_b128 v[190:193], v161 offset:18432
	ds_read_b128 v[196:199], v161 offset:19456
	ds_read_b128 v[200:203], v161 offset:20480
	ds_read_b128 v[204:207], v161 offset:21504
	ds_read_b128 v[208:211], v161 offset:22528
	ds_read_b128 v[212:215], v161 offset:23552
	global_load_lds_dwordx4 v130, s[62:63]
	s_add_i32 m0, s41, 0x2000
	s_add_u32 s94, s62, 0x20000
	s_addc_u32 s95, s63, 0
	s_add_i32 s41, s91, s80
	global_load_lds_dwordx4 v134, s[62:63]
	s_mov_b32 m0, s41
	s_mov_b64 s[98:99], s[70:71]
	global_load_lds_dwordx4 v130, s[94:95]
	s_add_i32 m0, s41, 0x2000
	s_nop 0
	global_load_lds_dwordx4 v134, s[94:95]
	s_waitcnt vmcnt(6)
	s_waitcnt lgkmcnt(0)
	s_barrier
	s_setprio 1
	s_waitcnt lgkmcnt(0)
	v_mfma_f32_16x16x32_bf16 v[60:63], v[144:147], v[182:185], v[60:63]
	v_mfma_f32_16x16x32_bf16 v[56:59], v[152:155], v[182:185], v[56:59]
	v_mfma_f32_16x16x32_bf16 v[44:47], v[144:147], v[190:193], v[44:47]
	v_mfma_f32_16x16x32_bf16 v[40:43], v[152:155], v[190:193], v[40:43]
	v_mfma_f32_16x16x32_bf16 v[28:31], v[144:147], v[200:203], v[28:31]
	v_mfma_f32_16x16x32_bf16 v[24:27], v[152:155], v[200:203], v[24:27]
	v_mfma_f32_16x16x32_bf16 v[12:15], v[144:147], v[208:211], v[12:15]
	v_mfma_f32_16x16x32_bf16 v[8:11], v[152:155], v[208:211], v[8:11]
	v_mfma_f32_16x16x32_bf16 v[60:63], v[148:151], v[186:189], v[60:63]
	v_mfma_f32_16x16x32_bf16 v[56:59], v[162:165], v[186:189], v[56:59]
	v_mfma_f32_16x16x32_bf16 v[44:47], v[148:151], v[196:199], v[44:47]
	v_mfma_f32_16x16x32_bf16 v[40:43], v[162:165], v[196:199], v[40:43]
	v_mfma_f32_16x16x32_bf16 v[28:31], v[148:151], v[204:207], v[28:31]
	v_mfma_f32_16x16x32_bf16 v[24:27], v[162:165], v[204:207], v[24:27]
	v_mfma_f32_16x16x32_bf16 v[12:15], v[148:151], v[212:215], v[12:15]
	v_mfma_f32_16x16x32_bf16 v[8:11], v[162:165], v[212:215], v[8:11]
	s_setprio 0
	s_setprio 1
	v_mfma_f32_16x16x32_bf16 v[52:55], v[166:169], v[182:185], v[52:55]
	v_mfma_f32_16x16x32_bf16 v[48:51], v[174:177], v[182:185], v[48:51]
	v_mfma_f32_16x16x32_bf16 v[36:39], v[166:169], v[190:193], v[36:39]
	v_mfma_f32_16x16x32_bf16 v[32:35], v[174:177], v[190:193], v[32:35]
	v_mfma_f32_16x16x32_bf16 v[20:23], v[166:169], v[200:203], v[20:23]
	v_mfma_f32_16x16x32_bf16 v[16:19], v[174:177], v[200:203], v[16:19]
	v_mfma_f32_16x16x32_bf16 v[4:7], v[166:169], v[208:211], v[4:7]
	v_mfma_f32_16x16x32_bf16 v[0:3], v[174:177], v[208:211], v[0:3]
	v_mfma_f32_16x16x32_bf16 v[52:55], v[170:173], v[186:189], v[52:55]
	v_mfma_f32_16x16x32_bf16 v[48:51], v[178:181], v[186:189], v[48:51]
	v_mfma_f32_16x16x32_bf16 v[36:39], v[170:173], v[196:199], v[36:39]
	v_mfma_f32_16x16x32_bf16 v[32:35], v[178:181], v[196:199], v[32:35]
	v_mfma_f32_16x16x32_bf16 v[20:23], v[170:173], v[204:207], v[20:23]
	v_mfma_f32_16x16x32_bf16 v[16:19], v[178:181], v[204:207], v[16:19]
	v_mfma_f32_16x16x32_bf16 v[4:7], v[170:173], v[212:215], v[4:7]
	v_mfma_f32_16x16x32_bf16 v[0:3], v[178:181], v[212:215], v[0:3]
	s_setprio 0
	s_barrier
	s_add_i32 s41, 0, 0x18000
	s_add_i32 s43, 0, 0x1c000
	v_add_u32_e32 v162, s41, v157
	v_add_u32_e32 v178, s43, v157
	ds_read_b128 v[144:147], v162
	ds_read_b128 v[148:151], v162 offset:1024
	ds_read_b128 v[152:155], v162 offset:2048
	ds_read_b128 v[162:165], v162 offset:3072
	ds_read_b128 v[166:169], v178
	ds_read_b128 v[170:173], v178 offset:1024
	ds_read_b128 v[174:177], v178 offset:2048
	ds_read_b128 v[178:181], v178 offset:3072
	s_add_u32 s70, s70, 0x20000
	s_addc_u32 s71, s71, 0
	ds_read_b128 v[182:185], v161 offset:32768
	ds_read_b128 v[186:189], v161 offset:33792
	ds_read_b128 v[190:193], v161 offset:34816
	ds_read_b128 v[196:199], v161 offset:35840
	ds_read_b128 v[200:203], v161 offset:36864
	ds_read_b128 v[204:207], v161 offset:37888
	ds_read_b128 v[208:211], v161 offset:38912
	ds_read_b128 v[212:215], v161 offset:39936
	s_mov_b32 m0, s83
	s_nop 0
	global_load_lds_dwordx4 v128, s[98:99]
	s_mov_b32 m0, s84
	s_nop 0
	global_load_lds_dwordx4 v132, s[98:99]
	s_mov_b32 m0, s85
	s_nop 0
	global_load_lds_dwordx4 v128, s[70:71]
	s_mov_b32 m0, s86
	s_nop 0
	global_load_lds_dwordx4 v132, s[70:71]
	s_waitcnt vmcnt(8)
	s_waitcnt lgkmcnt(0)
	s_barrier
	s_setprio 1
	s_waitcnt lgkmcnt(0)
	v_mfma_f32_16x16x32_bf16 v[124:127], v[144:147], v[182:185], v[124:127]
	v_mfma_f32_16x16x32_bf16 v[120:123], v[152:155], v[182:185], v[120:123]
	v_mfma_f32_16x16x32_bf16 v[108:111], v[144:147], v[190:193], v[108:111]
	v_mfma_f32_16x16x32_bf16 v[104:107], v[152:155], v[190:193], v[104:107]
	v_mfma_f32_16x16x32_bf16 v[92:95], v[144:147], v[200:203], v[92:95]
	v_mfma_f32_16x16x32_bf16 v[88:91], v[152:155], v[200:203], v[88:91]
	v_mfma_f32_16x16x32_bf16 v[76:79], v[144:147], v[208:211], v[76:79]
	v_mfma_f32_16x16x32_bf16 v[72:75], v[152:155], v[208:211], v[72:75]
	v_mfma_f32_16x16x32_bf16 v[124:127], v[148:151], v[186:189], v[124:127]
	v_mfma_f32_16x16x32_bf16 v[120:123], v[162:165], v[186:189], v[120:123]
	v_mfma_f32_16x16x32_bf16 v[108:111], v[148:151], v[196:199], v[108:111]
	v_mfma_f32_16x16x32_bf16 v[104:107], v[162:165], v[196:199], v[104:107]
	v_mfma_f32_16x16x32_bf16 v[92:95], v[148:151], v[204:207], v[92:95]
	v_mfma_f32_16x16x32_bf16 v[88:91], v[162:165], v[204:207], v[88:91]
	v_mfma_f32_16x16x32_bf16 v[76:79], v[148:151], v[212:215], v[76:79]
	v_mfma_f32_16x16x32_bf16 v[72:75], v[162:165], v[212:215], v[72:75]
	s_setprio 0
	s_setprio 1
	v_mfma_f32_16x16x32_bf16 v[116:119], v[166:169], v[182:185], v[116:119]
	v_mfma_f32_16x16x32_bf16 v[112:115], v[174:177], v[182:185], v[112:115]
	v_mfma_f32_16x16x32_bf16 v[100:103], v[166:169], v[190:193], v[100:103]
	v_mfma_f32_16x16x32_bf16 v[96:99], v[174:177], v[190:193], v[96:99]
	v_mfma_f32_16x16x32_bf16 v[84:87], v[166:169], v[200:203], v[84:87]
	v_mfma_f32_16x16x32_bf16 v[80:83], v[174:177], v[200:203], v[80:83]
	v_mfma_f32_16x16x32_bf16 v[68:71], v[166:169], v[208:211], v[68:71]
	v_mfma_f32_16x16x32_bf16 v[64:67], v[174:177], v[208:211], v[64:67]
	v_mfma_f32_16x16x32_bf16 v[116:119], v[170:173], v[186:189], v[116:119]
	v_mfma_f32_16x16x32_bf16 v[112:115], v[178:181], v[186:189], v[112:115]
	v_mfma_f32_16x16x32_bf16 v[100:103], v[170:173], v[196:199], v[100:103]
	v_mfma_f32_16x16x32_bf16 v[96:99], v[178:181], v[196:199], v[96:99]
	v_mfma_f32_16x16x32_bf16 v[84:87], v[170:173], v[204:207], v[84:87]
	v_mfma_f32_16x16x32_bf16 v[80:83], v[178:181], v[204:207], v[80:83]
	v_mfma_f32_16x16x32_bf16 v[68:71], v[170:173], v[212:215], v[68:71]
	v_mfma_f32_16x16x32_bf16 v[64:67], v[178:181], v[212:215], v[64:67]
	s_setprio 0
	s_barrier
	s_add_i32 s41, s41, s80
	s_add_i32 m0, s41, 0xffffff80
	ds_read_b128 v[182:185], v161 offset:49152
	ds_read_b128 v[186:189], v161 offset:50176
	ds_read_b128 v[190:193], v161 offset:51200
	ds_read_b128 v[196:199], v161 offset:52224
	ds_read_b128 v[200:203], v161 offset:53248
	ds_read_b128 v[204:207], v161 offset:54272
	ds_read_b128 v[208:211], v161 offset:55296
	ds_read_b128 v[212:215], v161 offset:56320
	global_load_lds_dwordx4 v130, s[62:63] offset:128
	s_add_i32 m0, s41, 0x1f80
	s_add_i32 s41, s43, s80
	global_load_lds_dwordx4 v134, s[62:63] offset:128
	s_add_u32 s62, s62, 0x20080
	s_addc_u32 s63, s63, 0
	s_mov_b32 m0, s41
	s_nop 0
	global_load_lds_dwordx4 v130, s[62:63]
	s_add_i32 m0, s41, 0x2000
	s_nop 0
	global_load_lds_dwordx4 v134, s[62:63]
	s_waitcnt vmcnt(6)
	s_waitcnt lgkmcnt(0)
	s_barrier
	s_setprio 1
	s_waitcnt lgkmcnt(0)
	v_mfma_f32_16x16x32_bf16 v[60:63], v[144:147], v[182:185], v[60:63]
	v_mfma_f32_16x16x32_bf16 v[56:59], v[152:155], v[182:185], v[56:59]
	v_mfma_f32_16x16x32_bf16 v[44:47], v[144:147], v[190:193], v[44:47]
	v_mfma_f32_16x16x32_bf16 v[40:43], v[152:155], v[190:193], v[40:43]
	v_mfma_f32_16x16x32_bf16 v[28:31], v[144:147], v[200:203], v[28:31]
	v_mfma_f32_16x16x32_bf16 v[24:27], v[152:155], v[200:203], v[24:27]
	v_mfma_f32_16x16x32_bf16 v[12:15], v[144:147], v[208:211], v[12:15]
	v_mfma_f32_16x16x32_bf16 v[8:11], v[152:155], v[208:211], v[8:11]
	v_mfma_f32_16x16x32_bf16 v[60:63], v[148:151], v[186:189], v[60:63]
	v_mfma_f32_16x16x32_bf16 v[56:59], v[162:165], v[186:189], v[56:59]
	v_mfma_f32_16x16x32_bf16 v[44:47], v[148:151], v[196:199], v[44:47]
	v_mfma_f32_16x16x32_bf16 v[40:43], v[162:165], v[196:199], v[40:43]
	v_mfma_f32_16x16x32_bf16 v[28:31], v[148:151], v[204:207], v[28:31]
	v_mfma_f32_16x16x32_bf16 v[24:27], v[162:165], v[204:207], v[24:27]
	v_mfma_f32_16x16x32_bf16 v[12:15], v[148:151], v[212:215], v[12:15]
	v_mfma_f32_16x16x32_bf16 v[8:11], v[162:165], v[212:215], v[8:11]
	s_setprio 0
	s_setprio 1
	v_mfma_f32_16x16x32_bf16 v[52:55], v[166:169], v[182:185], v[52:55]
	v_mfma_f32_16x16x32_bf16 v[48:51], v[174:177], v[182:185], v[48:51]
	v_mfma_f32_16x16x32_bf16 v[36:39], v[166:169], v[190:193], v[36:39]
	v_mfma_f32_16x16x32_bf16 v[32:35], v[174:177], v[190:193], v[32:35]
	v_mfma_f32_16x16x32_bf16 v[20:23], v[166:169], v[200:203], v[20:23]
	v_mfma_f32_16x16x32_bf16 v[16:19], v[174:177], v[200:203], v[16:19]
	v_mfma_f32_16x16x32_bf16 v[4:7], v[166:169], v[208:211], v[4:7]
	v_mfma_f32_16x16x32_bf16 v[0:3], v[174:177], v[208:211], v[0:3]
	v_mfma_f32_16x16x32_bf16 v[52:55], v[170:173], v[186:189], v[52:55]
	v_mfma_f32_16x16x32_bf16 v[48:51], v[178:181], v[186:189], v[48:51]
	v_mfma_f32_16x16x32_bf16 v[36:39], v[170:173], v[196:199], v[36:39]
	v_mfma_f32_16x16x32_bf16 v[32:35], v[178:181], v[196:199], v[32:35]
	v_mfma_f32_16x16x32_bf16 v[20:23], v[170:173], v[204:207], v[20:23]
	v_mfma_f32_16x16x32_bf16 v[16:19], v[178:181], v[204:207], v[16:19]
	v_mfma_f32_16x16x32_bf16 v[4:7], v[170:173], v[212:215], v[4:7]
	v_mfma_f32_16x16x32_bf16 v[0:3], v[178:181], v[212:215], v[0:3]
	s_setprio 0
	s_barrier
	s_add_i32 m0, s87, 0xffffff80
	s_nop 0
	global_load_lds_dwordx4 v128, s[98:99] offset:128
	s_add_i32 m0, s88, 0xffffff80
	s_nop 0
	global_load_lds_dwordx4 v132, s[98:99] offset:128
	s_add_i32 s39, s39, 2
	s_add_u32 s58, s58, 0x100
	s_addc_u32 s59, s59, 0
	s_add_u32 s15, s15, 0x100
	s_addc_u32 s17, s17, 0
	s_cmp_gt_u32 s39, 5
	s_cbranch_scc0 .LBB0_1451
	s_and_b64 vcc, exec, s[28:29]
	s_cbranch_vccz .LBB0_1454
	s_barrier

.LBB0_1625:
	ds_read_b128 v[144:147], v151
	ds_read_b128 v[156:159], v151 offset:1024
	ds_read_b128 v[160:163], v151 offset:2048
	ds_read_b128 v[164:167], v151 offset:3072
	ds_read_b128 v[168:171], v152
	ds_read_b128 v[172:175], v152 offset:1024
	ds_read_b128 v[176:179], v152 offset:2048
	ds_read_b128 v[180:183], v152 offset:3072
	s_add_u32 s42, s40, 0xfffc0080
	s_addc_u32 s43, s41, -1
	s_cmp_eq_u32 s87, 12
	s_cselect_b32 s45, s31, s43
	s_cselect_b32 s44, s39, s42
	s_cselect_b32 s43, s29, s86
	s_cselect_b32 s42, s84, s85
	s_add_i32 m0, s63, 0xc000
	ds_read_b128 v[184:187], v153
	ds_read_b128 v[188:191], v153 offset:1024
	ds_read_b128 v[196:199], v153 offset:2048
	ds_read_b128 v[200:203], v153 offset:3072
	ds_read_b128 v[204:207], v153 offset:4096
	ds_read_b128 v[208:211], v153 offset:5120
	ds_read_b128 v[212:215], v153 offset:6144
	ds_read_b128 v[216:219], v153 offset:7168
	global_load_lds_dwordx4 v136, s[40:41]
	s_add_i32 m0, s63, 0xe000
	s_nop 0
	global_load_lds_dwordx4 v138, s[40:41]
	s_waitcnt vmcnt(8)
	s_waitcnt lgkmcnt(0)
	s_barrier
	s_setprio 1
	s_waitcnt lgkmcnt(0)
	v_mfma_f32_16x16x32_bf16 v[124:127], v[144:147], v[184:187], v[124:127]
	v_mfma_f32_16x16x32_bf16 v[120:123], v[160:163], v[184:187], v[120:123]
	v_mfma_f32_16x16x32_bf16 v[108:111], v[144:147], v[196:199], v[108:111]
	v_mfma_f32_16x16x32_bf16 v[104:107], v[160:163], v[196:199], v[104:107]
	v_mfma_f32_16x16x32_bf16 v[92:95], v[144:147], v[204:207], v[92:95]
	v_mfma_f32_16x16x32_bf16 v[88:91], v[160:163], v[204:207], v[88:91]
	v_mfma_f32_16x16x32_bf16 v[76:79], v[144:147], v[212:215], v[76:79]
	v_mfma_f32_16x16x32_bf16 v[72:75], v[160:163], v[212:215], v[72:75]
	v_mfma_f32_16x16x32_bf16 v[124:127], v[156:159], v[188:191], v[124:127]
	v_mfma_f32_16x16x32_bf16 v[120:123], v[164:167], v[188:191], v[120:123]
	v_mfma_f32_16x16x32_bf16 v[108:111], v[156:159], v[200:203], v[108:111]
	v_mfma_f32_16x16x32_bf16 v[104:107], v[164:167], v[200:203], v[104:107]
	v_mfma_f32_16x16x32_bf16 v[92:95], v[156:159], v[208:211], v[92:95]
	v_mfma_f32_16x16x32_bf16 v[88:91], v[164:167], v[208:211], v[88:91]
	v_mfma_f32_16x16x32_bf16 v[76:79], v[156:159], v[216:219], v[76:79]
	v_mfma_f32_16x16x32_bf16 v[72:75], v[164:167], v[216:219], v[72:75]
	s_setprio 0
	s_setprio 1
	v_mfma_f32_16x16x32_bf16 v[116:119], v[168:171], v[184:187], v[116:119]
	v_mfma_f32_16x16x32_bf16 v[112:115], v[176:179], v[184:187], v[112:115]
	v_mfma_f32_16x16x32_bf16 v[100:103], v[168:171], v[196:199], v[100:103]
	v_mfma_f32_16x16x32_bf16 v[96:99], v[176:179], v[196:199], v[96:99]
	v_mfma_f32_16x16x32_bf16 v[84:87], v[168:171], v[204:207], v[84:87]
	v_mfma_f32_16x16x32_bf16 v[80:83], v[176:179], v[204:207], v[80:83]
	v_mfma_f32_16x16x32_bf16 v[68:71], v[168:171], v[212:215], v[68:71]
	v_mfma_f32_16x16x32_bf16 v[64:67], v[176:179], v[212:215], v[64:67]
	v_mfma_f32_16x16x32_bf16 v[116:119], v[172:175], v[188:191], v[116:119]
	v_mfma_f32_16x16x32_bf16 v[112:115], v[180:183], v[188:191], v[112:115]
	v_mfma_f32_16x16x32_bf16 v[100:103], v[172:175], v[200:203], v[100:103]
	v_mfma_f32_16x16x32_bf16 v[96:99], v[180:183], v[200:203], v[96:99]
	v_mfma_f32_16x16x32_bf16 v[84:87], v[172:175], v[208:211], v[84:87]
	v_mfma_f32_16x16x32_bf16 v[80:83], v[180:183], v[208:211], v[80:83]
	v_mfma_f32_16x16x32_bf16 v[68:71], v[172:175], v[216:219], v[68:71]
	v_mfma_f32_16x16x32_bf16 v[64:67], v[180:183], v[216:219], v[64:67]
	s_setprio 0
	s_barrier
	s_add_i32 s88, s81, s62
	s_mov_b32 m0, s88
	ds_read_b128 v[184:187], v153 offset:16384
	ds_read_b128 v[188:191], v153 offset:17408
	ds_read_b128 v[196:199], v153 offset:18432
	ds_read_b128 v[200:203], v153 offset:19456
	ds_read_b128 v[204:207], v153 offset:20480
	ds_read_b128 v[208:211], v153 offset:21504
	ds_read_b128 v[212:215], v153 offset:22528
	ds_read_b128 v[216:219], v153 offset:23552
	global_load_lds_dwordx4 v130, s[42:43]
	s_add_i32 m0, s88, 0x2000
	s_add_u32 s88, s42, 0x40000
	s_addc_u32 s89, s43, 0
	s_add_i32 s90, s82, s62
	global_load_lds_dwordx4 v134, s[42:43]
	s_mov_b32 m0, s90
	s_mov_b64 s[98:99], s[44:45]
	global_load_lds_dwordx4 v130, s[88:89]
	s_add_i32 m0, s90, 0x2000
	s_nop 0
	global_load_lds_dwordx4 v134, s[88:89]
	s_waitcnt vmcnt(6)
	s_waitcnt lgkmcnt(0)
	s_barrier
	s_setprio 1
	s_waitcnt lgkmcnt(0)
	v_mfma_f32_16x16x32_bf16 v[60:63], v[144:147], v[184:187], v[60:63]
	v_mfma_f32_16x16x32_bf16 v[56:59], v[160:163], v[184:187], v[56:59]
	v_mfma_f32_16x16x32_bf16 v[44:47], v[144:147], v[196:199], v[44:47]
	v_mfma_f32_16x16x32_bf16 v[40:43], v[160:163], v[196:199], v[40:43]
	v_mfma_f32_16x16x32_bf16 v[28:31], v[144:147], v[204:207], v[28:31]
	v_mfma_f32_16x16x32_bf16 v[24:27], v[160:163], v[204:207], v[24:27]
	v_mfma_f32_16x16x32_bf16 v[12:15], v[144:147], v[212:215], v[12:15]
	v_mfma_f32_16x16x32_bf16 v[8:11], v[160:163], v[212:215], v[8:11]
	v_mfma_f32_16x16x32_bf16 v[60:63], v[156:159], v[188:191], v[60:63]
	v_mfma_f32_16x16x32_bf16 v[56:59], v[164:167], v[188:191], v[56:59]
	v_mfma_f32_16x16x32_bf16 v[44:47], v[156:159], v[200:203], v[44:47]
	v_mfma_f32_16x16x32_bf16 v[40:43], v[164:167], v[200:203], v[40:43]
	v_mfma_f32_16x16x32_bf16 v[28:31], v[156:159], v[208:211], v[28:31]
	v_mfma_f32_16x16x32_bf16 v[24:27], v[164:167], v[208:211], v[24:27]
	v_mfma_f32_16x16x32_bf16 v[12:15], v[156:159], v[216:219], v[12:15]
	v_mfma_f32_16x16x32_bf16 v[8:11], v[164:167], v[216:219], v[8:11]
	s_setprio 0
	s_setprio 1
	v_mfma_f32_16x16x32_bf16 v[52:55], v[168:171], v[184:187], v[52:55]
	v_mfma_f32_16x16x32_bf16 v[48:51], v[176:179], v[184:187], v[48:51]
	v_mfma_f32_16x16x32_bf16 v[36:39], v[168:171], v[196:199], v[36:39]
	v_mfma_f32_16x16x32_bf16 v[32:35], v[176:179], v[196:199], v[32:35]
	v_mfma_f32_16x16x32_bf16 v[20:23], v[168:171], v[204:207], v[20:23]
	v_mfma_f32_16x16x32_bf16 v[16:19], v[176:179], v[204:207], v[16:19]
	v_mfma_f32_16x16x32_bf16 v[4:7], v[168:171], v[212:215], v[4:7]
	v_mfma_f32_16x16x32_bf16 v[0:3], v[176:179], v[212:215], v[0:3]
	v_mfma_f32_16x16x32_bf16 v[52:55], v[172:175], v[188:191], v[52:55]
	v_mfma_f32_16x16x32_bf16 v[48:51], v[180:183], v[188:191], v[48:51]
	v_mfma_f32_16x16x32_bf16 v[36:39], v[172:175], v[200:203], v[36:39]
	v_mfma_f32_16x16x32_bf16 v[32:35], v[180:183], v[200:203], v[32:35]
	v_mfma_f32_16x16x32_bf16 v[20:23], v[172:175], v[208:211], v[20:23]
	v_mfma_f32_16x16x32_bf16 v[16:19], v[180:183], v[208:211], v[16:19]
	v_mfma_f32_16x16x32_bf16 v[4:7], v[172:175], v[216:219], v[4:7]
	v_mfma_f32_16x16x32_bf16 v[0:3], v[180:183], v[216:219], v[0:3]
	s_setprio 0
	s_barrier
	s_add_i32 s88, 0, 0x18000
	v_add_u32_e32 v155, s88, v149
	s_add_i32 s89, 0, 0x1c000
	ds_read_b128 v[144:147], v155
	ds_read_b128 v[156:159], v155 offset:1024
	ds_read_b128 v[160:163], v155 offset:2048
	ds_read_b128 v[164:167], v155 offset:3072
	v_add_u32_e32 v155, s89, v149
	ds_read_b128 v[168:171], v155
	ds_read_b128 v[172:175], v155 offset:1024
	ds_read_b128 v[176:179], v155 offset:2048
	ds_read_b128 v[180:183], v155 offset:3072
	s_add_u32 s44, s44, 0x40000
	s_addc_u32 s45, s45, 0
	ds_read_b128 v[184:187], v153 offset:32768
	ds_read_b128 v[188:191], v153 offset:33792
	ds_read_b128 v[196:199], v153 offset:34816
	ds_read_b128 v[200:203], v153 offset:35840
	ds_read_b128 v[204:207], v153 offset:36864
	ds_read_b128 v[208:211], v153 offset:37888
	ds_read_b128 v[212:215], v153 offset:38912
	ds_read_b128 v[216:219], v153 offset:39936
	s_mov_b32 m0, s63
	s_nop 0
	global_load_lds_dwordx4 v128, s[98:99]
	s_mov_b32 m0, s70
	s_nop 0
	global_load_lds_dwordx4 v132, s[98:99]
	s_mov_b32 m0, s71
	s_nop 0
	global_load_lds_dwordx4 v128, s[44:45]
	s_mov_b32 m0, s72
	s_nop 0
	global_load_lds_dwordx4 v132, s[44:45]
	s_waitcnt vmcnt(8)
	s_waitcnt lgkmcnt(0)
	s_barrier
	s_setprio 1
	s_waitcnt lgkmcnt(0)
	v_mfma_f32_16x16x32_bf16 v[124:127], v[144:147], v[184:187], v[124:127]
	v_mfma_f32_16x16x32_bf16 v[120:123], v[160:163], v[184:187], v[120:123]
	v_mfma_f32_16x16x32_bf16 v[108:111], v[144:147], v[196:199], v[108:111]
	v_mfma_f32_16x16x32_bf16 v[104:107], v[160:163], v[196:199], v[104:107]
	v_mfma_f32_16x16x32_bf16 v[92:95], v[144:147], v[204:207], v[92:95]
	v_mfma_f32_16x16x32_bf16 v[88:91], v[160:163], v[204:207], v[88:91]
	v_mfma_f32_16x16x32_bf16 v[76:79], v[144:147], v[212:215], v[76:79]
	v_mfma_f32_16x16x32_bf16 v[72:75], v[160:163], v[212:215], v[72:75]
	v_mfma_f32_16x16x32_bf16 v[124:127], v[156:159], v[188:191], v[124:127]
	v_mfma_f32_16x16x32_bf16 v[120:123], v[164:167], v[188:191], v[120:123]
	v_mfma_f32_16x16x32_bf16 v[108:111], v[156:159], v[200:203], v[108:111]
	v_mfma_f32_16x16x32_bf16 v[104:107], v[164:167], v[200:203], v[104:107]
	v_mfma_f32_16x16x32_bf16 v[92:95], v[156:159], v[208:211], v[92:95]
	v_mfma_f32_16x16x32_bf16 v[88:91], v[164:167], v[208:211], v[88:91]
	v_mfma_f32_16x16x32_bf16 v[76:79], v[156:159], v[216:219], v[76:79]
	v_mfma_f32_16x16x32_bf16 v[72:75], v[164:167], v[216:219], v[72:75]
	s_setprio 0
	s_setprio 1
	v_mfma_f32_16x16x32_bf16 v[116:119], v[168:171], v[184:187], v[116:119]
	v_mfma_f32_16x16x32_bf16 v[112:115], v[176:179], v[184:187], v[112:115]
	v_mfma_f32_16x16x32_bf16 v[100:103], v[168:171], v[196:199], v[100:103]
	v_mfma_f32_16x16x32_bf16 v[96:99], v[176:179], v[196:199], v[96:99]
	v_mfma_f32_16x16x32_bf16 v[84:87], v[168:171], v[204:207], v[84:87]
	v_mfma_f32_16x16x32_bf16 v[80:83], v[176:179], v[204:207], v[80:83]
	v_mfma_f32_16x16x32_bf16 v[68:71], v[168:171], v[212:215], v[68:71]
	v_mfma_f32_16x16x32_bf16 v[64:67], v[176:179], v[212:215], v[64:67]
	v_mfma_f32_16x16x32_bf16 v[116:119], v[172:175], v[188:191], v[116:119]
	v_mfma_f32_16x16x32_bf16 v[112:115], v[180:183], v[188:191], v[112:115]
	v_mfma_f32_16x16x32_bf16 v[100:103], v[172:175], v[200:203], v[100:103]
	v_mfma_f32_16x16x32_bf16 v[96:99], v[180:183], v[200:203], v[96:99]
	v_mfma_f32_16x16x32_bf16 v[84:87], v[172:175], v[208:211], v[84:87]
	v_mfma_f32_16x16x32_bf16 v[80:83], v[180:183], v[208:211], v[80:83]
	v_mfma_f32_16x16x32_bf16 v[68:71], v[172:175], v[216:219], v[68:71]
	v_mfma_f32_16x16x32_bf16 v[64:67], v[180:183], v[216:219], v[64:67]
	s_setprio 0
	s_barrier
	s_add_i32 s44, s88, s62
	s_add_i32 m0, s44, 0xffffff80
	ds_read_b128 v[184:187], v153 offset:49152
	ds_read_b128 v[188:191], v153 offset:50176
	ds_read_b128 v[196:199], v153 offset:51200
	ds_read_b128 v[200:203], v153 offset:52224
	ds_read_b128 v[204:207], v153 offset:53248
	ds_read_b128 v[208:211], v153 offset:54272
	ds_read_b128 v[212:215], v153 offset:55296
	ds_read_b128 v[216:219], v153 offset:56320
	global_load_lds_dwordx4 v130, s[42:43] offset:128
	s_add_i32 m0, s44, 0x1f80
	s_add_i32 s44, s89, s62
	global_load_lds_dwordx4 v134, s[42:43] offset:128
	s_add_u32 s42, s42, 0x40080
	s_addc_u32 s43, s43, 0
	s_mov_b32 m0, s44
	s_nop 0
	global_load_lds_dwordx4 v130, s[42:43]
	s_add_i32 m0, s44, 0x2000
	s_nop 0
	global_load_lds_dwordx4 v134, s[42:43]
	s_waitcnt vmcnt(6)
	s_waitcnt lgkmcnt(0)
	s_barrier
	s_setprio 1
	s_waitcnt lgkmcnt(0)
	v_mfma_f32_16x16x32_bf16 v[60:63], v[144:147], v[184:187], v[60:63]
	v_mfma_f32_16x16x32_bf16 v[56:59], v[160:163], v[184:187], v[56:59]
	v_mfma_f32_16x16x32_bf16 v[44:47], v[144:147], v[196:199], v[44:47]
	v_mfma_f32_16x16x32_bf16 v[40:43], v[160:163], v[196:199], v[40:43]
	v_mfma_f32_16x16x32_bf16 v[28:31], v[144:147], v[204:207], v[28:31]
	v_mfma_f32_16x16x32_bf16 v[24:27], v[160:163], v[204:207], v[24:27]
	v_mfma_f32_16x16x32_bf16 v[12:15], v[144:147], v[212:215], v[12:15]
	v_mfma_f32_16x16x32_bf16 v[8:11], v[160:163], v[212:215], v[8:11]
	v_mfma_f32_16x16x32_bf16 v[60:63], v[156:159], v[188:191], v[60:63]
	v_mfma_f32_16x16x32_bf16 v[56:59], v[164:167], v[188:191], v[56:59]
	v_mfma_f32_16x16x32_bf16 v[44:47], v[156:159], v[200:203], v[44:47]
	v_mfma_f32_16x16x32_bf16 v[40:43], v[164:167], v[200:203], v[40:43]
	v_mfma_f32_16x16x32_bf16 v[28:31], v[156:159], v[208:211], v[28:31]
	v_mfma_f32_16x16x32_bf16 v[24:27], v[164:167], v[208:211], v[24:27]
	v_mfma_f32_16x16x32_bf16 v[12:15], v[156:159], v[216:219], v[12:15]
	v_mfma_f32_16x16x32_bf16 v[8:11], v[164:167], v[216:219], v[8:11]
	s_setprio 0
	s_setprio 1
	v_mfma_f32_16x16x32_bf16 v[52:55], v[168:171], v[184:187], v[52:55]
	v_mfma_f32_16x16x32_bf16 v[48:51], v[176:179], v[184:187], v[48:51]
	v_mfma_f32_16x16x32_bf16 v[36:39], v[168:171], v[196:199], v[36:39]
	v_mfma_f32_16x16x32_bf16 v[32:35], v[176:179], v[196:199], v[32:35]
	v_mfma_f32_16x16x32_bf16 v[20:23], v[168:171], v[204:207], v[20:23]
	v_mfma_f32_16x16x32_bf16 v[16:19], v[176:179], v[204:207], v[16:19]
	v_mfma_f32_16x16x32_bf16 v[4:7], v[168:171], v[212:215], v[4:7]
	v_mfma_f32_16x16x32_bf16 v[0:3], v[176:179], v[212:215], v[0:3]
	v_mfma_f32_16x16x32_bf16 v[52:55], v[172:175], v[188:191], v[52:55]
	v_mfma_f32_16x16x32_bf16 v[48:51], v[180:183], v[188:191], v[48:51]
	v_mfma_f32_16x16x32_bf16 v[36:39], v[172:175], v[200:203], v[36:39]
	v_mfma_f32_16x16x32_bf16 v[32:35], v[180:183], v[200:203], v[32:35]
	v_mfma_f32_16x16x32_bf16 v[20:23], v[172:175], v[208:211], v[20:23]
	v_mfma_f32_16x16x32_bf16 v[16:19], v[180:183], v[208:211], v[16:19]
	v_mfma_f32_16x16x32_bf16 v[4:7], v[172:175], v[216:219], v[4:7]
	v_mfma_f32_16x16x32_bf16 v[0:3], v[180:183], v[216:219], v[0:3]
	s_setprio 0
	s_barrier
	s_add_i32 m0, s78, 0xffffff80
	s_nop 0
	global_load_lds_dwordx4 v128, s[98:99] offset:128
	s_add_i32 m0, s79, 0xffffff80
	s_nop 0
	global_load_lds_dwordx4 v132, s[98:99] offset:128
	s_add_i32 s87, s87, 2
	s_add_u32 s40, s40, 0x100
	s_addc_u32 s41, s41, 0
	s_add_u32 s85, s85, 0x100
	s_addc_u32 s86, s86, 0
	s_cmp_gt_u32 s87, 13
	s_cbranch_scc0 .LBB0_1625
	s_and_b64 vcc, exec, s[26:27]
	s_cbranch_vccz .LBB0_1628
	s_barrier

.LBB0_1709:
	ds_read_b128 v[154:157], v149
	ds_read_b128 v[158:161], v149 offset:1024
	ds_read_b128 v[162:165], v149 offset:2048
	ds_read_b128 v[166:169], v149 offset:3072
	ds_read_b128 v[170:173], v150
	ds_read_b128 v[174:177], v150 offset:1024
	ds_read_b128 v[178:181], v150 offset:2048
	ds_read_b128 v[182:185], v150 offset:3072
	s_add_u32 s38, s36, 0xfffc0080
	s_addc_u32 s39, s37, -1
	s_cmp_eq_u32 s84, 12
	s_cselect_b32 s41, s27, s39
	s_cselect_b32 s40, s80, s38
	s_cselect_b32 s39, s25, s83
	s_cselect_b32 s38, s81, s82
	s_add_i32 m0, s35, 0xc000
	ds_read_b128 v[186:189], v151
	ds_read_b128 v[190:193], v151 offset:1024
	ds_read_b128 v[196:199], v151 offset:2048
	ds_read_b128 v[200:203], v151 offset:3072
	ds_read_b128 v[204:207], v151 offset:4096
	ds_read_b128 v[208:211], v151 offset:5120
	ds_read_b128 v[212:215], v151 offset:6144
	ds_read_b128 v[216:219], v151 offset:7168
	global_load_lds_dwordx4 v136, s[36:37]
	s_add_i32 m0, s35, 0xe000
	s_nop 0
	global_load_lds_dwordx4 v138, s[36:37]
	s_waitcnt vmcnt(8)
	s_waitcnt lgkmcnt(0)
	s_barrier
	s_setprio 1
	s_waitcnt lgkmcnt(0)
	v_mfma_f32_16x16x32_bf16 v[116:119], v[154:157], v[186:189], v[116:119]
	v_mfma_f32_16x16x32_bf16 v[112:115], v[162:165], v[186:189], v[112:115]
	v_mfma_f32_16x16x32_bf16 v[100:103], v[154:157], v[196:199], v[100:103]
	v_mfma_f32_16x16x32_bf16 v[96:99], v[162:165], v[196:199], v[96:99]
	v_mfma_f32_16x16x32_bf16 v[84:87], v[154:157], v[204:207], v[84:87]
	v_mfma_f32_16x16x32_bf16 v[80:83], v[162:165], v[204:207], v[80:83]
	v_mfma_f32_16x16x32_bf16 v[68:71], v[154:157], v[212:215], v[68:71]
	v_mfma_f32_16x16x32_bf16 v[64:67], v[162:165], v[212:215], v[64:67]
	v_mfma_f32_16x16x32_bf16 v[116:119], v[158:161], v[190:193], v[116:119]
	v_mfma_f32_16x16x32_bf16 v[112:115], v[166:169], v[190:193], v[112:115]
	v_mfma_f32_16x16x32_bf16 v[100:103], v[158:161], v[200:203], v[100:103]
	v_mfma_f32_16x16x32_bf16 v[96:99], v[166:169], v[200:203], v[96:99]
	v_mfma_f32_16x16x32_bf16 v[84:87], v[158:161], v[208:211], v[84:87]
	v_mfma_f32_16x16x32_bf16 v[80:83], v[166:169], v[208:211], v[80:83]
	v_mfma_f32_16x16x32_bf16 v[68:71], v[158:161], v[216:219], v[68:71]
	v_mfma_f32_16x16x32_bf16 v[64:67], v[166:169], v[216:219], v[64:67]
	s_setprio 0
	s_setprio 1
	v_mfma_f32_16x16x32_bf16 v[124:127], v[170:173], v[186:189], v[124:127]
	v_mfma_f32_16x16x32_bf16 v[120:123], v[178:181], v[186:189], v[120:123]
	v_mfma_f32_16x16x32_bf16 v[108:111], v[170:173], v[196:199], v[108:111]
	v_mfma_f32_16x16x32_bf16 v[104:107], v[178:181], v[196:199], v[104:107]
	v_mfma_f32_16x16x32_bf16 v[92:95], v[170:173], v[204:207], v[92:95]
	v_mfma_f32_16x16x32_bf16 v[88:91], v[178:181], v[204:207], v[88:91]
	v_mfma_f32_16x16x32_bf16 v[76:79], v[170:173], v[212:215], v[76:79]
	v_mfma_f32_16x16x32_bf16 v[72:75], v[178:181], v[212:215], v[72:75]
	v_mfma_f32_16x16x32_bf16 v[124:127], v[174:177], v[190:193], v[124:127]
	v_mfma_f32_16x16x32_bf16 v[120:123], v[182:185], v[190:193], v[120:123]
	v_mfma_f32_16x16x32_bf16 v[108:111], v[174:177], v[200:203], v[108:111]
	v_mfma_f32_16x16x32_bf16 v[104:107], v[182:185], v[200:203], v[104:107]
	v_mfma_f32_16x16x32_bf16 v[92:95], v[174:177], v[208:211], v[92:95]
	v_mfma_f32_16x16x32_bf16 v[88:91], v[182:185], v[208:211], v[88:91]
	v_mfma_f32_16x16x32_bf16 v[76:79], v[174:177], v[216:219], v[76:79]
	v_mfma_f32_16x16x32_bf16 v[72:75], v[182:185], v[216:219], v[72:75]
	s_setprio 0
	s_barrier
	s_add_i32 s85, s71, s56
	s_mov_b32 m0, s85
	ds_read_b128 v[186:189], v151 offset:16384
	ds_read_b128 v[190:193], v151 offset:17408
	ds_read_b128 v[196:199], v151 offset:18432
	ds_read_b128 v[200:203], v151 offset:19456
	ds_read_b128 v[204:207], v151 offset:20480
	ds_read_b128 v[208:211], v151 offset:21504
	ds_read_b128 v[212:215], v151 offset:22528
	ds_read_b128 v[216:219], v151 offset:23552
	global_load_lds_dwordx4 v132, s[38:39]
	s_add_i32 m0, s85, 0x2000
	s_add_u32 s86, s38, 0x40000
	s_addc_u32 s87, s39, 0
	s_add_i32 s85, s72, s56
	global_load_lds_dwordx4 v128, s[38:39]
	s_mov_b32 m0, s85
	s_mov_b64 s[98:99], s[40:41]
	global_load_lds_dwordx4 v132, s[86:87]
	s_add_i32 m0, s85, 0x2000
	s_nop 0
	global_load_lds_dwordx4 v128, s[86:87]
	s_waitcnt vmcnt(6)
	s_waitcnt lgkmcnt(0)
	s_barrier
	s_setprio 1
	s_waitcnt lgkmcnt(0)
	v_mfma_f32_16x16x32_bf16 v[52:55], v[154:157], v[186:189], v[52:55]
	v_mfma_f32_16x16x32_bf16 v[48:51], v[162:165], v[186:189], v[48:51]
	v_mfma_f32_16x16x32_bf16 v[36:39], v[154:157], v[196:199], v[36:39]
	v_mfma_f32_16x16x32_bf16 v[32:35], v[162:165], v[196:199], v[32:35]
	v_mfma_f32_16x16x32_bf16 v[20:23], v[154:157], v[204:207], v[20:23]
	v_mfma_f32_16x16x32_bf16 v[16:19], v[162:165], v[204:207], v[16:19]
	v_mfma_f32_16x16x32_bf16 v[4:7], v[154:157], v[212:215], v[4:7]
	v_mfma_f32_16x16x32_bf16 v[0:3], v[162:165], v[212:215], v[0:3]
	v_mfma_f32_16x16x32_bf16 v[52:55], v[158:161], v[190:193], v[52:55]
	v_mfma_f32_16x16x32_bf16 v[48:51], v[166:169], v[190:193], v[48:51]
	v_mfma_f32_16x16x32_bf16 v[36:39], v[158:161], v[200:203], v[36:39]
	v_mfma_f32_16x16x32_bf16 v[32:35], v[166:169], v[200:203], v[32:35]
	v_mfma_f32_16x16x32_bf16 v[20:23], v[158:161], v[208:211], v[20:23]
	v_mfma_f32_16x16x32_bf16 v[16:19], v[166:169], v[208:211], v[16:19]
	v_mfma_f32_16x16x32_bf16 v[4:7], v[158:161], v[216:219], v[4:7]
	v_mfma_f32_16x16x32_bf16 v[0:3], v[166:169], v[216:219], v[0:3]
	s_setprio 0
	s_setprio 1
	v_mfma_f32_16x16x32_bf16 v[60:63], v[170:173], v[186:189], v[60:63]
	v_mfma_f32_16x16x32_bf16 v[56:59], v[178:181], v[186:189], v[56:59]
	v_mfma_f32_16x16x32_bf16 v[44:47], v[170:173], v[196:199], v[44:47]
	v_mfma_f32_16x16x32_bf16 v[40:43], v[178:181], v[196:199], v[40:43]
	v_mfma_f32_16x16x32_bf16 v[28:31], v[170:173], v[204:207], v[28:31]
	v_mfma_f32_16x16x32_bf16 v[24:27], v[178:181], v[204:207], v[24:27]
	v_mfma_f32_16x16x32_bf16 v[12:15], v[170:173], v[212:215], v[12:15]
	v_mfma_f32_16x16x32_bf16 v[8:11], v[178:181], v[212:215], v[8:11]
	v_mfma_f32_16x16x32_bf16 v[60:63], v[174:177], v[190:193], v[60:63]
	v_mfma_f32_16x16x32_bf16 v[56:59], v[182:185], v[190:193], v[56:59]
	v_mfma_f32_16x16x32_bf16 v[44:47], v[174:177], v[200:203], v[44:47]
	v_mfma_f32_16x16x32_bf16 v[40:43], v[182:185], v[200:203], v[40:43]
	v_mfma_f32_16x16x32_bf16 v[28:31], v[174:177], v[208:211], v[28:31]
	v_mfma_f32_16x16x32_bf16 v[24:27], v[182:185], v[208:211], v[24:27]
	v_mfma_f32_16x16x32_bf16 v[12:15], v[174:177], v[216:219], v[12:15]
	v_mfma_f32_16x16x32_bf16 v[8:11], v[182:185], v[216:219], v[8:11]
	s_setprio 0
	s_barrier
	s_add_i32 s85, 0, 0x18000
	v_add_u32_e32 v153, s85, v147
	s_add_i32 s86, 0, 0x1c000
	ds_read_b128 v[154:157], v153
	ds_read_b128 v[158:161], v153 offset:1024
	ds_read_b128 v[162:165], v153 offset:2048
	ds_read_b128 v[166:169], v153 offset:3072
	v_add_u32_e32 v153, s86, v147
	ds_read_b128 v[170:173], v153
	ds_read_b128 v[174:177], v153 offset:1024
	ds_read_b128 v[178:181], v153 offset:2048
	ds_read_b128 v[182:185], v153 offset:3072
	s_add_u32 s40, s40, 0x40000
	s_addc_u32 s41, s41, 0
	ds_read_b128 v[186:189], v151 offset:32768
	ds_read_b128 v[190:193], v151 offset:33792
	ds_read_b128 v[196:199], v151 offset:34816
	ds_read_b128 v[200:203], v151 offset:35840
	ds_read_b128 v[204:207], v151 offset:36864
	ds_read_b128 v[208:211], v151 offset:37888
	ds_read_b128 v[212:215], v151 offset:38912
	ds_read_b128 v[216:219], v151 offset:39936
	s_mov_b32 m0, s35
	s_nop 0
	global_load_lds_dwordx4 v134, s[98:99]
	s_mov_b32 m0, s58
	s_nop 0
	global_load_lds_dwordx4 v130, s[98:99]
	s_mov_b32 m0, s59
	s_nop 0
	global_load_lds_dwordx4 v134, s[40:41]
	s_mov_b32 m0, s60
	s_nop 0
	global_load_lds_dwordx4 v130, s[40:41]
	s_waitcnt vmcnt(8)
	s_waitcnt lgkmcnt(0)
	s_barrier
	s_setprio 1
	s_waitcnt lgkmcnt(0)
	v_mfma_f32_16x16x32_bf16 v[116:119], v[154:157], v[186:189], v[116:119]
	v_mfma_f32_16x16x32_bf16 v[112:115], v[162:165], v[186:189], v[112:115]
	v_mfma_f32_16x16x32_bf16 v[100:103], v[154:157], v[196:199], v[100:103]
	v_mfma_f32_16x16x32_bf16 v[96:99], v[162:165], v[196:199], v[96:99]
	v_mfma_f32_16x16x32_bf16 v[84:87], v[154:157], v[204:207], v[84:87]
	v_mfma_f32_16x16x32_bf16 v[80:83], v[162:165], v[204:207], v[80:83]
	v_mfma_f32_16x16x32_bf16 v[68:71], v[154:157], v[212:215], v[68:71]
	v_mfma_f32_16x16x32_bf16 v[64:67], v[162:165], v[212:215], v[64:67]
	v_mfma_f32_16x16x32_bf16 v[116:119], v[158:161], v[190:193], v[116:119]
	v_mfma_f32_16x16x32_bf16 v[112:115], v[166:169], v[190:193], v[112:115]
	v_mfma_f32_16x16x32_bf16 v[100:103], v[158:161], v[200:203], v[100:103]
	v_mfma_f32_16x16x32_bf16 v[96:99], v[166:169], v[200:203], v[96:99]
	v_mfma_f32_16x16x32_bf16 v[84:87], v[158:161], v[208:211], v[84:87]
	v_mfma_f32_16x16x32_bf16 v[80:83], v[166:169], v[208:211], v[80:83]
	v_mfma_f32_16x16x32_bf16 v[68:71], v[158:161], v[216:219], v[68:71]
	v_mfma_f32_16x16x32_bf16 v[64:67], v[166:169], v[216:219], v[64:67]
	s_setprio 0
	s_setprio 1
	v_mfma_f32_16x16x32_bf16 v[124:127], v[170:173], v[186:189], v[124:127]
	v_mfma_f32_16x16x32_bf16 v[120:123], v[178:181], v[186:189], v[120:123]
	v_mfma_f32_16x16x32_bf16 v[108:111], v[170:173], v[196:199], v[108:111]
	v_mfma_f32_16x16x32_bf16 v[104:107], v[178:181], v[196:199], v[104:107]
	v_mfma_f32_16x16x32_bf16 v[92:95], v[170:173], v[204:207], v[92:95]
	v_mfma_f32_16x16x32_bf16 v[88:91], v[178:181], v[204:207], v[88:91]
	v_mfma_f32_16x16x32_bf16 v[76:79], v[170:173], v[212:215], v[76:79]
	v_mfma_f32_16x16x32_bf16 v[72:75], v[178:181], v[212:215], v[72:75]
	v_mfma_f32_16x16x32_bf16 v[124:127], v[174:177], v[190:193], v[124:127]
	v_mfma_f32_16x16x32_bf16 v[120:123], v[182:185], v[190:193], v[120:123]
	v_mfma_f32_16x16x32_bf16 v[108:111], v[174:177], v[200:203], v[108:111]
	v_mfma_f32_16x16x32_bf16 v[104:107], v[182:185], v[200:203], v[104:107]
	v_mfma_f32_16x16x32_bf16 v[92:95], v[174:177], v[208:211], v[92:95]
	v_mfma_f32_16x16x32_bf16 v[88:91], v[182:185], v[208:211], v[88:91]
	v_mfma_f32_16x16x32_bf16 v[76:79], v[174:177], v[216:219], v[76:79]
	v_mfma_f32_16x16x32_bf16 v[72:75], v[182:185], v[216:219], v[72:75]
	s_setprio 0
	s_barrier
	s_add_i32 s40, s85, s56
	s_add_i32 m0, s40, 0xffffff80
	ds_read_b128 v[186:189], v151 offset:49152
	ds_read_b128 v[190:193], v151 offset:50176
	ds_read_b128 v[196:199], v151 offset:51200
	ds_read_b128 v[200:203], v151 offset:52224
	ds_read_b128 v[204:207], v151 offset:53248
	ds_read_b128 v[208:211], v151 offset:54272
	ds_read_b128 v[212:215], v151 offset:55296
	ds_read_b128 v[216:219], v151 offset:56320
	global_load_lds_dwordx4 v132, s[38:39] offset:128
	s_add_i32 m0, s40, 0x1f80
	s_add_i32 s40, s86, s56
	global_load_lds_dwordx4 v128, s[38:39] offset:128
	s_add_u32 s38, s38, 0x40080
	s_addc_u32 s39, s39, 0
	s_mov_b32 m0, s40
	s_nop 0
	global_load_lds_dwordx4 v132, s[38:39]
	s_add_i32 m0, s40, 0x2000
	s_nop 0
	global_load_lds_dwordx4 v128, s[38:39]
	s_waitcnt vmcnt(6)
	s_waitcnt lgkmcnt(0)
	s_barrier
	s_setprio 1
	s_waitcnt lgkmcnt(0)
	v_mfma_f32_16x16x32_bf16 v[52:55], v[154:157], v[186:189], v[52:55]
	v_mfma_f32_16x16x32_bf16 v[48:51], v[162:165], v[186:189], v[48:51]
	v_mfma_f32_16x16x32_bf16 v[36:39], v[154:157], v[196:199], v[36:39]
	v_mfma_f32_16x16x32_bf16 v[32:35], v[162:165], v[196:199], v[32:35]
	v_mfma_f32_16x16x32_bf16 v[20:23], v[154:157], v[204:207], v[20:23]
	v_mfma_f32_16x16x32_bf16 v[16:19], v[162:165], v[204:207], v[16:19]
	v_mfma_f32_16x16x32_bf16 v[4:7], v[154:157], v[212:215], v[4:7]
	v_mfma_f32_16x16x32_bf16 v[0:3], v[162:165], v[212:215], v[0:3]
	v_mfma_f32_16x16x32_bf16 v[52:55], v[158:161], v[190:193], v[52:55]
	v_mfma_f32_16x16x32_bf16 v[48:51], v[166:169], v[190:193], v[48:51]
	v_mfma_f32_16x16x32_bf16 v[36:39], v[158:161], v[200:203], v[36:39]
	v_mfma_f32_16x16x32_bf16 v[32:35], v[166:169], v[200:203], v[32:35]
	v_mfma_f32_16x16x32_bf16 v[20:23], v[158:161], v[208:211], v[20:23]
	v_mfma_f32_16x16x32_bf16 v[16:19], v[166:169], v[208:211], v[16:19]
	v_mfma_f32_16x16x32_bf16 v[4:7], v[158:161], v[216:219], v[4:7]
	v_mfma_f32_16x16x32_bf16 v[0:3], v[166:169], v[216:219], v[0:3]
	s_setprio 0
	s_setprio 1
	v_mfma_f32_16x16x32_bf16 v[60:63], v[170:173], v[186:189], v[60:63]
	v_mfma_f32_16x16x32_bf16 v[56:59], v[178:181], v[186:189], v[56:59]
	v_mfma_f32_16x16x32_bf16 v[44:47], v[170:173], v[196:199], v[44:47]
	v_mfma_f32_16x16x32_bf16 v[40:43], v[178:181], v[196:199], v[40:43]
	v_mfma_f32_16x16x32_bf16 v[28:31], v[170:173], v[204:207], v[28:31]
	v_mfma_f32_16x16x32_bf16 v[24:27], v[178:181], v[204:207], v[24:27]
	v_mfma_f32_16x16x32_bf16 v[12:15], v[170:173], v[212:215], v[12:15]
	v_mfma_f32_16x16x32_bf16 v[8:11], v[178:181], v[212:215], v[8:11]
	v_mfma_f32_16x16x32_bf16 v[60:63], v[174:177], v[190:193], v[60:63]
	v_mfma_f32_16x16x32_bf16 v[56:59], v[182:185], v[190:193], v[56:59]
	v_mfma_f32_16x16x32_bf16 v[44:47], v[174:177], v[200:203], v[44:47]
	v_mfma_f32_16x16x32_bf16 v[40:43], v[182:185], v[200:203], v[40:43]
	v_mfma_f32_16x16x32_bf16 v[28:31], v[174:177], v[208:211], v[28:31]
	v_mfma_f32_16x16x32_bf16 v[24:27], v[182:185], v[208:211], v[24:27]
	v_mfma_f32_16x16x32_bf16 v[12:15], v[174:177], v[216:219], v[12:15]
	v_mfma_f32_16x16x32_bf16 v[8:11], v[182:185], v[216:219], v[8:11]
	s_setprio 0
	s_barrier
	s_add_i32 m0, s62, 0xffffff80
	s_nop 0
	global_load_lds_dwordx4 v134, s[98:99] offset:128
	s_add_i32 m0, s63, 0xffffff80
	s_nop 0
	global_load_lds_dwordx4 v130, s[98:99] offset:128
	s_add_i32 s84, s84, 2
	s_add_u32 s36, s36, 0x100
	s_addc_u32 s37, s37, 0
	s_add_u32 s82, s82, 0x100
	s_addc_u32 s83, s83, 0
	s_cmp_gt_u32 s84, 13
	s_cbranch_scc0 .LBB0_1709
	s_and_b64 vcc, exec, s[22:23]
	s_cbranch_vccz .LBB0_1712
	s_barrier

.LBB0_1791:
	ds_read_b128 v[144:147], v151
	ds_read_b128 v[156:159], v151 offset:1024
	ds_read_b128 v[160:163], v151 offset:2048
	ds_read_b128 v[164:167], v151 offset:3072
	ds_read_b128 v[168:171], v152
	ds_read_b128 v[172:175], v152 offset:1024
	ds_read_b128 v[176:179], v152 offset:2048
	ds_read_b128 v[180:183], v152 offset:3072
	s_add_u32 s38, s36, 0x100
	s_addc_u32 s39, s37, 0
	s_cmp_eq_u32 s85, 40
	s_cselect_b32 s43, s1, s39
	s_cselect_b32 s42, s0, s38
	s_cselect_b32 s41, s35, s84
	s_cselect_b32 s40, s34, s83
	v_lshl_add_u64 v[192:193], s[36:37], 0, v[136:137]
	s_add_i32 m0, s59, 0xc000
	ds_read_b128 v[184:187], v153
	ds_read_b128 v[188:191], v153 offset:1024
	ds_read_b128 v[196:199], v153 offset:2048
	ds_read_b128 v[200:203], v153 offset:3072
	ds_read_b128 v[204:207], v153 offset:4096
	ds_read_b128 v[208:211], v153 offset:5120
	ds_read_b128 v[212:215], v153 offset:6144
	ds_read_b128 v[216:219], v153 offset:7168
	global_load_lds_dwordx4 v[192:193], off
	v_lshl_add_u64 v[192:193], s[36:37], 0, v[138:139]
	s_add_i32 m0, s59, 0xe000
	s_nop 0
	global_load_lds_dwordx4 v[192:193], off
	s_waitcnt vmcnt(8)
	s_waitcnt lgkmcnt(0)
	s_barrier
	s_setprio 1
	s_waitcnt lgkmcnt(0)
	v_mfma_f32_16x16x32_bf16 v[124:127], v[144:147], v[184:187], v[124:127]
	v_mfma_f32_16x16x32_bf16 v[120:123], v[160:163], v[184:187], v[120:123]
	v_mfma_f32_16x16x32_bf16 v[108:111], v[144:147], v[196:199], v[108:111]
	v_mfma_f32_16x16x32_bf16 v[104:107], v[160:163], v[196:199], v[104:107]
	v_mfma_f32_16x16x32_bf16 v[92:95], v[144:147], v[204:207], v[92:95]
	v_mfma_f32_16x16x32_bf16 v[88:91], v[160:163], v[204:207], v[88:91]
	v_mfma_f32_16x16x32_bf16 v[76:79], v[144:147], v[212:215], v[76:79]
	v_mfma_f32_16x16x32_bf16 v[72:75], v[160:163], v[212:215], v[72:75]
	v_mfma_f32_16x16x32_bf16 v[124:127], v[156:159], v[188:191], v[124:127]
	v_mfma_f32_16x16x32_bf16 v[120:123], v[164:167], v[188:191], v[120:123]
	v_mfma_f32_16x16x32_bf16 v[108:111], v[156:159], v[200:203], v[108:111]
	v_mfma_f32_16x16x32_bf16 v[104:107], v[164:167], v[200:203], v[104:107]
	v_mfma_f32_16x16x32_bf16 v[92:95], v[156:159], v[208:211], v[92:95]
	v_mfma_f32_16x16x32_bf16 v[88:91], v[164:167], v[208:211], v[88:91]
	v_mfma_f32_16x16x32_bf16 v[76:79], v[156:159], v[216:219], v[76:79]
	v_mfma_f32_16x16x32_bf16 v[72:75], v[164:167], v[216:219], v[72:75]
	s_setprio 0
	s_setprio 1
	v_mfma_f32_16x16x32_bf16 v[116:119], v[168:171], v[184:187], v[116:119]
	v_mfma_f32_16x16x32_bf16 v[112:115], v[176:179], v[184:187], v[112:115]
	v_mfma_f32_16x16x32_bf16 v[100:103], v[168:171], v[196:199], v[100:103]
	v_mfma_f32_16x16x32_bf16 v[96:99], v[176:179], v[196:199], v[96:99]
	v_mfma_f32_16x16x32_bf16 v[84:87], v[168:171], v[204:207], v[84:87]
	v_mfma_f32_16x16x32_bf16 v[80:83], v[176:179], v[204:207], v[80:83]
	v_mfma_f32_16x16x32_bf16 v[68:71], v[168:171], v[212:215], v[68:71]
	v_mfma_f32_16x16x32_bf16 v[64:67], v[176:179], v[212:215], v[64:67]
	v_mfma_f32_16x16x32_bf16 v[116:119], v[172:175], v[188:191], v[116:119]
	v_mfma_f32_16x16x32_bf16 v[112:115], v[180:183], v[188:191], v[112:115]
	v_mfma_f32_16x16x32_bf16 v[100:103], v[172:175], v[200:203], v[100:103]
	v_mfma_f32_16x16x32_bf16 v[96:99], v[180:183], v[200:203], v[96:99]
	v_mfma_f32_16x16x32_bf16 v[84:87], v[172:175], v[208:211], v[84:87]
	v_mfma_f32_16x16x32_bf16 v[80:83], v[180:183], v[208:211], v[80:83]
	v_mfma_f32_16x16x32_bf16 v[68:71], v[172:175], v[216:219], v[68:71]
	v_mfma_f32_16x16x32_bf16 v[64:67], v[180:183], v[216:219], v[64:67]
	s_setprio 0
	s_barrier
	s_add_i32 s36, s73, s58
	v_lshl_add_u64 v[192:193], s[40:41], 0, v[130:131]
	s_mov_b32 m0, s36
	ds_read_b128 v[184:187], v153 offset:16384
	ds_read_b128 v[188:191], v153 offset:17408
	ds_read_b128 v[196:199], v153 offset:18432
	ds_read_b128 v[200:203], v153 offset:19456
	ds_read_b128 v[204:207], v153 offset:20480
	ds_read_b128 v[208:211], v153 offset:21504
	ds_read_b128 v[212:215], v153 offset:22528
	ds_read_b128 v[216:219], v153 offset:23552
	global_load_lds_dwordx4 v[192:193], off
	s_add_i32 m0, s36, 0x2000
	s_add_u32 s36, s40, 0xb0000
	v_lshl_add_u64 v[220:221], s[40:41], 0, v[134:135]
	s_addc_u32 s37, s41, 0
	s_add_i32 s86, s78, s58
	global_load_lds_dwordx4 v[220:221], off
	s_mov_b32 m0, s86
	s_mov_b64 s[98:99], s[42:43]
	global_load_lds_dwordx4 v130, s[36:37]
	s_add_i32 m0, s86, 0x2000
	s_nop 0
	global_load_lds_dwordx4 v134, s[36:37]
	s_waitcnt vmcnt(6)
	s_waitcnt lgkmcnt(0)
	s_barrier
	s_setprio 1
	s_waitcnt lgkmcnt(0)
	v_mfma_f32_16x16x32_bf16 v[60:63], v[144:147], v[184:187], v[60:63]
	v_mfma_f32_16x16x32_bf16 v[56:59], v[160:163], v[184:187], v[56:59]
	v_mfma_f32_16x16x32_bf16 v[44:47], v[144:147], v[196:199], v[44:47]
	v_mfma_f32_16x16x32_bf16 v[40:43], v[160:163], v[196:199], v[40:43]
	v_mfma_f32_16x16x32_bf16 v[28:31], v[144:147], v[204:207], v[28:31]
	v_mfma_f32_16x16x32_bf16 v[24:27], v[160:163], v[204:207], v[24:27]
	v_mfma_f32_16x16x32_bf16 v[12:15], v[144:147], v[212:215], v[12:15]
	v_mfma_f32_16x16x32_bf16 v[8:11], v[160:163], v[212:215], v[8:11]
	v_mfma_f32_16x16x32_bf16 v[60:63], v[156:159], v[188:191], v[60:63]
	v_mfma_f32_16x16x32_bf16 v[56:59], v[164:167], v[188:191], v[56:59]
	v_mfma_f32_16x16x32_bf16 v[44:47], v[156:159], v[200:203], v[44:47]
	v_mfma_f32_16x16x32_bf16 v[40:43], v[164:167], v[200:203], v[40:43]
	v_mfma_f32_16x16x32_bf16 v[28:31], v[156:159], v[208:211], v[28:31]
	v_mfma_f32_16x16x32_bf16 v[24:27], v[164:167], v[208:211], v[24:27]
	v_mfma_f32_16x16x32_bf16 v[12:15], v[156:159], v[216:219], v[12:15]
	v_mfma_f32_16x16x32_bf16 v[8:11], v[164:167], v[216:219], v[8:11]
	s_setprio 0
	s_setprio 1
	v_mfma_f32_16x16x32_bf16 v[52:55], v[168:171], v[184:187], v[52:55]
	v_mfma_f32_16x16x32_bf16 v[48:51], v[176:179], v[184:187], v[48:51]
	v_mfma_f32_16x16x32_bf16 v[36:39], v[168:171], v[196:199], v[36:39]
	v_mfma_f32_16x16x32_bf16 v[32:35], v[176:179], v[196:199], v[32:35]
	v_mfma_f32_16x16x32_bf16 v[20:23], v[168:171], v[204:207], v[20:23]
	v_mfma_f32_16x16x32_bf16 v[16:19], v[176:179], v[204:207], v[16:19]
	v_mfma_f32_16x16x32_bf16 v[4:7], v[168:171], v[212:215], v[4:7]
	v_mfma_f32_16x16x32_bf16 v[0:3], v[176:179], v[212:215], v[0:3]
	v_mfma_f32_16x16x32_bf16 v[52:55], v[172:175], v[188:191], v[52:55]
	v_mfma_f32_16x16x32_bf16 v[48:51], v[180:183], v[188:191], v[48:51]
	v_mfma_f32_16x16x32_bf16 v[36:39], v[172:175], v[200:203], v[36:39]
	v_mfma_f32_16x16x32_bf16 v[32:35], v[180:183], v[200:203], v[32:35]
	v_mfma_f32_16x16x32_bf16 v[20:23], v[172:175], v[208:211], v[20:23]
	v_mfma_f32_16x16x32_bf16 v[16:19], v[180:183], v[208:211], v[16:19]
	v_mfma_f32_16x16x32_bf16 v[4:7], v[172:175], v[216:219], v[4:7]
	v_mfma_f32_16x16x32_bf16 v[0:3], v[180:183], v[216:219], v[0:3]
	s_setprio 0
	s_barrier
	s_add_i32 s86, 0, 0x18000
	v_add_u32_e32 v155, s86, v149
	s_add_i32 s87, 0, 0x1c000
	ds_read_b128 v[144:147], v155
	ds_read_b128 v[156:159], v155 offset:1024
	ds_read_b128 v[160:163], v155 offset:2048
	ds_read_b128 v[164:167], v155 offset:3072
	v_add_u32_e32 v155, s87, v149
	ds_read_b128 v[168:171], v155
	ds_read_b128 v[172:175], v155 offset:1024
	ds_read_b128 v[176:179], v155 offset:2048
	ds_read_b128 v[180:183], v155 offset:3072
	s_add_u32 s36, s42, 0xb0000
	s_addc_u32 s37, s43, 0
	ds_read_b128 v[184:187], v153 offset:32768
	ds_read_b128 v[188:191], v153 offset:33792
	ds_read_b128 v[196:199], v153 offset:34816
	ds_read_b128 v[200:203], v153 offset:35840
	ds_read_b128 v[204:207], v153 offset:36864
	ds_read_b128 v[208:211], v153 offset:37888
	ds_read_b128 v[212:215], v153 offset:38912
	ds_read_b128 v[216:219], v153 offset:39936
	s_mov_b32 m0, s59
	s_nop 0
	global_load_lds_dwordx4 v128, s[98:99]
	s_mov_b32 m0, s60
	s_nop 0
	global_load_lds_dwordx4 v132, s[98:99]
	s_mov_b32 m0, s61
	s_nop 0
	global_load_lds_dwordx4 v128, s[36:37]
	s_mov_b32 m0, s62
	s_nop 0
	global_load_lds_dwordx4 v132, s[36:37]
	s_waitcnt vmcnt(8)
	s_waitcnt lgkmcnt(0)
	s_barrier
	s_setprio 1
	s_waitcnt lgkmcnt(0)
	v_mfma_f32_16x16x32_bf16 v[124:127], v[144:147], v[184:187], v[124:127]
	v_mfma_f32_16x16x32_bf16 v[120:123], v[160:163], v[184:187], v[120:123]
	v_mfma_f32_16x16x32_bf16 v[108:111], v[144:147], v[196:199], v[108:111]
	v_mfma_f32_16x16x32_bf16 v[104:107], v[160:163], v[196:199], v[104:107]
	v_mfma_f32_16x16x32_bf16 v[92:95], v[144:147], v[204:207], v[92:95]
	v_mfma_f32_16x16x32_bf16 v[88:91], v[160:163], v[204:207], v[88:91]
	v_mfma_f32_16x16x32_bf16 v[76:79], v[144:147], v[212:215], v[76:79]
	v_mfma_f32_16x16x32_bf16 v[72:75], v[160:163], v[212:215], v[72:75]
	v_mfma_f32_16x16x32_bf16 v[124:127], v[156:159], v[188:191], v[124:127]
	v_mfma_f32_16x16x32_bf16 v[120:123], v[164:167], v[188:191], v[120:123]
	v_mfma_f32_16x16x32_bf16 v[108:111], v[156:159], v[200:203], v[108:111]
	v_mfma_f32_16x16x32_bf16 v[104:107], v[164:167], v[200:203], v[104:107]
	v_mfma_f32_16x16x32_bf16 v[92:95], v[156:159], v[208:211], v[92:95]
	v_mfma_f32_16x16x32_bf16 v[88:91], v[164:167], v[208:211], v[88:91]
	v_mfma_f32_16x16x32_bf16 v[76:79], v[156:159], v[216:219], v[76:79]
	v_mfma_f32_16x16x32_bf16 v[72:75], v[164:167], v[216:219], v[72:75]
	s_setprio 0
	s_setprio 1
	v_mfma_f32_16x16x32_bf16 v[116:119], v[168:171], v[184:187], v[116:119]
	v_mfma_f32_16x16x32_bf16 v[112:115], v[176:179], v[184:187], v[112:115]
	v_mfma_f32_16x16x32_bf16 v[100:103], v[168:171], v[196:199], v[100:103]
	v_mfma_f32_16x16x32_bf16 v[96:99], v[176:179], v[196:199], v[96:99]
	v_mfma_f32_16x16x32_bf16 v[84:87], v[168:171], v[204:207], v[84:87]
	v_mfma_f32_16x16x32_bf16 v[80:83], v[176:179], v[204:207], v[80:83]
	v_mfma_f32_16x16x32_bf16 v[68:71], v[168:171], v[212:215], v[68:71]
	v_mfma_f32_16x16x32_bf16 v[64:67], v[176:179], v[212:215], v[64:67]
	v_mfma_f32_16x16x32_bf16 v[116:119], v[172:175], v[188:191], v[116:119]
	v_mfma_f32_16x16x32_bf16 v[112:115], v[180:183], v[188:191], v[112:115]
	v_mfma_f32_16x16x32_bf16 v[100:103], v[172:175], v[200:203], v[100:103]
	v_mfma_f32_16x16x32_bf16 v[96:99], v[180:183], v[200:203], v[96:99]
	v_mfma_f32_16x16x32_bf16 v[84:87], v[172:175], v[208:211], v[84:87]
	v_mfma_f32_16x16x32_bf16 v[80:83], v[180:183], v[208:211], v[80:83]
	v_mfma_f32_16x16x32_bf16 v[68:71], v[172:175], v[216:219], v[68:71]
	v_mfma_f32_16x16x32_bf16 v[64:67], v[180:183], v[216:219], v[64:67]
	s_setprio 0
	s_barrier
	s_add_i32 s36, s86, s58
	v_lshl_add_u64 v[192:193], v[192:193], 0, s[28:29]
	s_mov_b32 m0, s36
	ds_read_b128 v[184:187], v153 offset:49152
	ds_read_b128 v[188:191], v153 offset:50176
	ds_read_b128 v[196:199], v153 offset:51200
	ds_read_b128 v[200:203], v153 offset:52224
	ds_read_b128 v[204:207], v153 offset:53248
	ds_read_b128 v[208:211], v153 offset:54272
	ds_read_b128 v[212:215], v153 offset:55296
	ds_read_b128 v[216:219], v153 offset:56320
	global_load_lds_dwordx4 v[192:193], off
	s_add_i32 m0, s36, 0x2000
	s_add_u32 s36, s40, 0xb0080
	v_lshl_add_u64 v[192:193], v[220:221], 0, s[28:29]
	s_addc_u32 s37, s41, 0
	s_add_i32 s40, s87, s58
	global_load_lds_dwordx4 v[192:193], off
	s_mov_b32 m0, s40
	s_nop 0
	global_load_lds_dwordx4 v130, s[36:37]
	s_add_i32 m0, s40, 0x2000
	s_nop 0
	global_load_lds_dwordx4 v134, s[36:37]
	s_waitcnt vmcnt(6)
	s_waitcnt lgkmcnt(0)
	s_barrier
	s_setprio 1
	s_waitcnt lgkmcnt(0)
	v_mfma_f32_16x16x32_bf16 v[60:63], v[144:147], v[184:187], v[60:63]
	v_mfma_f32_16x16x32_bf16 v[56:59], v[160:163], v[184:187], v[56:59]
	v_mfma_f32_16x16x32_bf16 v[44:47], v[144:147], v[196:199], v[44:47]
	v_mfma_f32_16x16x32_bf16 v[40:43], v[160:163], v[196:199], v[40:43]
	v_mfma_f32_16x16x32_bf16 v[28:31], v[144:147], v[204:207], v[28:31]
	v_mfma_f32_16x16x32_bf16 v[24:27], v[160:163], v[204:207], v[24:27]
	v_mfma_f32_16x16x32_bf16 v[12:15], v[144:147], v[212:215], v[12:15]
	v_mfma_f32_16x16x32_bf16 v[8:11], v[160:163], v[212:215], v[8:11]
	v_mfma_f32_16x16x32_bf16 v[60:63], v[156:159], v[188:191], v[60:63]
	v_mfma_f32_16x16x32_bf16 v[56:59], v[164:167], v[188:191], v[56:59]
	v_mfma_f32_16x16x32_bf16 v[44:47], v[156:159], v[200:203], v[44:47]
	v_mfma_f32_16x16x32_bf16 v[40:43], v[164:167], v[200:203], v[40:43]
	v_mfma_f32_16x16x32_bf16 v[28:31], v[156:159], v[208:211], v[28:31]
	v_mfma_f32_16x16x32_bf16 v[24:27], v[164:167], v[208:211], v[24:27]
	v_mfma_f32_16x16x32_bf16 v[12:15], v[156:159], v[216:219], v[12:15]
	v_mfma_f32_16x16x32_bf16 v[8:11], v[164:167], v[216:219], v[8:11]
	s_setprio 0
	s_setprio 1
	v_mfma_f32_16x16x32_bf16 v[52:55], v[168:171], v[184:187], v[52:55]
	v_mfma_f32_16x16x32_bf16 v[48:51], v[176:179], v[184:187], v[48:51]
	v_mfma_f32_16x16x32_bf16 v[36:39], v[168:171], v[196:199], v[36:39]
	v_mfma_f32_16x16x32_bf16 v[32:35], v[176:179], v[196:199], v[32:35]
	v_mfma_f32_16x16x32_bf16 v[20:23], v[168:171], v[204:207], v[20:23]
	v_mfma_f32_16x16x32_bf16 v[16:19], v[176:179], v[204:207], v[16:19]
	v_mfma_f32_16x16x32_bf16 v[4:7], v[168:171], v[212:215], v[4:7]
	v_mfma_f32_16x16x32_bf16 v[0:3], v[176:179], v[212:215], v[0:3]
	v_mfma_f32_16x16x32_bf16 v[52:55], v[172:175], v[188:191], v[52:55]
	v_mfma_f32_16x16x32_bf16 v[48:51], v[180:183], v[188:191], v[48:51]
	v_mfma_f32_16x16x32_bf16 v[36:39], v[172:175], v[200:203], v[36:39]
	v_mfma_f32_16x16x32_bf16 v[32:35], v[180:183], v[200:203], v[32:35]
	v_mfma_f32_16x16x32_bf16 v[20:23], v[172:175], v[208:211], v[20:23]
	v_mfma_f32_16x16x32_bf16 v[16:19], v[180:183], v[208:211], v[16:19]
	v_mfma_f32_16x16x32_bf16 v[4:7], v[172:175], v[216:219], v[4:7]
	v_mfma_f32_16x16x32_bf16 v[0:3], v[180:183], v[216:219], v[0:3]
	s_setprio 0
	s_barrier
	s_add_i32 m0, s70, 0xffffff80
	s_nop 0
	global_load_lds_dwordx4 v128, s[98:99] offset:128
	s_add_i32 m0, s71, 0xffffff80
	s_nop 0
	global_load_lds_dwordx4 v132, s[98:99] offset:128
	s_add_i32 s85, s85, 2
	s_add_u32 s83, s83, 0x100
	s_addc_u32 s84, s84, 0
	s_cmp_gt_u32 s85, 41
	s_mov_b64 s[36:37], s[38:39]
	s_cbranch_scc0 .LBB0_1791
	s_and_b64 vcc, exec, s[30:31]
	s_cbranch_vccz .LBB0_1794
	s_barrier

.LBB0_2142:
	ds_read_b128 v[144:147], v151
	ds_read_b128 v[156:159], v151 offset:1024
	ds_read_b128 v[160:163], v151 offset:2048
	ds_read_b128 v[164:167], v151 offset:3072
	ds_read_b128 v[168:171], v152
	ds_read_b128 v[172:175], v152 offset:1024
	ds_read_b128 v[176:179], v152 offset:2048
	ds_read_b128 v[180:183], v152 offset:3072
	s_add_u32 s38, s36, 0x100
	s_addc_u32 s39, s37, 0
	s_cmp_eq_u32 s83, 40
	s_cselect_b32 s43, s1, s39
	s_cselect_b32 s42, s0, s38
	s_cselect_b32 s41, s35, s82
	s_cselect_b32 s40, s34, s81
	v_lshl_add_u64 v[192:193], s[36:37], 0, v[136:137]
	s_add_i32 m0, s57, 0xc000
	ds_read_b128 v[184:187], v153
	ds_read_b128 v[188:191], v153 offset:1024
	ds_read_b128 v[196:199], v153 offset:2048
	ds_read_b128 v[200:203], v153 offset:3072
	ds_read_b128 v[204:207], v153 offset:4096
	ds_read_b128 v[208:211], v153 offset:5120
	ds_read_b128 v[212:215], v153 offset:6144
	ds_read_b128 v[216:219], v153 offset:7168
	global_load_lds_dwordx4 v[192:193], off
	v_lshl_add_u64 v[192:193], s[36:37], 0, v[138:139]
	s_add_i32 m0, s57, 0xe000
	s_nop 0
	global_load_lds_dwordx4 v[192:193], off
	s_waitcnt vmcnt(8)
	s_waitcnt lgkmcnt(0)
	s_barrier
	s_setprio 1
	s_waitcnt lgkmcnt(0)
	v_mfma_f32_16x16x32_bf16 v[124:127], v[144:147], v[184:187], v[124:127]
	v_mfma_f32_16x16x32_bf16 v[120:123], v[160:163], v[184:187], v[120:123]
	v_mfma_f32_16x16x32_bf16 v[108:111], v[144:147], v[196:199], v[108:111]
	v_mfma_f32_16x16x32_bf16 v[104:107], v[160:163], v[196:199], v[104:107]
	v_mfma_f32_16x16x32_bf16 v[92:95], v[144:147], v[204:207], v[92:95]
	v_mfma_f32_16x16x32_bf16 v[88:91], v[160:163], v[204:207], v[88:91]
	v_mfma_f32_16x16x32_bf16 v[76:79], v[144:147], v[212:215], v[76:79]
	v_mfma_f32_16x16x32_bf16 v[72:75], v[160:163], v[212:215], v[72:75]
	v_mfma_f32_16x16x32_bf16 v[124:127], v[156:159], v[188:191], v[124:127]
	v_mfma_f32_16x16x32_bf16 v[120:123], v[164:167], v[188:191], v[120:123]
	v_mfma_f32_16x16x32_bf16 v[108:111], v[156:159], v[200:203], v[108:111]
	v_mfma_f32_16x16x32_bf16 v[104:107], v[164:167], v[200:203], v[104:107]
	v_mfma_f32_16x16x32_bf16 v[92:95], v[156:159], v[208:211], v[92:95]
	v_mfma_f32_16x16x32_bf16 v[88:91], v[164:167], v[208:211], v[88:91]
	v_mfma_f32_16x16x32_bf16 v[76:79], v[156:159], v[216:219], v[76:79]
	v_mfma_f32_16x16x32_bf16 v[72:75], v[164:167], v[216:219], v[72:75]
	s_setprio 0
	s_setprio 1
	v_mfma_f32_16x16x32_bf16 v[116:119], v[168:171], v[184:187], v[116:119]
	v_mfma_f32_16x16x32_bf16 v[112:115], v[176:179], v[184:187], v[112:115]
	v_mfma_f32_16x16x32_bf16 v[100:103], v[168:171], v[196:199], v[100:103]
	v_mfma_f32_16x16x32_bf16 v[96:99], v[176:179], v[196:199], v[96:99]
	v_mfma_f32_16x16x32_bf16 v[84:87], v[168:171], v[204:207], v[84:87]
	v_mfma_f32_16x16x32_bf16 v[80:83], v[176:179], v[204:207], v[80:83]
	v_mfma_f32_16x16x32_bf16 v[68:71], v[168:171], v[212:215], v[68:71]
	v_mfma_f32_16x16x32_bf16 v[64:67], v[176:179], v[212:215], v[64:67]
	v_mfma_f32_16x16x32_bf16 v[116:119], v[172:175], v[188:191], v[116:119]
	v_mfma_f32_16x16x32_bf16 v[112:115], v[180:183], v[188:191], v[112:115]
	v_mfma_f32_16x16x32_bf16 v[100:103], v[172:175], v[200:203], v[100:103]
	v_mfma_f32_16x16x32_bf16 v[96:99], v[180:183], v[200:203], v[96:99]
	v_mfma_f32_16x16x32_bf16 v[84:87], v[172:175], v[208:211], v[84:87]
	v_mfma_f32_16x16x32_bf16 v[80:83], v[180:183], v[208:211], v[80:83]
	v_mfma_f32_16x16x32_bf16 v[68:71], v[172:175], v[216:219], v[68:71]
	v_mfma_f32_16x16x32_bf16 v[64:67], v[180:183], v[216:219], v[64:67]
	s_setprio 0
	s_barrier
	s_add_i32 s36, s71, s56
	v_lshl_add_u64 v[192:193], s[40:41], 0, v[130:131]
	s_mov_b32 m0, s36
	ds_read_b128 v[184:187], v153 offset:16384
	ds_read_b128 v[188:191], v153 offset:17408
	ds_read_b128 v[196:199], v153 offset:18432
	ds_read_b128 v[200:203], v153 offset:19456
	ds_read_b128 v[204:207], v153 offset:20480
	ds_read_b128 v[208:211], v153 offset:21504
	ds_read_b128 v[212:215], v153 offset:22528
	ds_read_b128 v[216:219], v153 offset:23552
	global_load_lds_dwordx4 v[192:193], off
	s_add_i32 m0, s36, 0x2000
	s_add_u32 s36, s40, 0xb0000
	v_lshl_add_u64 v[220:221], s[40:41], 0, v[134:135]
	s_addc_u32 s37, s41, 0
	s_add_i32 s84, s72, s56
	global_load_lds_dwordx4 v[220:221], off
	s_mov_b32 m0, s84
	s_mov_b64 s[98:99], s[42:43]
	global_load_lds_dwordx4 v130, s[36:37]
	s_add_i32 m0, s84, 0x2000
	s_nop 0
	global_load_lds_dwordx4 v134, s[36:37]
	s_waitcnt vmcnt(6)
	s_waitcnt lgkmcnt(0)
	s_barrier
	s_setprio 1
	s_waitcnt lgkmcnt(0)
	v_mfma_f32_16x16x32_bf16 v[60:63], v[144:147], v[184:187], v[60:63]
	v_mfma_f32_16x16x32_bf16 v[56:59], v[160:163], v[184:187], v[56:59]
	v_mfma_f32_16x16x32_bf16 v[44:47], v[144:147], v[196:199], v[44:47]
	v_mfma_f32_16x16x32_bf16 v[40:43], v[160:163], v[196:199], v[40:43]
	v_mfma_f32_16x16x32_bf16 v[28:31], v[144:147], v[204:207], v[28:31]
	v_mfma_f32_16x16x32_bf16 v[24:27], v[160:163], v[204:207], v[24:27]
	v_mfma_f32_16x16x32_bf16 v[12:15], v[144:147], v[212:215], v[12:15]
	v_mfma_f32_16x16x32_bf16 v[8:11], v[160:163], v[212:215], v[8:11]
	v_mfma_f32_16x16x32_bf16 v[60:63], v[156:159], v[188:191], v[60:63]
	v_mfma_f32_16x16x32_bf16 v[56:59], v[164:167], v[188:191], v[56:59]
	v_mfma_f32_16x16x32_bf16 v[44:47], v[156:159], v[200:203], v[44:47]
	v_mfma_f32_16x16x32_bf16 v[40:43], v[164:167], v[200:203], v[40:43]
	v_mfma_f32_16x16x32_bf16 v[28:31], v[156:159], v[208:211], v[28:31]
	v_mfma_f32_16x16x32_bf16 v[24:27], v[164:167], v[208:211], v[24:27]
	v_mfma_f32_16x16x32_bf16 v[12:15], v[156:159], v[216:219], v[12:15]
	v_mfma_f32_16x16x32_bf16 v[8:11], v[164:167], v[216:219], v[8:11]
	s_setprio 0
	s_setprio 1
	v_mfma_f32_16x16x32_bf16 v[52:55], v[168:171], v[184:187], v[52:55]
	v_mfma_f32_16x16x32_bf16 v[48:51], v[176:179], v[184:187], v[48:51]
	v_mfma_f32_16x16x32_bf16 v[36:39], v[168:171], v[196:199], v[36:39]
	v_mfma_f32_16x16x32_bf16 v[32:35], v[176:179], v[196:199], v[32:35]
	v_mfma_f32_16x16x32_bf16 v[20:23], v[168:171], v[204:207], v[20:23]
	v_mfma_f32_16x16x32_bf16 v[16:19], v[176:179], v[204:207], v[16:19]
	v_mfma_f32_16x16x32_bf16 v[4:7], v[168:171], v[212:215], v[4:7]
	v_mfma_f32_16x16x32_bf16 v[0:3], v[176:179], v[212:215], v[0:3]
	v_mfma_f32_16x16x32_bf16 v[52:55], v[172:175], v[188:191], v[52:55]
	v_mfma_f32_16x16x32_bf16 v[48:51], v[180:183], v[188:191], v[48:51]
	v_mfma_f32_16x16x32_bf16 v[36:39], v[172:175], v[200:203], v[36:39]
	v_mfma_f32_16x16x32_bf16 v[32:35], v[180:183], v[200:203], v[32:35]
	v_mfma_f32_16x16x32_bf16 v[20:23], v[172:175], v[208:211], v[20:23]
	v_mfma_f32_16x16x32_bf16 v[16:19], v[180:183], v[208:211], v[16:19]
	v_mfma_f32_16x16x32_bf16 v[4:7], v[172:175], v[216:219], v[4:7]
	v_mfma_f32_16x16x32_bf16 v[0:3], v[180:183], v[216:219], v[0:3]
	s_setprio 0
	s_barrier
	s_add_i32 s84, 0, 0x18000
	v_add_u32_e32 v155, s84, v149
	s_add_i32 s85, 0, 0x1c000
	ds_read_b128 v[144:147], v155
	ds_read_b128 v[156:159], v155 offset:1024
	ds_read_b128 v[160:163], v155 offset:2048
	ds_read_b128 v[164:167], v155 offset:3072
	v_add_u32_e32 v155, s85, v149
	ds_read_b128 v[168:171], v155
	ds_read_b128 v[172:175], v155 offset:1024
	ds_read_b128 v[176:179], v155 offset:2048
	ds_read_b128 v[180:183], v155 offset:3072
	s_add_u32 s36, s42, 0xb0000
	s_addc_u32 s37, s43, 0
	ds_read_b128 v[184:187], v153 offset:32768
	ds_read_b128 v[188:191], v153 offset:33792
	ds_read_b128 v[196:199], v153 offset:34816
	ds_read_b128 v[200:203], v153 offset:35840
	ds_read_b128 v[204:207], v153 offset:36864
	ds_read_b128 v[208:211], v153 offset:37888
	ds_read_b128 v[212:215], v153 offset:38912
	ds_read_b128 v[216:219], v153 offset:39936
	s_mov_b32 m0, s57
	s_nop 0
	global_load_lds_dwordx4 v128, s[98:99]
	s_mov_b32 m0, s58
	s_nop 0
	global_load_lds_dwordx4 v132, s[98:99]
	s_mov_b32 m0, s59
	s_nop 0
	global_load_lds_dwordx4 v128, s[36:37]
	s_mov_b32 m0, s60
	s_nop 0
	global_load_lds_dwordx4 v132, s[36:37]
	s_waitcnt vmcnt(8)
	s_waitcnt lgkmcnt(0)
	s_barrier
	s_setprio 1
	s_waitcnt lgkmcnt(0)
	v_mfma_f32_16x16x32_bf16 v[124:127], v[144:147], v[184:187], v[124:127]
	v_mfma_f32_16x16x32_bf16 v[120:123], v[160:163], v[184:187], v[120:123]
	v_mfma_f32_16x16x32_bf16 v[108:111], v[144:147], v[196:199], v[108:111]
	v_mfma_f32_16x16x32_bf16 v[104:107], v[160:163], v[196:199], v[104:107]
	v_mfma_f32_16x16x32_bf16 v[92:95], v[144:147], v[204:207], v[92:95]
	v_mfma_f32_16x16x32_bf16 v[88:91], v[160:163], v[204:207], v[88:91]
	v_mfma_f32_16x16x32_bf16 v[76:79], v[144:147], v[212:215], v[76:79]
	v_mfma_f32_16x16x32_bf16 v[72:75], v[160:163], v[212:215], v[72:75]
	v_mfma_f32_16x16x32_bf16 v[124:127], v[156:159], v[188:191], v[124:127]
	v_mfma_f32_16x16x32_bf16 v[120:123], v[164:167], v[188:191], v[120:123]
	v_mfma_f32_16x16x32_bf16 v[108:111], v[156:159], v[200:203], v[108:111]
	v_mfma_f32_16x16x32_bf16 v[104:107], v[164:167], v[200:203], v[104:107]
	v_mfma_f32_16x16x32_bf16 v[92:95], v[156:159], v[208:211], v[92:95]
	v_mfma_f32_16x16x32_bf16 v[88:91], v[164:167], v[208:211], v[88:91]
	v_mfma_f32_16x16x32_bf16 v[76:79], v[156:159], v[216:219], v[76:79]
	v_mfma_f32_16x16x32_bf16 v[72:75], v[164:167], v[216:219], v[72:75]
	s_setprio 0
	s_setprio 1
	v_mfma_f32_16x16x32_bf16 v[116:119], v[168:171], v[184:187], v[116:119]
	v_mfma_f32_16x16x32_bf16 v[112:115], v[176:179], v[184:187], v[112:115]
	v_mfma_f32_16x16x32_bf16 v[100:103], v[168:171], v[196:199], v[100:103]
	v_mfma_f32_16x16x32_bf16 v[96:99], v[176:179], v[196:199], v[96:99]
	v_mfma_f32_16x16x32_bf16 v[84:87], v[168:171], v[204:207], v[84:87]
	v_mfma_f32_16x16x32_bf16 v[80:83], v[176:179], v[204:207], v[80:83]
	v_mfma_f32_16x16x32_bf16 v[68:71], v[168:171], v[212:215], v[68:71]
	v_mfma_f32_16x16x32_bf16 v[64:67], v[176:179], v[212:215], v[64:67]
	v_mfma_f32_16x16x32_bf16 v[116:119], v[172:175], v[188:191], v[116:119]
	v_mfma_f32_16x16x32_bf16 v[112:115], v[180:183], v[188:191], v[112:115]
	v_mfma_f32_16x16x32_bf16 v[100:103], v[172:175], v[200:203], v[100:103]
	v_mfma_f32_16x16x32_bf16 v[96:99], v[180:183], v[200:203], v[96:99]
	v_mfma_f32_16x16x32_bf16 v[84:87], v[172:175], v[208:211], v[84:87]
	v_mfma_f32_16x16x32_bf16 v[80:83], v[180:183], v[208:211], v[80:83]
	v_mfma_f32_16x16x32_bf16 v[68:71], v[172:175], v[216:219], v[68:71]
	v_mfma_f32_16x16x32_bf16 v[64:67], v[180:183], v[216:219], v[64:67]
	s_setprio 0
	s_barrier
	s_add_i32 s36, s84, s56
	v_lshl_add_u64 v[192:193], v[192:193], 0, s[28:29]
	s_mov_b32 m0, s36
	ds_read_b128 v[184:187], v153 offset:49152
	ds_read_b128 v[188:191], v153 offset:50176
	ds_read_b128 v[196:199], v153 offset:51200
	ds_read_b128 v[200:203], v153 offset:52224
	ds_read_b128 v[204:207], v153 offset:53248
	ds_read_b128 v[208:211], v153 offset:54272
	ds_read_b128 v[212:215], v153 offset:55296
	ds_read_b128 v[216:219], v153 offset:56320
	global_load_lds_dwordx4 v[192:193], off
	s_add_i32 m0, s36, 0x2000
	s_add_u32 s36, s40, 0xb0080
	v_lshl_add_u64 v[192:193], v[220:221], 0, s[28:29]
	s_addc_u32 s37, s41, 0
	s_add_i32 s40, s85, s56
	global_load_lds_dwordx4 v[192:193], off
	s_mov_b32 m0, s40
	s_nop 0
	global_load_lds_dwordx4 v130, s[36:37]
	s_add_i32 m0, s40, 0x2000
	s_nop 0
	global_load_lds_dwordx4 v134, s[36:37]
	s_waitcnt vmcnt(6)
	s_waitcnt lgkmcnt(0)
	s_barrier
	s_setprio 1
	s_waitcnt lgkmcnt(0)
	v_mfma_f32_16x16x32_bf16 v[60:63], v[144:147], v[184:187], v[60:63]
	v_mfma_f32_16x16x32_bf16 v[56:59], v[160:163], v[184:187], v[56:59]
	v_mfma_f32_16x16x32_bf16 v[44:47], v[144:147], v[196:199], v[44:47]
	v_mfma_f32_16x16x32_bf16 v[40:43], v[160:163], v[196:199], v[40:43]
	v_mfma_f32_16x16x32_bf16 v[28:31], v[144:147], v[204:207], v[28:31]
	v_mfma_f32_16x16x32_bf16 v[24:27], v[160:163], v[204:207], v[24:27]
	v_mfma_f32_16x16x32_bf16 v[12:15], v[144:147], v[212:215], v[12:15]
	v_mfma_f32_16x16x32_bf16 v[8:11], v[160:163], v[212:215], v[8:11]
	v_mfma_f32_16x16x32_bf16 v[60:63], v[156:159], v[188:191], v[60:63]
	v_mfma_f32_16x16x32_bf16 v[56:59], v[164:167], v[188:191], v[56:59]
	v_mfma_f32_16x16x32_bf16 v[44:47], v[156:159], v[200:203], v[44:47]
	v_mfma_f32_16x16x32_bf16 v[40:43], v[164:167], v[200:203], v[40:43]
	v_mfma_f32_16x16x32_bf16 v[28:31], v[156:159], v[208:211], v[28:31]
	v_mfma_f32_16x16x32_bf16 v[24:27], v[164:167], v[208:211], v[24:27]
	v_mfma_f32_16x16x32_bf16 v[12:15], v[156:159], v[216:219], v[12:15]
	v_mfma_f32_16x16x32_bf16 v[8:11], v[164:167], v[216:219], v[8:11]
	s_setprio 0
	s_setprio 1
	v_mfma_f32_16x16x32_bf16 v[52:55], v[168:171], v[184:187], v[52:55]
	v_mfma_f32_16x16x32_bf16 v[48:51], v[176:179], v[184:187], v[48:51]
	v_mfma_f32_16x16x32_bf16 v[36:39], v[168:171], v[196:199], v[36:39]
	v_mfma_f32_16x16x32_bf16 v[32:35], v[176:179], v[196:199], v[32:35]
	v_mfma_f32_16x16x32_bf16 v[20:23], v[168:171], v[204:207], v[20:23]
	v_mfma_f32_16x16x32_bf16 v[16:19], v[176:179], v[204:207], v[16:19]
	v_mfma_f32_16x16x32_bf16 v[4:7], v[168:171], v[212:215], v[4:7]
	v_mfma_f32_16x16x32_bf16 v[0:3], v[176:179], v[212:215], v[0:3]
	v_mfma_f32_16x16x32_bf16 v[52:55], v[172:175], v[188:191], v[52:55]
	v_mfma_f32_16x16x32_bf16 v[48:51], v[180:183], v[188:191], v[48:51]
	v_mfma_f32_16x16x32_bf16 v[36:39], v[172:175], v[200:203], v[36:39]
	v_mfma_f32_16x16x32_bf16 v[32:35], v[180:183], v[200:203], v[32:35]
	v_mfma_f32_16x16x32_bf16 v[20:23], v[172:175], v[208:211], v[20:23]
	v_mfma_f32_16x16x32_bf16 v[16:19], v[180:183], v[208:211], v[16:19]
	v_mfma_f32_16x16x32_bf16 v[4:7], v[172:175], v[216:219], v[4:7]
	v_mfma_f32_16x16x32_bf16 v[0:3], v[180:183], v[216:219], v[0:3]
	s_setprio 0
	s_barrier
	s_add_i32 m0, s62, 0xffffff80
	s_nop 0
	global_load_lds_dwordx4 v128, s[98:99] offset:128
	s_add_i32 m0, s63, 0xffffff80
	s_nop 0
	global_load_lds_dwordx4 v132, s[98:99] offset:128
	s_add_i32 s83, s83, 2
	s_add_u32 s81, s81, 0x100
	s_addc_u32 s82, s82, 0
	s_cmp_gt_u32 s83, 41
	s_mov_b64 s[36:37], s[38:39]
	s_cbranch_scc0 .LBB0_2142
	s_and_b64 vcc, exec, s[30:31]
	s_cbranch_vccz .LBB0_2145
	s_barrier

.LBB0_2236:
	ds_read_b128 v[152:155], v157
	ds_read_b128 v[162:165], v157 offset:1024
	ds_read_b128 v[166:169], v157 offset:2048
	ds_read_b128 v[170:173], v157 offset:3072
	ds_read_b128 v[174:177], v158
	ds_read_b128 v[178:181], v158 offset:1024
	ds_read_b128 v[182:185], v158 offset:2048
	ds_read_b128 v[186:189], v158 offset:3072
	s_add_u32 s42, s40, 0xfffc0080
	s_addc_u32 s43, s41, -1
	s_cmp_eq_u32 s88, 12
	s_cselect_b32 s45, s1, s43
	s_cselect_b32 s44, s15, s42
	s_cselect_b32 s43, s16, s87
	s_cselect_b32 s42, s31, s35
	s_add_i32 m0, s59, 0xc000
	ds_read_b128 v[190:193], v159
	ds_read_b128 v[196:199], v159 offset:1024
	ds_read_b128 v[200:203], v159 offset:2048
	ds_read_b128 v[204:207], v159 offset:3072
	ds_read_b128 v[208:211], v159 offset:4096
	ds_read_b128 v[212:215], v159 offset:5120
	ds_read_b128 v[216:219], v159 offset:6144
	ds_read_b128 v[220:223], v159 offset:7168
	global_load_lds_dwordx4 v144, s[40:41]
	s_add_i32 m0, s59, 0xe000
	s_nop 0
	global_load_lds_dwordx4 v146, s[40:41]
	s_waitcnt vmcnt(8)
	s_waitcnt lgkmcnt(0)
	s_barrier
	s_setprio 1
	s_waitcnt lgkmcnt(0)
	v_mfma_f32_16x16x32_bf16 v[124:127], v[152:155], v[190:193], v[124:127]
	v_mfma_f32_16x16x32_bf16 v[120:123], v[166:169], v[190:193], v[120:123]
	v_mfma_f32_16x16x32_bf16 v[108:111], v[152:155], v[200:203], v[108:111]
	v_mfma_f32_16x16x32_bf16 v[104:107], v[166:169], v[200:203], v[104:107]
	v_mfma_f32_16x16x32_bf16 v[92:95], v[152:155], v[208:211], v[92:95]
	v_mfma_f32_16x16x32_bf16 v[88:91], v[166:169], v[208:211], v[88:91]
	v_mfma_f32_16x16x32_bf16 v[76:79], v[152:155], v[216:219], v[76:79]
	v_mfma_f32_16x16x32_bf16 v[72:75], v[166:169], v[216:219], v[72:75]
	v_mfma_f32_16x16x32_bf16 v[124:127], v[162:165], v[196:199], v[124:127]
	v_mfma_f32_16x16x32_bf16 v[120:123], v[170:173], v[196:199], v[120:123]
	v_mfma_f32_16x16x32_bf16 v[108:111], v[162:165], v[204:207], v[108:111]
	v_mfma_f32_16x16x32_bf16 v[104:107], v[170:173], v[204:207], v[104:107]
	v_mfma_f32_16x16x32_bf16 v[92:95], v[162:165], v[212:215], v[92:95]
	v_mfma_f32_16x16x32_bf16 v[88:91], v[170:173], v[212:215], v[88:91]
	v_mfma_f32_16x16x32_bf16 v[76:79], v[162:165], v[220:223], v[76:79]
	v_mfma_f32_16x16x32_bf16 v[72:75], v[170:173], v[220:223], v[72:75]
	s_setprio 0
	s_setprio 1
	v_mfma_f32_16x16x32_bf16 v[116:119], v[174:177], v[190:193], v[116:119]
	v_mfma_f32_16x16x32_bf16 v[112:115], v[182:185], v[190:193], v[112:115]
	v_mfma_f32_16x16x32_bf16 v[100:103], v[174:177], v[200:203], v[100:103]
	v_mfma_f32_16x16x32_bf16 v[96:99], v[182:185], v[200:203], v[96:99]
	v_mfma_f32_16x16x32_bf16 v[84:87], v[174:177], v[208:211], v[84:87]
	v_mfma_f32_16x16x32_bf16 v[80:83], v[182:185], v[208:211], v[80:83]
	v_mfma_f32_16x16x32_bf16 v[68:71], v[174:177], v[216:219], v[68:71]
	v_mfma_f32_16x16x32_bf16 v[64:67], v[182:185], v[216:219], v[64:67]
	v_mfma_f32_16x16x32_bf16 v[116:119], v[178:181], v[196:199], v[116:119]
	v_mfma_f32_16x16x32_bf16 v[112:115], v[186:189], v[196:199], v[112:115]
	v_mfma_f32_16x16x32_bf16 v[100:103], v[178:181], v[204:207], v[100:103]
	v_mfma_f32_16x16x32_bf16 v[96:99], v[186:189], v[204:207], v[96:99]
	v_mfma_f32_16x16x32_bf16 v[84:87], v[178:181], v[212:215], v[84:87]
	v_mfma_f32_16x16x32_bf16 v[80:83], v[186:189], v[212:215], v[80:83]
	v_mfma_f32_16x16x32_bf16 v[68:71], v[178:181], v[220:223], v[68:71]
	v_mfma_f32_16x16x32_bf16 v[64:67], v[186:189], v[220:223], v[64:67]
	s_setprio 0
	s_barrier
	s_add_i32 s89, s78, s58
	s_mov_b32 m0, s89
	ds_read_b128 v[190:193], v159 offset:16384
	ds_read_b128 v[196:199], v159 offset:17408
	ds_read_b128 v[200:203], v159 offset:18432
	ds_read_b128 v[204:207], v159 offset:19456
	ds_read_b128 v[208:211], v159 offset:20480
	ds_read_b128 v[212:215], v159 offset:21504
	ds_read_b128 v[216:219], v159 offset:22528
	ds_read_b128 v[220:223], v159 offset:23552
	global_load_lds_dwordx4 v130, s[42:43]
	s_add_i32 m0, s89, 0x2000
	s_add_u32 s90, s42, 0x40000
	s_addc_u32 s91, s43, 0
	s_add_i32 s89, s79, s58
	global_load_lds_dwordx4 v134, s[42:43]
	s_mov_b32 m0, s89
	s_mov_b64 s[98:99], s[44:45]
	global_load_lds_dwordx4 v130, s[90:91]
	s_add_i32 m0, s89, 0x2000
	s_nop 0
	global_load_lds_dwordx4 v134, s[90:91]
	s_waitcnt vmcnt(6)
	s_waitcnt lgkmcnt(0)
	s_barrier
	s_setprio 1
	s_waitcnt lgkmcnt(0)
	v_mfma_f32_16x16x32_bf16 v[60:63], v[152:155], v[190:193], v[60:63]
	v_mfma_f32_16x16x32_bf16 v[56:59], v[166:169], v[190:193], v[56:59]
	v_mfma_f32_16x16x32_bf16 v[44:47], v[152:155], v[200:203], v[44:47]
	v_mfma_f32_16x16x32_bf16 v[40:43], v[166:169], v[200:203], v[40:43]
	v_mfma_f32_16x16x32_bf16 v[28:31], v[152:155], v[208:211], v[28:31]
	v_mfma_f32_16x16x32_bf16 v[24:27], v[166:169], v[208:211], v[24:27]
	v_mfma_f32_16x16x32_bf16 v[12:15], v[152:155], v[216:219], v[12:15]
	v_mfma_f32_16x16x32_bf16 v[8:11], v[166:169], v[216:219], v[8:11]
	v_mfma_f32_16x16x32_bf16 v[60:63], v[162:165], v[196:199], v[60:63]
	v_mfma_f32_16x16x32_bf16 v[56:59], v[170:173], v[196:199], v[56:59]
	v_mfma_f32_16x16x32_bf16 v[44:47], v[162:165], v[204:207], v[44:47]
	v_mfma_f32_16x16x32_bf16 v[40:43], v[170:173], v[204:207], v[40:43]
	v_mfma_f32_16x16x32_bf16 v[28:31], v[162:165], v[212:215], v[28:31]
	v_mfma_f32_16x16x32_bf16 v[24:27], v[170:173], v[212:215], v[24:27]
	v_mfma_f32_16x16x32_bf16 v[12:15], v[162:165], v[220:223], v[12:15]
	v_mfma_f32_16x16x32_bf16 v[8:11], v[170:173], v[220:223], v[8:11]
	s_setprio 0
	s_setprio 1
	v_mfma_f32_16x16x32_bf16 v[52:55], v[174:177], v[190:193], v[52:55]
	v_mfma_f32_16x16x32_bf16 v[48:51], v[182:185], v[190:193], v[48:51]
	v_mfma_f32_16x16x32_bf16 v[36:39], v[174:177], v[200:203], v[36:39]
	v_mfma_f32_16x16x32_bf16 v[32:35], v[182:185], v[200:203], v[32:35]
	v_mfma_f32_16x16x32_bf16 v[20:23], v[174:177], v[208:211], v[20:23]
	v_mfma_f32_16x16x32_bf16 v[16:19], v[182:185], v[208:211], v[16:19]
	v_mfma_f32_16x16x32_bf16 v[4:7], v[174:177], v[216:219], v[4:7]
	v_mfma_f32_16x16x32_bf16 v[0:3], v[182:185], v[216:219], v[0:3]
	v_mfma_f32_16x16x32_bf16 v[52:55], v[178:181], v[196:199], v[52:55]
	v_mfma_f32_16x16x32_bf16 v[48:51], v[186:189], v[196:199], v[48:51]
	v_mfma_f32_16x16x32_bf16 v[36:39], v[178:181], v[204:207], v[36:39]
	v_mfma_f32_16x16x32_bf16 v[32:35], v[186:189], v[204:207], v[32:35]
	v_mfma_f32_16x16x32_bf16 v[20:23], v[178:181], v[212:215], v[20:23]
	v_mfma_f32_16x16x32_bf16 v[16:19], v[186:189], v[212:215], v[16:19]
	v_mfma_f32_16x16x32_bf16 v[4:7], v[178:181], v[220:223], v[4:7]
	v_mfma_f32_16x16x32_bf16 v[0:3], v[186:189], v[220:223], v[0:3]
	s_setprio 0
	s_barrier
	s_add_i32 s89, 0, 0x18000
	v_add_u32_e32 v136, s89, v141
	s_add_i32 s90, 0, 0x1c000
	ds_read_b128 v[152:155], v136
	ds_read_b128 v[162:165], v136 offset:1024
	ds_read_b128 v[166:169], v136 offset:2048
	ds_read_b128 v[170:173], v136 offset:3072
	v_add_u32_e32 v136, s90, v141
	ds_read_b128 v[174:177], v136
	ds_read_b128 v[178:181], v136 offset:1024
	ds_read_b128 v[182:185], v136 offset:2048
	ds_read_b128 v[186:189], v136 offset:3072
	s_add_u32 s44, s44, 0x40000
	s_addc_u32 s45, s45, 0
	ds_read_b128 v[190:193], v159 offset:32768
	ds_read_b128 v[196:199], v159 offset:33792
	ds_read_b128 v[200:203], v159 offset:34816
	ds_read_b128 v[204:207], v159 offset:35840
	ds_read_b128 v[208:211], v159 offset:36864
	ds_read_b128 v[212:215], v159 offset:37888
	ds_read_b128 v[216:219], v159 offset:38912
	ds_read_b128 v[220:223], v159 offset:39936
	s_mov_b32 m0, s59
	s_nop 0
	global_load_lds_dwordx4 v128, s[98:99]
	s_mov_b32 m0, s60
	s_nop 0
	global_load_lds_dwordx4 v132, s[98:99]
	s_mov_b32 m0, s61
	s_nop 0
	global_load_lds_dwordx4 v128, s[44:45]
	s_mov_b32 m0, s62
	s_nop 0
	global_load_lds_dwordx4 v132, s[44:45]
	s_waitcnt vmcnt(8)
	s_waitcnt lgkmcnt(0)
	s_barrier
	s_setprio 1
	s_waitcnt lgkmcnt(0)
	v_mfma_f32_16x16x32_bf16 v[124:127], v[152:155], v[190:193], v[124:127]
	v_mfma_f32_16x16x32_bf16 v[120:123], v[166:169], v[190:193], v[120:123]
	v_mfma_f32_16x16x32_bf16 v[108:111], v[152:155], v[200:203], v[108:111]
	v_mfma_f32_16x16x32_bf16 v[104:107], v[166:169], v[200:203], v[104:107]
	v_mfma_f32_16x16x32_bf16 v[92:95], v[152:155], v[208:211], v[92:95]
	v_mfma_f32_16x16x32_bf16 v[88:91], v[166:169], v[208:211], v[88:91]
	v_mfma_f32_16x16x32_bf16 v[76:79], v[152:155], v[216:219], v[76:79]
	v_mfma_f32_16x16x32_bf16 v[72:75], v[166:169], v[216:219], v[72:75]
	v_mfma_f32_16x16x32_bf16 v[124:127], v[162:165], v[196:199], v[124:127]
	v_mfma_f32_16x16x32_bf16 v[120:123], v[170:173], v[196:199], v[120:123]
	v_mfma_f32_16x16x32_bf16 v[108:111], v[162:165], v[204:207], v[108:111]
	v_mfma_f32_16x16x32_bf16 v[104:107], v[170:173], v[204:207], v[104:107]
	v_mfma_f32_16x16x32_bf16 v[92:95], v[162:165], v[212:215], v[92:95]
	v_mfma_f32_16x16x32_bf16 v[88:91], v[170:173], v[212:215], v[88:91]
	v_mfma_f32_16x16x32_bf16 v[76:79], v[162:165], v[220:223], v[76:79]
	v_mfma_f32_16x16x32_bf16 v[72:75], v[170:173], v[220:223], v[72:75]
	s_setprio 0
	s_setprio 1
	v_mfma_f32_16x16x32_bf16 v[116:119], v[174:177], v[190:193], v[116:119]
	v_mfma_f32_16x16x32_bf16 v[112:115], v[182:185], v[190:193], v[112:115]
	v_mfma_f32_16x16x32_bf16 v[100:103], v[174:177], v[200:203], v[100:103]
	v_mfma_f32_16x16x32_bf16 v[96:99], v[182:185], v[200:203], v[96:99]
	v_mfma_f32_16x16x32_bf16 v[84:87], v[174:177], v[208:211], v[84:87]
	v_mfma_f32_16x16x32_bf16 v[80:83], v[182:185], v[208:211], v[80:83]
	v_mfma_f32_16x16x32_bf16 v[68:71], v[174:177], v[216:219], v[68:71]
	v_mfma_f32_16x16x32_bf16 v[64:67], v[182:185], v[216:219], v[64:67]
	v_mfma_f32_16x16x32_bf16 v[116:119], v[178:181], v[196:199], v[116:119]
	v_mfma_f32_16x16x32_bf16 v[112:115], v[186:189], v[196:199], v[112:115]
	v_mfma_f32_16x16x32_bf16 v[100:103], v[178:181], v[204:207], v[100:103]
	v_mfma_f32_16x16x32_bf16 v[96:99], v[186:189], v[204:207], v[96:99]
	v_mfma_f32_16x16x32_bf16 v[84:87], v[178:181], v[212:215], v[84:87]
	v_mfma_f32_16x16x32_bf16 v[80:83], v[186:189], v[212:215], v[80:83]
	v_mfma_f32_16x16x32_bf16 v[68:71], v[178:181], v[220:223], v[68:71]
	v_mfma_f32_16x16x32_bf16 v[64:67], v[186:189], v[220:223], v[64:67]
	s_setprio 0
	s_barrier
	s_add_i32 s44, s89, s58
	s_add_i32 m0, s44, 0xffffff80
	ds_read_b128 v[190:193], v159 offset:49152
	ds_read_b128 v[196:199], v159 offset:50176
	ds_read_b128 v[200:203], v159 offset:51200
	ds_read_b128 v[204:207], v159 offset:52224
	ds_read_b128 v[208:211], v159 offset:53248
	ds_read_b128 v[212:215], v159 offset:54272
	ds_read_b128 v[216:219], v159 offset:55296
	ds_read_b128 v[220:223], v159 offset:56320
	global_load_lds_dwordx4 v130, s[42:43] offset:128
	s_add_i32 m0, s44, 0x1f80
	s_add_i32 s44, s90, s58
	global_load_lds_dwordx4 v134, s[42:43] offset:128
	s_add_u32 s42, s42, 0x40080
	s_addc_u32 s43, s43, 0
	s_mov_b32 m0, s44
	s_nop 0
	global_load_lds_dwordx4 v130, s[42:43]
	s_add_i32 m0, s44, 0x2000
	s_nop 0
	global_load_lds_dwordx4 v134, s[42:43]
	s_waitcnt vmcnt(6)
	s_waitcnt lgkmcnt(0)
	s_barrier
	s_setprio 1
	s_waitcnt lgkmcnt(0)
	v_mfma_f32_16x16x32_bf16 v[60:63], v[152:155], v[190:193], v[60:63]
	v_mfma_f32_16x16x32_bf16 v[56:59], v[166:169], v[190:193], v[56:59]
	v_mfma_f32_16x16x32_bf16 v[44:47], v[152:155], v[200:203], v[44:47]
	v_mfma_f32_16x16x32_bf16 v[40:43], v[166:169], v[200:203], v[40:43]
	v_mfma_f32_16x16x32_bf16 v[28:31], v[152:155], v[208:211], v[28:31]
	v_mfma_f32_16x16x32_bf16 v[24:27], v[166:169], v[208:211], v[24:27]
	v_mfma_f32_16x16x32_bf16 v[12:15], v[152:155], v[216:219], v[12:15]
	v_mfma_f32_16x16x32_bf16 v[8:11], v[166:169], v[216:219], v[8:11]
	v_mfma_f32_16x16x32_bf16 v[60:63], v[162:165], v[196:199], v[60:63]
	v_mfma_f32_16x16x32_bf16 v[56:59], v[170:173], v[196:199], v[56:59]
	v_mfma_f32_16x16x32_bf16 v[44:47], v[162:165], v[204:207], v[44:47]
	v_mfma_f32_16x16x32_bf16 v[40:43], v[170:173], v[204:207], v[40:43]
	v_mfma_f32_16x16x32_bf16 v[28:31], v[162:165], v[212:215], v[28:31]
	v_mfma_f32_16x16x32_bf16 v[24:27], v[170:173], v[212:215], v[24:27]
	v_mfma_f32_16x16x32_bf16 v[12:15], v[162:165], v[220:223], v[12:15]
	v_mfma_f32_16x16x32_bf16 v[8:11], v[170:173], v[220:223], v[8:11]
	s_setprio 0
	s_setprio 1
	v_mfma_f32_16x16x32_bf16 v[52:55], v[174:177], v[190:193], v[52:55]
	v_mfma_f32_16x16x32_bf16 v[48:51], v[182:185], v[190:193], v[48:51]
	v_mfma_f32_16x16x32_bf16 v[36:39], v[174:177], v[200:203], v[36:39]
	v_mfma_f32_16x16x32_bf16 v[32:35], v[182:185], v[200:203], v[32:35]
	v_mfma_f32_16x16x32_bf16 v[20:23], v[174:177], v[208:211], v[20:23]
	v_mfma_f32_16x16x32_bf16 v[16:19], v[182:185], v[208:211], v[16:19]
	v_mfma_f32_16x16x32_bf16 v[4:7], v[174:177], v[216:219], v[4:7]
	v_mfma_f32_16x16x32_bf16 v[0:3], v[182:185], v[216:219], v[0:3]
	v_mfma_f32_16x16x32_bf16 v[52:55], v[178:181], v[196:199], v[52:55]
	v_mfma_f32_16x16x32_bf16 v[48:51], v[186:189], v[196:199], v[48:51]
	v_mfma_f32_16x16x32_bf16 v[36:39], v[178:181], v[204:207], v[36:39]
	v_mfma_f32_16x16x32_bf16 v[32:35], v[186:189], v[204:207], v[32:35]
	v_mfma_f32_16x16x32_bf16 v[20:23], v[178:181], v[212:215], v[20:23]
	v_mfma_f32_16x16x32_bf16 v[16:19], v[186:189], v[212:215], v[16:19]
	v_mfma_f32_16x16x32_bf16 v[4:7], v[178:181], v[220:223], v[4:7]
	v_mfma_f32_16x16x32_bf16 v[0:3], v[186:189], v[220:223], v[0:3]
	s_setprio 0
	s_barrier
	s_add_i32 m0, s71, 0xffffff80
	s_nop 0
	global_load_lds_dwordx4 v128, s[98:99] offset:128
	s_add_i32 m0, s72, 0xffffff80
	s_nop 0
	global_load_lds_dwordx4 v132, s[98:99] offset:128
	s_add_i32 s88, s88, 2
	s_add_u32 s40, s40, 0x100
	s_addc_u32 s41, s41, 0
	s_add_u32 s35, s35, 0x100
	s_addc_u32 s87, s87, 0
	s_cmp_gt_u32 s88, 13
	s_cbranch_scc0 .LBB0_2236
	s_and_b64 vcc, exec, s[28:29]
	s_cbranch_vccz .LBB0_2239
	s_barrier

.LBB0_2370:
	ds_read_b128 v[148:151], v144
	ds_read_b128 v[152:155], v144 offset:1024
	ds_read_b128 v[156:159], v144 offset:2048
	ds_read_b128 v[160:163], v144 offset:3072
	ds_read_b128 v[164:167], v145
	ds_read_b128 v[168:171], v145 offset:1024
	ds_read_b128 v[172:175], v145 offset:2048
	ds_read_b128 v[176:179], v145 offset:3072
	s_add_u32 s38, s36, 0x100
	s_addc_u32 s39, s37, 0
	s_cmp_eq_u32 s81, 4
	s_cselect_b32 s43, s31, s39
	s_cselect_b32 s42, s30, s38
	s_cselect_b32 s41, s35, s27
	s_cselect_b32 s40, s34, s17
	v_lshl_add_u64 v[192:193], s[36:37], 0, v[138:139]
	s_add_i32 m0, s55, 0xc000
	ds_read_b128 v[180:183], v146
	ds_read_b128 v[184:187], v146 offset:1024
	ds_read_b128 v[188:191], v146 offset:2048
	ds_read_b128 v[196:199], v146 offset:3072
	ds_read_b128 v[200:203], v146 offset:4096
	ds_read_b128 v[204:207], v146 offset:5120
	ds_read_b128 v[208:211], v146 offset:6144
	ds_read_b128 v[212:215], v146 offset:7168
	global_load_lds_dwordx4 v[192:193], off
	v_lshl_add_u64 v[192:193], s[36:37], 0, v[140:141]
	s_add_i32 m0, s55, 0xe000
	s_nop 0
	global_load_lds_dwordx4 v[192:193], off
	s_waitcnt vmcnt(8)
	s_waitcnt lgkmcnt(0)
	s_barrier
	s_setprio 1
	s_waitcnt lgkmcnt(0)
	v_mfma_f32_16x16x32_bf16 v[124:127], v[148:151], v[180:183], v[124:127]
	v_mfma_f32_16x16x32_bf16 v[120:123], v[156:159], v[180:183], v[120:123]
	v_mfma_f32_16x16x32_bf16 v[116:119], v[148:151], v[188:191], v[116:119]
	v_mfma_f32_16x16x32_bf16 v[112:115], v[156:159], v[188:191], v[112:115]
	v_mfma_f32_16x16x32_bf16 v[104:107], v[148:151], v[200:203], v[104:107]
	v_mfma_f32_16x16x32_bf16 v[96:99], v[156:159], v[200:203], v[96:99]
	v_mfma_f32_16x16x32_bf16 v[88:91], v[148:151], v[208:211], v[88:91]
	v_mfma_f32_16x16x32_bf16 v[80:83], v[156:159], v[208:211], v[80:83]
	v_mfma_f32_16x16x32_bf16 v[124:127], v[152:155], v[184:187], v[124:127]
	v_mfma_f32_16x16x32_bf16 v[120:123], v[160:163], v[184:187], v[120:123]
	v_mfma_f32_16x16x32_bf16 v[116:119], v[152:155], v[196:199], v[116:119]
	v_mfma_f32_16x16x32_bf16 v[112:115], v[160:163], v[196:199], v[112:115]
	v_mfma_f32_16x16x32_bf16 v[104:107], v[152:155], v[204:207], v[104:107]
	v_mfma_f32_16x16x32_bf16 v[96:99], v[160:163], v[204:207], v[96:99]
	v_mfma_f32_16x16x32_bf16 v[88:91], v[152:155], v[212:215], v[88:91]
	v_mfma_f32_16x16x32_bf16 v[80:83], v[160:163], v[212:215], v[80:83]
	s_setprio 0
	s_setprio 1
	v_mfma_f32_16x16x32_bf16 v[108:111], v[164:167], v[180:183], v[108:111]
	v_mfma_f32_16x16x32_bf16 v[100:103], v[172:175], v[180:183], v[100:103]
	v_mfma_f32_16x16x32_bf16 v[92:95], v[164:167], v[188:191], v[92:95]
	v_mfma_f32_16x16x32_bf16 v[84:87], v[172:175], v[188:191], v[84:87]
	v_mfma_f32_16x16x32_bf16 v[76:79], v[164:167], v[200:203], v[76:79]
	v_mfma_f32_16x16x32_bf16 v[72:75], v[172:175], v[200:203], v[72:75]
	v_mfma_f32_16x16x32_bf16 v[68:71], v[164:167], v[208:211], v[68:71]
	v_mfma_f32_16x16x32_bf16 v[64:67], v[172:175], v[208:211], v[64:67]
	v_mfma_f32_16x16x32_bf16 v[108:111], v[168:171], v[184:187], v[108:111]
	v_mfma_f32_16x16x32_bf16 v[100:103], v[176:179], v[184:187], v[100:103]
	v_mfma_f32_16x16x32_bf16 v[92:95], v[168:171], v[196:199], v[92:95]
	v_mfma_f32_16x16x32_bf16 v[84:87], v[176:179], v[196:199], v[84:87]
	v_mfma_f32_16x16x32_bf16 v[76:79], v[168:171], v[204:207], v[76:79]
	v_mfma_f32_16x16x32_bf16 v[72:75], v[176:179], v[204:207], v[72:75]
	v_mfma_f32_16x16x32_bf16 v[68:71], v[168:171], v[212:215], v[68:71]
	v_mfma_f32_16x16x32_bf16 v[64:67], v[176:179], v[212:215], v[64:67]
	s_setprio 0
	s_barrier
	s_add_i32 s36, s71, s54
	v_lshl_add_u64 v[192:193], s[40:41], 0, v[132:133]
	s_mov_b32 m0, s36
	ds_read_b128 v[180:183], v146 offset:16384
	ds_read_b128 v[184:187], v146 offset:17408
	ds_read_b128 v[188:191], v146 offset:18432
	ds_read_b128 v[196:199], v146 offset:19456
	ds_read_b128 v[200:203], v146 offset:20480
	ds_read_b128 v[204:207], v146 offset:21504
	ds_read_b128 v[208:211], v146 offset:22528
	ds_read_b128 v[212:215], v146 offset:23552
	global_load_lds_dwordx4 v[192:193], off
	s_add_i32 m0, s36, 0x2000
	s_add_u32 s36, s40, 0x20000
	v_lshl_add_u64 v[216:217], s[40:41], 0, v[128:129]
	s_addc_u32 s37, s41, 0
	s_add_i32 s82, s72, s54
	global_load_lds_dwordx4 v[216:217], off
	s_mov_b32 m0, s82
	s_mov_b64 s[98:99], s[42:43]
	global_load_lds_dwordx4 v132, s[36:37]
	s_add_i32 m0, s82, 0x2000
	s_nop 0
	global_load_lds_dwordx4 v128, s[36:37]
	s_waitcnt vmcnt(6)
	s_waitcnt lgkmcnt(0)
	s_barrier
	s_setprio 1
	s_waitcnt lgkmcnt(0)
	v_mfma_f32_16x16x32_bf16 v[60:63], v[148:151], v[180:183], v[60:63]
	v_mfma_f32_16x16x32_bf16 v[56:59], v[156:159], v[180:183], v[56:59]
	v_mfma_f32_16x16x32_bf16 v[52:55], v[148:151], v[188:191], v[52:55]
	v_mfma_f32_16x16x32_bf16 v[48:51], v[156:159], v[188:191], v[48:51]
	v_mfma_f32_16x16x32_bf16 v[40:43], v[148:151], v[200:203], v[40:43]
	v_mfma_f32_16x16x32_bf16 v[32:35], v[156:159], v[200:203], v[32:35]
	v_mfma_f32_16x16x32_bf16 v[24:27], v[148:151], v[208:211], v[24:27]
	v_mfma_f32_16x16x32_bf16 v[16:19], v[156:159], v[208:211], v[16:19]
	v_mfma_f32_16x16x32_bf16 v[60:63], v[152:155], v[184:187], v[60:63]
	v_mfma_f32_16x16x32_bf16 v[56:59], v[160:163], v[184:187], v[56:59]
	v_mfma_f32_16x16x32_bf16 v[52:55], v[152:155], v[196:199], v[52:55]
	v_mfma_f32_16x16x32_bf16 v[48:51], v[160:163], v[196:199], v[48:51]
	v_mfma_f32_16x16x32_bf16 v[40:43], v[152:155], v[204:207], v[40:43]
	v_mfma_f32_16x16x32_bf16 v[32:35], v[160:163], v[204:207], v[32:35]
	v_mfma_f32_16x16x32_bf16 v[24:27], v[152:155], v[212:215], v[24:27]
	v_mfma_f32_16x16x32_bf16 v[16:19], v[160:163], v[212:215], v[16:19]
	s_setprio 0
	s_setprio 1
	v_mfma_f32_16x16x32_bf16 v[44:47], v[164:167], v[180:183], v[44:47]
	v_mfma_f32_16x16x32_bf16 v[36:39], v[172:175], v[180:183], v[36:39]
	v_mfma_f32_16x16x32_bf16 v[28:31], v[164:167], v[188:191], v[28:31]
	v_mfma_f32_16x16x32_bf16 v[20:23], v[172:175], v[188:191], v[20:23]
	v_mfma_f32_16x16x32_bf16 v[12:15], v[164:167], v[200:203], v[12:15]
	v_mfma_f32_16x16x32_bf16 v[8:11], v[172:175], v[200:203], v[8:11]
	v_mfma_f32_16x16x32_bf16 v[4:7], v[164:167], v[208:211], v[4:7]
	v_mfma_f32_16x16x32_bf16 v[0:3], v[172:175], v[208:211], v[0:3]
	v_mfma_f32_16x16x32_bf16 v[44:47], v[168:171], v[184:187], v[44:47]
	v_mfma_f32_16x16x32_bf16 v[36:39], v[176:179], v[184:187], v[36:39]
	v_mfma_f32_16x16x32_bf16 v[28:31], v[168:171], v[196:199], v[28:31]
	v_mfma_f32_16x16x32_bf16 v[20:23], v[176:179], v[196:199], v[20:23]
	v_mfma_f32_16x16x32_bf16 v[12:15], v[168:171], v[204:207], v[12:15]
	v_mfma_f32_16x16x32_bf16 v[8:11], v[176:179], v[204:207], v[8:11]
	v_mfma_f32_16x16x32_bf16 v[4:7], v[168:171], v[212:215], v[4:7]
	v_mfma_f32_16x16x32_bf16 v[0:3], v[176:179], v[212:215], v[0:3]
	s_setprio 0
	s_barrier
	s_add_i32 s82, 0, 0x18000
	v_add_u32_e32 v147, s82, v143
	s_add_i32 s83, 0, 0x1c000
	ds_read_b128 v[148:151], v147
	ds_read_b128 v[152:155], v147 offset:1024
	ds_read_b128 v[156:159], v147 offset:2048
	ds_read_b128 v[160:163], v147 offset:3072
	v_add_u32_e32 v147, s83, v143
	ds_read_b128 v[164:167], v147
	ds_read_b128 v[168:171], v147 offset:1024
	ds_read_b128 v[172:175], v147 offset:2048
	ds_read_b128 v[176:179], v147 offset:3072
	s_add_u32 s36, s42, 0x30000
	s_addc_u32 s37, s43, 0
	ds_read_b128 v[180:183], v146 offset:32768
	ds_read_b128 v[184:187], v146 offset:33792
	ds_read_b128 v[188:191], v146 offset:34816
	ds_read_b128 v[196:199], v146 offset:35840
	ds_read_b128 v[200:203], v146 offset:36864
	ds_read_b128 v[204:207], v146 offset:37888
	ds_read_b128 v[208:211], v146 offset:38912
	ds_read_b128 v[212:215], v146 offset:39936
	s_mov_b32 m0, s55
	s_nop 0
	global_load_lds_dwordx4 v134, s[98:99]
	s_mov_b32 m0, s56
	s_nop 0
	global_load_lds_dwordx4 v130, s[98:99]
	s_mov_b32 m0, s57
	s_nop 0
	global_load_lds_dwordx4 v134, s[36:37]
	s_mov_b32 m0, s58
	s_nop 0
	global_load_lds_dwordx4 v130, s[36:37]
	s_waitcnt vmcnt(8)
	s_waitcnt lgkmcnt(0)
	s_barrier
	s_setprio 1
	s_waitcnt lgkmcnt(0)
	v_mfma_f32_16x16x32_bf16 v[124:127], v[148:151], v[180:183], v[124:127]
	v_mfma_f32_16x16x32_bf16 v[120:123], v[156:159], v[180:183], v[120:123]
	v_mfma_f32_16x16x32_bf16 v[116:119], v[148:151], v[188:191], v[116:119]
	v_mfma_f32_16x16x32_bf16 v[112:115], v[156:159], v[188:191], v[112:115]
	v_mfma_f32_16x16x32_bf16 v[104:107], v[148:151], v[200:203], v[104:107]
	v_mfma_f32_16x16x32_bf16 v[96:99], v[156:159], v[200:203], v[96:99]
	v_mfma_f32_16x16x32_bf16 v[88:91], v[148:151], v[208:211], v[88:91]
	v_mfma_f32_16x16x32_bf16 v[80:83], v[156:159], v[208:211], v[80:83]
	v_mfma_f32_16x16x32_bf16 v[124:127], v[152:155], v[184:187], v[124:127]
	v_mfma_f32_16x16x32_bf16 v[120:123], v[160:163], v[184:187], v[120:123]
	v_mfma_f32_16x16x32_bf16 v[116:119], v[152:155], v[196:199], v[116:119]
	v_mfma_f32_16x16x32_bf16 v[112:115], v[160:163], v[196:199], v[112:115]
	v_mfma_f32_16x16x32_bf16 v[104:107], v[152:155], v[204:207], v[104:107]
	v_mfma_f32_16x16x32_bf16 v[96:99], v[160:163], v[204:207], v[96:99]
	v_mfma_f32_16x16x32_bf16 v[88:91], v[152:155], v[212:215], v[88:91]
	v_mfma_f32_16x16x32_bf16 v[80:83], v[160:163], v[212:215], v[80:83]
	s_setprio 0
	s_setprio 1
	v_mfma_f32_16x16x32_bf16 v[108:111], v[164:167], v[180:183], v[108:111]
	v_mfma_f32_16x16x32_bf16 v[100:103], v[172:175], v[180:183], v[100:103]
	v_mfma_f32_16x16x32_bf16 v[92:95], v[164:167], v[188:191], v[92:95]
	v_mfma_f32_16x16x32_bf16 v[84:87], v[172:175], v[188:191], v[84:87]
	v_mfma_f32_16x16x32_bf16 v[76:79], v[164:167], v[200:203], v[76:79]
	v_mfma_f32_16x16x32_bf16 v[72:75], v[172:175], v[200:203], v[72:75]
	v_mfma_f32_16x16x32_bf16 v[68:71], v[164:167], v[208:211], v[68:71]
	v_mfma_f32_16x16x32_bf16 v[64:67], v[172:175], v[208:211], v[64:67]
	v_mfma_f32_16x16x32_bf16 v[108:111], v[168:171], v[184:187], v[108:111]
	v_mfma_f32_16x16x32_bf16 v[100:103], v[176:179], v[184:187], v[100:103]
	v_mfma_f32_16x16x32_bf16 v[92:95], v[168:171], v[196:199], v[92:95]
	v_mfma_f32_16x16x32_bf16 v[84:87], v[176:179], v[196:199], v[84:87]
	v_mfma_f32_16x16x32_bf16 v[76:79], v[168:171], v[204:207], v[76:79]
	v_mfma_f32_16x16x32_bf16 v[72:75], v[176:179], v[204:207], v[72:75]
	v_mfma_f32_16x16x32_bf16 v[68:71], v[168:171], v[212:215], v[68:71]
	v_mfma_f32_16x16x32_bf16 v[64:67], v[176:179], v[212:215], v[64:67]
	s_setprio 0
	s_barrier
	s_add_i32 s36, s82, s54
	v_lshl_add_u64 v[192:193], v[192:193], 0, s[14:15]
	s_mov_b32 m0, s36
	ds_read_b128 v[180:183], v146 offset:49152
	ds_read_b128 v[184:187], v146 offset:50176
	ds_read_b128 v[188:191], v146 offset:51200
	ds_read_b128 v[196:199], v146 offset:52224
	ds_read_b128 v[200:203], v146 offset:53248
	ds_read_b128 v[204:207], v146 offset:54272
	ds_read_b128 v[208:211], v146 offset:55296
	ds_read_b128 v[212:215], v146 offset:56320
	global_load_lds_dwordx4 v[192:193], off
	s_add_i32 m0, s36, 0x2000
	s_add_u32 s36, s40, 0x20080
	v_lshl_add_u64 v[192:193], v[216:217], 0, s[14:15]
	s_addc_u32 s37, s41, 0
	s_add_i32 s40, s83, s54
	global_load_lds_dwordx4 v[192:193], off
	s_mov_b32 m0, s40
	s_nop 0
	global_load_lds_dwordx4 v132, s[36:37]
	s_add_i32 m0, s40, 0x2000
	s_nop 0
	global_load_lds_dwordx4 v128, s[36:37]
	s_waitcnt vmcnt(6)
	s_waitcnt lgkmcnt(0)
	s_barrier
	s_setprio 1
	s_waitcnt lgkmcnt(0)
	v_mfma_f32_16x16x32_bf16 v[60:63], v[148:151], v[180:183], v[60:63]
	v_mfma_f32_16x16x32_bf16 v[56:59], v[156:159], v[180:183], v[56:59]
	v_mfma_f32_16x16x32_bf16 v[52:55], v[148:151], v[188:191], v[52:55]
	v_mfma_f32_16x16x32_bf16 v[48:51], v[156:159], v[188:191], v[48:51]
	v_mfma_f32_16x16x32_bf16 v[40:43], v[148:151], v[200:203], v[40:43]
	v_mfma_f32_16x16x32_bf16 v[32:35], v[156:159], v[200:203], v[32:35]
	v_mfma_f32_16x16x32_bf16 v[24:27], v[148:151], v[208:211], v[24:27]
	v_mfma_f32_16x16x32_bf16 v[16:19], v[156:159], v[208:211], v[16:19]
	v_mfma_f32_16x16x32_bf16 v[60:63], v[152:155], v[184:187], v[60:63]
	v_mfma_f32_16x16x32_bf16 v[56:59], v[160:163], v[184:187], v[56:59]
	v_mfma_f32_16x16x32_bf16 v[52:55], v[152:155], v[196:199], v[52:55]
	v_mfma_f32_16x16x32_bf16 v[48:51], v[160:163], v[196:199], v[48:51]
	v_mfma_f32_16x16x32_bf16 v[40:43], v[152:155], v[204:207], v[40:43]
	v_mfma_f32_16x16x32_bf16 v[32:35], v[160:163], v[204:207], v[32:35]
	v_mfma_f32_16x16x32_bf16 v[24:27], v[152:155], v[212:215], v[24:27]
	v_mfma_f32_16x16x32_bf16 v[16:19], v[160:163], v[212:215], v[16:19]
	s_setprio 0
	s_setprio 1
	v_mfma_f32_16x16x32_bf16 v[44:47], v[164:167], v[180:183], v[44:47]
	v_mfma_f32_16x16x32_bf16 v[36:39], v[172:175], v[180:183], v[36:39]
	v_mfma_f32_16x16x32_bf16 v[28:31], v[164:167], v[188:191], v[28:31]
	v_mfma_f32_16x16x32_bf16 v[20:23], v[172:175], v[188:191], v[20:23]
	v_mfma_f32_16x16x32_bf16 v[12:15], v[164:167], v[200:203], v[12:15]
	v_mfma_f32_16x16x32_bf16 v[8:11], v[172:175], v[200:203], v[8:11]
	v_mfma_f32_16x16x32_bf16 v[4:7], v[164:167], v[208:211], v[4:7]
	v_mfma_f32_16x16x32_bf16 v[0:3], v[172:175], v[208:211], v[0:3]
	v_mfma_f32_16x16x32_bf16 v[44:47], v[168:171], v[184:187], v[44:47]
	v_mfma_f32_16x16x32_bf16 v[36:39], v[176:179], v[184:187], v[36:39]
	v_mfma_f32_16x16x32_bf16 v[28:31], v[168:171], v[196:199], v[28:31]
	v_mfma_f32_16x16x32_bf16 v[20:23], v[176:179], v[196:199], v[20:23]
	v_mfma_f32_16x16x32_bf16 v[12:15], v[168:171], v[204:207], v[12:15]
	v_mfma_f32_16x16x32_bf16 v[8:11], v[176:179], v[204:207], v[8:11]
	v_mfma_f32_16x16x32_bf16 v[4:7], v[168:171], v[212:215], v[4:7]
	v_mfma_f32_16x16x32_bf16 v[0:3], v[176:179], v[212:215], v[0:3]
	s_setprio 0
	s_barrier
	s_add_i32 m0, s62, 0xffffff80
	s_nop 0
	global_load_lds_dwordx4 v134, s[98:99] offset:128
	s_add_i32 m0, s63, 0xffffff80
	s_nop 0
	global_load_lds_dwordx4 v130, s[98:99] offset:128
	s_add_i32 s81, s81, 2
	s_add_u32 s17, s17, 0x100
	s_addc_u32 s27, s27, 0
	s_cmp_gt_u32 s81, 5
	s_mov_b64 s[36:37], s[38:39]
	s_cbranch_scc0 .LBB0_2370
	s_and_b64 vcc, exec, s[18:19]
	s_cbranch_vccz .LBB0_2373
	s_barrier

.LBB0_2396:
	ds_read_b128 v[144:147], v153
	ds_read_b128 v[158:161], v153 offset:1024
	ds_read_b128 v[162:165], v153 offset:2048
	ds_read_b128 v[166:169], v153 offset:3072
	ds_read_b128 v[170:173], v154
	ds_read_b128 v[174:177], v154 offset:1024
	ds_read_b128 v[178:181], v154 offset:2048
	ds_read_b128 v[182:185], v154 offset:3072
	s_add_u32 s36, s34, 0xfffc0080
	s_addc_u32 s37, s35, -1
	s_cmp_eq_u32 s78, 12
	s_cselect_b32 s39, s27, s37
	s_cselect_b32 s38, s71, s36
	s_cselect_b32 s37, s25, s77
	s_cselect_b32 s36, s72, s73
	s_add_i32 m0, s53, 0xc000
	ds_read_b128 v[186:189], v155
	ds_read_b128 v[190:193], v155 offset:1024
	ds_read_b128 v[196:199], v155 offset:2048
	ds_read_b128 v[200:203], v155 offset:3072
	ds_read_b128 v[204:207], v155 offset:4096
	ds_read_b128 v[208:211], v155 offset:5120
	ds_read_b128 v[212:215], v155 offset:6144
	ds_read_b128 v[216:219], v155 offset:7168
	global_load_lds_dwordx4 v136, s[34:35]
	s_add_i32 m0, s53, 0xe000
	s_nop 0
	global_load_lds_dwordx4 v138, s[34:35]
	s_waitcnt vmcnt(8)
	s_waitcnt lgkmcnt(0)
	s_barrier
	s_setprio 1
	s_waitcnt lgkmcnt(0)
	v_mfma_f32_16x16x32_bf16 v[124:127], v[144:147], v[186:189], v[124:127]
	v_mfma_f32_16x16x32_bf16 v[120:123], v[162:165], v[186:189], v[120:123]
	v_mfma_f32_16x16x32_bf16 v[108:111], v[144:147], v[196:199], v[108:111]
	v_mfma_f32_16x16x32_bf16 v[104:107], v[162:165], v[196:199], v[104:107]
	v_mfma_f32_16x16x32_bf16 v[92:95], v[144:147], v[204:207], v[92:95]
	v_mfma_f32_16x16x32_bf16 v[88:91], v[162:165], v[204:207], v[88:91]
	v_mfma_f32_16x16x32_bf16 v[76:79], v[144:147], v[212:215], v[76:79]
	v_mfma_f32_16x16x32_bf16 v[72:75], v[162:165], v[212:215], v[72:75]
	v_mfma_f32_16x16x32_bf16 v[124:127], v[158:161], v[190:193], v[124:127]
	v_mfma_f32_16x16x32_bf16 v[120:123], v[166:169], v[190:193], v[120:123]
	v_mfma_f32_16x16x32_bf16 v[108:111], v[158:161], v[200:203], v[108:111]
	v_mfma_f32_16x16x32_bf16 v[104:107], v[166:169], v[200:203], v[104:107]
	v_mfma_f32_16x16x32_bf16 v[92:95], v[158:161], v[208:211], v[92:95]
	v_mfma_f32_16x16x32_bf16 v[88:91], v[166:169], v[208:211], v[88:91]
	v_mfma_f32_16x16x32_bf16 v[76:79], v[158:161], v[216:219], v[76:79]
	v_mfma_f32_16x16x32_bf16 v[72:75], v[166:169], v[216:219], v[72:75]
	s_setprio 0
	s_setprio 1
	v_mfma_f32_16x16x32_bf16 v[116:119], v[170:173], v[186:189], v[116:119]
	v_mfma_f32_16x16x32_bf16 v[112:115], v[178:181], v[186:189], v[112:115]
	v_mfma_f32_16x16x32_bf16 v[100:103], v[170:173], v[196:199], v[100:103]
	v_mfma_f32_16x16x32_bf16 v[96:99], v[178:181], v[196:199], v[96:99]
	v_mfma_f32_16x16x32_bf16 v[84:87], v[170:173], v[204:207], v[84:87]
	v_mfma_f32_16x16x32_bf16 v[80:83], v[178:181], v[204:207], v[80:83]
	v_mfma_f32_16x16x32_bf16 v[68:71], v[170:173], v[212:215], v[68:71]
	v_mfma_f32_16x16x32_bf16 v[64:67], v[178:181], v[212:215], v[64:67]
	v_mfma_f32_16x16x32_bf16 v[116:119], v[174:177], v[190:193], v[116:119]
	v_mfma_f32_16x16x32_bf16 v[112:115], v[182:185], v[190:193], v[112:115]
	v_mfma_f32_16x16x32_bf16 v[100:103], v[174:177], v[200:203], v[100:103]
	v_mfma_f32_16x16x32_bf16 v[96:99], v[182:185], v[200:203], v[96:99]
	v_mfma_f32_16x16x32_bf16 v[84:87], v[174:177], v[208:211], v[84:87]
	v_mfma_f32_16x16x32_bf16 v[80:83], v[182:185], v[208:211], v[80:83]
	v_mfma_f32_16x16x32_bf16 v[68:71], v[174:177], v[216:219], v[68:71]
	v_mfma_f32_16x16x32_bf16 v[64:67], v[182:185], v[216:219], v[64:67]
	s_setprio 0
	s_barrier
	s_add_i32 s79, s61, s52
	s_mov_b32 m0, s79
	ds_read_b128 v[186:189], v155 offset:16384
	ds_read_b128 v[190:193], v155 offset:17408
	ds_read_b128 v[196:199], v155 offset:18432
	ds_read_b128 v[200:203], v155 offset:19456
	ds_read_b128 v[204:207], v155 offset:20480
	ds_read_b128 v[208:211], v155 offset:21504
	ds_read_b128 v[212:215], v155 offset:22528
	ds_read_b128 v[216:219], v155 offset:23552
	global_load_lds_dwordx4 v130, s[36:37]
	s_add_i32 m0, s79, 0x2000
	s_add_u32 s80, s36, 0x40000
	s_addc_u32 s81, s37, 0
	s_add_i32 s79, s62, s52
	global_load_lds_dwordx4 v134, s[36:37]
	s_mov_b32 m0, s79
	s_mov_b64 s[98:99], s[38:39]
	global_load_lds_dwordx4 v130, s[80:81]
	s_add_i32 m0, s79, 0x2000
	s_nop 0
	global_load_lds_dwordx4 v134, s[80:81]
	s_waitcnt vmcnt(6)
	s_waitcnt lgkmcnt(0)
	s_barrier
	s_setprio 1
	s_waitcnt lgkmcnt(0)
	v_mfma_f32_16x16x32_bf16 v[60:63], v[144:147], v[186:189], v[60:63]
	v_mfma_f32_16x16x32_bf16 v[56:59], v[162:165], v[186:189], v[56:59]
	v_mfma_f32_16x16x32_bf16 v[44:47], v[144:147], v[196:199], v[44:47]
	v_mfma_f32_16x16x32_bf16 v[40:43], v[162:165], v[196:199], v[40:43]
	v_mfma_f32_16x16x32_bf16 v[28:31], v[144:147], v[204:207], v[28:31]
	v_mfma_f32_16x16x32_bf16 v[24:27], v[162:165], v[204:207], v[24:27]
	v_mfma_f32_16x16x32_bf16 v[12:15], v[144:147], v[212:215], v[12:15]
	v_mfma_f32_16x16x32_bf16 v[8:11], v[162:165], v[212:215], v[8:11]
	v_mfma_f32_16x16x32_bf16 v[60:63], v[158:161], v[190:193], v[60:63]
	v_mfma_f32_16x16x32_bf16 v[56:59], v[166:169], v[190:193], v[56:59]
	v_mfma_f32_16x16x32_bf16 v[44:47], v[158:161], v[200:203], v[44:47]
	v_mfma_f32_16x16x32_bf16 v[40:43], v[166:169], v[200:203], v[40:43]
	v_mfma_f32_16x16x32_bf16 v[28:31], v[158:161], v[208:211], v[28:31]
	v_mfma_f32_16x16x32_bf16 v[24:27], v[166:169], v[208:211], v[24:27]
	v_mfma_f32_16x16x32_bf16 v[12:15], v[158:161], v[216:219], v[12:15]
	v_mfma_f32_16x16x32_bf16 v[8:11], v[166:169], v[216:219], v[8:11]
	s_setprio 0
	s_setprio 1
	v_mfma_f32_16x16x32_bf16 v[52:55], v[170:173], v[186:189], v[52:55]
	v_mfma_f32_16x16x32_bf16 v[48:51], v[178:181], v[186:189], v[48:51]
	v_mfma_f32_16x16x32_bf16 v[36:39], v[170:173], v[196:199], v[36:39]
	v_mfma_f32_16x16x32_bf16 v[32:35], v[178:181], v[196:199], v[32:35]
	v_mfma_f32_16x16x32_bf16 v[20:23], v[170:173], v[204:207], v[20:23]
	v_mfma_f32_16x16x32_bf16 v[16:19], v[178:181], v[204:207], v[16:19]
	v_mfma_f32_16x16x32_bf16 v[4:7], v[170:173], v[212:215], v[4:7]
	v_mfma_f32_16x16x32_bf16 v[0:3], v[178:181], v[212:215], v[0:3]
	v_mfma_f32_16x16x32_bf16 v[52:55], v[174:177], v[190:193], v[52:55]
	v_mfma_f32_16x16x32_bf16 v[48:51], v[182:185], v[190:193], v[48:51]
	v_mfma_f32_16x16x32_bf16 v[36:39], v[174:177], v[200:203], v[36:39]
	v_mfma_f32_16x16x32_bf16 v[32:35], v[182:185], v[200:203], v[32:35]
	v_mfma_f32_16x16x32_bf16 v[20:23], v[174:177], v[208:211], v[20:23]
	v_mfma_f32_16x16x32_bf16 v[16:19], v[182:185], v[208:211], v[16:19]
	v_mfma_f32_16x16x32_bf16 v[4:7], v[174:177], v[216:219], v[4:7]
	v_mfma_f32_16x16x32_bf16 v[0:3], v[182:185], v[216:219], v[0:3]
	s_setprio 0
	s_barrier
	s_add_i32 s79, 0, 0x18000
	v_add_u32_e32 v157, s79, v151
	s_add_i32 s80, 0, 0x1c000
	ds_read_b128 v[144:147], v157
	ds_read_b128 v[158:161], v157 offset:1024
	ds_read_b128 v[162:165], v157 offset:2048
	ds_read_b128 v[166:169], v157 offset:3072
	v_add_u32_e32 v157, s80, v151
	ds_read_b128 v[170:173], v157
	ds_read_b128 v[174:177], v157 offset:1024
	ds_read_b128 v[178:181], v157 offset:2048
	ds_read_b128 v[182:185], v157 offset:3072
	s_add_u32 s38, s38, 0x40000
	s_addc_u32 s39, s39, 0
	ds_read_b128 v[186:189], v155 offset:32768
	ds_read_b128 v[190:193], v155 offset:33792
	ds_read_b128 v[196:199], v155 offset:34816
	ds_read_b128 v[200:203], v155 offset:35840
	ds_read_b128 v[204:207], v155 offset:36864
	ds_read_b128 v[208:211], v155 offset:37888
	ds_read_b128 v[212:215], v155 offset:38912
	ds_read_b128 v[216:219], v155 offset:39936
	s_mov_b32 m0, s53
	s_nop 0
	global_load_lds_dwordx4 v128, s[98:99]
	s_mov_b32 m0, s54
	s_nop 0
	global_load_lds_dwordx4 v132, s[98:99]
	s_mov_b32 m0, s55
	s_nop 0
	global_load_lds_dwordx4 v128, s[38:39]
	s_mov_b32 m0, s56
	s_nop 0
	global_load_lds_dwordx4 v132, s[38:39]
	s_waitcnt vmcnt(8)
	s_waitcnt lgkmcnt(0)
	s_barrier
	s_setprio 1
	s_waitcnt lgkmcnt(0)
	v_mfma_f32_16x16x32_bf16 v[124:127], v[144:147], v[186:189], v[124:127]
	v_mfma_f32_16x16x32_bf16 v[120:123], v[162:165], v[186:189], v[120:123]
	v_mfma_f32_16x16x32_bf16 v[108:111], v[144:147], v[196:199], v[108:111]
	v_mfma_f32_16x16x32_bf16 v[104:107], v[162:165], v[196:199], v[104:107]
	v_mfma_f32_16x16x32_bf16 v[92:95], v[144:147], v[204:207], v[92:95]
	v_mfma_f32_16x16x32_bf16 v[88:91], v[162:165], v[204:207], v[88:91]
	v_mfma_f32_16x16x32_bf16 v[76:79], v[144:147], v[212:215], v[76:79]
	v_mfma_f32_16x16x32_bf16 v[72:75], v[162:165], v[212:215], v[72:75]
	v_mfma_f32_16x16x32_bf16 v[124:127], v[158:161], v[190:193], v[124:127]
	v_mfma_f32_16x16x32_bf16 v[120:123], v[166:169], v[190:193], v[120:123]
	v_mfma_f32_16x16x32_bf16 v[108:111], v[158:161], v[200:203], v[108:111]
	v_mfma_f32_16x16x32_bf16 v[104:107], v[166:169], v[200:203], v[104:107]
	v_mfma_f32_16x16x32_bf16 v[92:95], v[158:161], v[208:211], v[92:95]
	v_mfma_f32_16x16x32_bf16 v[88:91], v[166:169], v[208:211], v[88:91]
	v_mfma_f32_16x16x32_bf16 v[76:79], v[158:161], v[216:219], v[76:79]
	v_mfma_f32_16x16x32_bf16 v[72:75], v[166:169], v[216:219], v[72:75]
	s_setprio 0
	s_setprio 1
	v_mfma_f32_16x16x32_bf16 v[116:119], v[170:173], v[186:189], v[116:119]
	v_mfma_f32_16x16x32_bf16 v[112:115], v[178:181], v[186:189], v[112:115]
	v_mfma_f32_16x16x32_bf16 v[100:103], v[170:173], v[196:199], v[100:103]
	v_mfma_f32_16x16x32_bf16 v[96:99], v[178:181], v[196:199], v[96:99]
	v_mfma_f32_16x16x32_bf16 v[84:87], v[170:173], v[204:207], v[84:87]
	v_mfma_f32_16x16x32_bf16 v[80:83], v[178:181], v[204:207], v[80:83]
	v_mfma_f32_16x16x32_bf16 v[68:71], v[170:173], v[212:215], v[68:71]
	v_mfma_f32_16x16x32_bf16 v[64:67], v[178:181], v[212:215], v[64:67]
	v_mfma_f32_16x16x32_bf16 v[116:119], v[174:177], v[190:193], v[116:119]
	v_mfma_f32_16x16x32_bf16 v[112:115], v[182:185], v[190:193], v[112:115]
	v_mfma_f32_16x16x32_bf16 v[100:103], v[174:177], v[200:203], v[100:103]
	v_mfma_f32_16x16x32_bf16 v[96:99], v[182:185], v[200:203], v[96:99]
	v_mfma_f32_16x16x32_bf16 v[84:87], v[174:177], v[208:211], v[84:87]
	v_mfma_f32_16x16x32_bf16 v[80:83], v[182:185], v[208:211], v[80:83]
	v_mfma_f32_16x16x32_bf16 v[68:71], v[174:177], v[216:219], v[68:71]
	v_mfma_f32_16x16x32_bf16 v[64:67], v[182:185], v[216:219], v[64:67]
	s_setprio 0
	s_barrier
	s_add_i32 s38, s79, s52
	s_add_i32 m0, s38, 0xffffff80
	ds_read_b128 v[186:189], v155 offset:49152
	ds_read_b128 v[190:193], v155 offset:50176
	ds_read_b128 v[196:199], v155 offset:51200
	ds_read_b128 v[200:203], v155 offset:52224
	ds_read_b128 v[204:207], v155 offset:53248
	ds_read_b128 v[208:211], v155 offset:54272
	ds_read_b128 v[212:215], v155 offset:55296
	ds_read_b128 v[216:219], v155 offset:56320
	global_load_lds_dwordx4 v130, s[36:37] offset:128
	s_add_i32 m0, s38, 0x1f80
	s_add_i32 s38, s80, s52
	global_load_lds_dwordx4 v134, s[36:37] offset:128
	s_add_u32 s36, s36, 0x40080
	s_addc_u32 s37, s37, 0
	s_mov_b32 m0, s38
	s_nop 0
	global_load_lds_dwordx4 v130, s[36:37]
	s_add_i32 m0, s38, 0x2000
	s_nop 0
	global_load_lds_dwordx4 v134, s[36:37]
	s_waitcnt vmcnt(6)
	s_waitcnt lgkmcnt(0)
	s_barrier
	s_setprio 1
	s_waitcnt lgkmcnt(0)
	v_mfma_f32_16x16x32_bf16 v[60:63], v[144:147], v[186:189], v[60:63]
	v_mfma_f32_16x16x32_bf16 v[56:59], v[162:165], v[186:189], v[56:59]
	v_mfma_f32_16x16x32_bf16 v[44:47], v[144:147], v[196:199], v[44:47]
	v_mfma_f32_16x16x32_bf16 v[40:43], v[162:165], v[196:199], v[40:43]
	v_mfma_f32_16x16x32_bf16 v[28:31], v[144:147], v[204:207], v[28:31]
	v_mfma_f32_16x16x32_bf16 v[24:27], v[162:165], v[204:207], v[24:27]
	v_mfma_f32_16x16x32_bf16 v[12:15], v[144:147], v[212:215], v[12:15]
	v_mfma_f32_16x16x32_bf16 v[8:11], v[162:165], v[212:215], v[8:11]
	v_mfma_f32_16x16x32_bf16 v[60:63], v[158:161], v[190:193], v[60:63]
	v_mfma_f32_16x16x32_bf16 v[56:59], v[166:169], v[190:193], v[56:59]
	v_mfma_f32_16x16x32_bf16 v[44:47], v[158:161], v[200:203], v[44:47]
	v_mfma_f32_16x16x32_bf16 v[40:43], v[166:169], v[200:203], v[40:43]
	v_mfma_f32_16x16x32_bf16 v[28:31], v[158:161], v[208:211], v[28:31]
	v_mfma_f32_16x16x32_bf16 v[24:27], v[166:169], v[208:211], v[24:27]
	v_mfma_f32_16x16x32_bf16 v[12:15], v[158:161], v[216:219], v[12:15]
	v_mfma_f32_16x16x32_bf16 v[8:11], v[166:169], v[216:219], v[8:11]
	s_setprio 0
	s_setprio 1
	v_mfma_f32_16x16x32_bf16 v[52:55], v[170:173], v[186:189], v[52:55]
	v_mfma_f32_16x16x32_bf16 v[48:51], v[178:181], v[186:189], v[48:51]
	v_mfma_f32_16x16x32_bf16 v[36:39], v[170:173], v[196:199], v[36:39]
	v_mfma_f32_16x16x32_bf16 v[32:35], v[178:181], v[196:199], v[32:35]
	v_mfma_f32_16x16x32_bf16 v[20:23], v[170:173], v[204:207], v[20:23]
	v_mfma_f32_16x16x32_bf16 v[16:19], v[178:181], v[204:207], v[16:19]
	v_mfma_f32_16x16x32_bf16 v[4:7], v[170:173], v[212:215], v[4:7]
	v_mfma_f32_16x16x32_bf16 v[0:3], v[178:181], v[212:215], v[0:3]
	v_mfma_f32_16x16x32_bf16 v[52:55], v[174:177], v[190:193], v[52:55]
	v_mfma_f32_16x16x32_bf16 v[48:51], v[182:185], v[190:193], v[48:51]
	v_mfma_f32_16x16x32_bf16 v[36:39], v[174:177], v[200:203], v[36:39]
	v_mfma_f32_16x16x32_bf16 v[32:35], v[182:185], v[200:203], v[32:35]
	v_mfma_f32_16x16x32_bf16 v[20:23], v[174:177], v[208:211], v[20:23]
	v_mfma_f32_16x16x32_bf16 v[16:19], v[182:185], v[208:211], v[16:19]
	v_mfma_f32_16x16x32_bf16 v[4:7], v[174:177], v[216:219], v[4:7]
	v_mfma_f32_16x16x32_bf16 v[0:3], v[182:185], v[216:219], v[0:3]
	s_setprio 0
	s_barrier
	s_add_i32 m0, s58, 0xffffff80
	s_nop 0
	global_load_lds_dwordx4 v128, s[98:99] offset:128
	s_add_i32 m0, s59, 0xffffff80
	s_nop 0
	global_load_lds_dwordx4 v132, s[98:99] offset:128
	s_add_i32 s78, s78, 2
	s_add_u32 s34, s34, 0x100
	s_addc_u32 s35, s35, 0
	s_add_u32 s73, s73, 0x100
	s_addc_u32 s77, s77, 0
	s_cmp_gt_u32 s78, 13
	s_cbranch_scc0 .LBB0_2396
	s_and_b64 vcc, exec, s[22:23]
	s_cbranch_vccz .LBB0_2399
	s_barrier

.LBB0_2533:
	ds_read_b128 v[152:155], v148
	ds_read_b128 v[156:159], v148 offset:1024
	ds_read_b128 v[160:163], v148 offset:2048
	ds_read_b128 v[164:167], v148 offset:3072
	ds_read_b128 v[168:171], v149
	ds_read_b128 v[172:175], v149 offset:1024
	ds_read_b128 v[176:179], v149 offset:2048
	ds_read_b128 v[180:183], v149 offset:3072
	s_add_u32 s26, s24, 0x100
	s_addc_u32 s27, s25, 0
	s_cmp_eq_u32 s62, 8
	s_cselect_b32 s31, s21, s27
	s_cselect_b32 s30, s20, s26
	s_cselect_b32 s29, s23, s61
	s_cselect_b32 s28, s22, s60
	s_mov_b32 m0, s53
	v_lshl_add_u64 v[192:193], s[24:25], 0, v[138:139]
	ds_read_b128 v[184:187], v150
	ds_read_b128 v[188:191], v150 offset:1024
	ds_read_b128 v[196:199], v150 offset:2048
	ds_read_b128 v[200:203], v150 offset:3072
	ds_read_b128 v[204:207], v150 offset:4096
	ds_read_b128 v[208:211], v150 offset:5120
	ds_read_b128 v[212:215], v150 offset:6144
	ds_read_b128 v[216:219], v150 offset:7168
	global_load_lds_dwordx4 v[192:193], off
	v_lshl_add_u64 v[192:193], s[24:25], 0, v[140:141]
	s_add_i32 m0, s40, 0xe000
	s_nop 0
	global_load_lds_dwordx4 v[192:193], off
	s_waitcnt vmcnt(8)
	s_waitcnt lgkmcnt(0)
	s_barrier
	s_setprio 1
	s_waitcnt lgkmcnt(0)
	v_mfma_f32_16x16x32_bf16 v[124:127], v[152:155], v[184:187], v[124:127]
	v_mfma_f32_16x16x32_bf16 v[120:123], v[160:163], v[184:187], v[120:123]
	v_mfma_f32_16x16x32_bf16 v[108:111], v[152:155], v[196:199], v[108:111]
	v_mfma_f32_16x16x32_bf16 v[104:107], v[160:163], v[196:199], v[104:107]
	v_mfma_f32_16x16x32_bf16 v[92:95], v[152:155], v[204:207], v[92:95]
	v_mfma_f32_16x16x32_bf16 v[88:91], v[160:163], v[204:207], v[88:91]
	v_mfma_f32_16x16x32_bf16 v[76:79], v[152:155], v[212:215], v[76:79]
	v_mfma_f32_16x16x32_bf16 v[72:75], v[160:163], v[212:215], v[72:75]
	v_mfma_f32_16x16x32_bf16 v[124:127], v[156:159], v[188:191], v[124:127]
	v_mfma_f32_16x16x32_bf16 v[120:123], v[164:167], v[188:191], v[120:123]
	v_mfma_f32_16x16x32_bf16 v[108:111], v[156:159], v[200:203], v[108:111]
	v_mfma_f32_16x16x32_bf16 v[104:107], v[164:167], v[200:203], v[104:107]
	v_mfma_f32_16x16x32_bf16 v[92:95], v[156:159], v[208:211], v[92:95]
	v_mfma_f32_16x16x32_bf16 v[88:91], v[164:167], v[208:211], v[88:91]
	v_mfma_f32_16x16x32_bf16 v[76:79], v[156:159], v[216:219], v[76:79]
	v_mfma_f32_16x16x32_bf16 v[72:75], v[164:167], v[216:219], v[72:75]
	s_setprio 0
	s_setprio 1
	v_mfma_f32_16x16x32_bf16 v[116:119], v[168:171], v[184:187], v[116:119]
	v_mfma_f32_16x16x32_bf16 v[112:115], v[176:179], v[184:187], v[112:115]
	v_mfma_f32_16x16x32_bf16 v[100:103], v[168:171], v[196:199], v[100:103]
	v_mfma_f32_16x16x32_bf16 v[96:99], v[176:179], v[196:199], v[96:99]
	v_mfma_f32_16x16x32_bf16 v[84:87], v[168:171], v[204:207], v[84:87]
	v_mfma_f32_16x16x32_bf16 v[80:83], v[176:179], v[204:207], v[80:83]
	v_mfma_f32_16x16x32_bf16 v[68:71], v[168:171], v[212:215], v[68:71]
	v_mfma_f32_16x16x32_bf16 v[64:67], v[176:179], v[212:215], v[64:67]
	v_mfma_f32_16x16x32_bf16 v[116:119], v[172:175], v[188:191], v[116:119]
	v_mfma_f32_16x16x32_bf16 v[112:115], v[180:183], v[188:191], v[112:115]
	v_mfma_f32_16x16x32_bf16 v[100:103], v[172:175], v[200:203], v[100:103]
	v_mfma_f32_16x16x32_bf16 v[96:99], v[180:183], v[200:203], v[96:99]
	v_mfma_f32_16x16x32_bf16 v[84:87], v[172:175], v[208:211], v[84:87]
	v_mfma_f32_16x16x32_bf16 v[80:83], v[180:183], v[208:211], v[80:83]
	v_mfma_f32_16x16x32_bf16 v[68:71], v[172:175], v[216:219], v[68:71]
	v_mfma_f32_16x16x32_bf16 v[64:67], v[180:183], v[216:219], v[64:67]
	s_setprio 0
	s_barrier
	s_add_i32 s24, s51, s39
	v_lshl_add_u64 v[192:193], s[28:29], 0, v[132:133]
	s_mov_b32 m0, s24
	ds_read_b128 v[184:187], v150 offset:16384
	ds_read_b128 v[188:191], v150 offset:17408
	ds_read_b128 v[196:199], v150 offset:18432
	ds_read_b128 v[200:203], v150 offset:19456
	ds_read_b128 v[204:207], v150 offset:20480
	ds_read_b128 v[208:211], v150 offset:21504
	ds_read_b128 v[212:215], v150 offset:22528
	ds_read_b128 v[216:219], v150 offset:23552
	global_load_lds_dwordx4 v[192:193], off
	s_add_i32 m0, s24, 0x2000
	s_add_u32 s24, s28, 0x30000
	v_lshl_add_u64 v[220:221], s[28:29], 0, v[128:129]
	s_addc_u32 s25, s29, 0
	s_add_i32 s63, s52, s39
	global_load_lds_dwordx4 v[220:221], off
	s_mov_b32 m0, s63
	s_mov_b64 s[98:99], s[30:31]
	global_load_lds_dwordx4 v132, s[24:25]
	s_add_i32 m0, s63, 0x2000
	s_nop 0
	global_load_lds_dwordx4 v128, s[24:25]
	s_waitcnt vmcnt(6)
	s_waitcnt lgkmcnt(0)
	s_barrier
	s_setprio 1
	s_waitcnt lgkmcnt(0)
	v_mfma_f32_16x16x32_bf16 v[60:63], v[152:155], v[184:187], v[60:63]
	v_mfma_f32_16x16x32_bf16 v[56:59], v[160:163], v[184:187], v[56:59]
	v_mfma_f32_16x16x32_bf16 v[44:47], v[152:155], v[196:199], v[44:47]
	v_mfma_f32_16x16x32_bf16 v[40:43], v[160:163], v[196:199], v[40:43]
	v_mfma_f32_16x16x32_bf16 v[28:31], v[152:155], v[204:207], v[28:31]
	v_mfma_f32_16x16x32_bf16 v[24:27], v[160:163], v[204:207], v[24:27]
	v_mfma_f32_16x16x32_bf16 v[12:15], v[152:155], v[212:215], v[12:15]
	v_mfma_f32_16x16x32_bf16 v[8:11], v[160:163], v[212:215], v[8:11]
	v_mfma_f32_16x16x32_bf16 v[60:63], v[156:159], v[188:191], v[60:63]
	v_mfma_f32_16x16x32_bf16 v[56:59], v[164:167], v[188:191], v[56:59]
	v_mfma_f32_16x16x32_bf16 v[44:47], v[156:159], v[200:203], v[44:47]
	v_mfma_f32_16x16x32_bf16 v[40:43], v[164:167], v[200:203], v[40:43]
	v_mfma_f32_16x16x32_bf16 v[28:31], v[156:159], v[208:211], v[28:31]
	v_mfma_f32_16x16x32_bf16 v[24:27], v[164:167], v[208:211], v[24:27]
	v_mfma_f32_16x16x32_bf16 v[12:15], v[156:159], v[216:219], v[12:15]
	v_mfma_f32_16x16x32_bf16 v[8:11], v[164:167], v[216:219], v[8:11]
	s_setprio 0
	s_setprio 1
	v_mfma_f32_16x16x32_bf16 v[52:55], v[168:171], v[184:187], v[52:55]
	v_mfma_f32_16x16x32_bf16 v[48:51], v[176:179], v[184:187], v[48:51]
	v_mfma_f32_16x16x32_bf16 v[36:39], v[168:171], v[196:199], v[36:39]
	v_mfma_f32_16x16x32_bf16 v[32:35], v[176:179], v[196:199], v[32:35]
	v_mfma_f32_16x16x32_bf16 v[20:23], v[168:171], v[204:207], v[20:23]
	v_mfma_f32_16x16x32_bf16 v[16:19], v[176:179], v[204:207], v[16:19]
	v_mfma_f32_16x16x32_bf16 v[4:7], v[168:171], v[212:215], v[4:7]
	v_mfma_f32_16x16x32_bf16 v[0:3], v[176:179], v[212:215], v[0:3]
	v_mfma_f32_16x16x32_bf16 v[52:55], v[172:175], v[188:191], v[52:55]
	v_mfma_f32_16x16x32_bf16 v[48:51], v[180:183], v[188:191], v[48:51]
	v_mfma_f32_16x16x32_bf16 v[36:39], v[172:175], v[200:203], v[36:39]
	v_mfma_f32_16x16x32_bf16 v[32:35], v[180:183], v[200:203], v[32:35]
	v_mfma_f32_16x16x32_bf16 v[20:23], v[172:175], v[208:211], v[20:23]
	v_mfma_f32_16x16x32_bf16 v[16:19], v[180:183], v[208:211], v[16:19]
	v_mfma_f32_16x16x32_bf16 v[4:7], v[172:175], v[216:219], v[4:7]
	v_mfma_f32_16x16x32_bf16 v[0:3], v[180:183], v[216:219], v[0:3]
	s_setprio 0
	s_barrier
	s_add_i32 s63, 0, 0x18000
	v_add_u32_e32 v151, s63, v142
	s_add_i32 s70, 0, 0x1c000
	ds_read_b128 v[152:155], v151
	ds_read_b128 v[156:159], v151 offset:1024
	ds_read_b128 v[160:163], v151 offset:2048
	ds_read_b128 v[164:167], v151 offset:3072
	v_add_u32_e32 v151, s70, v142
	ds_read_b128 v[168:171], v151
	ds_read_b128 v[172:175], v151 offset:1024
	ds_read_b128 v[176:179], v151 offset:2048
	ds_read_b128 v[180:183], v151 offset:3072
	s_add_u32 s24, s30, 0x30000
	s_addc_u32 s25, s31, 0
	ds_read_b128 v[184:187], v150 offset:32768
	ds_read_b128 v[188:191], v150 offset:33792
	ds_read_b128 v[196:199], v150 offset:34816
	ds_read_b128 v[200:203], v150 offset:35840
	ds_read_b128 v[204:207], v150 offset:36864
	ds_read_b128 v[208:211], v150 offset:37888
	ds_read_b128 v[212:215], v150 offset:38912
	ds_read_b128 v[216:219], v150 offset:39936
	s_mov_b32 m0, s40
	s_nop 0
	global_load_lds_dwordx4 v134, s[98:99]
	s_mov_b32 m0, s41
	s_nop 0
	global_load_lds_dwordx4 v130, s[98:99]
	s_mov_b32 m0, s42
	s_nop 0
	global_load_lds_dwordx4 v134, s[24:25]
	s_mov_b32 m0, s43
	s_nop 0
	global_load_lds_dwordx4 v130, s[24:25]
	s_waitcnt vmcnt(8)
	s_waitcnt lgkmcnt(0)
	s_barrier
	s_setprio 1
	s_waitcnt lgkmcnt(0)
	v_mfma_f32_16x16x32_bf16 v[124:127], v[152:155], v[184:187], v[124:127]
	v_mfma_f32_16x16x32_bf16 v[120:123], v[160:163], v[184:187], v[120:123]
	v_mfma_f32_16x16x32_bf16 v[108:111], v[152:155], v[196:199], v[108:111]
	v_mfma_f32_16x16x32_bf16 v[104:107], v[160:163], v[196:199], v[104:107]
	v_mfma_f32_16x16x32_bf16 v[92:95], v[152:155], v[204:207], v[92:95]
	v_mfma_f32_16x16x32_bf16 v[88:91], v[160:163], v[204:207], v[88:91]
	v_mfma_f32_16x16x32_bf16 v[76:79], v[152:155], v[212:215], v[76:79]
	v_mfma_f32_16x16x32_bf16 v[72:75], v[160:163], v[212:215], v[72:75]
	v_mfma_f32_16x16x32_bf16 v[124:127], v[156:159], v[188:191], v[124:127]
	v_mfma_f32_16x16x32_bf16 v[120:123], v[164:167], v[188:191], v[120:123]
	v_mfma_f32_16x16x32_bf16 v[108:111], v[156:159], v[200:203], v[108:111]
	v_mfma_f32_16x16x32_bf16 v[104:107], v[164:167], v[200:203], v[104:107]
	v_mfma_f32_16x16x32_bf16 v[92:95], v[156:159], v[208:211], v[92:95]
	v_mfma_f32_16x16x32_bf16 v[88:91], v[164:167], v[208:211], v[88:91]
	v_mfma_f32_16x16x32_bf16 v[76:79], v[156:159], v[216:219], v[76:79]
	v_mfma_f32_16x16x32_bf16 v[72:75], v[164:167], v[216:219], v[72:75]
	s_setprio 0
	s_setprio 1
	v_mfma_f32_16x16x32_bf16 v[116:119], v[168:171], v[184:187], v[116:119]
	v_mfma_f32_16x16x32_bf16 v[112:115], v[176:179], v[184:187], v[112:115]
	v_mfma_f32_16x16x32_bf16 v[100:103], v[168:171], v[196:199], v[100:103]
	v_mfma_f32_16x16x32_bf16 v[96:99], v[176:179], v[196:199], v[96:99]
	v_mfma_f32_16x16x32_bf16 v[84:87], v[168:171], v[204:207], v[84:87]
	v_mfma_f32_16x16x32_bf16 v[80:83], v[176:179], v[204:207], v[80:83]
	v_mfma_f32_16x16x32_bf16 v[68:71], v[168:171], v[212:215], v[68:71]
	v_mfma_f32_16x16x32_bf16 v[64:67], v[176:179], v[212:215], v[64:67]
	v_mfma_f32_16x16x32_bf16 v[116:119], v[172:175], v[188:191], v[116:119]
	v_mfma_f32_16x16x32_bf16 v[112:115], v[180:183], v[188:191], v[112:115]
	v_mfma_f32_16x16x32_bf16 v[100:103], v[172:175], v[200:203], v[100:103]
	v_mfma_f32_16x16x32_bf16 v[96:99], v[180:183], v[200:203], v[96:99]
	v_mfma_f32_16x16x32_bf16 v[84:87], v[172:175], v[208:211], v[84:87]
	v_mfma_f32_16x16x32_bf16 v[80:83], v[180:183], v[208:211], v[80:83]
	v_mfma_f32_16x16x32_bf16 v[68:71], v[172:175], v[216:219], v[68:71]
	v_mfma_f32_16x16x32_bf16 v[64:67], v[180:183], v[216:219], v[64:67]
	s_setprio 0
	s_barrier
	s_add_i32 s24, s63, s39
	v_lshl_add_u64 v[192:193], v[192:193], 0, s[16:17]
	s_mov_b32 m0, s24
	ds_read_b128 v[184:187], v150 offset:49152
	ds_read_b128 v[188:191], v150 offset:50176
	ds_read_b128 v[196:199], v150 offset:51200
	ds_read_b128 v[200:203], v150 offset:52224
	ds_read_b128 v[204:207], v150 offset:53248
	ds_read_b128 v[208:211], v150 offset:54272
	ds_read_b128 v[212:215], v150 offset:55296
	ds_read_b128 v[216:219], v150 offset:56320
	global_load_lds_dwordx4 v[192:193], off
	s_add_i32 m0, s24, 0x2000
	s_add_u32 s24, s28, 0x30080
	v_lshl_add_u64 v[192:193], v[220:221], 0, s[16:17]
	s_addc_u32 s25, s29, 0
	s_add_i32 s28, s70, s39
	global_load_lds_dwordx4 v[192:193], off
	s_mov_b32 m0, s28
	s_nop 0
	global_load_lds_dwordx4 v132, s[24:25]
	s_add_i32 m0, s28, 0x2000
	s_nop 0
	global_load_lds_dwordx4 v128, s[24:25]
	s_waitcnt vmcnt(6)
	s_waitcnt lgkmcnt(0)
	s_barrier
	s_setprio 1
	s_waitcnt lgkmcnt(0)
	v_mfma_f32_16x16x32_bf16 v[60:63], v[152:155], v[184:187], v[60:63]
	v_mfma_f32_16x16x32_bf16 v[56:59], v[160:163], v[184:187], v[56:59]
	v_mfma_f32_16x16x32_bf16 v[44:47], v[152:155], v[196:199], v[44:47]
	v_mfma_f32_16x16x32_bf16 v[40:43], v[160:163], v[196:199], v[40:43]
	v_mfma_f32_16x16x32_bf16 v[28:31], v[152:155], v[204:207], v[28:31]
	v_mfma_f32_16x16x32_bf16 v[24:27], v[160:163], v[204:207], v[24:27]
	v_mfma_f32_16x16x32_bf16 v[12:15], v[152:155], v[212:215], v[12:15]
	v_mfma_f32_16x16x32_bf16 v[8:11], v[160:163], v[212:215], v[8:11]
	v_mfma_f32_16x16x32_bf16 v[60:63], v[156:159], v[188:191], v[60:63]
	v_mfma_f32_16x16x32_bf16 v[56:59], v[164:167], v[188:191], v[56:59]
	v_mfma_f32_16x16x32_bf16 v[44:47], v[156:159], v[200:203], v[44:47]
	v_mfma_f32_16x16x32_bf16 v[40:43], v[164:167], v[200:203], v[40:43]
	v_mfma_f32_16x16x32_bf16 v[28:31], v[156:159], v[208:211], v[28:31]
	v_mfma_f32_16x16x32_bf16 v[24:27], v[164:167], v[208:211], v[24:27]
	v_mfma_f32_16x16x32_bf16 v[12:15], v[156:159], v[216:219], v[12:15]
	v_mfma_f32_16x16x32_bf16 v[8:11], v[164:167], v[216:219], v[8:11]
	s_setprio 0
	s_setprio 1
	v_mfma_f32_16x16x32_bf16 v[52:55], v[168:171], v[184:187], v[52:55]
	v_mfma_f32_16x16x32_bf16 v[48:51], v[176:179], v[184:187], v[48:51]
	v_mfma_f32_16x16x32_bf16 v[36:39], v[168:171], v[196:199], v[36:39]
	v_mfma_f32_16x16x32_bf16 v[32:35], v[176:179], v[196:199], v[32:35]
	v_mfma_f32_16x16x32_bf16 v[20:23], v[168:171], v[204:207], v[20:23]
	v_mfma_f32_16x16x32_bf16 v[16:19], v[176:179], v[204:207], v[16:19]
	v_mfma_f32_16x16x32_bf16 v[4:7], v[168:171], v[212:215], v[4:7]
	v_mfma_f32_16x16x32_bf16 v[0:3], v[176:179], v[212:215], v[0:3]
	v_mfma_f32_16x16x32_bf16 v[52:55], v[172:175], v[188:191], v[52:55]
	v_mfma_f32_16x16x32_bf16 v[48:51], v[180:183], v[188:191], v[48:51]
	v_mfma_f32_16x16x32_bf16 v[36:39], v[172:175], v[200:203], v[36:39]
	v_mfma_f32_16x16x32_bf16 v[32:35], v[180:183], v[200:203], v[32:35]
	v_mfma_f32_16x16x32_bf16 v[20:23], v[172:175], v[208:211], v[20:23]
	v_mfma_f32_16x16x32_bf16 v[16:19], v[180:183], v[208:211], v[16:19]
	v_mfma_f32_16x16x32_bf16 v[4:7], v[172:175], v[216:219], v[4:7]
	v_mfma_f32_16x16x32_bf16 v[0:3], v[180:183], v[216:219], v[0:3]
	s_setprio 0
	s_barrier
	s_add_i32 m0, s45, 0xffffff80
	s_nop 0
	global_load_lds_dwordx4 v134, s[98:99] offset:128
	s_add_i32 m0, s48, 0xffffff80
	s_nop 0
	global_load_lds_dwordx4 v130, s[98:99] offset:128
	s_add_i32 s62, s62, 2
	s_add_u32 s60, s60, 0x100
	s_addc_u32 s61, s61, 0
	s_cmp_gt_u32 s62, 9
	s_mov_b64 s[24:25], s[26:27]
	s_cbranch_scc0 .LBB0_2533
	s_and_b64 vcc, exec, s[18:19]
	s_cbranch_vccz .LBB0_2536
	s_barrier

.LBB0_2557:
	ds_read_b128 v[144:147], v153
	ds_read_b128 v[158:161], v153 offset:1024
	ds_read_b128 v[162:165], v153 offset:2048
	ds_read_b128 v[166:169], v153 offset:3072
	ds_read_b128 v[170:173], v154
	ds_read_b128 v[174:177], v154 offset:1024
	ds_read_b128 v[178:181], v154 offset:2048
	ds_read_b128 v[182:185], v154 offset:3072
	s_add_u32 s36, s34, 0xfffc0080
	s_addc_u32 s37, s35, -1
	s_cmp_eq_u32 s73, 12
	s_cselect_b32 s39, s27, s37
	s_cselect_b32 s38, s63, s36
	s_cselect_b32 s37, s25, s72
	s_cselect_b32 s36, s70, s71
	s_add_i32 m0, s51, 0xc000
	ds_read_b128 v[186:189], v155
	ds_read_b128 v[190:193], v155 offset:1024
	ds_read_b128 v[196:199], v155 offset:2048
	ds_read_b128 v[200:203], v155 offset:3072
	ds_read_b128 v[204:207], v155 offset:4096
	ds_read_b128 v[208:211], v155 offset:5120
	ds_read_b128 v[212:215], v155 offset:6144
	ds_read_b128 v[216:219], v155 offset:7168
	global_load_lds_dwordx4 v136, s[34:35]
	s_add_i32 m0, s51, 0xe000
	s_nop 0
	global_load_lds_dwordx4 v138, s[34:35]
	s_waitcnt vmcnt(8)
	s_waitcnt lgkmcnt(0)
	s_barrier
	s_setprio 1
	s_waitcnt lgkmcnt(0)
	v_mfma_f32_16x16x32_bf16 v[124:127], v[144:147], v[186:189], v[124:127]
	v_mfma_f32_16x16x32_bf16 v[120:123], v[162:165], v[186:189], v[120:123]
	v_mfma_f32_16x16x32_bf16 v[108:111], v[144:147], v[196:199], v[108:111]
	v_mfma_f32_16x16x32_bf16 v[104:107], v[162:165], v[196:199], v[104:107]
	v_mfma_f32_16x16x32_bf16 v[92:95], v[144:147], v[204:207], v[92:95]
	v_mfma_f32_16x16x32_bf16 v[88:91], v[162:165], v[204:207], v[88:91]
	v_mfma_f32_16x16x32_bf16 v[76:79], v[144:147], v[212:215], v[76:79]
	v_mfma_f32_16x16x32_bf16 v[72:75], v[162:165], v[212:215], v[72:75]
	v_mfma_f32_16x16x32_bf16 v[124:127], v[158:161], v[190:193], v[124:127]
	v_mfma_f32_16x16x32_bf16 v[120:123], v[166:169], v[190:193], v[120:123]
	v_mfma_f32_16x16x32_bf16 v[108:111], v[158:161], v[200:203], v[108:111]
	v_mfma_f32_16x16x32_bf16 v[104:107], v[166:169], v[200:203], v[104:107]
	v_mfma_f32_16x16x32_bf16 v[92:95], v[158:161], v[208:211], v[92:95]
	v_mfma_f32_16x16x32_bf16 v[88:91], v[166:169], v[208:211], v[88:91]
	v_mfma_f32_16x16x32_bf16 v[76:79], v[158:161], v[216:219], v[76:79]
	v_mfma_f32_16x16x32_bf16 v[72:75], v[166:169], v[216:219], v[72:75]
	s_setprio 0
	s_setprio 1
	v_mfma_f32_16x16x32_bf16 v[116:119], v[170:173], v[186:189], v[116:119]
	v_mfma_f32_16x16x32_bf16 v[112:115], v[178:181], v[186:189], v[112:115]
	v_mfma_f32_16x16x32_bf16 v[100:103], v[170:173], v[196:199], v[100:103]
	v_mfma_f32_16x16x32_bf16 v[96:99], v[178:181], v[196:199], v[96:99]
	v_mfma_f32_16x16x32_bf16 v[84:87], v[170:173], v[204:207], v[84:87]
	v_mfma_f32_16x16x32_bf16 v[80:83], v[178:181], v[204:207], v[80:83]
	v_mfma_f32_16x16x32_bf16 v[68:71], v[170:173], v[212:215], v[68:71]
	v_mfma_f32_16x16x32_bf16 v[64:67], v[178:181], v[212:215], v[64:67]
	v_mfma_f32_16x16x32_bf16 v[116:119], v[174:177], v[190:193], v[116:119]
	v_mfma_f32_16x16x32_bf16 v[112:115], v[182:185], v[190:193], v[112:115]
	v_mfma_f32_16x16x32_bf16 v[100:103], v[174:177], v[200:203], v[100:103]
	v_mfma_f32_16x16x32_bf16 v[96:99], v[182:185], v[200:203], v[96:99]
	v_mfma_f32_16x16x32_bf16 v[84:87], v[174:177], v[208:211], v[84:87]
	v_mfma_f32_16x16x32_bf16 v[80:83], v[182:185], v[208:211], v[80:83]
	v_mfma_f32_16x16x32_bf16 v[68:71], v[174:177], v[216:219], v[68:71]
	v_mfma_f32_16x16x32_bf16 v[64:67], v[182:185], v[216:219], v[64:67]
	s_setprio 0
	s_barrier
	s_add_i32 s77, s59, s49
	s_mov_b32 m0, s77
	ds_read_b128 v[186:189], v155 offset:16384
	ds_read_b128 v[190:193], v155 offset:17408
	ds_read_b128 v[196:199], v155 offset:18432
	ds_read_b128 v[200:203], v155 offset:19456
	ds_read_b128 v[204:207], v155 offset:20480
	ds_read_b128 v[208:211], v155 offset:21504
	ds_read_b128 v[212:215], v155 offset:22528
	ds_read_b128 v[216:219], v155 offset:23552
	global_load_lds_dwordx4 v130, s[36:37]
	s_add_i32 m0, s77, 0x2000
	s_add_u32 s78, s36, 0x40000
	s_addc_u32 s79, s37, 0
	s_add_i32 s77, s60, s49
	global_load_lds_dwordx4 v134, s[36:37]
	s_mov_b32 m0, s77
	s_mov_b64 s[98:99], s[38:39]
	global_load_lds_dwordx4 v130, s[78:79]
	s_add_i32 m0, s77, 0x2000
	s_nop 0
	global_load_lds_dwordx4 v134, s[78:79]
	s_waitcnt vmcnt(6)
	s_waitcnt lgkmcnt(0)
	s_barrier
	s_setprio 1
	s_waitcnt lgkmcnt(0)
	v_mfma_f32_16x16x32_bf16 v[60:63], v[144:147], v[186:189], v[60:63]
	v_mfma_f32_16x16x32_bf16 v[56:59], v[162:165], v[186:189], v[56:59]
	v_mfma_f32_16x16x32_bf16 v[44:47], v[144:147], v[196:199], v[44:47]
	v_mfma_f32_16x16x32_bf16 v[40:43], v[162:165], v[196:199], v[40:43]
	v_mfma_f32_16x16x32_bf16 v[28:31], v[144:147], v[204:207], v[28:31]
	v_mfma_f32_16x16x32_bf16 v[24:27], v[162:165], v[204:207], v[24:27]
	v_mfma_f32_16x16x32_bf16 v[12:15], v[144:147], v[212:215], v[12:15]
	v_mfma_f32_16x16x32_bf16 v[8:11], v[162:165], v[212:215], v[8:11]
	v_mfma_f32_16x16x32_bf16 v[60:63], v[158:161], v[190:193], v[60:63]
	v_mfma_f32_16x16x32_bf16 v[56:59], v[166:169], v[190:193], v[56:59]
	v_mfma_f32_16x16x32_bf16 v[44:47], v[158:161], v[200:203], v[44:47]
	v_mfma_f32_16x16x32_bf16 v[40:43], v[166:169], v[200:203], v[40:43]
	v_mfma_f32_16x16x32_bf16 v[28:31], v[158:161], v[208:211], v[28:31]
	v_mfma_f32_16x16x32_bf16 v[24:27], v[166:169], v[208:211], v[24:27]
	v_mfma_f32_16x16x32_bf16 v[12:15], v[158:161], v[216:219], v[12:15]
	v_mfma_f32_16x16x32_bf16 v[8:11], v[166:169], v[216:219], v[8:11]
	s_setprio 0
	s_setprio 1
	v_mfma_f32_16x16x32_bf16 v[52:55], v[170:173], v[186:189], v[52:55]
	v_mfma_f32_16x16x32_bf16 v[48:51], v[178:181], v[186:189], v[48:51]
	v_mfma_f32_16x16x32_bf16 v[36:39], v[170:173], v[196:199], v[36:39]
	v_mfma_f32_16x16x32_bf16 v[32:35], v[178:181], v[196:199], v[32:35]
	v_mfma_f32_16x16x32_bf16 v[20:23], v[170:173], v[204:207], v[20:23]
	v_mfma_f32_16x16x32_bf16 v[16:19], v[178:181], v[204:207], v[16:19]
	v_mfma_f32_16x16x32_bf16 v[4:7], v[170:173], v[212:215], v[4:7]
	v_mfma_f32_16x16x32_bf16 v[0:3], v[178:181], v[212:215], v[0:3]
	v_mfma_f32_16x16x32_bf16 v[52:55], v[174:177], v[190:193], v[52:55]
	v_mfma_f32_16x16x32_bf16 v[48:51], v[182:185], v[190:193], v[48:51]
	v_mfma_f32_16x16x32_bf16 v[36:39], v[174:177], v[200:203], v[36:39]
	v_mfma_f32_16x16x32_bf16 v[32:35], v[182:185], v[200:203], v[32:35]
	v_mfma_f32_16x16x32_bf16 v[20:23], v[174:177], v[208:211], v[20:23]
	v_mfma_f32_16x16x32_bf16 v[16:19], v[182:185], v[208:211], v[16:19]
	v_mfma_f32_16x16x32_bf16 v[4:7], v[174:177], v[216:219], v[4:7]
	v_mfma_f32_16x16x32_bf16 v[0:3], v[182:185], v[216:219], v[0:3]
	s_setprio 0
	s_barrier
	s_add_i32 s77, 0, 0x18000
	v_add_u32_e32 v157, s77, v151
	s_add_i32 s78, 0, 0x1c000
	ds_read_b128 v[144:147], v157
	ds_read_b128 v[158:161], v157 offset:1024
	ds_read_b128 v[162:165], v157 offset:2048
	ds_read_b128 v[166:169], v157 offset:3072
	v_add_u32_e32 v157, s78, v151
	ds_read_b128 v[170:173], v157
	ds_read_b128 v[174:177], v157 offset:1024
	ds_read_b128 v[178:181], v157 offset:2048
	ds_read_b128 v[182:185], v157 offset:3072
	s_add_u32 s38, s38, 0x40000
	s_addc_u32 s39, s39, 0
	ds_read_b128 v[186:189], v155 offset:32768
	ds_read_b128 v[190:193], v155 offset:33792
	ds_read_b128 v[196:199], v155 offset:34816
	ds_read_b128 v[200:203], v155 offset:35840
	ds_read_b128 v[204:207], v155 offset:36864
	ds_read_b128 v[208:211], v155 offset:37888
	ds_read_b128 v[212:215], v155 offset:38912
	ds_read_b128 v[216:219], v155 offset:39936
	s_mov_b32 m0, s51
	s_nop 0
	global_load_lds_dwordx4 v128, s[98:99]
	s_mov_b32 m0, s52
	s_nop 0
	global_load_lds_dwordx4 v132, s[98:99]
	s_mov_b32 m0, s53
	s_nop 0
	global_load_lds_dwordx4 v128, s[38:39]
	s_mov_b32 m0, s54
	s_nop 0
	global_load_lds_dwordx4 v132, s[38:39]
	s_waitcnt vmcnt(8)
	s_waitcnt lgkmcnt(0)
	s_barrier
	s_setprio 1
	s_waitcnt lgkmcnt(0)
	v_mfma_f32_16x16x32_bf16 v[124:127], v[144:147], v[186:189], v[124:127]
	v_mfma_f32_16x16x32_bf16 v[120:123], v[162:165], v[186:189], v[120:123]
	v_mfma_f32_16x16x32_bf16 v[108:111], v[144:147], v[196:199], v[108:111]
	v_mfma_f32_16x16x32_bf16 v[104:107], v[162:165], v[196:199], v[104:107]
	v_mfma_f32_16x16x32_bf16 v[92:95], v[144:147], v[204:207], v[92:95]
	v_mfma_f32_16x16x32_bf16 v[88:91], v[162:165], v[204:207], v[88:91]
	v_mfma_f32_16x16x32_bf16 v[76:79], v[144:147], v[212:215], v[76:79]
	v_mfma_f32_16x16x32_bf16 v[72:75], v[162:165], v[212:215], v[72:75]
	v_mfma_f32_16x16x32_bf16 v[124:127], v[158:161], v[190:193], v[124:127]
	v_mfma_f32_16x16x32_bf16 v[120:123], v[166:169], v[190:193], v[120:123]
	v_mfma_f32_16x16x32_bf16 v[108:111], v[158:161], v[200:203], v[108:111]
	v_mfma_f32_16x16x32_bf16 v[104:107], v[166:169], v[200:203], v[104:107]
	v_mfma_f32_16x16x32_bf16 v[92:95], v[158:161], v[208:211], v[92:95]
	v_mfma_f32_16x16x32_bf16 v[88:91], v[166:169], v[208:211], v[88:91]
	v_mfma_f32_16x16x32_bf16 v[76:79], v[158:161], v[216:219], v[76:79]
	v_mfma_f32_16x16x32_bf16 v[72:75], v[166:169], v[216:219], v[72:75]
	s_setprio 0
	s_setprio 1
	v_mfma_f32_16x16x32_bf16 v[116:119], v[170:173], v[186:189], v[116:119]
	v_mfma_f32_16x16x32_bf16 v[112:115], v[178:181], v[186:189], v[112:115]
	v_mfma_f32_16x16x32_bf16 v[100:103], v[170:173], v[196:199], v[100:103]
	v_mfma_f32_16x16x32_bf16 v[96:99], v[178:181], v[196:199], v[96:99]
	v_mfma_f32_16x16x32_bf16 v[84:87], v[170:173], v[204:207], v[84:87]
	v_mfma_f32_16x16x32_bf16 v[80:83], v[178:181], v[204:207], v[80:83]
	v_mfma_f32_16x16x32_bf16 v[68:71], v[170:173], v[212:215], v[68:71]
	v_mfma_f32_16x16x32_bf16 v[64:67], v[178:181], v[212:215], v[64:67]
	v_mfma_f32_16x16x32_bf16 v[116:119], v[174:177], v[190:193], v[116:119]
	v_mfma_f32_16x16x32_bf16 v[112:115], v[182:185], v[190:193], v[112:115]
	v_mfma_f32_16x16x32_bf16 v[100:103], v[174:177], v[200:203], v[100:103]
	v_mfma_f32_16x16x32_bf16 v[96:99], v[182:185], v[200:203], v[96:99]
	v_mfma_f32_16x16x32_bf16 v[84:87], v[174:177], v[208:211], v[84:87]
	v_mfma_f32_16x16x32_bf16 v[80:83], v[182:185], v[208:211], v[80:83]
	v_mfma_f32_16x16x32_bf16 v[68:71], v[174:177], v[216:219], v[68:71]
	v_mfma_f32_16x16x32_bf16 v[64:67], v[182:185], v[216:219], v[64:67]
	s_setprio 0
	s_barrier
	s_add_i32 s38, s77, s49
	s_add_i32 m0, s38, 0xffffff80
	ds_read_b128 v[186:189], v155 offset:49152
	ds_read_b128 v[190:193], v155 offset:50176
	ds_read_b128 v[196:199], v155 offset:51200
	ds_read_b128 v[200:203], v155 offset:52224
	ds_read_b128 v[204:207], v155 offset:53248
	ds_read_b128 v[208:211], v155 offset:54272
	ds_read_b128 v[212:215], v155 offset:55296
	ds_read_b128 v[216:219], v155 offset:56320
	global_load_lds_dwordx4 v130, s[36:37] offset:128
	s_add_i32 m0, s38, 0x1f80
	s_add_i32 s38, s78, s49
	global_load_lds_dwordx4 v134, s[36:37] offset:128
	s_add_u32 s36, s36, 0x40080
	s_addc_u32 s37, s37, 0
	s_mov_b32 m0, s38
	s_nop 0
	global_load_lds_dwordx4 v130, s[36:37]
	s_add_i32 m0, s38, 0x2000
	s_nop 0
	global_load_lds_dwordx4 v134, s[36:37]
	s_waitcnt vmcnt(6)
	s_waitcnt lgkmcnt(0)
	s_barrier
	s_setprio 1
	s_waitcnt lgkmcnt(0)
	v_mfma_f32_16x16x32_bf16 v[60:63], v[144:147], v[186:189], v[60:63]
	v_mfma_f32_16x16x32_bf16 v[56:59], v[162:165], v[186:189], v[56:59]
	v_mfma_f32_16x16x32_bf16 v[44:47], v[144:147], v[196:199], v[44:47]
	v_mfma_f32_16x16x32_bf16 v[40:43], v[162:165], v[196:199], v[40:43]
	v_mfma_f32_16x16x32_bf16 v[28:31], v[144:147], v[204:207], v[28:31]
	v_mfma_f32_16x16x32_bf16 v[24:27], v[162:165], v[204:207], v[24:27]
	v_mfma_f32_16x16x32_bf16 v[12:15], v[144:147], v[212:215], v[12:15]
	v_mfma_f32_16x16x32_bf16 v[8:11], v[162:165], v[212:215], v[8:11]
	v_mfma_f32_16x16x32_bf16 v[60:63], v[158:161], v[190:193], v[60:63]
	v_mfma_f32_16x16x32_bf16 v[56:59], v[166:169], v[190:193], v[56:59]
	v_mfma_f32_16x16x32_bf16 v[44:47], v[158:161], v[200:203], v[44:47]
	v_mfma_f32_16x16x32_bf16 v[40:43], v[166:169], v[200:203], v[40:43]
	v_mfma_f32_16x16x32_bf16 v[28:31], v[158:161], v[208:211], v[28:31]
	v_mfma_f32_16x16x32_bf16 v[24:27], v[166:169], v[208:211], v[24:27]
	v_mfma_f32_16x16x32_bf16 v[12:15], v[158:161], v[216:219], v[12:15]
	v_mfma_f32_16x16x32_bf16 v[8:11], v[166:169], v[216:219], v[8:11]
	s_setprio 0
	s_setprio 1
	v_mfma_f32_16x16x32_bf16 v[52:55], v[170:173], v[186:189], v[52:55]
	v_mfma_f32_16x16x32_bf16 v[48:51], v[178:181], v[186:189], v[48:51]
	v_mfma_f32_16x16x32_bf16 v[36:39], v[170:173], v[196:199], v[36:39]
	v_mfma_f32_16x16x32_bf16 v[32:35], v[178:181], v[196:199], v[32:35]
	v_mfma_f32_16x16x32_bf16 v[20:23], v[170:173], v[204:207], v[20:23]
	v_mfma_f32_16x16x32_bf16 v[16:19], v[178:181], v[204:207], v[16:19]
	v_mfma_f32_16x16x32_bf16 v[4:7], v[170:173], v[212:215], v[4:7]
	v_mfma_f32_16x16x32_bf16 v[0:3], v[178:181], v[212:215], v[0:3]
	v_mfma_f32_16x16x32_bf16 v[52:55], v[174:177], v[190:193], v[52:55]
	v_mfma_f32_16x16x32_bf16 v[48:51], v[182:185], v[190:193], v[48:51]
	v_mfma_f32_16x16x32_bf16 v[36:39], v[174:177], v[200:203], v[36:39]
	v_mfma_f32_16x16x32_bf16 v[32:35], v[182:185], v[200:203], v[32:35]
	v_mfma_f32_16x16x32_bf16 v[20:23], v[174:177], v[208:211], v[20:23]
	v_mfma_f32_16x16x32_bf16 v[16:19], v[182:185], v[208:211], v[16:19]
	v_mfma_f32_16x16x32_bf16 v[4:7], v[174:177], v[216:219], v[4:7]
	v_mfma_f32_16x16x32_bf16 v[0:3], v[182:185], v[216:219], v[0:3]
	s_setprio 0
	s_barrier
	s_add_i32 m0, s56, 0xffffff80
	s_nop 0
	global_load_lds_dwordx4 v128, s[98:99] offset:128
	s_add_i32 m0, s57, 0xffffff80
	s_nop 0
	global_load_lds_dwordx4 v132, s[98:99] offset:128
	s_add_i32 s73, s73, 2
	s_add_u32 s34, s34, 0x100
	s_addc_u32 s35, s35, 0
	s_add_u32 s71, s71, 0x100
	s_addc_u32 s72, s72, 0
	s_cmp_gt_u32 s73, 13
	s_cbranch_scc0 .LBB0_2557
	s_and_b64 vcc, exec, s[22:23]
	s_cbranch_vccz .LBB0_2560
	s_barrier

.LBB0_2633:
	ds_read_b128 v[144:147], v153
	ds_read_b128 v[156:159], v153 offset:1024
	ds_read_b128 v[160:163], v153 offset:2048
	ds_read_b128 v[164:167], v153 offset:3072
	ds_read_b128 v[168:171], v154
	ds_read_b128 v[172:175], v154 offset:1024
	ds_read_b128 v[176:179], v154 offset:2048
	ds_read_b128 v[180:183], v154 offset:3072
	s_add_u32 s42, s40, 0xfffe0080
	s_addc_u32 s43, s41, -1
	s_cmp_eq_u32 s73, 4
	s_cselect_b32 s45, s31, s43
	s_cselect_b32 s44, s63, s42
	s_cselect_b32 s43, s29, s72
	s_cselect_b32 s42, s70, s71
	s_add_i32 m0, s39, 0xc000
	ds_read_b128 v[184:187], v155
	ds_read_b128 v[188:191], v155 offset:1024
	ds_read_b128 v[196:199], v155 offset:2048
	ds_read_b128 v[200:203], v155 offset:3072
	ds_read_b128 v[204:207], v155 offset:4096
	ds_read_b128 v[208:211], v155 offset:5120
	ds_read_b128 v[212:215], v155 offset:6144
	ds_read_b128 v[216:219], v155 offset:7168
	global_load_lds_dwordx4 v136, s[40:41]
	s_add_i32 m0, s39, 0xe000
	s_nop 0
	global_load_lds_dwordx4 v138, s[40:41]
	s_waitcnt vmcnt(8)
	s_waitcnt lgkmcnt(0)
	s_barrier
	s_setprio 1
	s_waitcnt lgkmcnt(0)
	v_mfma_f32_16x16x32_bf16 v[124:127], v[144:147], v[184:187], v[124:127]
	v_mfma_f32_16x16x32_bf16 v[120:123], v[160:163], v[184:187], v[120:123]
	v_mfma_f32_16x16x32_bf16 v[108:111], v[144:147], v[196:199], v[108:111]
	v_mfma_f32_16x16x32_bf16 v[104:107], v[160:163], v[196:199], v[104:107]
	v_mfma_f32_16x16x32_bf16 v[92:95], v[144:147], v[204:207], v[92:95]
	v_mfma_f32_16x16x32_bf16 v[88:91], v[160:163], v[204:207], v[88:91]
	v_mfma_f32_16x16x32_bf16 v[76:79], v[144:147], v[212:215], v[76:79]
	v_mfma_f32_16x16x32_bf16 v[72:75], v[160:163], v[212:215], v[72:75]
	v_mfma_f32_16x16x32_bf16 v[124:127], v[156:159], v[188:191], v[124:127]
	v_mfma_f32_16x16x32_bf16 v[120:123], v[164:167], v[188:191], v[120:123]
	v_mfma_f32_16x16x32_bf16 v[108:111], v[156:159], v[200:203], v[108:111]
	v_mfma_f32_16x16x32_bf16 v[104:107], v[164:167], v[200:203], v[104:107]
	v_mfma_f32_16x16x32_bf16 v[92:95], v[156:159], v[208:211], v[92:95]
	v_mfma_f32_16x16x32_bf16 v[88:91], v[164:167], v[208:211], v[88:91]
	v_mfma_f32_16x16x32_bf16 v[76:79], v[156:159], v[216:219], v[76:79]
	v_mfma_f32_16x16x32_bf16 v[72:75], v[164:167], v[216:219], v[72:75]
	s_setprio 0
	s_setprio 1
	v_mfma_f32_16x16x32_bf16 v[116:119], v[168:171], v[184:187], v[116:119]
	v_mfma_f32_16x16x32_bf16 v[112:115], v[176:179], v[184:187], v[112:115]
	v_mfma_f32_16x16x32_bf16 v[100:103], v[168:171], v[196:199], v[100:103]
	v_mfma_f32_16x16x32_bf16 v[96:99], v[176:179], v[196:199], v[96:99]
	v_mfma_f32_16x16x32_bf16 v[84:87], v[168:171], v[204:207], v[84:87]
	v_mfma_f32_16x16x32_bf16 v[80:83], v[176:179], v[204:207], v[80:83]
	v_mfma_f32_16x16x32_bf16 v[68:71], v[168:171], v[212:215], v[68:71]
	v_mfma_f32_16x16x32_bf16 v[64:67], v[176:179], v[212:215], v[64:67]
	v_mfma_f32_16x16x32_bf16 v[116:119], v[172:175], v[188:191], v[116:119]
	v_mfma_f32_16x16x32_bf16 v[112:115], v[180:183], v[188:191], v[112:115]
	v_mfma_f32_16x16x32_bf16 v[100:103], v[172:175], v[200:203], v[100:103]
	v_mfma_f32_16x16x32_bf16 v[96:99], v[180:183], v[200:203], v[96:99]
	v_mfma_f32_16x16x32_bf16 v[84:87], v[172:175], v[208:211], v[84:87]
	v_mfma_f32_16x16x32_bf16 v[80:83], v[180:183], v[208:211], v[80:83]
	v_mfma_f32_16x16x32_bf16 v[68:71], v[172:175], v[216:219], v[68:71]
	v_mfma_f32_16x16x32_bf16 v[64:67], v[180:183], v[216:219], v[64:67]
	s_setprio 0
	s_barrier
	s_add_i32 s77, s60, s52
	s_mov_b32 m0, s77
	ds_read_b128 v[184:187], v155 offset:16384
	ds_read_b128 v[188:191], v155 offset:17408
	ds_read_b128 v[196:199], v155 offset:18432
	ds_read_b128 v[200:203], v155 offset:19456
	ds_read_b128 v[204:207], v155 offset:20480
	ds_read_b128 v[208:211], v155 offset:21504
	ds_read_b128 v[212:215], v155 offset:22528
	ds_read_b128 v[216:219], v155 offset:23552
	global_load_lds_dwordx4 v130, s[42:43]
	s_add_i32 m0, s77, 0x2000
	s_add_u32 s78, s42, 0x20000
	s_addc_u32 s79, s43, 0
	s_add_i32 s77, s61, s52
	global_load_lds_dwordx4 v134, s[42:43]
	s_mov_b32 m0, s77
	s_mov_b64 s[98:99], s[44:45]
	global_load_lds_dwordx4 v130, s[78:79]
	s_add_i32 m0, s77, 0x2000
	s_nop 0
	global_load_lds_dwordx4 v134, s[78:79]
	s_waitcnt vmcnt(6)
	s_waitcnt lgkmcnt(0)
	s_barrier
	s_setprio 1
	s_waitcnt lgkmcnt(0)
	v_mfma_f32_16x16x32_bf16 v[60:63], v[144:147], v[184:187], v[60:63]
	v_mfma_f32_16x16x32_bf16 v[56:59], v[160:163], v[184:187], v[56:59]
	v_mfma_f32_16x16x32_bf16 v[44:47], v[144:147], v[196:199], v[44:47]
	v_mfma_f32_16x16x32_bf16 v[40:43], v[160:163], v[196:199], v[40:43]
	v_mfma_f32_16x16x32_bf16 v[28:31], v[144:147], v[204:207], v[28:31]
	v_mfma_f32_16x16x32_bf16 v[24:27], v[160:163], v[204:207], v[24:27]
	v_mfma_f32_16x16x32_bf16 v[12:15], v[144:147], v[212:215], v[12:15]
	v_mfma_f32_16x16x32_bf16 v[8:11], v[160:163], v[212:215], v[8:11]
	v_mfma_f32_16x16x32_bf16 v[60:63], v[156:159], v[188:191], v[60:63]
	v_mfma_f32_16x16x32_bf16 v[56:59], v[164:167], v[188:191], v[56:59]
	v_mfma_f32_16x16x32_bf16 v[44:47], v[156:159], v[200:203], v[44:47]
	v_mfma_f32_16x16x32_bf16 v[40:43], v[164:167], v[200:203], v[40:43]
	v_mfma_f32_16x16x32_bf16 v[28:31], v[156:159], v[208:211], v[28:31]
	v_mfma_f32_16x16x32_bf16 v[24:27], v[164:167], v[208:211], v[24:27]
	v_mfma_f32_16x16x32_bf16 v[12:15], v[156:159], v[216:219], v[12:15]
	v_mfma_f32_16x16x32_bf16 v[8:11], v[164:167], v[216:219], v[8:11]
	s_setprio 0
	s_setprio 1
	v_mfma_f32_16x16x32_bf16 v[52:55], v[168:171], v[184:187], v[52:55]
	v_mfma_f32_16x16x32_bf16 v[48:51], v[176:179], v[184:187], v[48:51]
	v_mfma_f32_16x16x32_bf16 v[36:39], v[168:171], v[196:199], v[36:39]
	v_mfma_f32_16x16x32_bf16 v[32:35], v[176:179], v[196:199], v[32:35]
	v_mfma_f32_16x16x32_bf16 v[20:23], v[168:171], v[204:207], v[20:23]
	v_mfma_f32_16x16x32_bf16 v[16:19], v[176:179], v[204:207], v[16:19]
	v_mfma_f32_16x16x32_bf16 v[4:7], v[168:171], v[212:215], v[4:7]
	v_mfma_f32_16x16x32_bf16 v[0:3], v[176:179], v[212:215], v[0:3]
	v_mfma_f32_16x16x32_bf16 v[52:55], v[172:175], v[188:191], v[52:55]
	v_mfma_f32_16x16x32_bf16 v[48:51], v[180:183], v[188:191], v[48:51]
	v_mfma_f32_16x16x32_bf16 v[36:39], v[172:175], v[200:203], v[36:39]
	v_mfma_f32_16x16x32_bf16 v[32:35], v[180:183], v[200:203], v[32:35]
	v_mfma_f32_16x16x32_bf16 v[20:23], v[172:175], v[208:211], v[20:23]
	v_mfma_f32_16x16x32_bf16 v[16:19], v[180:183], v[208:211], v[16:19]
	v_mfma_f32_16x16x32_bf16 v[4:7], v[172:175], v[216:219], v[4:7]
	v_mfma_f32_16x16x32_bf16 v[0:3], v[180:183], v[216:219], v[0:3]
	s_setprio 0
	s_barrier
	s_add_i32 s77, 0, 0x18000
	s_add_i32 s78, 0, 0x1c000
	v_add_u32_e32 v164, s77, v151
	v_add_u32_e32 v180, s78, v151
	ds_read_b128 v[144:147], v164
	ds_read_b128 v[156:159], v164 offset:1024
	ds_read_b128 v[160:163], v164 offset:2048
	ds_read_b128 v[164:167], v164 offset:3072
	ds_read_b128 v[168:171], v180
	ds_read_b128 v[172:175], v180 offset:1024
	ds_read_b128 v[176:179], v180 offset:2048
	ds_read_b128 v[180:183], v180 offset:3072
	s_add_u32 s44, s44, 0x20000
	s_addc_u32 s45, s45, 0
	ds_read_b128 v[184:187], v155 offset:32768
	ds_read_b128 v[188:191], v155 offset:33792
	ds_read_b128 v[196:199], v155 offset:34816
	ds_read_b128 v[200:203], v155 offset:35840
	ds_read_b128 v[204:207], v155 offset:36864
	ds_read_b128 v[208:211], v155 offset:37888
	ds_read_b128 v[212:215], v155 offset:38912
	ds_read_b128 v[216:219], v155 offset:39936
	s_mov_b32 m0, s39
	s_nop 0
	global_load_lds_dwordx4 v128, s[98:99]
	s_mov_b32 m0, s53
	s_nop 0
	global_load_lds_dwordx4 v132, s[98:99]
	s_mov_b32 m0, s54
	s_nop 0
	global_load_lds_dwordx4 v128, s[44:45]
	s_mov_b32 m0, s55
	s_nop 0
	global_load_lds_dwordx4 v132, s[44:45]
	s_waitcnt vmcnt(8)
	s_waitcnt lgkmcnt(0)
	s_barrier
	s_setprio 1
	s_waitcnt lgkmcnt(0)
	v_mfma_f32_16x16x32_bf16 v[124:127], v[144:147], v[184:187], v[124:127]
	v_mfma_f32_16x16x32_bf16 v[120:123], v[160:163], v[184:187], v[120:123]
	v_mfma_f32_16x16x32_bf16 v[108:111], v[144:147], v[196:199], v[108:111]
	v_mfma_f32_16x16x32_bf16 v[104:107], v[160:163], v[196:199], v[104:107]
	v_mfma_f32_16x16x32_bf16 v[92:95], v[144:147], v[204:207], v[92:95]
	v_mfma_f32_16x16x32_bf16 v[88:91], v[160:163], v[204:207], v[88:91]
	v_mfma_f32_16x16x32_bf16 v[76:79], v[144:147], v[212:215], v[76:79]
	v_mfma_f32_16x16x32_bf16 v[72:75], v[160:163], v[212:215], v[72:75]
	v_mfma_f32_16x16x32_bf16 v[124:127], v[156:159], v[188:191], v[124:127]
	v_mfma_f32_16x16x32_bf16 v[120:123], v[164:167], v[188:191], v[120:123]
	v_mfma_f32_16x16x32_bf16 v[108:111], v[156:159], v[200:203], v[108:111]
	v_mfma_f32_16x16x32_bf16 v[104:107], v[164:167], v[200:203], v[104:107]
	v_mfma_f32_16x16x32_bf16 v[92:95], v[156:159], v[208:211], v[92:95]
	v_mfma_f32_16x16x32_bf16 v[88:91], v[164:167], v[208:211], v[88:91]
	v_mfma_f32_16x16x32_bf16 v[76:79], v[156:159], v[216:219], v[76:79]
	v_mfma_f32_16x16x32_bf16 v[72:75], v[164:167], v[216:219], v[72:75]
	s_setprio 0
	s_setprio 1
	v_mfma_f32_16x16x32_bf16 v[116:119], v[168:171], v[184:187], v[116:119]
	v_mfma_f32_16x16x32_bf16 v[112:115], v[176:179], v[184:187], v[112:115]
	v_mfma_f32_16x16x32_bf16 v[100:103], v[168:171], v[196:199], v[100:103]
	v_mfma_f32_16x16x32_bf16 v[96:99], v[176:179], v[196:199], v[96:99]
	v_mfma_f32_16x16x32_bf16 v[84:87], v[168:171], v[204:207], v[84:87]
	v_mfma_f32_16x16x32_bf16 v[80:83], v[176:179], v[204:207], v[80:83]
	v_mfma_f32_16x16x32_bf16 v[68:71], v[168:171], v[212:215], v[68:71]
	v_mfma_f32_16x16x32_bf16 v[64:67], v[176:179], v[212:215], v[64:67]
	v_mfma_f32_16x16x32_bf16 v[116:119], v[172:175], v[188:191], v[116:119]
	v_mfma_f32_16x16x32_bf16 v[112:115], v[180:183], v[188:191], v[112:115]
	v_mfma_f32_16x16x32_bf16 v[100:103], v[172:175], v[200:203], v[100:103]
	v_mfma_f32_16x16x32_bf16 v[96:99], v[180:183], v[200:203], v[96:99]
	v_mfma_f32_16x16x32_bf16 v[84:87], v[172:175], v[208:211], v[84:87]
	v_mfma_f32_16x16x32_bf16 v[80:83], v[180:183], v[208:211], v[80:83]
	v_mfma_f32_16x16x32_bf16 v[68:71], v[172:175], v[216:219], v[68:71]
	v_mfma_f32_16x16x32_bf16 v[64:67], v[180:183], v[216:219], v[64:67]
	s_setprio 0
	s_barrier
	s_add_i32 s44, s77, s52
	s_add_i32 m0, s44, 0xffffff80
	ds_read_b128 v[184:187], v155 offset:49152
	ds_read_b128 v[188:191], v155 offset:50176
	ds_read_b128 v[196:199], v155 offset:51200
	ds_read_b128 v[200:203], v155 offset:52224
	ds_read_b128 v[204:207], v155 offset:53248
	ds_read_b128 v[208:211], v155 offset:54272
	ds_read_b128 v[212:215], v155 offset:55296
	ds_read_b128 v[216:219], v155 offset:56320
	global_load_lds_dwordx4 v130, s[42:43] offset:128
	s_add_i32 m0, s44, 0x1f80
	s_add_i32 s44, s78, s52
	global_load_lds_dwordx4 v134, s[42:43] offset:128
	s_add_u32 s42, s42, 0x20080
	s_addc_u32 s43, s43, 0
	s_mov_b32 m0, s44
	s_nop 0
	global_load_lds_dwordx4 v130, s[42:43]
	s_add_i32 m0, s44, 0x2000
	s_nop 0
	global_load_lds_dwordx4 v134, s[42:43]
	s_waitcnt vmcnt(6)
	s_waitcnt lgkmcnt(0)
	s_barrier
	s_setprio 1
	s_waitcnt lgkmcnt(0)
	v_mfma_f32_16x16x32_bf16 v[60:63], v[144:147], v[184:187], v[60:63]
	v_mfma_f32_16x16x32_bf16 v[56:59], v[160:163], v[184:187], v[56:59]
	v_mfma_f32_16x16x32_bf16 v[44:47], v[144:147], v[196:199], v[44:47]
	v_mfma_f32_16x16x32_bf16 v[40:43], v[160:163], v[196:199], v[40:43]
	v_mfma_f32_16x16x32_bf16 v[28:31], v[144:147], v[204:207], v[28:31]
	v_mfma_f32_16x16x32_bf16 v[24:27], v[160:163], v[204:207], v[24:27]
	v_mfma_f32_16x16x32_bf16 v[12:15], v[144:147], v[212:215], v[12:15]
	v_mfma_f32_16x16x32_bf16 v[8:11], v[160:163], v[212:215], v[8:11]
	v_mfma_f32_16x16x32_bf16 v[60:63], v[156:159], v[188:191], v[60:63]
	v_mfma_f32_16x16x32_bf16 v[56:59], v[164:167], v[188:191], v[56:59]
	v_mfma_f32_16x16x32_bf16 v[44:47], v[156:159], v[200:203], v[44:47]
	v_mfma_f32_16x16x32_bf16 v[40:43], v[164:167], v[200:203], v[40:43]
	v_mfma_f32_16x16x32_bf16 v[28:31], v[156:159], v[208:211], v[28:31]
	v_mfma_f32_16x16x32_bf16 v[24:27], v[164:167], v[208:211], v[24:27]
	v_mfma_f32_16x16x32_bf16 v[12:15], v[156:159], v[216:219], v[12:15]
	v_mfma_f32_16x16x32_bf16 v[8:11], v[164:167], v[216:219], v[8:11]
	s_setprio 0
	s_setprio 1
	v_mfma_f32_16x16x32_bf16 v[52:55], v[168:171], v[184:187], v[52:55]
	v_mfma_f32_16x16x32_bf16 v[48:51], v[176:179], v[184:187], v[48:51]
	v_mfma_f32_16x16x32_bf16 v[36:39], v[168:171], v[196:199], v[36:39]
	v_mfma_f32_16x16x32_bf16 v[32:35], v[176:179], v[196:199], v[32:35]
	v_mfma_f32_16x16x32_bf16 v[20:23], v[168:171], v[204:207], v[20:23]
	v_mfma_f32_16x16x32_bf16 v[16:19], v[176:179], v[204:207], v[16:19]
	v_mfma_f32_16x16x32_bf16 v[4:7], v[168:171], v[212:215], v[4:7]
	v_mfma_f32_16x16x32_bf16 v[0:3], v[176:179], v[212:215], v[0:3]
	v_mfma_f32_16x16x32_bf16 v[52:55], v[172:175], v[188:191], v[52:55]
	v_mfma_f32_16x16x32_bf16 v[48:51], v[180:183], v[188:191], v[48:51]
	v_mfma_f32_16x16x32_bf16 v[36:39], v[172:175], v[200:203], v[36:39]
	v_mfma_f32_16x16x32_bf16 v[32:35], v[180:183], v[200:203], v[32:35]
	v_mfma_f32_16x16x32_bf16 v[20:23], v[172:175], v[208:211], v[20:23]
	v_mfma_f32_16x16x32_bf16 v[16:19], v[180:183], v[208:211], v[16:19]
	v_mfma_f32_16x16x32_bf16 v[4:7], v[172:175], v[216:219], v[4:7]
	v_mfma_f32_16x16x32_bf16 v[0:3], v[180:183], v[216:219], v[0:3]
	s_setprio 0
	s_barrier
	s_add_i32 m0, s57, 0xffffff80
	s_nop 0
	global_load_lds_dwordx4 v128, s[98:99] offset:128
	s_add_i32 m0, s58, 0xffffff80
	s_nop 0
	global_load_lds_dwordx4 v132, s[98:99] offset:128
	s_add_i32 s73, s73, 2
	s_add_u32 s40, s40, 0x100
	s_addc_u32 s41, s41, 0
	s_add_u32 s71, s71, 0x100
	s_addc_u32 s72, s72, 0
	s_cmp_gt_u32 s73, 5
	s_cbranch_scc0 .LBB0_2633
	s_and_b64 vcc, exec, s[20:21]
	s_cbranch_vccz .LBB0_2636
	s_barrier

.LBB0_2657:
	ds_read_b128 v[144:147], v153
	ds_read_b128 v[158:161], v153 offset:1024
	ds_read_b128 v[162:165], v153 offset:2048
	ds_read_b128 v[166:169], v153 offset:3072
	ds_read_b128 v[170:173], v154
	ds_read_b128 v[174:177], v154 offset:1024
	ds_read_b128 v[178:181], v154 offset:2048
	ds_read_b128 v[182:185], v154 offset:3072
	s_add_u32 s34, s30, 0xfffc0080
	s_addc_u32 s35, s31, -1
	s_cmp_eq_u32 s70, 12
	s_cselect_b32 s37, s25, s35
	s_cselect_b32 s36, s60, s34
	s_cselect_b32 s35, s23, s63
	s_cselect_b32 s34, s61, s62
	s_add_i32 m0, s48, 0xc000
	ds_read_b128 v[186:189], v155
	ds_read_b128 v[190:193], v155 offset:1024
	ds_read_b128 v[196:199], v155 offset:2048
	ds_read_b128 v[200:203], v155 offset:3072
	ds_read_b128 v[204:207], v155 offset:4096
	ds_read_b128 v[208:211], v155 offset:5120
	ds_read_b128 v[212:215], v155 offset:6144
	ds_read_b128 v[216:219], v155 offset:7168
	global_load_lds_dwordx4 v136, s[30:31]
	s_add_i32 m0, s48, 0xe000
	s_nop 0
	global_load_lds_dwordx4 v138, s[30:31]
	s_waitcnt vmcnt(8)
	s_waitcnt lgkmcnt(0)
	s_barrier
	s_setprio 1
	s_waitcnt lgkmcnt(0)
	v_mfma_f32_16x16x32_bf16 v[124:127], v[144:147], v[186:189], v[124:127]
	v_mfma_f32_16x16x32_bf16 v[120:123], v[162:165], v[186:189], v[120:123]
	v_mfma_f32_16x16x32_bf16 v[108:111], v[144:147], v[196:199], v[108:111]
	v_mfma_f32_16x16x32_bf16 v[104:107], v[162:165], v[196:199], v[104:107]
	v_mfma_f32_16x16x32_bf16 v[92:95], v[144:147], v[204:207], v[92:95]
	v_mfma_f32_16x16x32_bf16 v[88:91], v[162:165], v[204:207], v[88:91]
	v_mfma_f32_16x16x32_bf16 v[76:79], v[144:147], v[212:215], v[76:79]
	v_mfma_f32_16x16x32_bf16 v[72:75], v[162:165], v[212:215], v[72:75]
	v_mfma_f32_16x16x32_bf16 v[124:127], v[158:161], v[190:193], v[124:127]
	v_mfma_f32_16x16x32_bf16 v[120:123], v[166:169], v[190:193], v[120:123]
	v_mfma_f32_16x16x32_bf16 v[108:111], v[158:161], v[200:203], v[108:111]
	v_mfma_f32_16x16x32_bf16 v[104:107], v[166:169], v[200:203], v[104:107]
	v_mfma_f32_16x16x32_bf16 v[92:95], v[158:161], v[208:211], v[92:95]
	v_mfma_f32_16x16x32_bf16 v[88:91], v[166:169], v[208:211], v[88:91]
	v_mfma_f32_16x16x32_bf16 v[76:79], v[158:161], v[216:219], v[76:79]
	v_mfma_f32_16x16x32_bf16 v[72:75], v[166:169], v[216:219], v[72:75]
	s_setprio 0
	s_setprio 1
	v_mfma_f32_16x16x32_bf16 v[116:119], v[170:173], v[186:189], v[116:119]
	v_mfma_f32_16x16x32_bf16 v[112:115], v[178:181], v[186:189], v[112:115]
	v_mfma_f32_16x16x32_bf16 v[100:103], v[170:173], v[196:199], v[100:103]
	v_mfma_f32_16x16x32_bf16 v[96:99], v[178:181], v[196:199], v[96:99]
	v_mfma_f32_16x16x32_bf16 v[84:87], v[170:173], v[204:207], v[84:87]
	v_mfma_f32_16x16x32_bf16 v[80:83], v[178:181], v[204:207], v[80:83]
	v_mfma_f32_16x16x32_bf16 v[68:71], v[170:173], v[212:215], v[68:71]
	v_mfma_f32_16x16x32_bf16 v[64:67], v[178:181], v[212:215], v[64:67]
	v_mfma_f32_16x16x32_bf16 v[116:119], v[174:177], v[190:193], v[116:119]
	v_mfma_f32_16x16x32_bf16 v[112:115], v[182:185], v[190:193], v[112:115]
	v_mfma_f32_16x16x32_bf16 v[100:103], v[174:177], v[200:203], v[100:103]
	v_mfma_f32_16x16x32_bf16 v[96:99], v[182:185], v[200:203], v[96:99]
	v_mfma_f32_16x16x32_bf16 v[84:87], v[174:177], v[208:211], v[84:87]
	v_mfma_f32_16x16x32_bf16 v[80:83], v[182:185], v[208:211], v[80:83]
	v_mfma_f32_16x16x32_bf16 v[68:71], v[174:177], v[216:219], v[68:71]
	v_mfma_f32_16x16x32_bf16 v[64:67], v[182:185], v[216:219], v[64:67]
	s_setprio 0
	s_barrier
	s_add_i32 s71, s56, s45
	s_mov_b32 m0, s71
	ds_read_b128 v[186:189], v155 offset:16384
	ds_read_b128 v[190:193], v155 offset:17408
	ds_read_b128 v[196:199], v155 offset:18432
	ds_read_b128 v[200:203], v155 offset:19456
	ds_read_b128 v[204:207], v155 offset:20480
	ds_read_b128 v[208:211], v155 offset:21504
	ds_read_b128 v[212:215], v155 offset:22528
	ds_read_b128 v[216:219], v155 offset:23552
	global_load_lds_dwordx4 v130, s[34:35]
	s_add_i32 m0, s71, 0x2000
	s_add_u32 s72, s34, 0x40000
	s_addc_u32 s73, s35, 0
	s_add_i32 s71, s57, s45
	global_load_lds_dwordx4 v134, s[34:35]
	s_mov_b32 m0, s71
	s_mov_b64 s[98:99], s[36:37]
	global_load_lds_dwordx4 v130, s[72:73]
	s_add_i32 m0, s71, 0x2000
	s_nop 0
	global_load_lds_dwordx4 v134, s[72:73]
	s_waitcnt vmcnt(6)
	s_waitcnt lgkmcnt(0)
	s_barrier
	s_setprio 1
	s_waitcnt lgkmcnt(0)
	v_mfma_f32_16x16x32_bf16 v[60:63], v[144:147], v[186:189], v[60:63]
	v_mfma_f32_16x16x32_bf16 v[56:59], v[162:165], v[186:189], v[56:59]
	v_mfma_f32_16x16x32_bf16 v[44:47], v[144:147], v[196:199], v[44:47]
	v_mfma_f32_16x16x32_bf16 v[40:43], v[162:165], v[196:199], v[40:43]
	v_mfma_f32_16x16x32_bf16 v[28:31], v[144:147], v[204:207], v[28:31]
	v_mfma_f32_16x16x32_bf16 v[24:27], v[162:165], v[204:207], v[24:27]
	v_mfma_f32_16x16x32_bf16 v[12:15], v[144:147], v[212:215], v[12:15]
	v_mfma_f32_16x16x32_bf16 v[8:11], v[162:165], v[212:215], v[8:11]
	v_mfma_f32_16x16x32_bf16 v[60:63], v[158:161], v[190:193], v[60:63]
	v_mfma_f32_16x16x32_bf16 v[56:59], v[166:169], v[190:193], v[56:59]
	v_mfma_f32_16x16x32_bf16 v[44:47], v[158:161], v[200:203], v[44:47]
	v_mfma_f32_16x16x32_bf16 v[40:43], v[166:169], v[200:203], v[40:43]
	v_mfma_f32_16x16x32_bf16 v[28:31], v[158:161], v[208:211], v[28:31]
	v_mfma_f32_16x16x32_bf16 v[24:27], v[166:169], v[208:211], v[24:27]
	v_mfma_f32_16x16x32_bf16 v[12:15], v[158:161], v[216:219], v[12:15]
	v_mfma_f32_16x16x32_bf16 v[8:11], v[166:169], v[216:219], v[8:11]
	s_setprio 0
	s_setprio 1
	v_mfma_f32_16x16x32_bf16 v[52:55], v[170:173], v[186:189], v[52:55]
	v_mfma_f32_16x16x32_bf16 v[48:51], v[178:181], v[186:189], v[48:51]
	v_mfma_f32_16x16x32_bf16 v[36:39], v[170:173], v[196:199], v[36:39]
	v_mfma_f32_16x16x32_bf16 v[32:35], v[178:181], v[196:199], v[32:35]
	v_mfma_f32_16x16x32_bf16 v[20:23], v[170:173], v[204:207], v[20:23]
	v_mfma_f32_16x16x32_bf16 v[16:19], v[178:181], v[204:207], v[16:19]
	v_mfma_f32_16x16x32_bf16 v[4:7], v[170:173], v[212:215], v[4:7]
	v_mfma_f32_16x16x32_bf16 v[0:3], v[178:181], v[212:215], v[0:3]
	v_mfma_f32_16x16x32_bf16 v[52:55], v[174:177], v[190:193], v[52:55]
	v_mfma_f32_16x16x32_bf16 v[48:51], v[182:185], v[190:193], v[48:51]
	v_mfma_f32_16x16x32_bf16 v[36:39], v[174:177], v[200:203], v[36:39]
	v_mfma_f32_16x16x32_bf16 v[32:35], v[182:185], v[200:203], v[32:35]
	v_mfma_f32_16x16x32_bf16 v[20:23], v[174:177], v[208:211], v[20:23]
	v_mfma_f32_16x16x32_bf16 v[16:19], v[182:185], v[208:211], v[16:19]
	v_mfma_f32_16x16x32_bf16 v[4:7], v[174:177], v[216:219], v[4:7]
	v_mfma_f32_16x16x32_bf16 v[0:3], v[182:185], v[216:219], v[0:3]
	s_setprio 0
	s_barrier
	s_add_i32 s71, 0, 0x18000
	v_add_u32_e32 v157, s71, v151
	s_add_i32 s72, 0, 0x1c000
	ds_read_b128 v[144:147], v157
	ds_read_b128 v[158:161], v157 offset:1024
	ds_read_b128 v[162:165], v157 offset:2048
	ds_read_b128 v[166:169], v157 offset:3072
	v_add_u32_e32 v157, s72, v151
	ds_read_b128 v[170:173], v157
	ds_read_b128 v[174:177], v157 offset:1024
	ds_read_b128 v[178:181], v157 offset:2048
	ds_read_b128 v[182:185], v157 offset:3072
	s_add_u32 s36, s36, 0x40000
	s_addc_u32 s37, s37, 0
	ds_read_b128 v[186:189], v155 offset:32768
	ds_read_b128 v[190:193], v155 offset:33792
	ds_read_b128 v[196:199], v155 offset:34816
	ds_read_b128 v[200:203], v155 offset:35840
	ds_read_b128 v[204:207], v155 offset:36864
	ds_read_b128 v[208:211], v155 offset:37888
	ds_read_b128 v[212:215], v155 offset:38912
	ds_read_b128 v[216:219], v155 offset:39936
	s_mov_b32 m0, s48
	s_nop 0
	global_load_lds_dwordx4 v128, s[98:99]
	s_mov_b32 m0, s49
	s_nop 0
	global_load_lds_dwordx4 v132, s[98:99]
	s_mov_b32 m0, s50
	s_nop 0
	global_load_lds_dwordx4 v128, s[36:37]
	s_mov_b32 m0, s51
	s_nop 0
	global_load_lds_dwordx4 v132, s[36:37]
	s_waitcnt vmcnt(8)
	s_waitcnt lgkmcnt(0)
	s_barrier
	s_setprio 1
	s_waitcnt lgkmcnt(0)
	v_mfma_f32_16x16x32_bf16 v[124:127], v[144:147], v[186:189], v[124:127]
	v_mfma_f32_16x16x32_bf16 v[120:123], v[162:165], v[186:189], v[120:123]
	v_mfma_f32_16x16x32_bf16 v[108:111], v[144:147], v[196:199], v[108:111]
	v_mfma_f32_16x16x32_bf16 v[104:107], v[162:165], v[196:199], v[104:107]
	v_mfma_f32_16x16x32_bf16 v[92:95], v[144:147], v[204:207], v[92:95]
	v_mfma_f32_16x16x32_bf16 v[88:91], v[162:165], v[204:207], v[88:91]
	v_mfma_f32_16x16x32_bf16 v[76:79], v[144:147], v[212:215], v[76:79]
	v_mfma_f32_16x16x32_bf16 v[72:75], v[162:165], v[212:215], v[72:75]
	v_mfma_f32_16x16x32_bf16 v[124:127], v[158:161], v[190:193], v[124:127]
	v_mfma_f32_16x16x32_bf16 v[120:123], v[166:169], v[190:193], v[120:123]
	v_mfma_f32_16x16x32_bf16 v[108:111], v[158:161], v[200:203], v[108:111]
	v_mfma_f32_16x16x32_bf16 v[104:107], v[166:169], v[200:203], v[104:107]
	v_mfma_f32_16x16x32_bf16 v[92:95], v[158:161], v[208:211], v[92:95]
	v_mfma_f32_16x16x32_bf16 v[88:91], v[166:169], v[208:211], v[88:91]
	v_mfma_f32_16x16x32_bf16 v[76:79], v[158:161], v[216:219], v[76:79]
	v_mfma_f32_16x16x32_bf16 v[72:75], v[166:169], v[216:219], v[72:75]
	s_setprio 0
	s_setprio 1
	v_mfma_f32_16x16x32_bf16 v[116:119], v[170:173], v[186:189], v[116:119]
	v_mfma_f32_16x16x32_bf16 v[112:115], v[178:181], v[186:189], v[112:115]
	v_mfma_f32_16x16x32_bf16 v[100:103], v[170:173], v[196:199], v[100:103]
	v_mfma_f32_16x16x32_bf16 v[96:99], v[178:181], v[196:199], v[96:99]
	v_mfma_f32_16x16x32_bf16 v[84:87], v[170:173], v[204:207], v[84:87]
	v_mfma_f32_16x16x32_bf16 v[80:83], v[178:181], v[204:207], v[80:83]
	v_mfma_f32_16x16x32_bf16 v[68:71], v[170:173], v[212:215], v[68:71]
	v_mfma_f32_16x16x32_bf16 v[64:67], v[178:181], v[212:215], v[64:67]
	v_mfma_f32_16x16x32_bf16 v[116:119], v[174:177], v[190:193], v[116:119]
	v_mfma_f32_16x16x32_bf16 v[112:115], v[182:185], v[190:193], v[112:115]
	v_mfma_f32_16x16x32_bf16 v[100:103], v[174:177], v[200:203], v[100:103]
	v_mfma_f32_16x16x32_bf16 v[96:99], v[182:185], v[200:203], v[96:99]
	v_mfma_f32_16x16x32_bf16 v[84:87], v[174:177], v[208:211], v[84:87]
	v_mfma_f32_16x16x32_bf16 v[80:83], v[182:185], v[208:211], v[80:83]
	v_mfma_f32_16x16x32_bf16 v[68:71], v[174:177], v[216:219], v[68:71]
	v_mfma_f32_16x16x32_bf16 v[64:67], v[182:185], v[216:219], v[64:67]
	s_setprio 0
	s_barrier
	s_add_i32 s36, s71, s45
	s_add_i32 m0, s36, 0xffffff80
	ds_read_b128 v[186:189], v155 offset:49152
	ds_read_b128 v[190:193], v155 offset:50176
	ds_read_b128 v[196:199], v155 offset:51200
	ds_read_b128 v[200:203], v155 offset:52224
	ds_read_b128 v[204:207], v155 offset:53248
	ds_read_b128 v[208:211], v155 offset:54272
	ds_read_b128 v[212:215], v155 offset:55296
	ds_read_b128 v[216:219], v155 offset:56320
	global_load_lds_dwordx4 v130, s[34:35] offset:128
	s_add_i32 m0, s36, 0x1f80
	s_add_i32 s36, s72, s45
	global_load_lds_dwordx4 v134, s[34:35] offset:128
	s_add_u32 s34, s34, 0x40080
	s_addc_u32 s35, s35, 0
	s_mov_b32 m0, s36
	s_nop 0
	global_load_lds_dwordx4 v130, s[34:35]
	s_add_i32 m0, s36, 0x2000
	s_nop 0
	global_load_lds_dwordx4 v134, s[34:35]
	s_waitcnt vmcnt(6)
	s_waitcnt lgkmcnt(0)
	s_barrier
	s_setprio 1
	s_waitcnt lgkmcnt(0)
	v_mfma_f32_16x16x32_bf16 v[60:63], v[144:147], v[186:189], v[60:63]
	v_mfma_f32_16x16x32_bf16 v[56:59], v[162:165], v[186:189], v[56:59]
	v_mfma_f32_16x16x32_bf16 v[44:47], v[144:147], v[196:199], v[44:47]
	v_mfma_f32_16x16x32_bf16 v[40:43], v[162:165], v[196:199], v[40:43]
	v_mfma_f32_16x16x32_bf16 v[28:31], v[144:147], v[204:207], v[28:31]
	v_mfma_f32_16x16x32_bf16 v[24:27], v[162:165], v[204:207], v[24:27]
	v_mfma_f32_16x16x32_bf16 v[12:15], v[144:147], v[212:215], v[12:15]
	v_mfma_f32_16x16x32_bf16 v[8:11], v[162:165], v[212:215], v[8:11]
	v_mfma_f32_16x16x32_bf16 v[60:63], v[158:161], v[190:193], v[60:63]
	v_mfma_f32_16x16x32_bf16 v[56:59], v[166:169], v[190:193], v[56:59]
	v_mfma_f32_16x16x32_bf16 v[44:47], v[158:161], v[200:203], v[44:47]
	v_mfma_f32_16x16x32_bf16 v[40:43], v[166:169], v[200:203], v[40:43]
	v_mfma_f32_16x16x32_bf16 v[28:31], v[158:161], v[208:211], v[28:31]
	v_mfma_f32_16x16x32_bf16 v[24:27], v[166:169], v[208:211], v[24:27]
	v_mfma_f32_16x16x32_bf16 v[12:15], v[158:161], v[216:219], v[12:15]
	v_mfma_f32_16x16x32_bf16 v[8:11], v[166:169], v[216:219], v[8:11]
	s_setprio 0
	s_setprio 1
	v_mfma_f32_16x16x32_bf16 v[52:55], v[170:173], v[186:189], v[52:55]
	v_mfma_f32_16x16x32_bf16 v[48:51], v[178:181], v[186:189], v[48:51]
	v_mfma_f32_16x16x32_bf16 v[36:39], v[170:173], v[196:199], v[36:39]
	v_mfma_f32_16x16x32_bf16 v[32:35], v[178:181], v[196:199], v[32:35]
	v_mfma_f32_16x16x32_bf16 v[20:23], v[170:173], v[204:207], v[20:23]
	v_mfma_f32_16x16x32_bf16 v[16:19], v[178:181], v[204:207], v[16:19]
	v_mfma_f32_16x16x32_bf16 v[4:7], v[170:173], v[212:215], v[4:7]
	v_mfma_f32_16x16x32_bf16 v[0:3], v[178:181], v[212:215], v[0:3]
	v_mfma_f32_16x16x32_bf16 v[52:55], v[174:177], v[190:193], v[52:55]
	v_mfma_f32_16x16x32_bf16 v[48:51], v[182:185], v[190:193], v[48:51]
	v_mfma_f32_16x16x32_bf16 v[36:39], v[174:177], v[200:203], v[36:39]
	v_mfma_f32_16x16x32_bf16 v[32:35], v[182:185], v[200:203], v[32:35]
	v_mfma_f32_16x16x32_bf16 v[20:23], v[174:177], v[208:211], v[20:23]
	v_mfma_f32_16x16x32_bf16 v[16:19], v[182:185], v[208:211], v[16:19]
	v_mfma_f32_16x16x32_bf16 v[4:7], v[174:177], v[216:219], v[4:7]
	v_mfma_f32_16x16x32_bf16 v[0:3], v[182:185], v[216:219], v[0:3]
	s_setprio 0
	s_barrier
	s_add_i32 m0, s53, 0xffffff80
	s_nop 0
	global_load_lds_dwordx4 v128, s[98:99] offset:128
	s_add_i32 m0, s54, 0xffffff80
	s_nop 0
	global_load_lds_dwordx4 v132, s[98:99] offset:128
	s_add_i32 s70, s70, 2
	s_add_u32 s30, s30, 0x100
	s_addc_u32 s31, s31, 0
	s_add_u32 s62, s62, 0x100
	s_addc_u32 s63, s63, 0
	s_cmp_gt_u32 s70, 13
	s_cbranch_scc0 .LBB0_2657
	s_and_b64 vcc, exec, s[20:21]
	s_cbranch_vccz .LBB0_2660
	s_barrier

.LBB0_3031:
	ds_read_b128 v[146:149], v155
	ds_read_b128 v[160:163], v155 offset:1024
	ds_read_b128 v[164:167], v155 offset:2048
	ds_read_b128 v[168:171], v155 offset:3072
	ds_read_b128 v[172:175], v156
	ds_read_b128 v[176:179], v156 offset:1024
	ds_read_b128 v[180:183], v156 offset:2048
	ds_read_b128 v[184:187], v156 offset:3072
	s_add_u32 s36, s0, 0xfffc0080
	s_addc_u32 s37, s1, -1
	s_cmp_eq_u32 s60, 12
	s_cselect_b32 s39, s21, s37
	s_cselect_b32 s38, s23, s36
	s_cselect_b32 s37, s27, s59
	s_cselect_b32 s36, s26, s25
	s_add_i32 m0, s35, 0xc000
	ds_read_b128 v[188:191], v157
	ds_read_b128 v[196:199], v157 offset:1024
	ds_read_b128 v[200:203], v157 offset:2048
	ds_read_b128 v[204:207], v157 offset:3072
	ds_read_b128 v[208:211], v157 offset:4096
	ds_read_b128 v[212:215], v157 offset:5120
	ds_read_b128 v[216:219], v157 offset:6144
	ds_read_b128 v[220:223], v157 offset:7168
	global_load_lds_dwordx4 v138, s[0:1]
	s_add_i32 m0, s35, 0xe000
	s_nop 0
	global_load_lds_dwordx4 v140, s[0:1]
	s_waitcnt vmcnt(8)
	s_waitcnt lgkmcnt(0)
	s_barrier
	s_setprio 1
	s_waitcnt lgkmcnt(0)
	v_mfma_f32_16x16x32_bf16 v[124:127], v[146:149], v[188:191], v[124:127]
	v_mfma_f32_16x16x32_bf16 v[120:123], v[164:167], v[188:191], v[120:123]
	v_mfma_f32_16x16x32_bf16 v[108:111], v[146:149], v[200:203], v[108:111]
	v_mfma_f32_16x16x32_bf16 v[104:107], v[164:167], v[200:203], v[104:107]
	v_mfma_f32_16x16x32_bf16 v[92:95], v[146:149], v[208:211], v[92:95]
	v_mfma_f32_16x16x32_bf16 v[88:91], v[164:167], v[208:211], v[88:91]
	v_mfma_f32_16x16x32_bf16 v[76:79], v[146:149], v[216:219], v[76:79]
	v_mfma_f32_16x16x32_bf16 v[72:75], v[164:167], v[216:219], v[72:75]
	v_mfma_f32_16x16x32_bf16 v[124:127], v[160:163], v[196:199], v[124:127]
	v_mfma_f32_16x16x32_bf16 v[120:123], v[168:171], v[196:199], v[120:123]
	v_mfma_f32_16x16x32_bf16 v[108:111], v[160:163], v[204:207], v[108:111]
	v_mfma_f32_16x16x32_bf16 v[104:107], v[168:171], v[204:207], v[104:107]
	v_mfma_f32_16x16x32_bf16 v[92:95], v[160:163], v[212:215], v[92:95]
	v_mfma_f32_16x16x32_bf16 v[88:91], v[168:171], v[212:215], v[88:91]
	v_mfma_f32_16x16x32_bf16 v[76:79], v[160:163], v[220:223], v[76:79]
	v_mfma_f32_16x16x32_bf16 v[72:75], v[168:171], v[220:223], v[72:75]
	s_setprio 0
	s_setprio 1
	v_mfma_f32_16x16x32_bf16 v[116:119], v[172:175], v[188:191], v[116:119]
	v_mfma_f32_16x16x32_bf16 v[112:115], v[180:183], v[188:191], v[112:115]
	v_mfma_f32_16x16x32_bf16 v[100:103], v[172:175], v[200:203], v[100:103]
	v_mfma_f32_16x16x32_bf16 v[96:99], v[180:183], v[200:203], v[96:99]
	v_mfma_f32_16x16x32_bf16 v[84:87], v[172:175], v[208:211], v[84:87]
	v_mfma_f32_16x16x32_bf16 v[80:83], v[180:183], v[208:211], v[80:83]
	v_mfma_f32_16x16x32_bf16 v[68:71], v[172:175], v[216:219], v[68:71]
	v_mfma_f32_16x16x32_bf16 v[64:67], v[180:183], v[216:219], v[64:67]
	v_mfma_f32_16x16x32_bf16 v[116:119], v[176:179], v[196:199], v[116:119]
	v_mfma_f32_16x16x32_bf16 v[112:115], v[184:187], v[196:199], v[112:115]
	v_mfma_f32_16x16x32_bf16 v[100:103], v[176:179], v[204:207], v[100:103]
	v_mfma_f32_16x16x32_bf16 v[96:99], v[184:187], v[204:207], v[96:99]
	v_mfma_f32_16x16x32_bf16 v[84:87], v[176:179], v[212:215], v[84:87]
	v_mfma_f32_16x16x32_bf16 v[80:83], v[184:187], v[212:215], v[80:83]
	v_mfma_f32_16x16x32_bf16 v[68:71], v[176:179], v[220:223], v[68:71]
	v_mfma_f32_16x16x32_bf16 v[64:67], v[184:187], v[220:223], v[64:67]
	s_setprio 0
	s_barrier
	s_add_i32 s61, s55, s44
	s_mov_b32 m0, s61
	ds_read_b128 v[188:191], v157 offset:16384
	ds_read_b128 v[196:199], v157 offset:17408
	ds_read_b128 v[200:203], v157 offset:18432
	ds_read_b128 v[204:207], v157 offset:19456
	ds_read_b128 v[208:211], v157 offset:20480
	ds_read_b128 v[212:215], v157 offset:21504
	ds_read_b128 v[216:219], v157 offset:22528
	ds_read_b128 v[220:223], v157 offset:23552
	global_load_lds_dwordx4 v130, s[36:37]
	s_add_i32 m0, s61, 0x2000
	s_add_u32 s62, s36, 0x40000
	s_addc_u32 s63, s37, 0
	s_add_i32 s61, s56, s44
	global_load_lds_dwordx4 v134, s[36:37]
	s_mov_b32 m0, s61
	s_mov_b64 s[98:99], s[38:39]
	global_load_lds_dwordx4 v130, s[62:63]
	s_add_i32 m0, s61, 0x2000
	s_nop 0
	global_load_lds_dwordx4 v134, s[62:63]
	s_waitcnt vmcnt(6)
	s_waitcnt lgkmcnt(0)
	s_barrier
	s_setprio 1
	s_waitcnt lgkmcnt(0)
	v_mfma_f32_16x16x32_bf16 v[60:63], v[146:149], v[188:191], v[60:63]
	v_mfma_f32_16x16x32_bf16 v[56:59], v[164:167], v[188:191], v[56:59]
	v_mfma_f32_16x16x32_bf16 v[44:47], v[146:149], v[200:203], v[44:47]
	v_mfma_f32_16x16x32_bf16 v[40:43], v[164:167], v[200:203], v[40:43]
	v_mfma_f32_16x16x32_bf16 v[28:31], v[146:149], v[208:211], v[28:31]
	v_mfma_f32_16x16x32_bf16 v[24:27], v[164:167], v[208:211], v[24:27]
	v_mfma_f32_16x16x32_bf16 v[12:15], v[146:149], v[216:219], v[12:15]
	v_mfma_f32_16x16x32_bf16 v[8:11], v[164:167], v[216:219], v[8:11]
	v_mfma_f32_16x16x32_bf16 v[60:63], v[160:163], v[196:199], v[60:63]
	v_mfma_f32_16x16x32_bf16 v[56:59], v[168:171], v[196:199], v[56:59]
	v_mfma_f32_16x16x32_bf16 v[44:47], v[160:163], v[204:207], v[44:47]
	v_mfma_f32_16x16x32_bf16 v[40:43], v[168:171], v[204:207], v[40:43]
	v_mfma_f32_16x16x32_bf16 v[28:31], v[160:163], v[212:215], v[28:31]
	v_mfma_f32_16x16x32_bf16 v[24:27], v[168:171], v[212:215], v[24:27]
	v_mfma_f32_16x16x32_bf16 v[12:15], v[160:163], v[220:223], v[12:15]
	v_mfma_f32_16x16x32_bf16 v[8:11], v[168:171], v[220:223], v[8:11]
	s_setprio 0
	s_setprio 1
	v_mfma_f32_16x16x32_bf16 v[52:55], v[172:175], v[188:191], v[52:55]
	v_mfma_f32_16x16x32_bf16 v[48:51], v[180:183], v[188:191], v[48:51]
	v_mfma_f32_16x16x32_bf16 v[36:39], v[172:175], v[200:203], v[36:39]
	v_mfma_f32_16x16x32_bf16 v[32:35], v[180:183], v[200:203], v[32:35]
	v_mfma_f32_16x16x32_bf16 v[20:23], v[172:175], v[208:211], v[20:23]
	v_mfma_f32_16x16x32_bf16 v[16:19], v[180:183], v[208:211], v[16:19]
	v_mfma_f32_16x16x32_bf16 v[4:7], v[172:175], v[216:219], v[4:7]
	v_mfma_f32_16x16x32_bf16 v[0:3], v[180:183], v[216:219], v[0:3]
	v_mfma_f32_16x16x32_bf16 v[52:55], v[176:179], v[196:199], v[52:55]
	v_mfma_f32_16x16x32_bf16 v[48:51], v[184:187], v[196:199], v[48:51]
	v_mfma_f32_16x16x32_bf16 v[36:39], v[176:179], v[204:207], v[36:39]
	v_mfma_f32_16x16x32_bf16 v[32:35], v[184:187], v[204:207], v[32:35]
	v_mfma_f32_16x16x32_bf16 v[20:23], v[176:179], v[212:215], v[20:23]
	v_mfma_f32_16x16x32_bf16 v[16:19], v[184:187], v[212:215], v[16:19]
	v_mfma_f32_16x16x32_bf16 v[4:7], v[176:179], v[220:223], v[4:7]
	v_mfma_f32_16x16x32_bf16 v[0:3], v[184:187], v[220:223], v[0:3]
	s_setprio 0
	s_barrier
	s_add_i32 s61, 0, 0x18000
	v_add_u32_e32 v159, s61, v153
	s_add_i32 s62, 0, 0x1c000
	ds_read_b128 v[146:149], v159
	ds_read_b128 v[160:163], v159 offset:1024
	ds_read_b128 v[164:167], v159 offset:2048
	ds_read_b128 v[168:171], v159 offset:3072
	v_add_u32_e32 v159, s62, v153
	ds_read_b128 v[172:175], v159
	ds_read_b128 v[176:179], v159 offset:1024
	ds_read_b128 v[180:183], v159 offset:2048
	ds_read_b128 v[184:187], v159 offset:3072
	s_add_u32 s38, s38, 0x40000
	s_addc_u32 s39, s39, 0
	ds_read_b128 v[188:191], v157 offset:32768
	ds_read_b128 v[196:199], v157 offset:33792
	ds_read_b128 v[200:203], v157 offset:34816
	ds_read_b128 v[204:207], v157 offset:35840
	ds_read_b128 v[208:211], v157 offset:36864
	ds_read_b128 v[212:215], v157 offset:37888
	ds_read_b128 v[216:219], v157 offset:38912
	ds_read_b128 v[220:223], v157 offset:39936
	s_mov_b32 m0, s35
	s_nop 0
	global_load_lds_dwordx4 v128, s[98:99]
	s_mov_b32 m0, s45
	s_nop 0
	global_load_lds_dwordx4 v132, s[98:99]
	s_mov_b32 m0, s48
	s_nop 0
	global_load_lds_dwordx4 v128, s[38:39]
	s_mov_b32 m0, s49
	s_nop 0
	global_load_lds_dwordx4 v132, s[38:39]
	s_waitcnt vmcnt(8)
	s_waitcnt lgkmcnt(0)
	s_barrier
	s_setprio 1
	s_waitcnt lgkmcnt(0)
	v_mfma_f32_16x16x32_bf16 v[124:127], v[146:149], v[188:191], v[124:127]
	v_mfma_f32_16x16x32_bf16 v[120:123], v[164:167], v[188:191], v[120:123]
	v_mfma_f32_16x16x32_bf16 v[108:111], v[146:149], v[200:203], v[108:111]
	v_mfma_f32_16x16x32_bf16 v[104:107], v[164:167], v[200:203], v[104:107]
	v_mfma_f32_16x16x32_bf16 v[92:95], v[146:149], v[208:211], v[92:95]
	v_mfma_f32_16x16x32_bf16 v[88:91], v[164:167], v[208:211], v[88:91]
	v_mfma_f32_16x16x32_bf16 v[76:79], v[146:149], v[216:219], v[76:79]
	v_mfma_f32_16x16x32_bf16 v[72:75], v[164:167], v[216:219], v[72:75]
	v_mfma_f32_16x16x32_bf16 v[124:127], v[160:163], v[196:199], v[124:127]
	v_mfma_f32_16x16x32_bf16 v[120:123], v[168:171], v[196:199], v[120:123]
	v_mfma_f32_16x16x32_bf16 v[108:111], v[160:163], v[204:207], v[108:111]
	v_mfma_f32_16x16x32_bf16 v[104:107], v[168:171], v[204:207], v[104:107]
	v_mfma_f32_16x16x32_bf16 v[92:95], v[160:163], v[212:215], v[92:95]
	v_mfma_f32_16x16x32_bf16 v[88:91], v[168:171], v[212:215], v[88:91]
	v_mfma_f32_16x16x32_bf16 v[76:79], v[160:163], v[220:223], v[76:79]
	v_mfma_f32_16x16x32_bf16 v[72:75], v[168:171], v[220:223], v[72:75]
	s_setprio 0
	s_setprio 1
	v_mfma_f32_16x16x32_bf16 v[116:119], v[172:175], v[188:191], v[116:119]
	v_mfma_f32_16x16x32_bf16 v[112:115], v[180:183], v[188:191], v[112:115]
	v_mfma_f32_16x16x32_bf16 v[100:103], v[172:175], v[200:203], v[100:103]
	v_mfma_f32_16x16x32_bf16 v[96:99], v[180:183], v[200:203], v[96:99]
	v_mfma_f32_16x16x32_bf16 v[84:87], v[172:175], v[208:211], v[84:87]
	v_mfma_f32_16x16x32_bf16 v[80:83], v[180:183], v[208:211], v[80:83]
	v_mfma_f32_16x16x32_bf16 v[68:71], v[172:175], v[216:219], v[68:71]
	v_mfma_f32_16x16x32_bf16 v[64:67], v[180:183], v[216:219], v[64:67]
	v_mfma_f32_16x16x32_bf16 v[116:119], v[176:179], v[196:199], v[116:119]
	v_mfma_f32_16x16x32_bf16 v[112:115], v[184:187], v[196:199], v[112:115]
	v_mfma_f32_16x16x32_bf16 v[100:103], v[176:179], v[204:207], v[100:103]
	v_mfma_f32_16x16x32_bf16 v[96:99], v[184:187], v[204:207], v[96:99]
	v_mfma_f32_16x16x32_bf16 v[84:87], v[176:179], v[212:215], v[84:87]
	v_mfma_f32_16x16x32_bf16 v[80:83], v[184:187], v[212:215], v[80:83]
	v_mfma_f32_16x16x32_bf16 v[68:71], v[176:179], v[220:223], v[68:71]
	v_mfma_f32_16x16x32_bf16 v[64:67], v[184:187], v[220:223], v[64:67]
	s_setprio 0
	s_barrier
	s_add_i32 s38, s61, s44
	s_add_i32 m0, s38, 0xffffff80
	ds_read_b128 v[188:191], v157 offset:49152
	ds_read_b128 v[196:199], v157 offset:50176
	ds_read_b128 v[200:203], v157 offset:51200
	ds_read_b128 v[204:207], v157 offset:52224
	ds_read_b128 v[208:211], v157 offset:53248
	ds_read_b128 v[212:215], v157 offset:54272
	ds_read_b128 v[216:219], v157 offset:55296
	ds_read_b128 v[220:223], v157 offset:56320
	global_load_lds_dwordx4 v130, s[36:37] offset:128
	s_add_i32 m0, s38, 0x1f80
	s_add_i32 s38, s62, s44
	global_load_lds_dwordx4 v134, s[36:37] offset:128
	s_add_u32 s36, s36, 0x40080
	s_addc_u32 s37, s37, 0
	s_mov_b32 m0, s38
	s_nop 0
	global_load_lds_dwordx4 v130, s[36:37]
	s_add_i32 m0, s38, 0x2000
	s_nop 0
	global_load_lds_dwordx4 v134, s[36:37]
	s_waitcnt vmcnt(6)
	s_waitcnt lgkmcnt(0)
	s_barrier
	s_setprio 1
	s_waitcnt lgkmcnt(0)
	v_mfma_f32_16x16x32_bf16 v[60:63], v[146:149], v[188:191], v[60:63]
	v_mfma_f32_16x16x32_bf16 v[56:59], v[164:167], v[188:191], v[56:59]
	v_mfma_f32_16x16x32_bf16 v[44:47], v[146:149], v[200:203], v[44:47]
	v_mfma_f32_16x16x32_bf16 v[40:43], v[164:167], v[200:203], v[40:43]
	v_mfma_f32_16x16x32_bf16 v[28:31], v[146:149], v[208:211], v[28:31]
	v_mfma_f32_16x16x32_bf16 v[24:27], v[164:167], v[208:211], v[24:27]
	v_mfma_f32_16x16x32_bf16 v[12:15], v[146:149], v[216:219], v[12:15]
	v_mfma_f32_16x16x32_bf16 v[8:11], v[164:167], v[216:219], v[8:11]
	v_mfma_f32_16x16x32_bf16 v[60:63], v[160:163], v[196:199], v[60:63]
	v_mfma_f32_16x16x32_bf16 v[56:59], v[168:171], v[196:199], v[56:59]
	v_mfma_f32_16x16x32_bf16 v[44:47], v[160:163], v[204:207], v[44:47]
	v_mfma_f32_16x16x32_bf16 v[40:43], v[168:171], v[204:207], v[40:43]
	v_mfma_f32_16x16x32_bf16 v[28:31], v[160:163], v[212:215], v[28:31]
	v_mfma_f32_16x16x32_bf16 v[24:27], v[168:171], v[212:215], v[24:27]
	v_mfma_f32_16x16x32_bf16 v[12:15], v[160:163], v[220:223], v[12:15]
	v_mfma_f32_16x16x32_bf16 v[8:11], v[168:171], v[220:223], v[8:11]
	s_setprio 0
	s_setprio 1
	v_mfma_f32_16x16x32_bf16 v[52:55], v[172:175], v[188:191], v[52:55]
	v_mfma_f32_16x16x32_bf16 v[48:51], v[180:183], v[188:191], v[48:51]
	v_mfma_f32_16x16x32_bf16 v[36:39], v[172:175], v[200:203], v[36:39]
	v_mfma_f32_16x16x32_bf16 v[32:35], v[180:183], v[200:203], v[32:35]
	v_mfma_f32_16x16x32_bf16 v[20:23], v[172:175], v[208:211], v[20:23]
	v_mfma_f32_16x16x32_bf16 v[16:19], v[180:183], v[208:211], v[16:19]
	v_mfma_f32_16x16x32_bf16 v[4:7], v[172:175], v[216:219], v[4:7]
	v_mfma_f32_16x16x32_bf16 v[0:3], v[180:183], v[216:219], v[0:3]
	v_mfma_f32_16x16x32_bf16 v[52:55], v[176:179], v[196:199], v[52:55]
	v_mfma_f32_16x16x32_bf16 v[48:51], v[184:187], v[196:199], v[48:51]
	v_mfma_f32_16x16x32_bf16 v[36:39], v[176:179], v[204:207], v[36:39]
	v_mfma_f32_16x16x32_bf16 v[32:35], v[184:187], v[204:207], v[32:35]
	v_mfma_f32_16x16x32_bf16 v[20:23], v[176:179], v[212:215], v[20:23]
	v_mfma_f32_16x16x32_bf16 v[16:19], v[184:187], v[212:215], v[16:19]
	v_mfma_f32_16x16x32_bf16 v[4:7], v[176:179], v[220:223], v[4:7]
	v_mfma_f32_16x16x32_bf16 v[0:3], v[184:187], v[220:223], v[0:3]
	s_setprio 0
	s_barrier
	s_add_i32 m0, s50, 0xffffff80
	s_nop 0
	global_load_lds_dwordx4 v128, s[98:99] offset:128
	s_add_i32 m0, s51, 0xffffff80
	s_nop 0
	global_load_lds_dwordx4 v132, s[98:99] offset:128
	s_add_i32 s60, s60, 2
	s_add_u32 s0, s0, 0x100
	s_addc_u32 s1, s1, 0
	s_add_u32 s25, s25, 0x100
	s_addc_u32 s59, s59, 0
	s_cmp_gt_u32 s60, 13
	s_cbranch_scc0 .LBB0_3031
	s_and_b64 vcc, exec, s[18:19]
	s_cbranch_vccz .LBB0_3034
	s_barrier

.LBB0_3061:
	ds_read_b128 v[144:147], v159
	ds_read_b128 v[148:151], v159 offset:1024
	ds_read_b128 v[152:155], v159 offset:2048
	ds_read_b128 v[162:165], v159 offset:3072
	ds_read_b128 v[166:169], v160
	ds_read_b128 v[170:173], v160 offset:1024
	ds_read_b128 v[174:177], v160 offset:2048
	ds_read_b128 v[178:181], v160 offset:3072
	s_add_u32 s37, s42, 0xfffe0080
	s_addc_u32 s39, s43, -1
	s_cmp_eq_u32 s35, 4
	s_cselect_b32 s51, s1, s39
	s_cselect_b32 s50, s0, s37
	s_cselect_b32 s49, s41, s13
	s_cselect_b32 s48, s40, s11
	s_add_i32 m0, s60, 0xc000
	ds_read_b128 v[182:185], v161
	ds_read_b128 v[186:189], v161 offset:1024
	ds_read_b128 v[190:193], v161 offset:2048
	ds_read_b128 v[196:199], v161 offset:3072
	ds_read_b128 v[200:203], v161 offset:4096
	ds_read_b128 v[204:207], v161 offset:5120
	ds_read_b128 v[208:211], v161 offset:6144
	ds_read_b128 v[212:215], v161 offset:7168
	global_load_lds_dwordx4 v136, s[42:43]
	s_add_i32 m0, s60, 0xe000
	s_nop 0
	global_load_lds_dwordx4 v138, s[42:43]
	s_waitcnt vmcnt(8)
	s_waitcnt lgkmcnt(0)
	s_barrier
	s_setprio 1
	s_waitcnt lgkmcnt(0)
	v_mfma_f32_16x16x32_bf16 v[124:127], v[144:147], v[182:185], v[124:127]
	v_mfma_f32_16x16x32_bf16 v[120:123], v[152:155], v[182:185], v[120:123]
	v_mfma_f32_16x16x32_bf16 v[108:111], v[144:147], v[190:193], v[108:111]
	v_mfma_f32_16x16x32_bf16 v[104:107], v[152:155], v[190:193], v[104:107]
	v_mfma_f32_16x16x32_bf16 v[92:95], v[144:147], v[200:203], v[92:95]
	v_mfma_f32_16x16x32_bf16 v[88:91], v[152:155], v[200:203], v[88:91]
	v_mfma_f32_16x16x32_bf16 v[76:79], v[144:147], v[208:211], v[76:79]
	v_mfma_f32_16x16x32_bf16 v[72:75], v[152:155], v[208:211], v[72:75]
	v_mfma_f32_16x16x32_bf16 v[124:127], v[148:151], v[186:189], v[124:127]
	v_mfma_f32_16x16x32_bf16 v[120:123], v[162:165], v[186:189], v[120:123]
	v_mfma_f32_16x16x32_bf16 v[108:111], v[148:151], v[196:199], v[108:111]
	v_mfma_f32_16x16x32_bf16 v[104:107], v[162:165], v[196:199], v[104:107]
	v_mfma_f32_16x16x32_bf16 v[92:95], v[148:151], v[204:207], v[92:95]
	v_mfma_f32_16x16x32_bf16 v[88:91], v[162:165], v[204:207], v[88:91]
	v_mfma_f32_16x16x32_bf16 v[76:79], v[148:151], v[212:215], v[76:79]
	v_mfma_f32_16x16x32_bf16 v[72:75], v[162:165], v[212:215], v[72:75]
	s_setprio 0
	s_setprio 1
	v_mfma_f32_16x16x32_bf16 v[116:119], v[166:169], v[182:185], v[116:119]
	v_mfma_f32_16x16x32_bf16 v[112:115], v[174:177], v[182:185], v[112:115]
	v_mfma_f32_16x16x32_bf16 v[100:103], v[166:169], v[190:193], v[100:103]
	v_mfma_f32_16x16x32_bf16 v[96:99], v[174:177], v[190:193], v[96:99]
	v_mfma_f32_16x16x32_bf16 v[84:87], v[166:169], v[200:203], v[84:87]
	v_mfma_f32_16x16x32_bf16 v[80:83], v[174:177], v[200:203], v[80:83]
	v_mfma_f32_16x16x32_bf16 v[68:71], v[166:169], v[208:211], v[68:71]
	v_mfma_f32_16x16x32_bf16 v[64:67], v[174:177], v[208:211], v[64:67]
	v_mfma_f32_16x16x32_bf16 v[116:119], v[170:173], v[186:189], v[116:119]
	v_mfma_f32_16x16x32_bf16 v[112:115], v[178:181], v[186:189], v[112:115]
	v_mfma_f32_16x16x32_bf16 v[100:103], v[170:173], v[196:199], v[100:103]
	v_mfma_f32_16x16x32_bf16 v[96:99], v[178:181], v[196:199], v[96:99]
	v_mfma_f32_16x16x32_bf16 v[84:87], v[170:173], v[204:207], v[84:87]
	v_mfma_f32_16x16x32_bf16 v[80:83], v[178:181], v[204:207], v[80:83]
	v_mfma_f32_16x16x32_bf16 v[68:71], v[170:173], v[212:215], v[68:71]
	v_mfma_f32_16x16x32_bf16 v[64:67], v[178:181], v[212:215], v[64:67]
	s_setprio 0
	s_barrier
	s_add_i32 s37, s73, s57
	s_mov_b32 m0, s37
	ds_read_b128 v[182:185], v161 offset:16384
	ds_read_b128 v[186:189], v161 offset:17408
	ds_read_b128 v[190:193], v161 offset:18432
	ds_read_b128 v[196:199], v161 offset:19456
	ds_read_b128 v[200:203], v161 offset:20480
	ds_read_b128 v[204:207], v161 offset:21504
	ds_read_b128 v[208:211], v161 offset:22528
	ds_read_b128 v[212:215], v161 offset:23552
	global_load_lds_dwordx4 v130, s[48:49]
	s_add_i32 m0, s37, 0x2000
	s_add_u32 s80, s48, 0x20000
	s_addc_u32 s81, s49, 0
	s_add_i32 s37, s77, s57
	global_load_lds_dwordx4 v134, s[48:49]
	s_mov_b32 m0, s37
	s_mov_b64 s[98:99], s[50:51]
	global_load_lds_dwordx4 v130, s[80:81]
	s_add_i32 m0, s37, 0x2000
	s_nop 0
	global_load_lds_dwordx4 v134, s[80:81]
	s_waitcnt vmcnt(6)
	s_waitcnt lgkmcnt(0)
	s_barrier
	s_setprio 1
	s_waitcnt lgkmcnt(0)
	v_mfma_f32_16x16x32_bf16 v[60:63], v[144:147], v[182:185], v[60:63]
	v_mfma_f32_16x16x32_bf16 v[56:59], v[152:155], v[182:185], v[56:59]
	v_mfma_f32_16x16x32_bf16 v[44:47], v[144:147], v[190:193], v[44:47]
	v_mfma_f32_16x16x32_bf16 v[40:43], v[152:155], v[190:193], v[40:43]
	v_mfma_f32_16x16x32_bf16 v[28:31], v[144:147], v[200:203], v[28:31]
	v_mfma_f32_16x16x32_bf16 v[24:27], v[152:155], v[200:203], v[24:27]
	v_mfma_f32_16x16x32_bf16 v[12:15], v[144:147], v[208:211], v[12:15]
	v_mfma_f32_16x16x32_bf16 v[8:11], v[152:155], v[208:211], v[8:11]
	v_mfma_f32_16x16x32_bf16 v[60:63], v[148:151], v[186:189], v[60:63]
	v_mfma_f32_16x16x32_bf16 v[56:59], v[162:165], v[186:189], v[56:59]
	v_mfma_f32_16x16x32_bf16 v[44:47], v[148:151], v[196:199], v[44:47]
	v_mfma_f32_16x16x32_bf16 v[40:43], v[162:165], v[196:199], v[40:43]
	v_mfma_f32_16x16x32_bf16 v[28:31], v[148:151], v[204:207], v[28:31]
	v_mfma_f32_16x16x32_bf16 v[24:27], v[162:165], v[204:207], v[24:27]
	v_mfma_f32_16x16x32_bf16 v[12:15], v[148:151], v[212:215], v[12:15]
	v_mfma_f32_16x16x32_bf16 v[8:11], v[162:165], v[212:215], v[8:11]
	s_setprio 0
	s_setprio 1
	v_mfma_f32_16x16x32_bf16 v[52:55], v[166:169], v[182:185], v[52:55]
	v_mfma_f32_16x16x32_bf16 v[48:51], v[174:177], v[182:185], v[48:51]
	v_mfma_f32_16x16x32_bf16 v[36:39], v[166:169], v[190:193], v[36:39]
	v_mfma_f32_16x16x32_bf16 v[32:35], v[174:177], v[190:193], v[32:35]
	v_mfma_f32_16x16x32_bf16 v[20:23], v[166:169], v[200:203], v[20:23]
	v_mfma_f32_16x16x32_bf16 v[16:19], v[174:177], v[200:203], v[16:19]
	v_mfma_f32_16x16x32_bf16 v[4:7], v[166:169], v[208:211], v[4:7]
	v_mfma_f32_16x16x32_bf16 v[0:3], v[174:177], v[208:211], v[0:3]
	v_mfma_f32_16x16x32_bf16 v[52:55], v[170:173], v[186:189], v[52:55]
	v_mfma_f32_16x16x32_bf16 v[48:51], v[178:181], v[186:189], v[48:51]
	v_mfma_f32_16x16x32_bf16 v[36:39], v[170:173], v[196:199], v[36:39]
	v_mfma_f32_16x16x32_bf16 v[32:35], v[178:181], v[196:199], v[32:35]
	v_mfma_f32_16x16x32_bf16 v[20:23], v[170:173], v[204:207], v[20:23]
	v_mfma_f32_16x16x32_bf16 v[16:19], v[178:181], v[204:207], v[16:19]
	v_mfma_f32_16x16x32_bf16 v[4:7], v[170:173], v[212:215], v[4:7]
	v_mfma_f32_16x16x32_bf16 v[0:3], v[178:181], v[212:215], v[0:3]
	s_setprio 0
	s_barrier
	s_add_i32 s37, 0, 0x18000
	s_add_i32 s39, 0, 0x1c000
	v_add_u32_e32 v162, s37, v157
	v_add_u32_e32 v178, s39, v157
	ds_read_b128 v[144:147], v162
	ds_read_b128 v[148:151], v162 offset:1024
	ds_read_b128 v[152:155], v162 offset:2048
	ds_read_b128 v[162:165], v162 offset:3072
	ds_read_b128 v[166:169], v178
	ds_read_b128 v[170:173], v178 offset:1024
	ds_read_b128 v[174:177], v178 offset:2048
	ds_read_b128 v[178:181], v178 offset:3072
	s_add_u32 s50, s50, 0x20000
	s_addc_u32 s51, s51, 0
	ds_read_b128 v[182:185], v161 offset:32768
	ds_read_b128 v[186:189], v161 offset:33792
	ds_read_b128 v[190:193], v161 offset:34816
	ds_read_b128 v[196:199], v161 offset:35840
	ds_read_b128 v[200:203], v161 offset:36864
	ds_read_b128 v[204:207], v161 offset:37888
	ds_read_b128 v[208:211], v161 offset:38912
	ds_read_b128 v[212:215], v161 offset:39936
	s_mov_b32 m0, s60
	s_nop 0
	global_load_lds_dwordx4 v128, s[98:99]
	s_mov_b32 m0, s61
	s_nop 0
	global_load_lds_dwordx4 v132, s[98:99]
	s_mov_b32 m0, s62
	s_nop 0
	global_load_lds_dwordx4 v128, s[50:51]
	s_mov_b32 m0, s63
	s_nop 0
	global_load_lds_dwordx4 v132, s[50:51]
	s_waitcnt vmcnt(8)
	s_waitcnt lgkmcnt(0)
	s_barrier
	s_setprio 1
	s_waitcnt lgkmcnt(0)
	v_mfma_f32_16x16x32_bf16 v[124:127], v[144:147], v[182:185], v[124:127]
	v_mfma_f32_16x16x32_bf16 v[120:123], v[152:155], v[182:185], v[120:123]
	v_mfma_f32_16x16x32_bf16 v[108:111], v[144:147], v[190:193], v[108:111]
	v_mfma_f32_16x16x32_bf16 v[104:107], v[152:155], v[190:193], v[104:107]
	v_mfma_f32_16x16x32_bf16 v[92:95], v[144:147], v[200:203], v[92:95]
	v_mfma_f32_16x16x32_bf16 v[88:91], v[152:155], v[200:203], v[88:91]
	v_mfma_f32_16x16x32_bf16 v[76:79], v[144:147], v[208:211], v[76:79]
	v_mfma_f32_16x16x32_bf16 v[72:75], v[152:155], v[208:211], v[72:75]
	v_mfma_f32_16x16x32_bf16 v[124:127], v[148:151], v[186:189], v[124:127]
	v_mfma_f32_16x16x32_bf16 v[120:123], v[162:165], v[186:189], v[120:123]
	v_mfma_f32_16x16x32_bf16 v[108:111], v[148:151], v[196:199], v[108:111]
	v_mfma_f32_16x16x32_bf16 v[104:107], v[162:165], v[196:199], v[104:107]
	v_mfma_f32_16x16x32_bf16 v[92:95], v[148:151], v[204:207], v[92:95]
	v_mfma_f32_16x16x32_bf16 v[88:91], v[162:165], v[204:207], v[88:91]
	v_mfma_f32_16x16x32_bf16 v[76:79], v[148:151], v[212:215], v[76:79]
	v_mfma_f32_16x16x32_bf16 v[72:75], v[162:165], v[212:215], v[72:75]
	s_setprio 0
	s_setprio 1
	v_mfma_f32_16x16x32_bf16 v[116:119], v[166:169], v[182:185], v[116:119]
	v_mfma_f32_16x16x32_bf16 v[112:115], v[174:177], v[182:185], v[112:115]
	v_mfma_f32_16x16x32_bf16 v[100:103], v[166:169], v[190:193], v[100:103]
	v_mfma_f32_16x16x32_bf16 v[96:99], v[174:177], v[190:193], v[96:99]
	v_mfma_f32_16x16x32_bf16 v[84:87], v[166:169], v[200:203], v[84:87]
	v_mfma_f32_16x16x32_bf16 v[80:83], v[174:177], v[200:203], v[80:83]
	v_mfma_f32_16x16x32_bf16 v[68:71], v[166:169], v[208:211], v[68:71]
	v_mfma_f32_16x16x32_bf16 v[64:67], v[174:177], v[208:211], v[64:67]
	v_mfma_f32_16x16x32_bf16 v[116:119], v[170:173], v[186:189], v[116:119]
	v_mfma_f32_16x16x32_bf16 v[112:115], v[178:181], v[186:189], v[112:115]
	v_mfma_f32_16x16x32_bf16 v[100:103], v[170:173], v[196:199], v[100:103]
	v_mfma_f32_16x16x32_bf16 v[96:99], v[178:181], v[196:199], v[96:99]
	v_mfma_f32_16x16x32_bf16 v[84:87], v[170:173], v[204:207], v[84:87]
	v_mfma_f32_16x16x32_bf16 v[80:83], v[178:181], v[204:207], v[80:83]
	v_mfma_f32_16x16x32_bf16 v[68:71], v[170:173], v[212:215], v[68:71]
	v_mfma_f32_16x16x32_bf16 v[64:67], v[178:181], v[212:215], v[64:67]
	s_setprio 0
	s_barrier
	s_add_i32 s37, s37, s57
	s_add_i32 m0, s37, 0xffffff80
	ds_read_b128 v[182:185], v161 offset:49152
	ds_read_b128 v[186:189], v161 offset:50176
	ds_read_b128 v[190:193], v161 offset:51200
	ds_read_b128 v[196:199], v161 offset:52224
	ds_read_b128 v[200:203], v161 offset:53248
	ds_read_b128 v[204:207], v161 offset:54272
	ds_read_b128 v[208:211], v161 offset:55296
	ds_read_b128 v[212:215], v161 offset:56320
	global_load_lds_dwordx4 v130, s[48:49] offset:128
	s_add_i32 m0, s37, 0x1f80
	s_add_i32 s37, s39, s57
	global_load_lds_dwordx4 v134, s[48:49] offset:128
	s_add_u32 s48, s48, 0x20080
	s_addc_u32 s49, s49, 0
	s_mov_b32 m0, s37
	s_nop 0
	global_load_lds_dwordx4 v130, s[48:49]
	s_add_i32 m0, s37, 0x2000
	s_nop 0
	global_load_lds_dwordx4 v134, s[48:49]
	s_waitcnt vmcnt(6)
	s_waitcnt lgkmcnt(0)
	s_barrier
	s_setprio 1
	s_waitcnt lgkmcnt(0)
	v_mfma_f32_16x16x32_bf16 v[60:63], v[144:147], v[182:185], v[60:63]
	v_mfma_f32_16x16x32_bf16 v[56:59], v[152:155], v[182:185], v[56:59]
	v_mfma_f32_16x16x32_bf16 v[44:47], v[144:147], v[190:193], v[44:47]
	v_mfma_f32_16x16x32_bf16 v[40:43], v[152:155], v[190:193], v[40:43]
	v_mfma_f32_16x16x32_bf16 v[28:31], v[144:147], v[200:203], v[28:31]
	v_mfma_f32_16x16x32_bf16 v[24:27], v[152:155], v[200:203], v[24:27]
	v_mfma_f32_16x16x32_bf16 v[12:15], v[144:147], v[208:211], v[12:15]
	v_mfma_f32_16x16x32_bf16 v[8:11], v[152:155], v[208:211], v[8:11]
	v_mfma_f32_16x16x32_bf16 v[60:63], v[148:151], v[186:189], v[60:63]
	v_mfma_f32_16x16x32_bf16 v[56:59], v[162:165], v[186:189], v[56:59]
	v_mfma_f32_16x16x32_bf16 v[44:47], v[148:151], v[196:199], v[44:47]
	v_mfma_f32_16x16x32_bf16 v[40:43], v[162:165], v[196:199], v[40:43]
	v_mfma_f32_16x16x32_bf16 v[28:31], v[148:151], v[204:207], v[28:31]
	v_mfma_f32_16x16x32_bf16 v[24:27], v[162:165], v[204:207], v[24:27]
	v_mfma_f32_16x16x32_bf16 v[12:15], v[148:151], v[212:215], v[12:15]
	v_mfma_f32_16x16x32_bf16 v[8:11], v[162:165], v[212:215], v[8:11]
	s_setprio 0
	s_setprio 1
	v_mfma_f32_16x16x32_bf16 v[52:55], v[166:169], v[182:185], v[52:55]
	v_mfma_f32_16x16x32_bf16 v[48:51], v[174:177], v[182:185], v[48:51]
	v_mfma_f32_16x16x32_bf16 v[36:39], v[166:169], v[190:193], v[36:39]
	v_mfma_f32_16x16x32_bf16 v[32:35], v[174:177], v[190:193], v[32:35]
	v_mfma_f32_16x16x32_bf16 v[20:23], v[166:169], v[200:203], v[20:23]
	v_mfma_f32_16x16x32_bf16 v[16:19], v[174:177], v[200:203], v[16:19]
	v_mfma_f32_16x16x32_bf16 v[4:7], v[166:169], v[208:211], v[4:7]
	v_mfma_f32_16x16x32_bf16 v[0:3], v[174:177], v[208:211], v[0:3]
	v_mfma_f32_16x16x32_bf16 v[52:55], v[170:173], v[186:189], v[52:55]
	v_mfma_f32_16x16x32_bf16 v[48:51], v[178:181], v[186:189], v[48:51]
	v_mfma_f32_16x16x32_bf16 v[36:39], v[170:173], v[196:199], v[36:39]
	v_mfma_f32_16x16x32_bf16 v[32:35], v[178:181], v[196:199], v[32:35]
	v_mfma_f32_16x16x32_bf16 v[20:23], v[170:173], v[204:207], v[20:23]
	v_mfma_f32_16x16x32_bf16 v[16:19], v[178:181], v[204:207], v[16:19]
	v_mfma_f32_16x16x32_bf16 v[4:7], v[170:173], v[212:215], v[4:7]
	v_mfma_f32_16x16x32_bf16 v[0:3], v[178:181], v[212:215], v[0:3]
	s_setprio 0
	s_barrier
	s_add_i32 m0, s70, 0xffffff80
	s_nop 0
	global_load_lds_dwordx4 v128, s[98:99] offset:128
	s_add_i32 m0, s71, 0xffffff80
	s_nop 0
	global_load_lds_dwordx4 v132, s[98:99] offset:128
	s_add_i32 s35, s35, 2
	s_add_u32 s42, s42, 0x100
	s_addc_u32 s43, s43, 0
	s_add_u32 s11, s11, 0x100
	s_addc_u32 s13, s13, 0
	s_cmp_gt_u32 s35, 5
	s_cbranch_scc0 .LBB0_3061
	s_and_b64 vcc, exec, s[24:25]
	s_cbranch_vccz .LBB0_3064
	s_barrier

.LBB0_3235:
	ds_read_b128 v[144:147], v151
	ds_read_b128 v[156:159], v151 offset:1024
	ds_read_b128 v[160:163], v151 offset:2048
	ds_read_b128 v[164:167], v151 offset:3072
	ds_read_b128 v[168:171], v152
	ds_read_b128 v[172:175], v152 offset:1024
	ds_read_b128 v[176:179], v152 offset:2048
	ds_read_b128 v[180:183], v152 offset:3072
	s_add_u32 s38, s36, 0xfffc0080
	s_addc_u32 s39, s37, -1
	s_cmp_eq_u32 s70, 12
	s_cselect_b32 s41, s27, s39
	s_cselect_b32 s40, s35, s38
	s_cselect_b32 s39, s25, s63
	s_cselect_b32 s38, s61, s62
	s_add_i32 m0, s50, 0xc000
	ds_read_b128 v[184:187], v153
	ds_read_b128 v[188:191], v153 offset:1024
	ds_read_b128 v[196:199], v153 offset:2048
	ds_read_b128 v[200:203], v153 offset:3072
	ds_read_b128 v[204:207], v153 offset:4096
	ds_read_b128 v[208:211], v153 offset:5120
	ds_read_b128 v[212:215], v153 offset:6144
	ds_read_b128 v[216:219], v153 offset:7168
	global_load_lds_dwordx4 v136, s[36:37]
	s_add_i32 m0, s50, 0xe000
	s_nop 0
	global_load_lds_dwordx4 v138, s[36:37]
	s_waitcnt vmcnt(8)
	s_waitcnt lgkmcnt(0)
	s_barrier
	s_setprio 1
	s_waitcnt lgkmcnt(0)
	v_mfma_f32_16x16x32_bf16 v[124:127], v[144:147], v[184:187], v[124:127]
	v_mfma_f32_16x16x32_bf16 v[120:123], v[160:163], v[184:187], v[120:123]
	v_mfma_f32_16x16x32_bf16 v[108:111], v[144:147], v[196:199], v[108:111]
	v_mfma_f32_16x16x32_bf16 v[104:107], v[160:163], v[196:199], v[104:107]
	v_mfma_f32_16x16x32_bf16 v[92:95], v[144:147], v[204:207], v[92:95]
	v_mfma_f32_16x16x32_bf16 v[88:91], v[160:163], v[204:207], v[88:91]
	v_mfma_f32_16x16x32_bf16 v[76:79], v[144:147], v[212:215], v[76:79]
	v_mfma_f32_16x16x32_bf16 v[72:75], v[160:163], v[212:215], v[72:75]
	v_mfma_f32_16x16x32_bf16 v[124:127], v[156:159], v[188:191], v[124:127]
	v_mfma_f32_16x16x32_bf16 v[120:123], v[164:167], v[188:191], v[120:123]
	v_mfma_f32_16x16x32_bf16 v[108:111], v[156:159], v[200:203], v[108:111]
	v_mfma_f32_16x16x32_bf16 v[104:107], v[164:167], v[200:203], v[104:107]
	v_mfma_f32_16x16x32_bf16 v[92:95], v[156:159], v[208:211], v[92:95]
	v_mfma_f32_16x16x32_bf16 v[88:91], v[164:167], v[208:211], v[88:91]
	v_mfma_f32_16x16x32_bf16 v[76:79], v[156:159], v[216:219], v[76:79]
	v_mfma_f32_16x16x32_bf16 v[72:75], v[164:167], v[216:219], v[72:75]
	s_setprio 0
	s_setprio 1
	v_mfma_f32_16x16x32_bf16 v[116:119], v[168:171], v[184:187], v[116:119]
	v_mfma_f32_16x16x32_bf16 v[112:115], v[176:179], v[184:187], v[112:115]
	v_mfma_f32_16x16x32_bf16 v[100:103], v[168:171], v[196:199], v[100:103]
	v_mfma_f32_16x16x32_bf16 v[96:99], v[176:179], v[196:199], v[96:99]
	v_mfma_f32_16x16x32_bf16 v[84:87], v[168:171], v[204:207], v[84:87]
	v_mfma_f32_16x16x32_bf16 v[80:83], v[176:179], v[204:207], v[80:83]
	v_mfma_f32_16x16x32_bf16 v[68:71], v[168:171], v[212:215], v[68:71]
	v_mfma_f32_16x16x32_bf16 v[64:67], v[176:179], v[212:215], v[64:67]
	v_mfma_f32_16x16x32_bf16 v[116:119], v[172:175], v[188:191], v[116:119]
	v_mfma_f32_16x16x32_bf16 v[112:115], v[180:183], v[188:191], v[112:115]
	v_mfma_f32_16x16x32_bf16 v[100:103], v[172:175], v[200:203], v[100:103]
	v_mfma_f32_16x16x32_bf16 v[96:99], v[180:183], v[200:203], v[96:99]
	v_mfma_f32_16x16x32_bf16 v[84:87], v[172:175], v[208:211], v[84:87]
	v_mfma_f32_16x16x32_bf16 v[80:83], v[180:183], v[208:211], v[80:83]
	v_mfma_f32_16x16x32_bf16 v[68:71], v[172:175], v[216:219], v[68:71]
	v_mfma_f32_16x16x32_bf16 v[64:67], v[180:183], v[216:219], v[64:67]
	s_setprio 0
	s_barrier
	s_add_i32 s71, s58, s49
	s_mov_b32 m0, s71
	ds_read_b128 v[184:187], v153 offset:16384
	ds_read_b128 v[188:191], v153 offset:17408
	ds_read_b128 v[196:199], v153 offset:18432
	ds_read_b128 v[200:203], v153 offset:19456
	ds_read_b128 v[204:207], v153 offset:20480
	ds_read_b128 v[208:211], v153 offset:21504
	ds_read_b128 v[212:215], v153 offset:22528
	ds_read_b128 v[216:219], v153 offset:23552
	global_load_lds_dwordx4 v130, s[38:39]
	s_add_i32 m0, s71, 0x2000
	s_add_u32 s72, s38, 0x40000
	s_addc_u32 s73, s39, 0
	s_add_i32 s71, s59, s49
	global_load_lds_dwordx4 v134, s[38:39]
	s_mov_b32 m0, s71
	s_mov_b64 s[98:99], s[40:41]
	global_load_lds_dwordx4 v130, s[72:73]
	s_add_i32 m0, s71, 0x2000
	s_nop 0
	global_load_lds_dwordx4 v134, s[72:73]
	s_waitcnt vmcnt(6)
	s_waitcnt lgkmcnt(0)
	s_barrier
	s_setprio 1
	s_waitcnt lgkmcnt(0)
	v_mfma_f32_16x16x32_bf16 v[60:63], v[144:147], v[184:187], v[60:63]
	v_mfma_f32_16x16x32_bf16 v[56:59], v[160:163], v[184:187], v[56:59]
	v_mfma_f32_16x16x32_bf16 v[44:47], v[144:147], v[196:199], v[44:47]
	v_mfma_f32_16x16x32_bf16 v[40:43], v[160:163], v[196:199], v[40:43]
	v_mfma_f32_16x16x32_bf16 v[28:31], v[144:147], v[204:207], v[28:31]
	v_mfma_f32_16x16x32_bf16 v[24:27], v[160:163], v[204:207], v[24:27]
	v_mfma_f32_16x16x32_bf16 v[12:15], v[144:147], v[212:215], v[12:15]
	v_mfma_f32_16x16x32_bf16 v[8:11], v[160:163], v[212:215], v[8:11]
	v_mfma_f32_16x16x32_bf16 v[60:63], v[156:159], v[188:191], v[60:63]
	v_mfma_f32_16x16x32_bf16 v[56:59], v[164:167], v[188:191], v[56:59]
	v_mfma_f32_16x16x32_bf16 v[44:47], v[156:159], v[200:203], v[44:47]
	v_mfma_f32_16x16x32_bf16 v[40:43], v[164:167], v[200:203], v[40:43]
	v_mfma_f32_16x16x32_bf16 v[28:31], v[156:159], v[208:211], v[28:31]
	v_mfma_f32_16x16x32_bf16 v[24:27], v[164:167], v[208:211], v[24:27]
	v_mfma_f32_16x16x32_bf16 v[12:15], v[156:159], v[216:219], v[12:15]
	v_mfma_f32_16x16x32_bf16 v[8:11], v[164:167], v[216:219], v[8:11]
	s_setprio 0
	s_setprio 1
	v_mfma_f32_16x16x32_bf16 v[52:55], v[168:171], v[184:187], v[52:55]
	v_mfma_f32_16x16x32_bf16 v[48:51], v[176:179], v[184:187], v[48:51]
	v_mfma_f32_16x16x32_bf16 v[36:39], v[168:171], v[196:199], v[36:39]
	v_mfma_f32_16x16x32_bf16 v[32:35], v[176:179], v[196:199], v[32:35]
	v_mfma_f32_16x16x32_bf16 v[20:23], v[168:171], v[204:207], v[20:23]
	v_mfma_f32_16x16x32_bf16 v[16:19], v[176:179], v[204:207], v[16:19]
	v_mfma_f32_16x16x32_bf16 v[4:7], v[168:171], v[212:215], v[4:7]
	v_mfma_f32_16x16x32_bf16 v[0:3], v[176:179], v[212:215], v[0:3]
	v_mfma_f32_16x16x32_bf16 v[52:55], v[172:175], v[188:191], v[52:55]
	v_mfma_f32_16x16x32_bf16 v[48:51], v[180:183], v[188:191], v[48:51]
	v_mfma_f32_16x16x32_bf16 v[36:39], v[172:175], v[200:203], v[36:39]
	v_mfma_f32_16x16x32_bf16 v[32:35], v[180:183], v[200:203], v[32:35]
	v_mfma_f32_16x16x32_bf16 v[20:23], v[172:175], v[208:211], v[20:23]
	v_mfma_f32_16x16x32_bf16 v[16:19], v[180:183], v[208:211], v[16:19]
	v_mfma_f32_16x16x32_bf16 v[4:7], v[172:175], v[216:219], v[4:7]
	v_mfma_f32_16x16x32_bf16 v[0:3], v[180:183], v[216:219], v[0:3]
	s_setprio 0
	s_barrier
	s_add_i32 s71, 0, 0x18000
	v_add_u32_e32 v155, s71, v149
	s_add_i32 s72, 0, 0x1c000
	ds_read_b128 v[144:147], v155
	ds_read_b128 v[156:159], v155 offset:1024
	ds_read_b128 v[160:163], v155 offset:2048
	ds_read_b128 v[164:167], v155 offset:3072
	v_add_u32_e32 v155, s72, v149
	ds_read_b128 v[168:171], v155
	ds_read_b128 v[172:175], v155 offset:1024
	ds_read_b128 v[176:179], v155 offset:2048
	ds_read_b128 v[180:183], v155 offset:3072
	s_add_u32 s40, s40, 0x40000
	s_addc_u32 s41, s41, 0
	ds_read_b128 v[184:187], v153 offset:32768
	ds_read_b128 v[188:191], v153 offset:33792
	ds_read_b128 v[196:199], v153 offset:34816
	ds_read_b128 v[200:203], v153 offset:35840
	ds_read_b128 v[204:207], v153 offset:36864
	ds_read_b128 v[208:211], v153 offset:37888
	ds_read_b128 v[212:215], v153 offset:38912
	ds_read_b128 v[216:219], v153 offset:39936
	s_mov_b32 m0, s50
	s_nop 0
	global_load_lds_dwordx4 v128, s[98:99]
	s_mov_b32 m0, s51
	s_nop 0
	global_load_lds_dwordx4 v132, s[98:99]
	s_mov_b32 m0, s52
	s_nop 0
	global_load_lds_dwordx4 v128, s[40:41]
	s_mov_b32 m0, s53
	s_nop 0
	global_load_lds_dwordx4 v132, s[40:41]
	s_waitcnt vmcnt(8)
	s_waitcnt lgkmcnt(0)
	s_barrier
	s_setprio 1
	s_waitcnt lgkmcnt(0)
	v_mfma_f32_16x16x32_bf16 v[124:127], v[144:147], v[184:187], v[124:127]
	v_mfma_f32_16x16x32_bf16 v[120:123], v[160:163], v[184:187], v[120:123]
	v_mfma_f32_16x16x32_bf16 v[108:111], v[144:147], v[196:199], v[108:111]
	v_mfma_f32_16x16x32_bf16 v[104:107], v[160:163], v[196:199], v[104:107]
	v_mfma_f32_16x16x32_bf16 v[92:95], v[144:147], v[204:207], v[92:95]
	v_mfma_f32_16x16x32_bf16 v[88:91], v[160:163], v[204:207], v[88:91]
	v_mfma_f32_16x16x32_bf16 v[76:79], v[144:147], v[212:215], v[76:79]
	v_mfma_f32_16x16x32_bf16 v[72:75], v[160:163], v[212:215], v[72:75]
	v_mfma_f32_16x16x32_bf16 v[124:127], v[156:159], v[188:191], v[124:127]
	v_mfma_f32_16x16x32_bf16 v[120:123], v[164:167], v[188:191], v[120:123]
	v_mfma_f32_16x16x32_bf16 v[108:111], v[156:159], v[200:203], v[108:111]
	v_mfma_f32_16x16x32_bf16 v[104:107], v[164:167], v[200:203], v[104:107]
	v_mfma_f32_16x16x32_bf16 v[92:95], v[156:159], v[208:211], v[92:95]
	v_mfma_f32_16x16x32_bf16 v[88:91], v[164:167], v[208:211], v[88:91]
	v_mfma_f32_16x16x32_bf16 v[76:79], v[156:159], v[216:219], v[76:79]
	v_mfma_f32_16x16x32_bf16 v[72:75], v[164:167], v[216:219], v[72:75]
	s_setprio 0
	s_setprio 1
	v_mfma_f32_16x16x32_bf16 v[116:119], v[168:171], v[184:187], v[116:119]
	v_mfma_f32_16x16x32_bf16 v[112:115], v[176:179], v[184:187], v[112:115]
	v_mfma_f32_16x16x32_bf16 v[100:103], v[168:171], v[196:199], v[100:103]
	v_mfma_f32_16x16x32_bf16 v[96:99], v[176:179], v[196:199], v[96:99]
	v_mfma_f32_16x16x32_bf16 v[84:87], v[168:171], v[204:207], v[84:87]
	v_mfma_f32_16x16x32_bf16 v[80:83], v[176:179], v[204:207], v[80:83]
	v_mfma_f32_16x16x32_bf16 v[68:71], v[168:171], v[212:215], v[68:71]
	v_mfma_f32_16x16x32_bf16 v[64:67], v[176:179], v[212:215], v[64:67]
	v_mfma_f32_16x16x32_bf16 v[116:119], v[172:175], v[188:191], v[116:119]
	v_mfma_f32_16x16x32_bf16 v[112:115], v[180:183], v[188:191], v[112:115]
	v_mfma_f32_16x16x32_bf16 v[100:103], v[172:175], v[200:203], v[100:103]
	v_mfma_f32_16x16x32_bf16 v[96:99], v[180:183], v[200:203], v[96:99]
	v_mfma_f32_16x16x32_bf16 v[84:87], v[172:175], v[208:211], v[84:87]
	v_mfma_f32_16x16x32_bf16 v[80:83], v[180:183], v[208:211], v[80:83]
	v_mfma_f32_16x16x32_bf16 v[68:71], v[172:175], v[216:219], v[68:71]
	v_mfma_f32_16x16x32_bf16 v[64:67], v[180:183], v[216:219], v[64:67]
	s_setprio 0
	s_barrier
	s_add_i32 s40, s71, s49
	s_add_i32 m0, s40, 0xffffff80
	ds_read_b128 v[184:187], v153 offset:49152
	ds_read_b128 v[188:191], v153 offset:50176
	ds_read_b128 v[196:199], v153 offset:51200
	ds_read_b128 v[200:203], v153 offset:52224
	ds_read_b128 v[204:207], v153 offset:53248
	ds_read_b128 v[208:211], v153 offset:54272
	ds_read_b128 v[212:215], v153 offset:55296
	ds_read_b128 v[216:219], v153 offset:56320
	global_load_lds_dwordx4 v130, s[38:39] offset:128
	s_add_i32 m0, s40, 0x1f80
	s_add_i32 s40, s72, s49
	global_load_lds_dwordx4 v134, s[38:39] offset:128
	s_add_u32 s38, s38, 0x40080
	s_addc_u32 s39, s39, 0
	s_mov_b32 m0, s40
	s_nop 0
	global_load_lds_dwordx4 v130, s[38:39]
	s_add_i32 m0, s40, 0x2000
	s_nop 0
	global_load_lds_dwordx4 v134, s[38:39]
	s_waitcnt vmcnt(6)
	s_waitcnt lgkmcnt(0)
	s_barrier
	s_setprio 1
	s_waitcnt lgkmcnt(0)
	v_mfma_f32_16x16x32_bf16 v[60:63], v[144:147], v[184:187], v[60:63]
	v_mfma_f32_16x16x32_bf16 v[56:59], v[160:163], v[184:187], v[56:59]
	v_mfma_f32_16x16x32_bf16 v[44:47], v[144:147], v[196:199], v[44:47]
	v_mfma_f32_16x16x32_bf16 v[40:43], v[160:163], v[196:199], v[40:43]
	v_mfma_f32_16x16x32_bf16 v[28:31], v[144:147], v[204:207], v[28:31]
	v_mfma_f32_16x16x32_bf16 v[24:27], v[160:163], v[204:207], v[24:27]
	v_mfma_f32_16x16x32_bf16 v[12:15], v[144:147], v[212:215], v[12:15]
	v_mfma_f32_16x16x32_bf16 v[8:11], v[160:163], v[212:215], v[8:11]
	v_mfma_f32_16x16x32_bf16 v[60:63], v[156:159], v[188:191], v[60:63]
	v_mfma_f32_16x16x32_bf16 v[56:59], v[164:167], v[188:191], v[56:59]
	v_mfma_f32_16x16x32_bf16 v[44:47], v[156:159], v[200:203], v[44:47]
	v_mfma_f32_16x16x32_bf16 v[40:43], v[164:167], v[200:203], v[40:43]
	v_mfma_f32_16x16x32_bf16 v[28:31], v[156:159], v[208:211], v[28:31]
	v_mfma_f32_16x16x32_bf16 v[24:27], v[164:167], v[208:211], v[24:27]
	v_mfma_f32_16x16x32_bf16 v[12:15], v[156:159], v[216:219], v[12:15]
	v_mfma_f32_16x16x32_bf16 v[8:11], v[164:167], v[216:219], v[8:11]
	s_setprio 0
	s_setprio 1
	v_mfma_f32_16x16x32_bf16 v[52:55], v[168:171], v[184:187], v[52:55]
	v_mfma_f32_16x16x32_bf16 v[48:51], v[176:179], v[184:187], v[48:51]
	v_mfma_f32_16x16x32_bf16 v[36:39], v[168:171], v[196:199], v[36:39]
	v_mfma_f32_16x16x32_bf16 v[32:35], v[176:179], v[196:199], v[32:35]
	v_mfma_f32_16x16x32_bf16 v[20:23], v[168:171], v[204:207], v[20:23]
	v_mfma_f32_16x16x32_bf16 v[16:19], v[176:179], v[204:207], v[16:19]
	v_mfma_f32_16x16x32_bf16 v[4:7], v[168:171], v[212:215], v[4:7]
	v_mfma_f32_16x16x32_bf16 v[0:3], v[176:179], v[212:215], v[0:3]
	v_mfma_f32_16x16x32_bf16 v[52:55], v[172:175], v[188:191], v[52:55]
	v_mfma_f32_16x16x32_bf16 v[48:51], v[180:183], v[188:191], v[48:51]
	v_mfma_f32_16x16x32_bf16 v[36:39], v[172:175], v[200:203], v[36:39]
	v_mfma_f32_16x16x32_bf16 v[32:35], v[180:183], v[200:203], v[32:35]
	v_mfma_f32_16x16x32_bf16 v[20:23], v[172:175], v[208:211], v[20:23]
	v_mfma_f32_16x16x32_bf16 v[16:19], v[180:183], v[208:211], v[16:19]
	v_mfma_f32_16x16x32_bf16 v[4:7], v[172:175], v[216:219], v[4:7]
	v_mfma_f32_16x16x32_bf16 v[0:3], v[180:183], v[216:219], v[0:3]
	s_setprio 0
	s_barrier
	s_add_i32 m0, s55, 0xffffff80
	s_nop 0
	global_load_lds_dwordx4 v128, s[98:99] offset:128
	s_add_i32 m0, s56, 0xffffff80
	s_nop 0
	global_load_lds_dwordx4 v132, s[98:99] offset:128
	s_add_i32 s70, s70, 2
	s_add_u32 s36, s36, 0x100
	s_addc_u32 s37, s37, 0
	s_add_u32 s62, s62, 0x100
	s_addc_u32 s63, s63, 0
	s_cmp_gt_u32 s70, 13
	s_cbranch_scc0 .LBB0_3235
	s_and_b64 vcc, exec, s[22:23]
	s_cbranch_vccz .LBB0_3238
	s_barrier

.LBB0_3319:
	ds_read_b128 v[154:157], v149
	ds_read_b128 v[158:161], v149 offset:1024
	ds_read_b128 v[162:165], v149 offset:2048
	ds_read_b128 v[166:169], v149 offset:3072
	ds_read_b128 v[170:173], v150
	ds_read_b128 v[174:177], v150 offset:1024
	ds_read_b128 v[178:181], v150 offset:2048
	ds_read_b128 v[182:185], v150 offset:3072
	s_add_u32 s28, s26, 0xfffc0080
	s_addc_u32 s29, s27, -1
	s_cmp_eq_u32 s59, 12
	s_cselect_b32 s31, s19, s29
	s_cselect_b32 s30, s55, s28
	s_cselect_b32 s29, s17, s58
	s_cselect_b32 s28, s56, s57
	s_add_i32 m0, s25, 0xc000
	ds_read_b128 v[186:189], v151
	ds_read_b128 v[190:193], v151 offset:1024
	ds_read_b128 v[196:199], v151 offset:2048
	ds_read_b128 v[200:203], v151 offset:3072
	ds_read_b128 v[204:207], v151 offset:4096
	ds_read_b128 v[208:211], v151 offset:5120
	ds_read_b128 v[212:215], v151 offset:6144
	ds_read_b128 v[216:219], v151 offset:7168
	global_load_lds_dwordx4 v136, s[26:27]
	s_add_i32 m0, s25, 0xe000
	s_nop 0
	global_load_lds_dwordx4 v138, s[26:27]
	s_waitcnt vmcnt(8)
	s_waitcnt lgkmcnt(0)
	s_barrier
	s_setprio 1
	s_waitcnt lgkmcnt(0)
	v_mfma_f32_16x16x32_bf16 v[116:119], v[154:157], v[186:189], v[116:119]
	v_mfma_f32_16x16x32_bf16 v[112:115], v[162:165], v[186:189], v[112:115]
	v_mfma_f32_16x16x32_bf16 v[100:103], v[154:157], v[196:199], v[100:103]
	v_mfma_f32_16x16x32_bf16 v[96:99], v[162:165], v[196:199], v[96:99]
	v_mfma_f32_16x16x32_bf16 v[84:87], v[154:157], v[204:207], v[84:87]
	v_mfma_f32_16x16x32_bf16 v[80:83], v[162:165], v[204:207], v[80:83]
	v_mfma_f32_16x16x32_bf16 v[68:71], v[154:157], v[212:215], v[68:71]
	v_mfma_f32_16x16x32_bf16 v[64:67], v[162:165], v[212:215], v[64:67]
	v_mfma_f32_16x16x32_bf16 v[116:119], v[158:161], v[190:193], v[116:119]
	v_mfma_f32_16x16x32_bf16 v[112:115], v[166:169], v[190:193], v[112:115]
	v_mfma_f32_16x16x32_bf16 v[100:103], v[158:161], v[200:203], v[100:103]
	v_mfma_f32_16x16x32_bf16 v[96:99], v[166:169], v[200:203], v[96:99]
	v_mfma_f32_16x16x32_bf16 v[84:87], v[158:161], v[208:211], v[84:87]
	v_mfma_f32_16x16x32_bf16 v[80:83], v[166:169], v[208:211], v[80:83]
	v_mfma_f32_16x16x32_bf16 v[68:71], v[158:161], v[216:219], v[68:71]
	v_mfma_f32_16x16x32_bf16 v[64:67], v[166:169], v[216:219], v[64:67]
	s_setprio 0
	s_setprio 1
	v_mfma_f32_16x16x32_bf16 v[124:127], v[170:173], v[186:189], v[124:127]
	v_mfma_f32_16x16x32_bf16 v[120:123], v[178:181], v[186:189], v[120:123]
	v_mfma_f32_16x16x32_bf16 v[108:111], v[170:173], v[196:199], v[108:111]
	v_mfma_f32_16x16x32_bf16 v[104:107], v[178:181], v[196:199], v[104:107]
	v_mfma_f32_16x16x32_bf16 v[92:95], v[170:173], v[204:207], v[92:95]
	v_mfma_f32_16x16x32_bf16 v[88:91], v[178:181], v[204:207], v[88:91]
	v_mfma_f32_16x16x32_bf16 v[76:79], v[170:173], v[212:215], v[76:79]
	v_mfma_f32_16x16x32_bf16 v[72:75], v[178:181], v[212:215], v[72:75]
	v_mfma_f32_16x16x32_bf16 v[124:127], v[174:177], v[190:193], v[124:127]
	v_mfma_f32_16x16x32_bf16 v[120:123], v[182:185], v[190:193], v[120:123]
	v_mfma_f32_16x16x32_bf16 v[108:111], v[174:177], v[200:203], v[108:111]
	v_mfma_f32_16x16x32_bf16 v[104:107], v[182:185], v[200:203], v[104:107]
	v_mfma_f32_16x16x32_bf16 v[92:95], v[174:177], v[208:211], v[92:95]
	v_mfma_f32_16x16x32_bf16 v[88:91], v[182:185], v[208:211], v[88:91]
	v_mfma_f32_16x16x32_bf16 v[76:79], v[174:177], v[216:219], v[76:79]
	v_mfma_f32_16x16x32_bf16 v[72:75], v[182:185], v[216:219], v[72:75]
	s_setprio 0
	s_barrier
	s_add_i32 s60, s50, s39
	s_mov_b32 m0, s60
	ds_read_b128 v[186:189], v151 offset:16384
	ds_read_b128 v[190:193], v151 offset:17408
	ds_read_b128 v[196:199], v151 offset:18432
	ds_read_b128 v[200:203], v151 offset:19456
	ds_read_b128 v[204:207], v151 offset:20480
	ds_read_b128 v[208:211], v151 offset:21504
	ds_read_b128 v[212:215], v151 offset:22528
	ds_read_b128 v[216:219], v151 offset:23552
	global_load_lds_dwordx4 v132, s[28:29]
	s_add_i32 m0, s60, 0x2000
	s_add_u32 s60, s28, 0x40000
	s_addc_u32 s61, s29, 0
	s_add_i32 s62, s51, s39
	global_load_lds_dwordx4 v128, s[28:29]
	s_mov_b32 m0, s62
	s_mov_b64 s[98:99], s[30:31]
	global_load_lds_dwordx4 v132, s[60:61]
	s_add_i32 m0, s62, 0x2000
	s_nop 0
	global_load_lds_dwordx4 v128, s[60:61]
	s_waitcnt vmcnt(6)
	s_waitcnt lgkmcnt(0)
	s_barrier
	s_setprio 1
	s_waitcnt lgkmcnt(0)
	v_mfma_f32_16x16x32_bf16 v[52:55], v[154:157], v[186:189], v[52:55]
	v_mfma_f32_16x16x32_bf16 v[48:51], v[162:165], v[186:189], v[48:51]
	v_mfma_f32_16x16x32_bf16 v[36:39], v[154:157], v[196:199], v[36:39]
	v_mfma_f32_16x16x32_bf16 v[32:35], v[162:165], v[196:199], v[32:35]
	v_mfma_f32_16x16x32_bf16 v[20:23], v[154:157], v[204:207], v[20:23]
	v_mfma_f32_16x16x32_bf16 v[16:19], v[162:165], v[204:207], v[16:19]
	v_mfma_f32_16x16x32_bf16 v[4:7], v[154:157], v[212:215], v[4:7]
	v_mfma_f32_16x16x32_bf16 v[0:3], v[162:165], v[212:215], v[0:3]
	v_mfma_f32_16x16x32_bf16 v[52:55], v[158:161], v[190:193], v[52:55]
	v_mfma_f32_16x16x32_bf16 v[48:51], v[166:169], v[190:193], v[48:51]
	v_mfma_f32_16x16x32_bf16 v[36:39], v[158:161], v[200:203], v[36:39]
	v_mfma_f32_16x16x32_bf16 v[32:35], v[166:169], v[200:203], v[32:35]
	v_mfma_f32_16x16x32_bf16 v[20:23], v[158:161], v[208:211], v[20:23]
	v_mfma_f32_16x16x32_bf16 v[16:19], v[166:169], v[208:211], v[16:19]
	v_mfma_f32_16x16x32_bf16 v[4:7], v[158:161], v[216:219], v[4:7]
	v_mfma_f32_16x16x32_bf16 v[0:3], v[166:169], v[216:219], v[0:3]
	s_setprio 0
	s_setprio 1
	v_mfma_f32_16x16x32_bf16 v[60:63], v[170:173], v[186:189], v[60:63]
	v_mfma_f32_16x16x32_bf16 v[56:59], v[178:181], v[186:189], v[56:59]
	v_mfma_f32_16x16x32_bf16 v[44:47], v[170:173], v[196:199], v[44:47]
	v_mfma_f32_16x16x32_bf16 v[40:43], v[178:181], v[196:199], v[40:43]
	v_mfma_f32_16x16x32_bf16 v[28:31], v[170:173], v[204:207], v[28:31]
	v_mfma_f32_16x16x32_bf16 v[24:27], v[178:181], v[204:207], v[24:27]
	v_mfma_f32_16x16x32_bf16 v[12:15], v[170:173], v[212:215], v[12:15]
	v_mfma_f32_16x16x32_bf16 v[8:11], v[178:181], v[212:215], v[8:11]
	v_mfma_f32_16x16x32_bf16 v[60:63], v[174:177], v[190:193], v[60:63]
	v_mfma_f32_16x16x32_bf16 v[56:59], v[182:185], v[190:193], v[56:59]
	v_mfma_f32_16x16x32_bf16 v[44:47], v[174:177], v[200:203], v[44:47]
	v_mfma_f32_16x16x32_bf16 v[40:43], v[182:185], v[200:203], v[40:43]
	v_mfma_f32_16x16x32_bf16 v[28:31], v[174:177], v[208:211], v[28:31]
	v_mfma_f32_16x16x32_bf16 v[24:27], v[182:185], v[208:211], v[24:27]
	v_mfma_f32_16x16x32_bf16 v[12:15], v[174:177], v[216:219], v[12:15]
	v_mfma_f32_16x16x32_bf16 v[8:11], v[182:185], v[216:219], v[8:11]
	s_setprio 0
	s_barrier
	s_add_i32 s60, 0, 0x18000
	v_add_u32_e32 v153, s60, v147
	s_add_i32 s61, 0, 0x1c000
	ds_read_b128 v[154:157], v153
	ds_read_b128 v[158:161], v153 offset:1024
	ds_read_b128 v[162:165], v153 offset:2048
	ds_read_b128 v[166:169], v153 offset:3072
	v_add_u32_e32 v153, s61, v147
	ds_read_b128 v[170:173], v153
	ds_read_b128 v[174:177], v153 offset:1024
	ds_read_b128 v[178:181], v153 offset:2048
	ds_read_b128 v[182:185], v153 offset:3072
	s_add_u32 s30, s30, 0x40000
	s_addc_u32 s31, s31, 0
	ds_read_b128 v[186:189], v151 offset:32768
	ds_read_b128 v[190:193], v151 offset:33792
	ds_read_b128 v[196:199], v151 offset:34816
	ds_read_b128 v[200:203], v151 offset:35840
	ds_read_b128 v[204:207], v151 offset:36864
	ds_read_b128 v[208:211], v151 offset:37888
	ds_read_b128 v[212:215], v151 offset:38912
	ds_read_b128 v[216:219], v151 offset:39936
	s_mov_b32 m0, s25
	s_nop 0
	global_load_lds_dwordx4 v134, s[98:99]
	s_mov_b32 m0, s41
	s_nop 0
	global_load_lds_dwordx4 v130, s[98:99]
	s_mov_b32 m0, s42
	s_nop 0
	global_load_lds_dwordx4 v134, s[30:31]
	s_mov_b32 m0, s43
	s_nop 0
	global_load_lds_dwordx4 v130, s[30:31]
	s_waitcnt vmcnt(8)
	s_waitcnt lgkmcnt(0)
	s_barrier
	s_setprio 1
	s_waitcnt lgkmcnt(0)
	v_mfma_f32_16x16x32_bf16 v[116:119], v[154:157], v[186:189], v[116:119]
	v_mfma_f32_16x16x32_bf16 v[112:115], v[162:165], v[186:189], v[112:115]
	v_mfma_f32_16x16x32_bf16 v[100:103], v[154:157], v[196:199], v[100:103]
	v_mfma_f32_16x16x32_bf16 v[96:99], v[162:165], v[196:199], v[96:99]
	v_mfma_f32_16x16x32_bf16 v[84:87], v[154:157], v[204:207], v[84:87]
	v_mfma_f32_16x16x32_bf16 v[80:83], v[162:165], v[204:207], v[80:83]
	v_mfma_f32_16x16x32_bf16 v[68:71], v[154:157], v[212:215], v[68:71]
	v_mfma_f32_16x16x32_bf16 v[64:67], v[162:165], v[212:215], v[64:67]
	v_mfma_f32_16x16x32_bf16 v[116:119], v[158:161], v[190:193], v[116:119]
	v_mfma_f32_16x16x32_bf16 v[112:115], v[166:169], v[190:193], v[112:115]
	v_mfma_f32_16x16x32_bf16 v[100:103], v[158:161], v[200:203], v[100:103]
	v_mfma_f32_16x16x32_bf16 v[96:99], v[166:169], v[200:203], v[96:99]
	v_mfma_f32_16x16x32_bf16 v[84:87], v[158:161], v[208:211], v[84:87]
	v_mfma_f32_16x16x32_bf16 v[80:83], v[166:169], v[208:211], v[80:83]
	v_mfma_f32_16x16x32_bf16 v[68:71], v[158:161], v[216:219], v[68:71]
	v_mfma_f32_16x16x32_bf16 v[64:67], v[166:169], v[216:219], v[64:67]
	s_setprio 0
	s_setprio 1
	v_mfma_f32_16x16x32_bf16 v[124:127], v[170:173], v[186:189], v[124:127]
	v_mfma_f32_16x16x32_bf16 v[120:123], v[178:181], v[186:189], v[120:123]
	v_mfma_f32_16x16x32_bf16 v[108:111], v[170:173], v[196:199], v[108:111]
	v_mfma_f32_16x16x32_bf16 v[104:107], v[178:181], v[196:199], v[104:107]
	v_mfma_f32_16x16x32_bf16 v[92:95], v[170:173], v[204:207], v[92:95]
	v_mfma_f32_16x16x32_bf16 v[88:91], v[178:181], v[204:207], v[88:91]
	v_mfma_f32_16x16x32_bf16 v[76:79], v[170:173], v[212:215], v[76:79]
	v_mfma_f32_16x16x32_bf16 v[72:75], v[178:181], v[212:215], v[72:75]
	v_mfma_f32_16x16x32_bf16 v[124:127], v[174:177], v[190:193], v[124:127]
	v_mfma_f32_16x16x32_bf16 v[120:123], v[182:185], v[190:193], v[120:123]
	v_mfma_f32_16x16x32_bf16 v[108:111], v[174:177], v[200:203], v[108:111]
	v_mfma_f32_16x16x32_bf16 v[104:107], v[182:185], v[200:203], v[104:107]
	v_mfma_f32_16x16x32_bf16 v[92:95], v[174:177], v[208:211], v[92:95]
	v_mfma_f32_16x16x32_bf16 v[88:91], v[182:185], v[208:211], v[88:91]
	v_mfma_f32_16x16x32_bf16 v[76:79], v[174:177], v[216:219], v[76:79]
	v_mfma_f32_16x16x32_bf16 v[72:75], v[182:185], v[216:219], v[72:75]
	s_setprio 0
	s_barrier
	s_add_i32 s30, s60, s39
	s_add_i32 m0, s30, 0xffffff80
	ds_read_b128 v[186:189], v151 offset:49152
	ds_read_b128 v[190:193], v151 offset:50176
	ds_read_b128 v[196:199], v151 offset:51200
	ds_read_b128 v[200:203], v151 offset:52224
	ds_read_b128 v[204:207], v151 offset:53248
	ds_read_b128 v[208:211], v151 offset:54272
	ds_read_b128 v[212:215], v151 offset:55296
	ds_read_b128 v[216:219], v151 offset:56320
	global_load_lds_dwordx4 v132, s[28:29] offset:128
	s_add_i32 m0, s30, 0x1f80
	s_add_i32 s30, s61, s39
	global_load_lds_dwordx4 v128, s[28:29] offset:128
	s_add_u32 s28, s28, 0x40080
	s_addc_u32 s29, s29, 0
	s_mov_b32 m0, s30
	s_nop 0
	global_load_lds_dwordx4 v132, s[28:29]
	s_add_i32 m0, s30, 0x2000
	s_nop 0
	global_load_lds_dwordx4 v128, s[28:29]
	s_waitcnt vmcnt(6)
	s_waitcnt lgkmcnt(0)
	s_barrier
	s_setprio 1
	s_waitcnt lgkmcnt(0)
	v_mfma_f32_16x16x32_bf16 v[52:55], v[154:157], v[186:189], v[52:55]
	v_mfma_f32_16x16x32_bf16 v[48:51], v[162:165], v[186:189], v[48:51]
	v_mfma_f32_16x16x32_bf16 v[36:39], v[154:157], v[196:199], v[36:39]
	v_mfma_f32_16x16x32_bf16 v[32:35], v[162:165], v[196:199], v[32:35]
	v_mfma_f32_16x16x32_bf16 v[20:23], v[154:157], v[204:207], v[20:23]
	v_mfma_f32_16x16x32_bf16 v[16:19], v[162:165], v[204:207], v[16:19]
	v_mfma_f32_16x16x32_bf16 v[4:7], v[154:157], v[212:215], v[4:7]
	v_mfma_f32_16x16x32_bf16 v[0:3], v[162:165], v[212:215], v[0:3]
	v_mfma_f32_16x16x32_bf16 v[52:55], v[158:161], v[190:193], v[52:55]
	v_mfma_f32_16x16x32_bf16 v[48:51], v[166:169], v[190:193], v[48:51]
	v_mfma_f32_16x16x32_bf16 v[36:39], v[158:161], v[200:203], v[36:39]
	v_mfma_f32_16x16x32_bf16 v[32:35], v[166:169], v[200:203], v[32:35]
	v_mfma_f32_16x16x32_bf16 v[20:23], v[158:161], v[208:211], v[20:23]
	v_mfma_f32_16x16x32_bf16 v[16:19], v[166:169], v[208:211], v[16:19]
	v_mfma_f32_16x16x32_bf16 v[4:7], v[158:161], v[216:219], v[4:7]
	v_mfma_f32_16x16x32_bf16 v[0:3], v[166:169], v[216:219], v[0:3]
	s_setprio 0
	s_setprio 1
	v_mfma_f32_16x16x32_bf16 v[60:63], v[170:173], v[186:189], v[60:63]
	v_mfma_f32_16x16x32_bf16 v[56:59], v[178:181], v[186:189], v[56:59]
	v_mfma_f32_16x16x32_bf16 v[44:47], v[170:173], v[196:199], v[44:47]
	v_mfma_f32_16x16x32_bf16 v[40:43], v[178:181], v[196:199], v[40:43]
	v_mfma_f32_16x16x32_bf16 v[28:31], v[170:173], v[204:207], v[28:31]
	v_mfma_f32_16x16x32_bf16 v[24:27], v[178:181], v[204:207], v[24:27]
	v_mfma_f32_16x16x32_bf16 v[12:15], v[170:173], v[212:215], v[12:15]
	v_mfma_f32_16x16x32_bf16 v[8:11], v[178:181], v[212:215], v[8:11]
	v_mfma_f32_16x16x32_bf16 v[60:63], v[174:177], v[190:193], v[60:63]
	v_mfma_f32_16x16x32_bf16 v[56:59], v[182:185], v[190:193], v[56:59]
	v_mfma_f32_16x16x32_bf16 v[44:47], v[174:177], v[200:203], v[44:47]
	v_mfma_f32_16x16x32_bf16 v[40:43], v[182:185], v[200:203], v[40:43]
	v_mfma_f32_16x16x32_bf16 v[28:31], v[174:177], v[208:211], v[28:31]
	v_mfma_f32_16x16x32_bf16 v[24:27], v[182:185], v[208:211], v[24:27]
	v_mfma_f32_16x16x32_bf16 v[12:15], v[174:177], v[216:219], v[12:15]
	v_mfma_f32_16x16x32_bf16 v[8:11], v[182:185], v[216:219], v[8:11]
	s_setprio 0
	s_barrier
	s_add_i32 m0, s45, 0xffffff80
	s_nop 0
	global_load_lds_dwordx4 v134, s[98:99] offset:128
	s_add_i32 m0, s48, 0xffffff80
	s_nop 0
	global_load_lds_dwordx4 v130, s[98:99] offset:128
	s_add_i32 s59, s59, 2
	s_add_u32 s26, s26, 0x100
	s_addc_u32 s27, s27, 0
	s_add_u32 s57, s57, 0x100
	s_addc_u32 s58, s58, 0
	s_cmp_gt_u32 s59, 13
	s_cbranch_scc0 .LBB0_3319
	s_and_b64 vcc, exec, s[14:15]
	s_cbranch_vccz .LBB0_3322
	s_barrier

.LBB0_3401:
	ds_read_b128 v[144:147], v151
	ds_read_b128 v[156:159], v151 offset:1024
	ds_read_b128 v[160:163], v151 offset:2048
	ds_read_b128 v[164:167], v151 offset:3072
	ds_read_b128 v[168:171], v152
	ds_read_b128 v[172:175], v152 offset:1024
	ds_read_b128 v[176:179], v152 offset:2048
	ds_read_b128 v[180:183], v152 offset:3072
	s_add_u32 s24, s22, 0x100
	s_addc_u32 s25, s23, 0
	s_cmp_eq_u32 s56, 40
	s_cselect_b32 s29, s1, s25
	s_cselect_b32 s28, s0, s24
	s_cselect_b32 s27, s21, s55
	s_cselect_b32 s26, s20, s54
	v_lshl_add_u64 v[192:193], s[22:23], 0, v[136:137]
	s_add_i32 m0, s38, 0xc000
	ds_read_b128 v[184:187], v153
	ds_read_b128 v[188:191], v153 offset:1024
	ds_read_b128 v[196:199], v153 offset:2048
	ds_read_b128 v[200:203], v153 offset:3072
	ds_read_b128 v[204:207], v153 offset:4096
	ds_read_b128 v[208:211], v153 offset:5120
	ds_read_b128 v[212:215], v153 offset:6144
	ds_read_b128 v[216:219], v153 offset:7168
	global_load_lds_dwordx4 v[192:193], off
	v_lshl_add_u64 v[192:193], s[22:23], 0, v[138:139]
	s_add_i32 m0, s38, 0xe000
	s_nop 0
	global_load_lds_dwordx4 v[192:193], off
	s_waitcnt vmcnt(8)
	s_waitcnt lgkmcnt(0)
	s_barrier
	s_setprio 1
	s_waitcnt lgkmcnt(0)
	v_mfma_f32_16x16x32_bf16 v[124:127], v[144:147], v[184:187], v[124:127]
	v_mfma_f32_16x16x32_bf16 v[120:123], v[160:163], v[184:187], v[120:123]
	v_mfma_f32_16x16x32_bf16 v[108:111], v[144:147], v[196:199], v[108:111]
	v_mfma_f32_16x16x32_bf16 v[104:107], v[160:163], v[196:199], v[104:107]
	v_mfma_f32_16x16x32_bf16 v[92:95], v[144:147], v[204:207], v[92:95]
	v_mfma_f32_16x16x32_bf16 v[88:91], v[160:163], v[204:207], v[88:91]
	v_mfma_f32_16x16x32_bf16 v[76:79], v[144:147], v[212:215], v[76:79]
	v_mfma_f32_16x16x32_bf16 v[72:75], v[160:163], v[212:215], v[72:75]
	v_mfma_f32_16x16x32_bf16 v[124:127], v[156:159], v[188:191], v[124:127]
	v_mfma_f32_16x16x32_bf16 v[120:123], v[164:167], v[188:191], v[120:123]
	v_mfma_f32_16x16x32_bf16 v[108:111], v[156:159], v[200:203], v[108:111]
	v_mfma_f32_16x16x32_bf16 v[104:107], v[164:167], v[200:203], v[104:107]
	v_mfma_f32_16x16x32_bf16 v[92:95], v[156:159], v[208:211], v[92:95]
	v_mfma_f32_16x16x32_bf16 v[88:91], v[164:167], v[208:211], v[88:91]
	v_mfma_f32_16x16x32_bf16 v[76:79], v[156:159], v[216:219], v[76:79]
	v_mfma_f32_16x16x32_bf16 v[72:75], v[164:167], v[216:219], v[72:75]
	s_setprio 0
	s_setprio 1
	v_mfma_f32_16x16x32_bf16 v[116:119], v[168:171], v[184:187], v[116:119]
	v_mfma_f32_16x16x32_bf16 v[112:115], v[176:179], v[184:187], v[112:115]
	v_mfma_f32_16x16x32_bf16 v[100:103], v[168:171], v[196:199], v[100:103]
	v_mfma_f32_16x16x32_bf16 v[96:99], v[176:179], v[196:199], v[96:99]
	v_mfma_f32_16x16x32_bf16 v[84:87], v[168:171], v[204:207], v[84:87]
	v_mfma_f32_16x16x32_bf16 v[80:83], v[176:179], v[204:207], v[80:83]
	v_mfma_f32_16x16x32_bf16 v[68:71], v[168:171], v[212:215], v[68:71]
	v_mfma_f32_16x16x32_bf16 v[64:67], v[176:179], v[212:215], v[64:67]
	v_mfma_f32_16x16x32_bf16 v[116:119], v[172:175], v[188:191], v[116:119]
	v_mfma_f32_16x16x32_bf16 v[112:115], v[180:183], v[188:191], v[112:115]
	v_mfma_f32_16x16x32_bf16 v[100:103], v[172:175], v[200:203], v[100:103]
	v_mfma_f32_16x16x32_bf16 v[96:99], v[180:183], v[200:203], v[96:99]
	v_mfma_f32_16x16x32_bf16 v[84:87], v[172:175], v[208:211], v[84:87]
	v_mfma_f32_16x16x32_bf16 v[80:83], v[180:183], v[208:211], v[80:83]
	v_mfma_f32_16x16x32_bf16 v[68:71], v[172:175], v[216:219], v[68:71]
	v_mfma_f32_16x16x32_bf16 v[64:67], v[180:183], v[216:219], v[64:67]
	s_setprio 0
	s_barrier
	s_add_i32 s22, s48, s37
	v_lshl_add_u64 v[192:193], s[26:27], 0, v[130:131]
	s_mov_b32 m0, s22
	ds_read_b128 v[184:187], v153 offset:16384
	ds_read_b128 v[188:191], v153 offset:17408
	ds_read_b128 v[196:199], v153 offset:18432
	ds_read_b128 v[200:203], v153 offset:19456
	ds_read_b128 v[204:207], v153 offset:20480
	ds_read_b128 v[208:211], v153 offset:21504
	ds_read_b128 v[212:215], v153 offset:22528
	ds_read_b128 v[216:219], v153 offset:23552
	global_load_lds_dwordx4 v[192:193], off
	s_add_i32 m0, s22, 0x2000
	s_add_u32 s22, s26, 0xb0000
	v_lshl_add_u64 v[220:221], s[26:27], 0, v[134:135]
	s_addc_u32 s23, s27, 0
	s_add_i32 s57, s49, s37
	global_load_lds_dwordx4 v[220:221], off
	s_mov_b32 m0, s57
	s_mov_b64 s[98:99], s[28:29]
	global_load_lds_dwordx4 v130, s[22:23]
	s_add_i32 m0, s57, 0x2000
	s_nop 0
	global_load_lds_dwordx4 v134, s[22:23]
	s_waitcnt vmcnt(6)
	s_waitcnt lgkmcnt(0)
	s_barrier
	s_setprio 1
	s_waitcnt lgkmcnt(0)
	v_mfma_f32_16x16x32_bf16 v[60:63], v[144:147], v[184:187], v[60:63]
	v_mfma_f32_16x16x32_bf16 v[56:59], v[160:163], v[184:187], v[56:59]
	v_mfma_f32_16x16x32_bf16 v[44:47], v[144:147], v[196:199], v[44:47]
	v_mfma_f32_16x16x32_bf16 v[40:43], v[160:163], v[196:199], v[40:43]
	v_mfma_f32_16x16x32_bf16 v[28:31], v[144:147], v[204:207], v[28:31]
	v_mfma_f32_16x16x32_bf16 v[24:27], v[160:163], v[204:207], v[24:27]
	v_mfma_f32_16x16x32_bf16 v[12:15], v[144:147], v[212:215], v[12:15]
	v_mfma_f32_16x16x32_bf16 v[8:11], v[160:163], v[212:215], v[8:11]
	v_mfma_f32_16x16x32_bf16 v[60:63], v[156:159], v[188:191], v[60:63]
	v_mfma_f32_16x16x32_bf16 v[56:59], v[164:167], v[188:191], v[56:59]
	v_mfma_f32_16x16x32_bf16 v[44:47], v[156:159], v[200:203], v[44:47]
	v_mfma_f32_16x16x32_bf16 v[40:43], v[164:167], v[200:203], v[40:43]
	v_mfma_f32_16x16x32_bf16 v[28:31], v[156:159], v[208:211], v[28:31]
	v_mfma_f32_16x16x32_bf16 v[24:27], v[164:167], v[208:211], v[24:27]
	v_mfma_f32_16x16x32_bf16 v[12:15], v[156:159], v[216:219], v[12:15]
	v_mfma_f32_16x16x32_bf16 v[8:11], v[164:167], v[216:219], v[8:11]
	s_setprio 0
	s_setprio 1
	v_mfma_f32_16x16x32_bf16 v[52:55], v[168:171], v[184:187], v[52:55]
	v_mfma_f32_16x16x32_bf16 v[48:51], v[176:179], v[184:187], v[48:51]
	v_mfma_f32_16x16x32_bf16 v[36:39], v[168:171], v[196:199], v[36:39]
	v_mfma_f32_16x16x32_bf16 v[32:35], v[176:179], v[196:199], v[32:35]
	v_mfma_f32_16x16x32_bf16 v[20:23], v[168:171], v[204:207], v[20:23]
	v_mfma_f32_16x16x32_bf16 v[16:19], v[176:179], v[204:207], v[16:19]
	v_mfma_f32_16x16x32_bf16 v[4:7], v[168:171], v[212:215], v[4:7]
	v_mfma_f32_16x16x32_bf16 v[0:3], v[176:179], v[212:215], v[0:3]
	v_mfma_f32_16x16x32_bf16 v[52:55], v[172:175], v[188:191], v[52:55]
	v_mfma_f32_16x16x32_bf16 v[48:51], v[180:183], v[188:191], v[48:51]
	v_mfma_f32_16x16x32_bf16 v[36:39], v[172:175], v[200:203], v[36:39]
	v_mfma_f32_16x16x32_bf16 v[32:35], v[180:183], v[200:203], v[32:35]
	v_mfma_f32_16x16x32_bf16 v[20:23], v[172:175], v[208:211], v[20:23]
	v_mfma_f32_16x16x32_bf16 v[16:19], v[180:183], v[208:211], v[16:19]
	v_mfma_f32_16x16x32_bf16 v[4:7], v[172:175], v[216:219], v[4:7]
	v_mfma_f32_16x16x32_bf16 v[0:3], v[180:183], v[216:219], v[0:3]
	s_setprio 0
	s_barrier
	s_add_i32 s57, 0, 0x18000
	v_add_u32_e32 v155, s57, v149
	s_add_i32 s58, 0, 0x1c000
	ds_read_b128 v[144:147], v155
	ds_read_b128 v[156:159], v155 offset:1024
	ds_read_b128 v[160:163], v155 offset:2048
	ds_read_b128 v[164:167], v155 offset:3072
	v_add_u32_e32 v155, s58, v149
	ds_read_b128 v[168:171], v155
	ds_read_b128 v[172:175], v155 offset:1024
	ds_read_b128 v[176:179], v155 offset:2048
	ds_read_b128 v[180:183], v155 offset:3072
	s_add_u32 s22, s28, 0xb0000
	s_addc_u32 s23, s29, 0
	ds_read_b128 v[184:187], v153 offset:32768
	ds_read_b128 v[188:191], v153 offset:33792
	ds_read_b128 v[196:199], v153 offset:34816
	ds_read_b128 v[200:203], v153 offset:35840
	ds_read_b128 v[204:207], v153 offset:36864
	ds_read_b128 v[208:211], v153 offset:37888
	ds_read_b128 v[212:215], v153 offset:38912
	ds_read_b128 v[216:219], v153 offset:39936
	s_mov_b32 m0, s38
	s_nop 0
	global_load_lds_dwordx4 v128, s[98:99]
	s_mov_b32 m0, s39
	s_nop 0
	global_load_lds_dwordx4 v132, s[98:99]
	s_mov_b32 m0, s40
	s_nop 0
	global_load_lds_dwordx4 v128, s[22:23]
	s_mov_b32 m0, s41
	s_nop 0
	global_load_lds_dwordx4 v132, s[22:23]
	s_waitcnt vmcnt(8)
	s_waitcnt lgkmcnt(0)
	s_barrier
	s_setprio 1
	s_waitcnt lgkmcnt(0)
	v_mfma_f32_16x16x32_bf16 v[124:127], v[144:147], v[184:187], v[124:127]
	v_mfma_f32_16x16x32_bf16 v[120:123], v[160:163], v[184:187], v[120:123]
	v_mfma_f32_16x16x32_bf16 v[108:111], v[144:147], v[196:199], v[108:111]
	v_mfma_f32_16x16x32_bf16 v[104:107], v[160:163], v[196:199], v[104:107]
	v_mfma_f32_16x16x32_bf16 v[92:95], v[144:147], v[204:207], v[92:95]
	v_mfma_f32_16x16x32_bf16 v[88:91], v[160:163], v[204:207], v[88:91]
	v_mfma_f32_16x16x32_bf16 v[76:79], v[144:147], v[212:215], v[76:79]
	v_mfma_f32_16x16x32_bf16 v[72:75], v[160:163], v[212:215], v[72:75]
	v_mfma_f32_16x16x32_bf16 v[124:127], v[156:159], v[188:191], v[124:127]
	v_mfma_f32_16x16x32_bf16 v[120:123], v[164:167], v[188:191], v[120:123]
	v_mfma_f32_16x16x32_bf16 v[108:111], v[156:159], v[200:203], v[108:111]
	v_mfma_f32_16x16x32_bf16 v[104:107], v[164:167], v[200:203], v[104:107]
	v_mfma_f32_16x16x32_bf16 v[92:95], v[156:159], v[208:211], v[92:95]
	v_mfma_f32_16x16x32_bf16 v[88:91], v[164:167], v[208:211], v[88:91]
	v_mfma_f32_16x16x32_bf16 v[76:79], v[156:159], v[216:219], v[76:79]
	v_mfma_f32_16x16x32_bf16 v[72:75], v[164:167], v[216:219], v[72:75]
	s_setprio 0
	s_setprio 1
	v_mfma_f32_16x16x32_bf16 v[116:119], v[168:171], v[184:187], v[116:119]
	v_mfma_f32_16x16x32_bf16 v[112:115], v[176:179], v[184:187], v[112:115]
	v_mfma_f32_16x16x32_bf16 v[100:103], v[168:171], v[196:199], v[100:103]
	v_mfma_f32_16x16x32_bf16 v[96:99], v[176:179], v[196:199], v[96:99]
	v_mfma_f32_16x16x32_bf16 v[84:87], v[168:171], v[204:207], v[84:87]
	v_mfma_f32_16x16x32_bf16 v[80:83], v[176:179], v[204:207], v[80:83]
	v_mfma_f32_16x16x32_bf16 v[68:71], v[168:171], v[212:215], v[68:71]
	v_mfma_f32_16x16x32_bf16 v[64:67], v[176:179], v[212:215], v[64:67]
	v_mfma_f32_16x16x32_bf16 v[116:119], v[172:175], v[188:191], v[116:119]
	v_mfma_f32_16x16x32_bf16 v[112:115], v[180:183], v[188:191], v[112:115]
	v_mfma_f32_16x16x32_bf16 v[100:103], v[172:175], v[200:203], v[100:103]
	v_mfma_f32_16x16x32_bf16 v[96:99], v[180:183], v[200:203], v[96:99]
	v_mfma_f32_16x16x32_bf16 v[84:87], v[172:175], v[208:211], v[84:87]
	v_mfma_f32_16x16x32_bf16 v[80:83], v[180:183], v[208:211], v[80:83]
	v_mfma_f32_16x16x32_bf16 v[68:71], v[172:175], v[216:219], v[68:71]
	v_mfma_f32_16x16x32_bf16 v[64:67], v[180:183], v[216:219], v[64:67]
	s_setprio 0
	s_barrier
	s_add_i32 s22, s57, s37
	v_lshl_add_u64 v[192:193], v[192:193], 0, s[16:17]
	s_mov_b32 m0, s22
	ds_read_b128 v[184:187], v153 offset:49152
	ds_read_b128 v[188:191], v153 offset:50176
	ds_read_b128 v[196:199], v153 offset:51200
	ds_read_b128 v[200:203], v153 offset:52224
	ds_read_b128 v[204:207], v153 offset:53248
	ds_read_b128 v[208:211], v153 offset:54272
	ds_read_b128 v[212:215], v153 offset:55296
	ds_read_b128 v[216:219], v153 offset:56320
	global_load_lds_dwordx4 v[192:193], off
	s_add_i32 m0, s22, 0x2000
	s_add_u32 s22, s26, 0xb0080
	v_lshl_add_u64 v[192:193], v[220:221], 0, s[16:17]
	s_addc_u32 s23, s27, 0
	s_add_i32 s26, s58, s37
	global_load_lds_dwordx4 v[192:193], off
	s_mov_b32 m0, s26
	s_nop 0
	global_load_lds_dwordx4 v130, s[22:23]
	s_add_i32 m0, s26, 0x2000
	s_nop 0
	global_load_lds_dwordx4 v134, s[22:23]
	s_waitcnt vmcnt(6)
	s_waitcnt lgkmcnt(0)
	s_barrier
	s_setprio 1
	s_waitcnt lgkmcnt(0)
	v_mfma_f32_16x16x32_bf16 v[60:63], v[144:147], v[184:187], v[60:63]
	v_mfma_f32_16x16x32_bf16 v[56:59], v[160:163], v[184:187], v[56:59]
	v_mfma_f32_16x16x32_bf16 v[44:47], v[144:147], v[196:199], v[44:47]
	v_mfma_f32_16x16x32_bf16 v[40:43], v[160:163], v[196:199], v[40:43]
	v_mfma_f32_16x16x32_bf16 v[28:31], v[144:147], v[204:207], v[28:31]
	v_mfma_f32_16x16x32_bf16 v[24:27], v[160:163], v[204:207], v[24:27]
	v_mfma_f32_16x16x32_bf16 v[12:15], v[144:147], v[212:215], v[12:15]
	v_mfma_f32_16x16x32_bf16 v[8:11], v[160:163], v[212:215], v[8:11]
	v_mfma_f32_16x16x32_bf16 v[60:63], v[156:159], v[188:191], v[60:63]
	v_mfma_f32_16x16x32_bf16 v[56:59], v[164:167], v[188:191], v[56:59]
	v_mfma_f32_16x16x32_bf16 v[44:47], v[156:159], v[200:203], v[44:47]
	v_mfma_f32_16x16x32_bf16 v[40:43], v[164:167], v[200:203], v[40:43]
	v_mfma_f32_16x16x32_bf16 v[28:31], v[156:159], v[208:211], v[28:31]
	v_mfma_f32_16x16x32_bf16 v[24:27], v[164:167], v[208:211], v[24:27]
	v_mfma_f32_16x16x32_bf16 v[12:15], v[156:159], v[216:219], v[12:15]
	v_mfma_f32_16x16x32_bf16 v[8:11], v[164:167], v[216:219], v[8:11]
	s_setprio 0
	s_setprio 1
	v_mfma_f32_16x16x32_bf16 v[52:55], v[168:171], v[184:187], v[52:55]
	v_mfma_f32_16x16x32_bf16 v[48:51], v[176:179], v[184:187], v[48:51]
	v_mfma_f32_16x16x32_bf16 v[36:39], v[168:171], v[196:199], v[36:39]
	v_mfma_f32_16x16x32_bf16 v[32:35], v[176:179], v[196:199], v[32:35]
	v_mfma_f32_16x16x32_bf16 v[20:23], v[168:171], v[204:207], v[20:23]
	v_mfma_f32_16x16x32_bf16 v[16:19], v[176:179], v[204:207], v[16:19]
	v_mfma_f32_16x16x32_bf16 v[4:7], v[168:171], v[212:215], v[4:7]
	v_mfma_f32_16x16x32_bf16 v[0:3], v[176:179], v[212:215], v[0:3]
	v_mfma_f32_16x16x32_bf16 v[52:55], v[172:175], v[188:191], v[52:55]
	v_mfma_f32_16x16x32_bf16 v[48:51], v[180:183], v[188:191], v[48:51]
	v_mfma_f32_16x16x32_bf16 v[36:39], v[172:175], v[200:203], v[36:39]
	v_mfma_f32_16x16x32_bf16 v[32:35], v[180:183], v[200:203], v[32:35]
	v_mfma_f32_16x16x32_bf16 v[20:23], v[172:175], v[208:211], v[20:23]
	v_mfma_f32_16x16x32_bf16 v[16:19], v[180:183], v[208:211], v[16:19]
	v_mfma_f32_16x16x32_bf16 v[4:7], v[172:175], v[216:219], v[4:7]
	v_mfma_f32_16x16x32_bf16 v[0:3], v[180:183], v[216:219], v[0:3]
	s_setprio 0
	s_barrier
	s_add_i32 m0, s43, 0xffffff80
	s_nop 0
	global_load_lds_dwordx4 v128, s[98:99] offset:128
	s_add_i32 m0, s44, 0xffffff80
	s_nop 0
	global_load_lds_dwordx4 v132, s[98:99] offset:128
	s_add_i32 s56, s56, 2
	s_add_u32 s54, s54, 0x100
	s_addc_u32 s55, s55, 0
	s_cmp_gt_u32 s56, 41
	s_mov_b64 s[22:23], s[24:25]
	s_cbranch_scc0 .LBB0_3401
	s_and_b64 vcc, exec, s[18:19]
	s_cbranch_vccz .LBB0_3404
	s_barrier
